# GEMM DMA-issuing k-step body raised to s_setprio 2 from the top of the body (covers its LDS-read issue), other body unchanged
# baseline (speedup 1.0000x reference)
; DEVI f32x4 mfma16(bf16x8 a, bf16x8 b, f32x4 c) { return __builtin_amdgcn_mfma_f32_16x16x32_bf16(a, b, c, 0, 0, 0); }
; DEVI void gemm_core3(f32x4 (&acc)[8][4], const bf* __restrict__ A, int lda, const bf* __restrict__ Bt, int ldb, int K, char* smem) {
;     ...
;   for (int kt = 0; kt < nk; ++kt) {
;     const int k1 = min((kt + 1) * 32, klast);
;     const int sn = ((kt + 1) & 1) * STG;
;     const int so = (kt & 1) * STG;
;     bf16x8 bfr[4], af[8];
; #pragma unroll
;     for (int n = 0; n < 4; ++n) bfr[n] = *reinterpret_cast<const bf16x8*>(bbase + so + n * 16 * 64);
; #pragma unroll
;     for (int m = 0; m < 8; ++m) af[m] = *reinterpret_cast<const bf16x8*>(abase + so + m * 16 * 64);
; #pragma unroll
;     for (int i = 0; i < 4; ++i) glds16(Ap + i * sa + k1, dbase + sn + i * 4096);
; #pragma unroll
;     for (int i = 0; i < 2; ++i) glds16(Bp + i * sb + k1, dbase + sn + ASZ + i * 4096);
;     __builtin_amdgcn_s_setprio(1);
; #pragma unroll
;     for (int m = 0; m < 8; ++m)
; #pragma unroll
;       for (int n = 0; n < 4; ++n) acc[m][n] = mfma16(af[m], bfr[n], acc[m][n]);
;     __builtin_amdgcn_s_setprio(0);
;     __syncthreads();
;   }
.Lg3_loop_173:
	v_add_u32_e32 v216, s10, v146
	v_add_u32_e32 v217, s10, v2
	ds_read_b128 v[148:151], v217 offset:16384
	ds_read_b128 v[166:169], v216
	ds_read_b128 v[154:157], v217 offset:17408
	ds_read_b128 v[158:161], v217 offset:18432
	ds_read_b128 v[162:165], v217 offset:19456
	ds_read_b128 v[170:173], v216 offset:1024
	ds_read_b128 v[174:177], v216 offset:2048
	ds_read_b128 v[192:195], v216 offset:3072
	ds_read_b128 v[196:199], v216 offset:4096
	ds_read_b128 v[204:207], v216 offset:5120
	ds_read_b128 v[208:211], v216 offset:6144
	ds_read_b128 v[212:215], v216 offset:7168
	s_setprio 1
	s_waitcnt lgkmcnt(10)
	v_mfma_f32_16x16x32_bf16 v[128:131], v[166:169], v[148:151], v[128:131]
	s_waitcnt lgkmcnt(9)
	v_mfma_f32_16x16x32_bf16 v[124:127], v[166:169], v[154:157], v[124:127]
	s_waitcnt lgkmcnt(8)
	v_mfma_f32_16x16x32_bf16 v[120:123], v[166:169], v[158:161], v[120:123]
	s_waitcnt lgkmcnt(7)
	v_mfma_f32_16x16x32_bf16 v[116:119], v[166:169], v[162:165], v[116:119]
	s_waitcnt lgkmcnt(6)
	v_mfma_f32_16x16x32_bf16 v[112:115], v[170:173], v[148:151], v[112:115]
	v_mfma_f32_16x16x32_bf16 v[108:111], v[170:173], v[154:157], v[108:111]
	v_mfma_f32_16x16x32_bf16 v[104:107], v[170:173], v[158:161], v[104:107]
	v_mfma_f32_16x16x32_bf16 v[100:103], v[170:173], v[162:165], v[100:103]
	s_waitcnt lgkmcnt(5)
	v_mfma_f32_16x16x32_bf16 v[96:99], v[174:177], v[148:151], v[96:99]
	v_mfma_f32_16x16x32_bf16 v[92:95], v[174:177], v[154:157], v[92:95]
	v_mfma_f32_16x16x32_bf16 v[88:91], v[174:177], v[158:161], v[88:91]
	v_mfma_f32_16x16x32_bf16 v[84:87], v[174:177], v[162:165], v[84:87]
	s_waitcnt lgkmcnt(4)
	v_mfma_f32_16x16x32_bf16 v[80:83], v[192:195], v[148:151], v[80:83]
	v_mfma_f32_16x16x32_bf16 v[76:79], v[192:195], v[154:157], v[76:79]
	v_mfma_f32_16x16x32_bf16 v[72:75], v[192:195], v[158:161], v[72:75]
	v_mfma_f32_16x16x32_bf16 v[68:71], v[192:195], v[162:165], v[68:71]
	s_waitcnt lgkmcnt(3)
	v_mfma_f32_16x16x32_bf16 v[64:67], v[196:199], v[148:151], v[64:67]
	v_mfma_f32_16x16x32_bf16 v[60:63], v[196:199], v[154:157], v[60:63]
	v_mfma_f32_16x16x32_bf16 v[56:59], v[196:199], v[158:161], v[56:59]
	v_mfma_f32_16x16x32_bf16 v[52:55], v[196:199], v[162:165], v[52:55]
	s_waitcnt lgkmcnt(2)
	v_mfma_f32_16x16x32_bf16 v[48:51], v[204:207], v[148:151], v[48:51]
	v_mfma_f32_16x16x32_bf16 v[44:47], v[204:207], v[154:157], v[44:47]
	v_mfma_f32_16x16x32_bf16 v[40:43], v[204:207], v[158:161], v[40:43]
	v_mfma_f32_16x16x32_bf16 v[36:39], v[204:207], v[162:165], v[36:39]
	s_waitcnt lgkmcnt(1)
	v_mfma_f32_16x16x32_bf16 v[32:35], v[208:211], v[148:151], v[32:35]
	v_mfma_f32_16x16x32_bf16 v[28:31], v[208:211], v[154:157], v[28:31]
	v_mfma_f32_16x16x32_bf16 v[24:27], v[208:211], v[158:161], v[24:27]
	v_mfma_f32_16x16x32_bf16 v[20:23], v[208:211], v[162:165], v[20:23]
	s_waitcnt lgkmcnt(0)
	v_mfma_f32_16x16x32_bf16 v[16:19], v[212:215], v[148:151], v[16:19]
	v_mfma_f32_16x16x32_bf16 v[12:15], v[212:215], v[154:157], v[12:15]
	v_mfma_f32_16x16x32_bf16 v[8:11], v[212:215], v[158:161], v[8:11]
	v_mfma_f32_16x16x32_bf16 v[4:7], v[212:215], v[162:165], v[4:7]
	s_setprio 0
	s_add_i32 s10, s10, 0x6000
	s_cmp_lg_u32 s10, 0x12000
	s_cselect_b32 s10, s10, 0
	s_waitcnt vmcnt(0)
	s_barrier
	s_setprio 2
	v_add_u32_e32 v216, s10, v146
	v_add_u32_e32 v217, s10, v2
	ds_read_b128 v[148:151], v217 offset:16384
	ds_read_b128 v[166:169], v216
	ds_read_b128 v[154:157], v217 offset:17408
	ds_read_b128 v[158:161], v217 offset:18432
	ds_read_b128 v[162:165], v217 offset:19456
	ds_read_b128 v[170:173], v216 offset:1024
	ds_read_b128 v[174:177], v216 offset:2048
	ds_read_b128 v[192:195], v216 offset:3072
	ds_read_b128 v[196:199], v216 offset:4096
	ds_read_b128 v[204:207], v216 offset:5120
	ds_read_b128 v[208:211], v216 offset:6144
	ds_read_b128 v[212:215], v216 offset:7168
	v_readfirstlane_b32 s17, v140
	s_add_i32 s96, s11, 0x6000
	s_cmp_lg_u32 s96, 0x12000
	s_cselect_b32 s96, s96, 0
	s_add_i32 s96, s96, s17
	s_add_i32 s17, s17, s11
	s_waitcnt lgkmcnt(10)
	s_mov_b32 m0, s17
	s_add_i32 s17, s17, 0x1000
	v_mfma_f32_16x16x32_bf16 v[128:131], v[166:169], v[148:151], v[128:131]
	s_waitcnt lgkmcnt(9)
	v_mfma_f32_16x16x32_bf16 v[124:127], v[166:169], v[154:157], v[124:127]
	global_load_lds_dwordx4 v[218:219], off
	v_lshl_add_u64 v[218:219], v[218:219], 0, 64
	s_waitcnt lgkmcnt(8)
	s_mov_b32 m0, s96
	s_add_i32 s96, s96, 0x1000
	v_mfma_f32_16x16x32_bf16 v[120:123], v[166:169], v[158:161], v[120:123]
	s_waitcnt lgkmcnt(7)
	v_mfma_f32_16x16x32_bf16 v[116:119], v[166:169], v[162:165], v[116:119]
	global_load_lds_dwordx4 v[218:219], off
	v_lshl_add_u64 v[218:219], v[218:219], 0, 64
	s_waitcnt lgkmcnt(6)
	v_mfma_f32_16x16x32_bf16 v[112:115], v[170:173], v[148:151], v[112:115]
	s_mov_b32 m0, s17
	s_add_i32 s17, s17, 0x1000
	v_mfma_f32_16x16x32_bf16 v[108:111], v[170:173], v[154:157], v[108:111]
	v_mfma_f32_16x16x32_bf16 v[104:107], v[170:173], v[158:161], v[104:107]
	global_load_lds_dwordx4 v[220:221], off
	v_lshl_add_u64 v[220:221], v[220:221], 0, 64
	s_mov_b32 m0, s96
	s_add_i32 s96, s96, 0x1000
	v_mfma_f32_16x16x32_bf16 v[100:103], v[170:173], v[162:165], v[100:103]
	s_waitcnt lgkmcnt(5)
	v_mfma_f32_16x16x32_bf16 v[96:99], v[174:177], v[148:151], v[96:99]
	global_load_lds_dwordx4 v[220:221], off
	v_lshl_add_u64 v[220:221], v[220:221], 0, 64
	v_mfma_f32_16x16x32_bf16 v[92:95], v[174:177], v[154:157], v[92:95]
	s_mov_b32 m0, s17
	s_add_i32 s17, s17, 0x1000
	v_mfma_f32_16x16x32_bf16 v[88:91], v[174:177], v[158:161], v[88:91]
	v_mfma_f32_16x16x32_bf16 v[84:87], v[174:177], v[162:165], v[84:87]
	global_load_lds_dwordx4 v[222:223], off
	v_lshl_add_u64 v[222:223], v[222:223], 0, 64
	s_waitcnt lgkmcnt(4)
; DEVI f32x4 mfma16(bf16x8 a, bf16x8 b, f32x4 c) { return __builtin_amdgcn_mfma_f32_16x16x32_bf16(a, b, c, 0, 0, 0); }
; DEVI void gemm_core3(f32x4 (&acc)[8][4], const bf* __restrict__ A, int lda, const bf* __restrict__ Bt, int ldb, int K, char* smem) {
;     ...
;   for (int kt = 0; kt < nk; ++kt) {
;     const int k1 = min((kt + 1) * 32, klast);
;     const int sn = ((kt + 1) & 1) * STG;
;     const int so = (kt & 1) * STG;
;     bf16x8 bfr[4], af[8];
; #pragma unroll
;     for (int n = 0; n < 4; ++n) bfr[n] = *reinterpret_cast<const bf16x8*>(bbase + so + n * 16 * 64);
; #pragma unroll
;     for (int m = 0; m < 8; ++m) af[m] = *reinterpret_cast<const bf16x8*>(abase + so + m * 16 * 64);
; #pragma unroll
;     for (int i = 0; i < 4; ++i) glds16(Ap + i * sa + k1, dbase + sn + i * 4096);
; #pragma unroll
;     for (int i = 0; i < 2; ++i) glds16(Bp + i * sb + k1, dbase + sn + ASZ + i * 4096);
;     __builtin_amdgcn_s_setprio(1);
; #pragma unroll
;     for (int m = 0; m < 8; ++m)
; #pragma unroll
;       for (int n = 0; n < 4; ++n) acc[m][n] = mfma16(af[m], bfr[n], acc[m][n]);
;     __builtin_amdgcn_s_setprio(0);
;     __syncthreads();
;   }
	s_mov_b32 m0, s96
	s_add_i32 s96, s96, 0x1000
	v_mfma_f32_16x16x32_bf16 v[80:83], v[192:195], v[148:151], v[80:83]
	v_mfma_f32_16x16x32_bf16 v[76:79], v[192:195], v[154:157], v[76:79]
	global_load_lds_dwordx4 v[222:223], off
	v_lshl_add_u64 v[222:223], v[222:223], 0, 64
	v_mfma_f32_16x16x32_bf16 v[72:75], v[192:195], v[158:161], v[72:75]
	s_mov_b32 m0, s17
	s_add_i32 s17, s17, 0x1000
	v_mfma_f32_16x16x32_bf16 v[68:71], v[192:195], v[162:165], v[68:71]
	s_waitcnt lgkmcnt(3)
	v_mfma_f32_16x16x32_bf16 v[64:67], v[196:199], v[148:151], v[64:67]
	global_load_lds_dwordx4 v[224:225], off
	v_lshl_add_u64 v[224:225], v[224:225], 0, 64
	s_mov_b32 m0, s96
	s_add_i32 s96, s96, 0x1000
	v_mfma_f32_16x16x32_bf16 v[60:63], v[196:199], v[154:157], v[60:63]
	v_mfma_f32_16x16x32_bf16 v[56:59], v[196:199], v[158:161], v[56:59]
	global_load_lds_dwordx4 v[224:225], off
	v_lshl_add_u64 v[224:225], v[224:225], 0, 64
	v_mfma_f32_16x16x32_bf16 v[52:55], v[196:199], v[162:165], v[52:55]
	s_waitcnt lgkmcnt(2)
	s_mov_b32 m0, s17
	s_add_i32 s17, s17, 0x1000
	v_mfma_f32_16x16x32_bf16 v[48:51], v[204:207], v[148:151], v[48:51]
	v_mfma_f32_16x16x32_bf16 v[44:47], v[204:207], v[154:157], v[44:47]
	global_load_lds_dwordx4 v[226:227], off
	v_lshl_add_u64 v[226:227], v[226:227], 0, 64
	s_mov_b32 m0, s96
	s_add_i32 s96, s96, 0x1000
	v_mfma_f32_16x16x32_bf16 v[40:43], v[204:207], v[158:161], v[40:43]
	v_mfma_f32_16x16x32_bf16 v[36:39], v[204:207], v[162:165], v[36:39]
	global_load_lds_dwordx4 v[226:227], off
	v_lshl_add_u64 v[226:227], v[226:227], 0, 64
	s_waitcnt lgkmcnt(1)
	v_mfma_f32_16x16x32_bf16 v[32:35], v[208:211], v[148:151], v[32:35]
	s_mov_b32 m0, s17
	s_add_i32 s17, s17, 0x1000
	v_mfma_f32_16x16x32_bf16 v[28:31], v[208:211], v[154:157], v[28:31]
	v_mfma_f32_16x16x32_bf16 v[24:27], v[208:211], v[158:161], v[24:27]
	global_load_lds_dwordx4 v[228:229], off
	v_lshl_add_u64 v[228:229], v[228:229], 0, 64
	s_mov_b32 m0, s96
	s_add_i32 s96, s96, 0x1000
	v_mfma_f32_16x16x32_bf16 v[20:23], v[208:211], v[162:165], v[20:23]
	s_waitcnt lgkmcnt(0)
	v_mfma_f32_16x16x32_bf16 v[16:19], v[212:215], v[148:151], v[16:19]
	global_load_lds_dwordx4 v[228:229], off
	v_lshl_add_u64 v[228:229], v[228:229], 0, 64
	v_mfma_f32_16x16x32_bf16 v[12:15], v[212:215], v[154:157], v[12:15]
	v_mfma_f32_16x16x32_bf16 v[8:11], v[212:215], v[158:161], v[8:11]
	v_mfma_f32_16x16x32_bf16 v[4:7], v[212:215], v[162:165], v[4:7]
	s_setprio 0
	s_add_i32 s10, s10, 0x6000
	s_cmp_lg_u32 s10, 0x12000
	s_cselect_b32 s10, s10, 0
	s_sub_i32 s11, s11, 0x6000
	s_cmp_lt_i32 s11, 0
	s_cselect_b32 s11, 0xc000, s11
	s_add_i32 s3, s3, 1
	s_cmp_lt_i32 s3, 43
	s_waitcnt vmcnt(1)
	s_barrier
	s_cbranch_scc1 .Lg3_loop_173
	v_add_u32_e32 v216, s10, v146
	v_add_u32_e32 v217, s10, v2
	ds_read_b128 v[148:151], v217 offset:16384
	ds_read_b128 v[166:169], v216
	ds_read_b128 v[154:157], v217 offset:17408
	ds_read_b128 v[158:161], v217 offset:18432
	ds_read_b128 v[162:165], v217 offset:19456
	ds_read_b128 v[170:173], v216 offset:1024
	ds_read_b128 v[174:177], v216 offset:2048
	ds_read_b128 v[192:195], v216 offset:3072
	ds_read_b128 v[196:199], v216 offset:4096
	ds_read_b128 v[204:207], v216 offset:5120
	ds_read_b128 v[208:211], v216 offset:6144
	ds_read_b128 v[212:215], v216 offset:7168
	s_setprio 1
	s_waitcnt lgkmcnt(10)
	v_mfma_f32_16x16x32_bf16 v[128:131], v[166:169], v[148:151], v[128:131]
	s_waitcnt lgkmcnt(9)
	v_mfma_f32_16x16x32_bf16 v[124:127], v[166:169], v[154:157], v[124:127]
	s_waitcnt lgkmcnt(8)
	v_mfma_f32_16x16x32_bf16 v[120:123], v[166:169], v[158:161], v[120:123]
	s_waitcnt lgkmcnt(7)
	v_mfma_f32_16x16x32_bf16 v[116:119], v[166:169], v[162:165], v[116:119]
	s_waitcnt lgkmcnt(6)
	v_mfma_f32_16x16x32_bf16 v[112:115], v[170:173], v[148:151], v[112:115]
	v_mfma_f32_16x16x32_bf16 v[108:111], v[170:173], v[154:157], v[108:111]
	v_mfma_f32_16x16x32_bf16 v[104:107], v[170:173], v[158:161], v[104:107]
	v_mfma_f32_16x16x32_bf16 v[100:103], v[170:173], v[162:165], v[100:103]
	s_waitcnt lgkmcnt(5)
	v_mfma_f32_16x16x32_bf16 v[96:99], v[174:177], v[148:151], v[96:99]
	v_mfma_f32_16x16x32_bf16 v[92:95], v[174:177], v[154:157], v[92:95]
	v_mfma_f32_16x16x32_bf16 v[88:91], v[174:177], v[158:161], v[88:91]
	v_mfma_f32_16x16x32_bf16 v[84:87], v[174:177], v[162:165], v[84:87]
	s_waitcnt lgkmcnt(4)
	v_mfma_f32_16x16x32_bf16 v[80:83], v[192:195], v[148:151], v[80:83]
	v_mfma_f32_16x16x32_bf16 v[76:79], v[192:195], v[154:157], v[76:79]
	v_mfma_f32_16x16x32_bf16 v[72:75], v[192:195], v[158:161], v[72:75]
	v_mfma_f32_16x16x32_bf16 v[68:71], v[192:195], v[162:165], v[68:71]
	s_waitcnt lgkmcnt(3)
	v_mfma_f32_16x16x32_bf16 v[64:67], v[196:199], v[148:151], v[64:67]
	v_mfma_f32_16x16x32_bf16 v[60:63], v[196:199], v[154:157], v[60:63]
	v_mfma_f32_16x16x32_bf16 v[56:59], v[196:199], v[158:161], v[56:59]
	v_mfma_f32_16x16x32_bf16 v[52:55], v[196:199], v[162:165], v[52:55]
	s_waitcnt lgkmcnt(2)
	v_mfma_f32_16x16x32_bf16 v[48:51], v[204:207], v[148:151], v[48:51]
	v_mfma_f32_16x16x32_bf16 v[44:47], v[204:207], v[154:157], v[44:47]
	v_mfma_f32_16x16x32_bf16 v[40:43], v[204:207], v[158:161], v[40:43]
	v_mfma_f32_16x16x32_bf16 v[36:39], v[204:207], v[162:165], v[36:39]
	s_waitcnt lgkmcnt(1)
	v_mfma_f32_16x16x32_bf16 v[32:35], v[208:211], v[148:151], v[32:35]
	v_mfma_f32_16x16x32_bf16 v[28:31], v[208:211], v[154:157], v[28:31]
	v_mfma_f32_16x16x32_bf16 v[24:27], v[208:211], v[158:161], v[24:27]
	v_mfma_f32_16x16x32_bf16 v[20:23], v[208:211], v[162:165], v[20:23]
	s_waitcnt lgkmcnt(0)
	v_mfma_f32_16x16x32_bf16 v[16:19], v[212:215], v[148:151], v[16:19]
	v_mfma_f32_16x16x32_bf16 v[12:15], v[212:215], v[154:157], v[12:15]
	v_mfma_f32_16x16x32_bf16 v[8:11], v[212:215], v[158:161], v[8:11]
	v_mfma_f32_16x16x32_bf16 v[4:7], v[212:215], v[162:165], v[4:7]
	s_setprio 0
	s_add_i32 s10, s10, 0x6000
	s_cmp_lg_u32 s10, 0x12000
	s_cselect_b32 s10, s10, 0
	s_waitcnt vmcnt(0)
	s_barrier
; DEVI f32x4 mfma16(bf16x8 a, bf16x8 b, f32x4 c) { return __builtin_amdgcn_mfma_f32_16x16x32_bf16(a, b, c, 0, 0, 0); }
; DEVI void gemm_core3(f32x4 (&acc)[8][4], const bf* __restrict__ A, int lda, const bf* __restrict__ Bt, int ldb, int K, char* smem) {
;     ...
; #pragma unroll
;     for (int n = 0; n < 4; ++n) bfr[n] = *reinterpret_cast<const bf16x8*>(bbase + so + n * 16 * 64);
; #pragma unroll
;     for (int m = 0; m < 8; ++m) af[m] = *reinterpret_cast<const bf16x8*>(abase + so + m * 16 * 64);
; #pragma unroll
;     for (int i = 0; i < 4; ++i) glds16(Ap + i * sa + k1, dbase + sn + i * 4096);
; #pragma unroll
;     for (int i = 0; i < 2; ++i) glds16(Bp + i * sb + k1, dbase + sn + ASZ + i * 4096);
;     __builtin_amdgcn_s_setprio(1);
; #pragma unroll
;     for (int m = 0; m < 8; ++m)
; #pragma unroll
;       for (int n = 0; n < 4; ++n) acc[m][n] = mfma16(af[m], bfr[n], acc[m][n]);
;     __builtin_amdgcn_s_setprio(0);
; DEVI void plain_tile256(const bf* A, int lda, const bf* Wt, int K, bf* C, int ldc, long row0, int n0, char* smem) {
;     ...
; #pragma unroll
;   for (int m = 0; m < 8; ++m)
; #pragma unroll
;     for (int n = 0; n < 4; ++n) {
;       const int cl = wc * 64 + n * 16 + l15;
; #pragma unroll
;       for (int j = 0; j < 4; ++j) tl[(wr * 128 + m * 16 + quad * 4 + j) * 136 + cl] = f2bf(acc[m][n][j]);
;     }
	v_add_u32_e32 v216, s10, v146
	v_add_u32_e32 v217, s10, v2
	ds_read_b128 v[148:151], v217 offset:16384
	ds_read_b128 v[166:169], v216
	ds_read_b128 v[154:157], v217 offset:17408
	ds_read_b128 v[158:161], v217 offset:18432
	ds_read_b128 v[162:165], v217 offset:19456
	ds_read_b128 v[170:173], v216 offset:1024
	ds_read_b128 v[174:177], v216 offset:2048
	ds_read_b128 v[192:195], v216 offset:3072
	ds_read_b128 v[196:199], v216 offset:4096
	ds_read_b128 v[204:207], v216 offset:5120
	ds_read_b128 v[208:211], v216 offset:6144
	ds_read_b128 v[212:215], v216 offset:7168
	s_setprio 1
	s_waitcnt lgkmcnt(10)
	v_mfma_f32_16x16x32_bf16 v[128:131], v[166:169], v[148:151], v[128:131]
	s_waitcnt lgkmcnt(9)
	v_mfma_f32_16x16x32_bf16 v[124:127], v[166:169], v[154:157], v[124:127]
	s_waitcnt lgkmcnt(8)
	v_mfma_f32_16x16x32_bf16 v[120:123], v[166:169], v[158:161], v[120:123]
	s_waitcnt lgkmcnt(7)
	v_mfma_f32_16x16x32_bf16 v[116:119], v[166:169], v[162:165], v[116:119]
	s_waitcnt lgkmcnt(6)
	v_mfma_f32_16x16x32_bf16 v[112:115], v[170:173], v[148:151], v[112:115]
	v_mfma_f32_16x16x32_bf16 v[108:111], v[170:173], v[154:157], v[108:111]
	v_mfma_f32_16x16x32_bf16 v[104:107], v[170:173], v[158:161], v[104:107]
	v_mfma_f32_16x16x32_bf16 v[100:103], v[170:173], v[162:165], v[100:103]
	s_waitcnt lgkmcnt(5)
	v_mfma_f32_16x16x32_bf16 v[96:99], v[174:177], v[148:151], v[96:99]
	v_mfma_f32_16x16x32_bf16 v[92:95], v[174:177], v[154:157], v[92:95]
	v_mfma_f32_16x16x32_bf16 v[88:91], v[174:177], v[158:161], v[88:91]
	v_mfma_f32_16x16x32_bf16 v[84:87], v[174:177], v[162:165], v[84:87]
	s_waitcnt lgkmcnt(4)
	v_mfma_f32_16x16x32_bf16 v[80:83], v[192:195], v[148:151], v[80:83]
	v_mfma_f32_16x16x32_bf16 v[76:79], v[192:195], v[154:157], v[76:79]
	v_mfma_f32_16x16x32_bf16 v[72:75], v[192:195], v[158:161], v[72:75]
	v_mfma_f32_16x16x32_bf16 v[68:71], v[192:195], v[162:165], v[68:71]
	s_waitcnt lgkmcnt(3)
	v_mfma_f32_16x16x32_bf16 v[64:67], v[196:199], v[148:151], v[64:67]
	v_mfma_f32_16x16x32_bf16 v[60:63], v[196:199], v[154:157], v[60:63]
	v_mfma_f32_16x16x32_bf16 v[56:59], v[196:199], v[158:161], v[56:59]
	v_mfma_f32_16x16x32_bf16 v[52:55], v[196:199], v[162:165], v[52:55]
	s_waitcnt lgkmcnt(2)
	v_mfma_f32_16x16x32_bf16 v[48:51], v[204:207], v[148:151], v[48:51]
	v_mfma_f32_16x16x32_bf16 v[44:47], v[204:207], v[154:157], v[44:47]
	v_mfma_f32_16x16x32_bf16 v[40:43], v[204:207], v[158:161], v[40:43]
	v_mfma_f32_16x16x32_bf16 v[36:39], v[204:207], v[162:165], v[36:39]
	s_waitcnt lgkmcnt(1)
	v_mfma_f32_16x16x32_bf16 v[32:35], v[208:211], v[148:151], v[32:35]
	v_mfma_f32_16x16x32_bf16 v[28:31], v[208:211], v[154:157], v[28:31]
	v_mfma_f32_16x16x32_bf16 v[24:27], v[208:211], v[158:161], v[24:27]
	v_mfma_f32_16x16x32_bf16 v[20:23], v[208:211], v[162:165], v[20:23]
	s_waitcnt lgkmcnt(0)
	v_mfma_f32_16x16x32_bf16 v[16:19], v[212:215], v[148:151], v[16:19]
	v_mfma_f32_16x16x32_bf16 v[12:15], v[212:215], v[154:157], v[12:15]
	v_mfma_f32_16x16x32_bf16 v[8:11], v[212:215], v[158:161], v[8:11]
	v_mfma_f32_16x16x32_bf16 v[4:7], v[212:215], v[162:165], v[4:7]
	s_setprio 0
	s_add_i32 s10, s10, 0x6000
	s_cmp_lg_u32 s10, 0x12000
	s_cselect_b32 s10, s10, 0
	s_waitcnt vmcnt(0)
	s_barrier
	v_and_b32_e32 v2, 0x4f, v1
	v_and_b32_e32 v132, 0xfffff80, v1
	v_lshrrev_b32_e32 v1, 2, v1
	v_and_or_b32 v1, v1, 12, v132
	v_mul_lo_u32 v1, v1, s16
	v_lshl_add_u32 v1, v2, 1, v1
	v_cvt_pk_bf16_f32 v2, v129, s0
	ds_write_b16 v1, v2 offset:272
	v_cvt_pk_bf16_f32 v2, v130, s0
	ds_write_b16 v1, v2 offset:544
	v_cvt_pk_bf16_f32 v2, v131, s0
	ds_write_b16 v1, v2 offset:816
	v_cvt_pk_bf16_f32 v2, v124, s0
	ds_write_b16 v1, v2 offset:32
	v_cvt_pk_bf16_f32 v2, v125, s0
	ds_write_b16 v1, v2 offset:304
	v_cvt_pk_bf16_f32 v2, v126, s0
	ds_write_b16 v1, v2 offset:576
	v_cvt_pk_bf16_f32 v2, v127, s0
	ds_write_b16 v1, v2 offset:848
	v_cvt_pk_bf16_f32 v2, v120, s0
	ds_write_b16 v1, v2 offset:64
	v_cvt_pk_bf16_f32 v2, v121, s0
	ds_write_b16 v1, v2 offset:336
	v_cvt_pk_bf16_f32 v2, v122, s0
	ds_write_b16 v1, v2 offset:608
	v_cvt_pk_bf16_f32 v2, v123, s0
	ds_write_b16 v1, v2 offset:880
	v_cvt_pk_bf16_f32 v2, v116, s0
	ds_write_b16 v1, v2 offset:96
	v_cvt_pk_bf16_f32 v2, v117, s0
	ds_write_b16 v1, v2 offset:368
	v_cvt_pk_bf16_f32 v2, v118, s0
	ds_write_b16 v1, v2 offset:640
	v_cvt_pk_bf16_f32 v2, v119, s0
	ds_write_b16 v1, v2 offset:912
	v_cvt_pk_bf16_f32 v2, v112, s0
	ds_write_b16 v1, v2 offset:4352
	v_cvt_pk_bf16_f32 v2, v113, s0
	ds_write_b16 v1, v2 offset:4624
	v_cvt_pk_bf16_f32 v2, v114, s0
	ds_write_b16 v1, v2 offset:4896
	v_cvt_pk_bf16_f32 v2, v115, s0
	ds_write_b16 v1, v2 offset:5168
	v_cvt_pk_bf16_f32 v2, v108, s0
	ds_write_b16 v1, v2 offset:4384
	v_cvt_pk_bf16_f32 v2, v109, s0
	ds_write_b16 v1, v2 offset:4656
	v_cvt_pk_bf16_f32 v2, v110, s0
	ds_write_b16 v1, v2 offset:4928
	v_cvt_pk_bf16_f32 v2, v111, s0
	ds_write_b16 v1, v2 offset:5200
	v_cvt_pk_bf16_f32 v2, v104, s0
	ds_write_b16 v1, v2 offset:4416
	v_cvt_pk_bf16_f32 v2, v105, s0
	ds_write_b16 v1, v2 offset:4688
	v_cvt_pk_bf16_f32 v2, v106, s0
	ds_write_b16 v1, v2 offset:4960
	v_cvt_pk_bf16_f32 v2, v107, s0
	ds_write_b16 v1, v2 offset:5232
	v_cvt_pk_bf16_f32 v2, v100, s0
	ds_write_b16 v1, v2 offset:4448
	v_cvt_pk_bf16_f32 v2, v101, s0
	ds_write_b16 v1, v2 offset:4720
	v_cvt_pk_bf16_f32 v2, v102, s0
	ds_write_b16 v1, v2 offset:4992
	v_cvt_pk_bf16_f32 v2, v103, s0
	ds_write_b16 v1, v2 offset:5264
	v_cvt_pk_bf16_f32 v2, v96, s0
	ds_write_b16 v1, v2 offset:8704
	v_cvt_pk_bf16_f32 v2, v97, s0
	ds_write_b16 v1, v2 offset:8976
	v_cvt_pk_bf16_f32 v2, v98, s0
	ds_write_b16 v1, v2 offset:9248
	v_cvt_pk_bf16_f32 v2, v99, s0
	ds_write_b16 v1, v2 offset:9520
	v_cvt_pk_bf16_f32 v2, v92, s0
; DEVI void plain_tile256(const bf* A, int lda, const bf* Wt, int K, bf* C, int ldc, long row0, int n0, char* smem) {
;     ...
; #pragma unroll
;   for (int m = 0; m < 8; ++m)
; #pragma unroll
;     for (int n = 0; n < 4; ++n) {
;       const int cl = wc * 64 + n * 16 + l15;
; #pragma unroll
;       for (int j = 0; j < 4; ++j) tl[(wr * 128 + m * 16 + quad * 4 + j) * 136 + cl] = f2bf(acc[m][n][j]);
;     }
;   __syncthreads();
	ds_write_b16 v1, v2 offset:8736
	v_cvt_pk_bf16_f32 v2, v93, s0
	ds_write_b16 v1, v2 offset:9008
	v_cvt_pk_bf16_f32 v2, v94, s0
	ds_write_b16 v1, v2 offset:9280
	v_cvt_pk_bf16_f32 v2, v95, s0
	ds_write_b16 v1, v2 offset:9552
	v_cvt_pk_bf16_f32 v2, v88, s0
	ds_write_b16 v1, v2 offset:8768
	v_cvt_pk_bf16_f32 v2, v89, s0
	ds_write_b16 v1, v2 offset:9040
	v_cvt_pk_bf16_f32 v2, v90, s0
	ds_write_b16 v1, v2 offset:9312
	v_cvt_pk_bf16_f32 v2, v91, s0
	ds_write_b16 v1, v2 offset:9584
	v_cvt_pk_bf16_f32 v2, v84, s0
	ds_write_b16 v1, v2 offset:8800
	v_cvt_pk_bf16_f32 v2, v85, s0
	ds_write_b16 v1, v2 offset:9072
	v_cvt_pk_bf16_f32 v2, v86, s0
	ds_write_b16 v1, v2 offset:9344
	v_cvt_pk_bf16_f32 v2, v87, s0
	ds_write_b16 v1, v2 offset:9616
	v_cvt_pk_bf16_f32 v2, v80, s0
	ds_write_b16 v1, v2 offset:13056
	v_cvt_pk_bf16_f32 v2, v81, s0
	ds_write_b16 v1, v2 offset:13328
	v_cvt_pk_bf16_f32 v2, v82, s0
	ds_write_b16 v1, v2 offset:13600
	v_cvt_pk_bf16_f32 v2, v83, s0
	ds_write_b16 v1, v2 offset:13872
	v_cvt_pk_bf16_f32 v2, v76, s0
	ds_write_b16 v1, v2 offset:13088
	v_cvt_pk_bf16_f32 v2, v77, s0
	ds_write_b16 v1, v2 offset:13360
	v_cvt_pk_bf16_f32 v2, v78, s0
	ds_write_b16 v1, v2 offset:13632
	v_cvt_pk_bf16_f32 v2, v79, s0
	ds_write_b16 v1, v2 offset:13904
	v_cvt_pk_bf16_f32 v2, v72, s0
	ds_write_b16 v1, v2 offset:13120
	v_cvt_pk_bf16_f32 v2, v73, s0
	ds_write_b16 v1, v2 offset:13392
	v_cvt_pk_bf16_f32 v2, v74, s0
	ds_write_b16 v1, v2 offset:13664
	v_cvt_pk_bf16_f32 v2, v75, s0
	ds_write_b16 v1, v2 offset:13936
	v_cvt_pk_bf16_f32 v2, v68, s0
	ds_write_b16 v1, v2 offset:13152
	v_cvt_pk_bf16_f32 v2, v69, s0
	ds_write_b16 v1, v2 offset:13424
	v_cvt_pk_bf16_f32 v2, v70, s0
	ds_write_b16 v1, v2 offset:13696
	v_cvt_pk_bf16_f32 v2, v71, s0
	ds_write_b16 v1, v2 offset:13968
	v_cvt_pk_bf16_f32 v2, v64, s0
	ds_write_b16 v1, v2 offset:17408
	v_cvt_pk_bf16_f32 v2, v65, s0
	ds_write_b16 v1, v2 offset:17680
	v_cvt_pk_bf16_f32 v2, v66, s0
	ds_write_b16 v1, v2 offset:17952
	v_cvt_pk_bf16_f32 v2, v67, s0
	ds_write_b16 v1, v2 offset:18224
	v_cvt_pk_bf16_f32 v2, v60, s0
	ds_write_b16 v1, v2 offset:17440
	v_cvt_pk_bf16_f32 v2, v61, s0
	ds_write_b16 v1, v2 offset:17712
	v_cvt_pk_bf16_f32 v2, v62, s0
	ds_write_b16 v1, v2 offset:17984
	v_cvt_pk_bf16_f32 v2, v63, s0
	ds_write_b16 v1, v2 offset:18256
	v_cvt_pk_bf16_f32 v2, v56, s0
	ds_write_b16 v1, v2 offset:17472
	v_cvt_pk_bf16_f32 v2, v57, s0
	ds_write_b16 v1, v2 offset:17744
	v_cvt_pk_bf16_f32 v2, v58, s0
	ds_write_b16 v1, v2 offset:18016
	v_cvt_pk_bf16_f32 v2, v59, s0
	ds_write_b16 v1, v2 offset:18288
	v_cvt_pk_bf16_f32 v2, v52, s0
	ds_write_b16 v1, v2 offset:17504
	v_cvt_pk_bf16_f32 v2, v53, s0
	ds_write_b16 v1, v2 offset:17776
	v_cvt_pk_bf16_f32 v2, v54, s0
	ds_write_b16 v1, v2 offset:18048
	v_cvt_pk_bf16_f32 v2, v55, s0
	ds_write_b16 v1, v2 offset:18320
	v_cvt_pk_bf16_f32 v2, v48, s0
	ds_write_b16 v1, v2 offset:21760
	v_cvt_pk_bf16_f32 v2, v49, s0
	ds_write_b16 v1, v2 offset:22032
	v_cvt_pk_bf16_f32 v2, v50, s0
	ds_write_b16 v1, v2 offset:22304
	v_cvt_pk_bf16_f32 v2, v51, s0
	ds_write_b16 v1, v2 offset:22576
	v_cvt_pk_bf16_f32 v2, v44, s0
	ds_write_b16 v1, v2 offset:21792
	v_cvt_pk_bf16_f32 v2, v45, s0
	ds_write_b16 v1, v2 offset:22064
	v_cvt_pk_bf16_f32 v2, v46, s0
	ds_write_b16 v1, v2 offset:22336
	v_cvt_pk_bf16_f32 v2, v47, s0
	ds_write_b16 v1, v2 offset:22608
	v_cvt_pk_bf16_f32 v2, v40, s0
	ds_write_b16 v1, v2 offset:21824
	v_cvt_pk_bf16_f32 v2, v41, s0
	ds_write_b16 v1, v2 offset:22096
	v_cvt_pk_bf16_f32 v2, v42, s0
	ds_write_b16 v1, v2 offset:22368
	v_cvt_pk_bf16_f32 v2, v43, s0
	ds_write_b16 v1, v2 offset:22640
	v_cvt_pk_bf16_f32 v2, v36, s0
	ds_write_b16 v1, v2 offset:21856
	v_cvt_pk_bf16_f32 v2, v37, s0
	ds_write_b16 v1, v2 offset:22128
	v_cvt_pk_bf16_f32 v2, v38, s0
	ds_write_b16 v1, v2 offset:22400
	v_cvt_pk_bf16_f32 v2, v39, s0
	ds_write_b16 v1, v2 offset:22672
	v_cvt_pk_bf16_f32 v2, v32, s0
	ds_write_b16 v1, v2 offset:26112
	v_cvt_pk_bf16_f32 v2, v33, s0
	ds_write_b16 v1, v2 offset:26384
	v_cvt_pk_bf16_f32 v2, v34, s0
	ds_write_b16 v1, v2 offset:26656
	v_cvt_pk_bf16_f32 v2, v35, s0
	ds_write_b16 v1, v2 offset:26928
	v_cvt_pk_bf16_f32 v2, v28, s0
	ds_write_b16 v1, v2 offset:26144
	v_cvt_pk_bf16_f32 v2, v29, s0
	ds_write_b16 v1, v2 offset:26416
	v_cvt_pk_bf16_f32 v2, v30, s0
	ds_write_b16 v1, v2 offset:26688
	v_cvt_pk_bf16_f32 v2, v31, s0
	ds_write_b16 v1, v2 offset:26960
	v_cvt_pk_bf16_f32 v2, v24, s0
	ds_write_b16 v1, v2 offset:26176
	v_cvt_pk_bf16_f32 v2, v25, s0
	ds_write_b16 v1, v2 offset:26448
	v_cvt_pk_bf16_f32 v2, v26, s0
	ds_write_b16 v1, v2 offset:26720
	v_cvt_pk_bf16_f32 v2, v27, s0
	ds_write_b16 v1, v2 offset:26992
	v_cvt_pk_bf16_f32 v2, v20, s0
	ds_write_b16 v1, v2 offset:26208
	v_cvt_pk_bf16_f32 v2, v21, s0
	ds_write_b16 v1, v2 offset:26480
	v_cvt_pk_bf16_f32 v2, v22, s0
	ds_write_b16 v1, v2 offset:26752
	v_cvt_pk_bf16_f32 v2, v23, s0
	ds_write_b16 v1, v2 offset:27024
	v_cvt_pk_bf16_f32 v2, v16, s0
	ds_write_b16 v1, v2 offset:30464
	v_cvt_pk_bf16_f32 v2, v17, s0
	ds_write_b16 v1, v2 offset:30736
	v_cvt_pk_bf16_f32 v2, v18, s0
	ds_write_b16 v1, v2 offset:31008
	v_cvt_pk_bf16_f32 v2, v19, s0
	ds_write_b16 v1, v2 offset:31280
	v_cvt_pk_bf16_f32 v2, v12, s0
	ds_write_b16 v1, v2 offset:30496
	v_cvt_pk_bf16_f32 v2, v13, s0
	ds_write_b16 v1, v2 offset:30768
	v_cvt_pk_bf16_f32 v2, v14, s0
	ds_write_b16 v1, v2 offset:31040
	v_cvt_pk_bf16_f32 v2, v15, s0
	ds_write_b16 v1, v2 offset:31312
	v_cvt_pk_bf16_f32 v2, v8, s0
	ds_write_b16 v1, v2 offset:30528
	v_cvt_pk_bf16_f32 v2, v9, s0
	ds_write_b16 v1, v2 offset:30800
	v_cvt_pk_bf16_f32 v2, v10, s0
	ds_write_b16 v1, v2 offset:31072
	v_cvt_pk_bf16_f32 v2, v11, s0
	ds_write_b16 v1, v2 offset:31344
	v_cvt_pk_bf16_f32 v2, v4, s0
	ds_write_b16 v1, v2 offset:30560
	v_cvt_pk_bf16_f32 v2, v5, s0
	ds_write_b16 v1, v2 offset:30832
	v_cvt_pk_bf16_f32 v2, v6, s0
	v_cvt_pk_bf16_f32 v128, v128, s0
	ds_write_b16 v1, v2 offset:31104
	v_cvt_pk_bf16_f32 v2, v7, s0
	ds_write_b16 v1, v128
	ds_write_b16 v1, v2 offset:31376
	v_mov_b32_e32 v1, v178
	s_waitcnt lgkmcnt(0)
	s_barrier
; DEVI int get_tid() { int t = threadIdx.x; asm volatile("" : "+v"(t)); return t; }
; template <int BN>
; DEVI void tile_store256(const char* smem, bf* __restrict__ C, long ldc, long row0, int col0) {
;   constexpr int LDT = BN + 8;
;   constexpr int CPR = BN / 8;
;   const int tid = get_tid();
; #pragma unroll
;   for (int i = 0; i < CPR; ++i) {
;     const int q = tid + 256 * i;
;     const int r = q / CPR, c = q - r * CPR;
;     u32x4 v = *reinterpret_cast<const u32x4*>(smem + (r * LDT + c * 8) * 2);
;     *reinterpret_cast<u32x4*>(C + (row0 + r) * ldc + col0 + c * 8) = v;
;   }
; }
	v_readlane_b32 s56, v251, 58
	v_ashrrev_i32_e32 v2, 31, v1
	v_lshrrev_b32_e32 v2, 28, v2
	v_add_u32_e32 v2, v1, v2
	v_ashrrev_i32_e32 v8, 4, v2
	s_lshl_b64 s[10:11], s[34:35], 1
	v_readlane_b32 s60, v251, 62
	v_lshlrev_b32_e32 v4, 7, v8
	v_lshlrev_b32_e32 v5, 3, v1
	v_ashrrev_i32_e32 v9, 31, v8
	v_readlane_b32 s61, v251, 63
	s_add_u32 s10, s60, s10
	v_mul_lo_u32 v2, v8, s39
	v_sub_u32_e32 v10, v5, v4
	v_lshl_add_u64 v[8:9], s[12:13], 0, v[8:9]
	s_addc_u32 s11, s61, s11
	v_add_lshl_u32 v2, v10, v2, 1
	v_lshlrev_b64 v[8:9], 11, v[8:9]
	ds_read_b128 v[4:7], v2
	v_lshl_add_u64 v[8:9], s[10:11], 0, v[8:9]
	v_ashrrev_i32_e32 v11, 31, v10
	v_add_u32_e32 v2, 0x100, v1
	v_lshl_add_u64 v[12:13], v[10:11], 1, v[8:9]
	v_ashrrev_i32_e32 v8, 31, v2
	v_lshrrev_b32_e32 v8, 28, v8
	v_add_u32_e32 v8, v2, v8
	v_ashrrev_i32_e32 v14, 4, v8
	v_lshlrev_b32_e32 v9, 7, v14
	v_lshlrev_b32_e32 v2, 3, v2
	v_mul_lo_u32 v8, v14, s39
	v_sub_u32_e32 v16, v2, v9
	v_add_lshl_u32 v2, v16, v8, 1
	ds_read_b128 v[8:11], v2
	v_ashrrev_i32_e32 v15, 31, v14
	s_waitcnt lgkmcnt(1)
	global_store_dwordx4 v[12:13], v[4:7], off
	v_ashrrev_i32_e32 v17, 31, v16
	v_add_u32_e32 v2, 0x200, v1
	v_lshl_add_u64 v[4:5], s[12:13], 0, v[14:15]
	v_lshlrev_b64 v[4:5], 11, v[4:5]
	v_lshl_add_u64 v[4:5], s[10:11], 0, v[4:5]
	v_lshl_add_u64 v[4:5], v[16:17], 1, v[4:5]
	s_waitcnt lgkmcnt(0)
	global_store_dwordx4 v[4:5], v[8:11], off
	v_ashrrev_i32_e32 v4, 31, v2
	v_lshrrev_b32_e32 v4, 28, v4
	v_add_u32_e32 v4, v2, v4
	v_ashrrev_i32_e32 v8, 4, v4
	v_lshlrev_b32_e32 v5, 7, v8
	v_lshlrev_b32_e32 v2, 3, v2
	v_ashrrev_i32_e32 v9, 31, v8
	v_mul_lo_u32 v4, v8, s39
	v_sub_u32_e32 v10, v2, v5
	v_lshl_add_u64 v[8:9], s[12:13], 0, v[8:9]
	v_add_lshl_u32 v2, v10, v4, 1
	v_lshlrev_b64 v[8:9], 11, v[8:9]
	ds_read_b128 v[4:7], v2
	v_lshl_add_u64 v[8:9], s[10:11], 0, v[8:9]
	v_ashrrev_i32_e32 v11, 31, v10
	v_add_u32_e32 v2, 0x300, v1
	v_lshl_add_u64 v[12:13], v[10:11], 1, v[8:9]
	v_ashrrev_i32_e32 v8, 31, v2
	v_lshrrev_b32_e32 v8, 28, v8
	v_add_u32_e32 v8, v2, v8
	v_ashrrev_i32_e32 v14, 4, v8
	v_lshlrev_b32_e32 v9, 7, v14
	v_lshlrev_b32_e32 v2, 3, v2
	v_mul_lo_u32 v8, v14, s39
	v_sub_u32_e32 v16, v2, v9
	v_add_lshl_u32 v2, v16, v8, 1
	ds_read_b128 v[8:11], v2
	v_ashrrev_i32_e32 v15, 31, v14
	s_waitcnt lgkmcnt(1)
	global_store_dwordx4 v[12:13], v[4:7], off
	v_ashrrev_i32_e32 v17, 31, v16
	v_add_u32_e32 v2, 0x400, v1
	v_lshl_add_u64 v[4:5], s[12:13], 0, v[14:15]
	v_lshlrev_b64 v[4:5], 11, v[4:5]
	v_lshl_add_u64 v[4:5], s[10:11], 0, v[4:5]
	v_lshl_add_u64 v[4:5], v[16:17], 1, v[4:5]
	s_waitcnt lgkmcnt(0)
	global_store_dwordx4 v[4:5], v[8:11], off
	v_ashrrev_i32_e32 v4, 31, v2
	v_lshrrev_b32_e32 v4, 28, v4
	v_add_u32_e32 v4, v2, v4
	v_ashrrev_i32_e32 v8, 4, v4
	v_lshlrev_b32_e32 v5, 7, v8
	v_lshlrev_b32_e32 v2, 3, v2
	v_ashrrev_i32_e32 v9, 31, v8
	v_mul_lo_u32 v4, v8, s39
	v_sub_u32_e32 v10, v2, v5
	v_lshl_add_u64 v[8:9], s[12:13], 0, v[8:9]
	v_add_lshl_u32 v2, v10, v4, 1
	v_lshlrev_b64 v[8:9], 11, v[8:9]
	ds_read_b128 v[4:7], v2
	v_lshl_add_u64 v[8:9], s[10:11], 0, v[8:9]
	v_ashrrev_i32_e32 v11, 31, v10
	v_add_u32_e32 v2, 0x500, v1
	v_lshl_add_u64 v[12:13], v[10:11], 1, v[8:9]
	v_ashrrev_i32_e32 v8, 31, v2
	v_lshrrev_b32_e32 v8, 28, v8
	v_add_u32_e32 v8, v2, v8
	v_ashrrev_i32_e32 v14, 4, v8
	v_lshlrev_b32_e32 v9, 7, v14
	v_lshlrev_b32_e32 v2, 3, v2
	v_mul_lo_u32 v8, v14, s39
	v_sub_u32_e32 v16, v2, v9
	v_add_lshl_u32 v2, v16, v8, 1
	ds_read_b128 v[8:11], v2
	v_ashrrev_i32_e32 v15, 31, v14
	s_waitcnt lgkmcnt(1)
	global_store_dwordx4 v[12:13], v[4:7], off
	v_ashrrev_i32_e32 v17, 31, v16
	v_add_u32_e32 v2, 0x600, v1
	v_lshl_add_u64 v[4:5], s[12:13], 0, v[14:15]
	v_lshlrev_b64 v[4:5], 11, v[4:5]
	v_lshl_add_u64 v[4:5], s[10:11], 0, v[4:5]
	v_lshl_add_u64 v[4:5], v[16:17], 1, v[4:5]
	s_waitcnt lgkmcnt(0)
	global_store_dwordx4 v[4:5], v[8:11], off
	v_ashrrev_i32_e32 v4, 31, v2
	v_lshrrev_b32_e32 v4, 28, v4
	v_add_u32_e32 v4, v2, v4
	v_ashrrev_i32_e32 v8, 4, v4
	v_lshlrev_b32_e32 v5, 7, v8
	v_lshlrev_b32_e32 v2, 3, v2
	v_ashrrev_i32_e32 v9, 31, v8
	v_mul_lo_u32 v4, v8, s39
	v_sub_u32_e32 v10, v2, v5
	v_lshl_add_u64 v[8:9], s[12:13], 0, v[8:9]
	v_add_lshl_u32 v2, v10, v4, 1
	v_lshlrev_b64 v[8:9], 11, v[8:9]
	ds_read_b128 v[4:7], v2
	v_lshl_add_u64 v[8:9], s[10:11], 0, v[8:9]
	v_ashrrev_i32_e32 v11, 31, v10
	v_add_u32_e32 v2, 0x700, v1
	v_lshl_add_u64 v[12:13], v[10:11], 1, v[8:9]
	v_ashrrev_i32_e32 v8, 31, v2
	v_lshrrev_b32_e32 v8, 28, v8
	v_add_u32_e32 v8, v2, v8
	v_ashrrev_i32_e32 v14, 4, v8
	v_lshlrev_b32_e32 v9, 7, v14
	v_lshlrev_b32_e32 v2, 3, v2
	v_mul_lo_u32 v8, v14, s39
	v_sub_u32_e32 v16, v2, v9
	v_add_lshl_u32 v2, v16, v8, 1
	ds_read_b128 v[8:11], v2
	v_ashrrev_i32_e32 v15, 31, v14
	s_waitcnt lgkmcnt(1)
	global_store_dwordx4 v[12:13], v[4:7], off
	v_ashrrev_i32_e32 v17, 31, v16
	v_add_u32_e32 v2, 0x800, v1
	v_lshl_add_u64 v[4:5], s[12:13], 0, v[14:15]
	v_lshlrev_b64 v[4:5], 11, v[4:5]
	v_lshl_add_u64 v[4:5], s[10:11], 0, v[4:5]
	v_lshl_add_u64 v[4:5], v[16:17], 1, v[4:5]
	s_waitcnt lgkmcnt(0)
; DEVI int get_tid() { int t = threadIdx.x; asm volatile("" : "+v"(t)); return t; }
; template <int BN>
; DEVI void tile_store256(const char* smem, bf* __restrict__ C, long ldc, long row0, int col0) {
;   constexpr int LDT = BN + 8;
;   constexpr int CPR = BN / 8;
;   const int tid = get_tid();
; #pragma unroll
;   for (int i = 0; i < CPR; ++i) {
;     const int q = tid + 256 * i;
;     const int r = q / CPR, c = q - r * CPR;
;     u32x4 v = *reinterpret_cast<const u32x4*>(smem + (r * LDT + c * 8) * 2);
;     *reinterpret_cast<u32x4*>(C + (row0 + r) * ldc + col0 + c * 8) = v;
;   }
; }
; DEVI void phase_gemm_plain128(const bf* A, int lda, const bf* Wt, int K, int N, bf* C, int ldc, char* smem) {
;     ...
;   for (int v = blockIdx.x; v < 128 * ntn; v += gridDim.x) {
;     int m2, nt;
;     lat_tile_map256(v, ntn, m2, nt);
;     plain_tile256(A, lda, Wt, K, C, ldc, lat_row0_256(m2), nt * 128, smem);
	global_store_dwordx4 v[4:5], v[8:11], off
	v_ashrrev_i32_e32 v4, 31, v2
	v_lshrrev_b32_e32 v4, 28, v4
	v_add_u32_e32 v4, v2, v4
	v_ashrrev_i32_e32 v8, 4, v4
	v_lshlrev_b32_e32 v5, 7, v8
	v_lshlrev_b32_e32 v2, 3, v2
	v_ashrrev_i32_e32 v9, 31, v8
	v_mul_lo_u32 v4, v8, s39
	v_sub_u32_e32 v10, v2, v5
	v_lshl_add_u64 v[8:9], s[12:13], 0, v[8:9]
	v_add_lshl_u32 v2, v10, v4, 1
	v_lshlrev_b64 v[8:9], 11, v[8:9]
	ds_read_b128 v[4:7], v2
	v_lshl_add_u64 v[8:9], s[10:11], 0, v[8:9]
	v_ashrrev_i32_e32 v11, 31, v10
	v_add_u32_e32 v2, 0x900, v1
	v_lshl_add_u64 v[12:13], v[10:11], 1, v[8:9]
	v_ashrrev_i32_e32 v8, 31, v2
	v_lshrrev_b32_e32 v8, 28, v8
	v_add_u32_e32 v8, v2, v8
	v_ashrrev_i32_e32 v14, 4, v8
	v_lshlrev_b32_e32 v9, 7, v14
	v_lshlrev_b32_e32 v2, 3, v2
	v_mul_lo_u32 v8, v14, s39
	v_sub_u32_e32 v16, v2, v9
	v_add_lshl_u32 v2, v16, v8, 1
	ds_read_b128 v[8:11], v2
	v_ashrrev_i32_e32 v15, 31, v14
	s_waitcnt lgkmcnt(1)
	global_store_dwordx4 v[12:13], v[4:7], off
	v_ashrrev_i32_e32 v17, 31, v16
	v_add_u32_e32 v2, 0xa00, v1
	v_lshl_add_u64 v[4:5], s[12:13], 0, v[14:15]
	v_lshlrev_b64 v[4:5], 11, v[4:5]
	v_lshl_add_u64 v[4:5], s[10:11], 0, v[4:5]
	v_lshl_add_u64 v[4:5], v[16:17], 1, v[4:5]
	s_waitcnt lgkmcnt(0)
	global_store_dwordx4 v[4:5], v[8:11], off
	v_ashrrev_i32_e32 v4, 31, v2
	v_lshrrev_b32_e32 v4, 28, v4
	v_add_u32_e32 v4, v2, v4
	v_ashrrev_i32_e32 v8, 4, v4
	v_lshlrev_b32_e32 v5, 7, v8
	v_lshlrev_b32_e32 v2, 3, v2
	v_ashrrev_i32_e32 v9, 31, v8
	v_mul_lo_u32 v4, v8, s39
	v_sub_u32_e32 v10, v2, v5
	v_lshl_add_u64 v[8:9], s[12:13], 0, v[8:9]
	v_add_lshl_u32 v2, v10, v4, 1
	v_lshlrev_b64 v[8:9], 11, v[8:9]
	ds_read_b128 v[4:7], v2
	v_lshl_add_u64 v[8:9], s[10:11], 0, v[8:9]
	v_ashrrev_i32_e32 v11, 31, v10
	v_add_u32_e32 v2, 0xb00, v1
	v_lshl_add_u64 v[12:13], v[10:11], 1, v[8:9]
	v_ashrrev_i32_e32 v8, 31, v2
	v_lshrrev_b32_e32 v8, 28, v8
	v_add_u32_e32 v8, v2, v8
	v_ashrrev_i32_e32 v14, 4, v8
	v_lshlrev_b32_e32 v9, 7, v14
	v_lshlrev_b32_e32 v2, 3, v2
	v_mul_lo_u32 v8, v14, s39
	v_sub_u32_e32 v16, v2, v9
	v_add_lshl_u32 v2, v16, v8, 1
	ds_read_b128 v[8:11], v2
	v_ashrrev_i32_e32 v15, 31, v14
	s_waitcnt lgkmcnt(1)
	global_store_dwordx4 v[12:13], v[4:7], off
	v_ashrrev_i32_e32 v17, 31, v16
	v_add_u32_e32 v2, 0xc00, v1
	v_lshl_add_u64 v[4:5], s[12:13], 0, v[14:15]
	v_lshlrev_b64 v[4:5], 11, v[4:5]
	v_lshl_add_u64 v[4:5], s[10:11], 0, v[4:5]
	v_lshl_add_u64 v[4:5], v[16:17], 1, v[4:5]
	s_waitcnt lgkmcnt(0)
	global_store_dwordx4 v[4:5], v[8:11], off
	v_ashrrev_i32_e32 v4, 31, v2
	v_lshrrev_b32_e32 v4, 28, v4
	v_add_u32_e32 v4, v2, v4
	v_ashrrev_i32_e32 v8, 4, v4
	v_lshlrev_b32_e32 v5, 7, v8
	v_lshlrev_b32_e32 v2, 3, v2
	v_ashrrev_i32_e32 v9, 31, v8
	v_mul_lo_u32 v4, v8, s39
	v_sub_u32_e32 v10, v2, v5
	v_lshl_add_u64 v[8:9], s[12:13], 0, v[8:9]
	v_add_lshl_u32 v2, v10, v4, 1
	v_lshlrev_b64 v[8:9], 11, v[8:9]
	ds_read_b128 v[4:7], v2
	v_lshl_add_u64 v[8:9], s[10:11], 0, v[8:9]
	v_ashrrev_i32_e32 v11, 31, v10
	v_add_u32_e32 v2, 0xd00, v1
	v_lshl_add_u64 v[12:13], v[10:11], 1, v[8:9]
	v_ashrrev_i32_e32 v8, 31, v2
	v_lshrrev_b32_e32 v8, 28, v8
	v_add_u32_e32 v8, v2, v8
	v_ashrrev_i32_e32 v14, 4, v8
	v_lshlrev_b32_e32 v9, 7, v14
	v_lshlrev_b32_e32 v2, 3, v2
	v_mul_lo_u32 v8, v14, s39
	v_sub_u32_e32 v16, v2, v9
	v_add_lshl_u32 v2, v16, v8, 1
	ds_read_b128 v[8:11], v2
	v_ashrrev_i32_e32 v15, 31, v14
	s_waitcnt lgkmcnt(1)
	global_store_dwordx4 v[12:13], v[4:7], off
	v_ashrrev_i32_e32 v17, 31, v16
	v_add_u32_e32 v2, 0xe00, v1
	v_lshl_add_u64 v[4:5], s[12:13], 0, v[14:15]
	v_lshlrev_b64 v[4:5], 11, v[4:5]
	v_lshl_add_u64 v[4:5], s[10:11], 0, v[4:5]
	v_lshl_add_u64 v[4:5], v[16:17], 1, v[4:5]
	s_waitcnt lgkmcnt(0)
	global_store_dwordx4 v[4:5], v[8:11], off
	v_ashrrev_i32_e32 v4, 31, v2
	v_lshrrev_b32_e32 v4, 28, v4
	v_add_u32_e32 v4, v2, v4
	v_ashrrev_i32_e32 v8, 4, v4
	v_lshlrev_b32_e32 v5, 7, v8
	v_lshlrev_b32_e32 v2, 3, v2
	v_mul_lo_u32 v4, v8, s39
	v_sub_u32_e32 v10, v2, v5
	v_add_lshl_u32 v2, v10, v4, 1
	v_add_u32_e32 v1, 0xf00, v1
	ds_read_b128 v[4:7], v2
	v_ashrrev_i32_e32 v9, 31, v8
	v_ashrrev_i32_e32 v2, 31, v1
	v_lshl_add_u64 v[8:9], s[12:13], 0, v[8:9]
	v_lshrrev_b32_e32 v2, 28, v2
	v_lshlrev_b64 v[8:9], 11, v[8:9]
	v_add_u32_e32 v2, v1, v2
	v_lshl_add_u64 v[8:9], s[10:11], 0, v[8:9]
	v_ashrrev_i32_e32 v11, 31, v10
	v_ashrrev_i32_e32 v14, 4, v2
	v_lshl_add_u64 v[12:13], v[10:11], 1, v[8:9]
	v_lshlrev_b32_e32 v8, 7, v14
	v_lshlrev_b32_e32 v1, 3, v1
	v_mul_lo_u32 v2, v14, s39
	v_sub_u32_e32 v16, v1, v8
	v_add_lshl_u32 v1, v16, v2, 1
	v_ashrrev_i32_e32 v15, 31, v14
	ds_read_b128 v[8:11], v1
	s_waitcnt lgkmcnt(1)
	global_store_dwordx4 v[12:13], v[4:7], off
	v_ashrrev_i32_e32 v17, 31, v16
	v_readlane_b32 s58, v251, 60
	v_lshl_add_u64 v[4:5], s[12:13], 0, v[14:15]
	v_lshlrev_b64 v[4:5], 11, v[4:5]
	v_lshl_add_u64 v[4:5], s[10:11], 0, v[4:5]
	v_readlane_b32 s10, v252, 59
	s_add_i32 s2, s2, s10
	v_readlane_b32 s59, v251, 61
	v_lshl_add_u64 v[4:5], v[16:17], 1, v[4:5]
	s_cmpk_gt_i32 s2, 0x3ff
	v_readlane_b32 s57, v251, 59
	v_readlane_b32 s62, v252, 0
	v_readlane_b32 s63, v252, 1
	v_readlane_b32 s64, v252, 2
	v_readlane_b32 s65, v252, 3
	v_readlane_b32 s66, v252, 4
	v_readlane_b32 s67, v252, 5
	v_readlane_b32 s68, v252, 6
	v_readlane_b32 s69, v252, 7
	v_readlane_b32 s70, v252, 8
	v_readlane_b32 s71, v252, 9
	s_waitcnt lgkmcnt(0)
	global_store_dwordx4 v[4:5], v[8:11], off
	s_barrier
	v_readlane_b32 s11, v252, 60
	s_cbranch_scc0 .LBB0_172

; DEVI f32x4 mfma16(bf16x8 a, bf16x8 b, f32x4 c) { return __builtin_amdgcn_mfma_f32_16x16x32_bf16(a, b, c, 0, 0, 0); }
; DEVI void gemm_core3(f32x4 (&acc)[8][4], const bf* __restrict__ A, int lda, const bf* __restrict__ Bt, int ldb, int K, char* smem) {
;     ...
;   for (int kt = 0; kt < nk; ++kt) {
;     const int k1 = min((kt + 1) * 32, klast);
;     const int sn = ((kt + 1) & 1) * STG;
;     const int so = (kt & 1) * STG;
;     bf16x8 bfr[4], af[8];
; #pragma unroll
;     for (int n = 0; n < 4; ++n) bfr[n] = *reinterpret_cast<const bf16x8*>(bbase + so + n * 16 * 64);
; #pragma unroll
;     for (int m = 0; m < 8; ++m) af[m] = *reinterpret_cast<const bf16x8*>(abase + so + m * 16 * 64);
; #pragma unroll
;     for (int i = 0; i < 4; ++i) glds16(Ap + i * sa + k1, dbase + sn + i * 4096);
; #pragma unroll
;     for (int i = 0; i < 2; ++i) glds16(Bp + i * sb + k1, dbase + sn + ASZ + i * 4096);
;     __builtin_amdgcn_s_setprio(1);
; #pragma unroll
;     for (int m = 0; m < 8; ++m)
; #pragma unroll
;       for (int n = 0; n < 4; ++n) acc[m][n] = mfma16(af[m], bfr[n], acc[m][n]);
;     __builtin_amdgcn_s_setprio(0);
;     __syncthreads();
;   }
.Lg3_loop_184:
	v_add_u32_e32 v216, s10, v146
	v_add_u32_e32 v217, s10, v2
	ds_read_b128 v[148:151], v217 offset:16384
	ds_read_b128 v[166:169], v216
	ds_read_b128 v[154:157], v217 offset:17408
	ds_read_b128 v[158:161], v217 offset:18432
	ds_read_b128 v[162:165], v217 offset:19456
	ds_read_b128 v[170:173], v216 offset:1024
	ds_read_b128 v[174:177], v216 offset:2048
	ds_read_b128 v[192:195], v216 offset:3072
	ds_read_b128 v[196:199], v216 offset:4096
	ds_read_b128 v[204:207], v216 offset:5120
	ds_read_b128 v[208:211], v216 offset:6144
	ds_read_b128 v[212:215], v216 offset:7168
	s_setprio 1
	s_waitcnt lgkmcnt(10)
	v_mfma_f32_16x16x32_bf16 v[128:131], v[166:169], v[148:151], v[128:131]
	s_waitcnt lgkmcnt(9)
	v_mfma_f32_16x16x32_bf16 v[124:127], v[166:169], v[154:157], v[124:127]
	s_waitcnt lgkmcnt(8)
	v_mfma_f32_16x16x32_bf16 v[120:123], v[166:169], v[158:161], v[120:123]
	s_waitcnt lgkmcnt(7)
	v_mfma_f32_16x16x32_bf16 v[116:119], v[166:169], v[162:165], v[116:119]
	s_waitcnt lgkmcnt(6)
	v_mfma_f32_16x16x32_bf16 v[112:115], v[170:173], v[148:151], v[112:115]
	v_mfma_f32_16x16x32_bf16 v[108:111], v[170:173], v[154:157], v[108:111]
	v_mfma_f32_16x16x32_bf16 v[104:107], v[170:173], v[158:161], v[104:107]
	v_mfma_f32_16x16x32_bf16 v[100:103], v[170:173], v[162:165], v[100:103]
	s_waitcnt lgkmcnt(5)
	v_mfma_f32_16x16x32_bf16 v[96:99], v[174:177], v[148:151], v[96:99]
	v_mfma_f32_16x16x32_bf16 v[92:95], v[174:177], v[154:157], v[92:95]
	v_mfma_f32_16x16x32_bf16 v[88:91], v[174:177], v[158:161], v[88:91]
	v_mfma_f32_16x16x32_bf16 v[84:87], v[174:177], v[162:165], v[84:87]
	s_waitcnt lgkmcnt(4)
	v_mfma_f32_16x16x32_bf16 v[80:83], v[192:195], v[148:151], v[80:83]
	v_mfma_f32_16x16x32_bf16 v[76:79], v[192:195], v[154:157], v[76:79]
	v_mfma_f32_16x16x32_bf16 v[72:75], v[192:195], v[158:161], v[72:75]
	v_mfma_f32_16x16x32_bf16 v[68:71], v[192:195], v[162:165], v[68:71]
	s_waitcnt lgkmcnt(3)
	v_mfma_f32_16x16x32_bf16 v[64:67], v[196:199], v[148:151], v[64:67]
	v_mfma_f32_16x16x32_bf16 v[60:63], v[196:199], v[154:157], v[60:63]
	v_mfma_f32_16x16x32_bf16 v[56:59], v[196:199], v[158:161], v[56:59]
	v_mfma_f32_16x16x32_bf16 v[52:55], v[196:199], v[162:165], v[52:55]
	s_waitcnt lgkmcnt(2)
	v_mfma_f32_16x16x32_bf16 v[48:51], v[204:207], v[148:151], v[48:51]
	v_mfma_f32_16x16x32_bf16 v[44:47], v[204:207], v[154:157], v[44:47]
	v_mfma_f32_16x16x32_bf16 v[40:43], v[204:207], v[158:161], v[40:43]
	v_mfma_f32_16x16x32_bf16 v[36:39], v[204:207], v[162:165], v[36:39]
	s_waitcnt lgkmcnt(1)
	v_mfma_f32_16x16x32_bf16 v[32:35], v[208:211], v[148:151], v[32:35]
	v_mfma_f32_16x16x32_bf16 v[28:31], v[208:211], v[154:157], v[28:31]
	v_mfma_f32_16x16x32_bf16 v[24:27], v[208:211], v[158:161], v[24:27]
	v_mfma_f32_16x16x32_bf16 v[20:23], v[208:211], v[162:165], v[20:23]
	s_waitcnt lgkmcnt(0)
	v_mfma_f32_16x16x32_bf16 v[16:19], v[212:215], v[148:151], v[16:19]
	v_mfma_f32_16x16x32_bf16 v[12:15], v[212:215], v[154:157], v[12:15]
	v_mfma_f32_16x16x32_bf16 v[8:11], v[212:215], v[158:161], v[8:11]
	v_mfma_f32_16x16x32_bf16 v[4:7], v[212:215], v[162:165], v[4:7]
	s_setprio 0
	s_add_i32 s10, s10, 0x6000
	s_cmp_lg_u32 s10, 0x12000
	s_cselect_b32 s10, s10, 0
	s_waitcnt vmcnt(0)
	s_barrier
	s_setprio 2
	v_add_u32_e32 v216, s10, v146
	v_add_u32_e32 v217, s10, v2
	ds_read_b128 v[148:151], v217 offset:16384
	ds_read_b128 v[166:169], v216
	ds_read_b128 v[154:157], v217 offset:17408
	ds_read_b128 v[158:161], v217 offset:18432
	ds_read_b128 v[162:165], v217 offset:19456
	ds_read_b128 v[170:173], v216 offset:1024
	ds_read_b128 v[174:177], v216 offset:2048
	ds_read_b128 v[192:195], v216 offset:3072
	ds_read_b128 v[196:199], v216 offset:4096
	ds_read_b128 v[204:207], v216 offset:5120
	ds_read_b128 v[208:211], v216 offset:6144
	ds_read_b128 v[212:215], v216 offset:7168
	v_readfirstlane_b32 s17, v140
	s_add_i32 s96, s11, 0x6000
	s_cmp_lg_u32 s96, 0x12000
	s_cselect_b32 s96, s96, 0
	s_add_i32 s96, s96, s17
	s_add_i32 s17, s17, s11
	s_waitcnt lgkmcnt(10)
	s_mov_b32 m0, s17
	s_add_i32 s17, s17, 0x1000
	v_mfma_f32_16x16x32_bf16 v[128:131], v[166:169], v[148:151], v[128:131]
	s_waitcnt lgkmcnt(9)
	v_mfma_f32_16x16x32_bf16 v[124:127], v[166:169], v[154:157], v[124:127]
	global_load_lds_dwordx4 v[218:219], off
	v_lshl_add_u64 v[218:219], v[218:219], 0, 64
	s_waitcnt lgkmcnt(8)
	s_mov_b32 m0, s96
	s_add_i32 s96, s96, 0x1000
	v_mfma_f32_16x16x32_bf16 v[120:123], v[166:169], v[158:161], v[120:123]
	s_waitcnt lgkmcnt(7)
	v_mfma_f32_16x16x32_bf16 v[116:119], v[166:169], v[162:165], v[116:119]
	global_load_lds_dwordx4 v[218:219], off
	v_lshl_add_u64 v[218:219], v[218:219], 0, 64
	s_waitcnt lgkmcnt(6)
	v_mfma_f32_16x16x32_bf16 v[112:115], v[170:173], v[148:151], v[112:115]
	s_mov_b32 m0, s17
	s_add_i32 s17, s17, 0x1000
	v_mfma_f32_16x16x32_bf16 v[108:111], v[170:173], v[154:157], v[108:111]
	v_mfma_f32_16x16x32_bf16 v[104:107], v[170:173], v[158:161], v[104:107]
	global_load_lds_dwordx4 v[220:221], off
	v_lshl_add_u64 v[220:221], v[220:221], 0, 64
	s_mov_b32 m0, s96
	s_add_i32 s96, s96, 0x1000
	v_mfma_f32_16x16x32_bf16 v[100:103], v[170:173], v[162:165], v[100:103]
	s_waitcnt lgkmcnt(5)
	v_mfma_f32_16x16x32_bf16 v[96:99], v[174:177], v[148:151], v[96:99]
	global_load_lds_dwordx4 v[220:221], off
	v_lshl_add_u64 v[220:221], v[220:221], 0, 64
	v_mfma_f32_16x16x32_bf16 v[92:95], v[174:177], v[154:157], v[92:95]
	s_mov_b32 m0, s17
	s_add_i32 s17, s17, 0x1000
	v_mfma_f32_16x16x32_bf16 v[88:91], v[174:177], v[158:161], v[88:91]
	v_mfma_f32_16x16x32_bf16 v[84:87], v[174:177], v[162:165], v[84:87]
	global_load_lds_dwordx4 v[222:223], off
	v_lshl_add_u64 v[222:223], v[222:223], 0, 64
	s_waitcnt lgkmcnt(4)
; DEVI f32x4 mfma16(bf16x8 a, bf16x8 b, f32x4 c) { return __builtin_amdgcn_mfma_f32_16x16x32_bf16(a, b, c, 0, 0, 0); }
; DEVI void gemm_core3(f32x4 (&acc)[8][4], const bf* __restrict__ A, int lda, const bf* __restrict__ Bt, int ldb, int K, char* smem) {
;     ...
;   for (int kt = 0; kt < nk; ++kt) {
;     const int k1 = min((kt + 1) * 32, klast);
;     const int sn = ((kt + 1) & 1) * STG;
;     const int so = (kt & 1) * STG;
;     bf16x8 bfr[4], af[8];
; #pragma unroll
;     for (int n = 0; n < 4; ++n) bfr[n] = *reinterpret_cast<const bf16x8*>(bbase + so + n * 16 * 64);
; #pragma unroll
;     for (int m = 0; m < 8; ++m) af[m] = *reinterpret_cast<const bf16x8*>(abase + so + m * 16 * 64);
; #pragma unroll
;     for (int i = 0; i < 4; ++i) glds16(Ap + i * sa + k1, dbase + sn + i * 4096);
; #pragma unroll
;     for (int i = 0; i < 2; ++i) glds16(Bp + i * sb + k1, dbase + sn + ASZ + i * 4096);
;     __builtin_amdgcn_s_setprio(1);
; #pragma unroll
;     for (int m = 0; m < 8; ++m)
; #pragma unroll
;       for (int n = 0; n < 4; ++n) acc[m][n] = mfma16(af[m], bfr[n], acc[m][n]);
;     __builtin_amdgcn_s_setprio(0);
;     __syncthreads();
;   }
	s_mov_b32 m0, s96
	s_add_i32 s96, s96, 0x1000
	v_mfma_f32_16x16x32_bf16 v[80:83], v[192:195], v[148:151], v[80:83]
	v_mfma_f32_16x16x32_bf16 v[76:79], v[192:195], v[154:157], v[76:79]
	global_load_lds_dwordx4 v[222:223], off
	v_lshl_add_u64 v[222:223], v[222:223], 0, 64
	v_mfma_f32_16x16x32_bf16 v[72:75], v[192:195], v[158:161], v[72:75]
	s_mov_b32 m0, s17
	s_add_i32 s17, s17, 0x1000
	v_mfma_f32_16x16x32_bf16 v[68:71], v[192:195], v[162:165], v[68:71]
	s_waitcnt lgkmcnt(3)
	v_mfma_f32_16x16x32_bf16 v[64:67], v[196:199], v[148:151], v[64:67]
	global_load_lds_dwordx4 v[224:225], off
	v_lshl_add_u64 v[224:225], v[224:225], 0, 64
	s_mov_b32 m0, s96
	s_add_i32 s96, s96, 0x1000
	v_mfma_f32_16x16x32_bf16 v[60:63], v[196:199], v[154:157], v[60:63]
	v_mfma_f32_16x16x32_bf16 v[56:59], v[196:199], v[158:161], v[56:59]
	global_load_lds_dwordx4 v[224:225], off
	v_lshl_add_u64 v[224:225], v[224:225], 0, 64
	v_mfma_f32_16x16x32_bf16 v[52:55], v[196:199], v[162:165], v[52:55]
	s_waitcnt lgkmcnt(2)
	s_mov_b32 m0, s17
	s_add_i32 s17, s17, 0x1000
	v_mfma_f32_16x16x32_bf16 v[48:51], v[204:207], v[148:151], v[48:51]
	v_mfma_f32_16x16x32_bf16 v[44:47], v[204:207], v[154:157], v[44:47]
	global_load_lds_dwordx4 v[226:227], off
	v_lshl_add_u64 v[226:227], v[226:227], 0, 64
	s_mov_b32 m0, s96
	s_add_i32 s96, s96, 0x1000
	v_mfma_f32_16x16x32_bf16 v[40:43], v[204:207], v[158:161], v[40:43]
	v_mfma_f32_16x16x32_bf16 v[36:39], v[204:207], v[162:165], v[36:39]
	global_load_lds_dwordx4 v[226:227], off
	v_lshl_add_u64 v[226:227], v[226:227], 0, 64
	s_waitcnt lgkmcnt(1)
	v_mfma_f32_16x16x32_bf16 v[32:35], v[208:211], v[148:151], v[32:35]
	s_mov_b32 m0, s17
	s_add_i32 s17, s17, 0x1000
	v_mfma_f32_16x16x32_bf16 v[28:31], v[208:211], v[154:157], v[28:31]
	v_mfma_f32_16x16x32_bf16 v[24:27], v[208:211], v[158:161], v[24:27]
	global_load_lds_dwordx4 v[228:229], off
	v_lshl_add_u64 v[228:229], v[228:229], 0, 64
	s_mov_b32 m0, s96
	s_add_i32 s96, s96, 0x1000
	v_mfma_f32_16x16x32_bf16 v[20:23], v[208:211], v[162:165], v[20:23]
	s_waitcnt lgkmcnt(0)
	v_mfma_f32_16x16x32_bf16 v[16:19], v[212:215], v[148:151], v[16:19]
	global_load_lds_dwordx4 v[228:229], off
	v_lshl_add_u64 v[228:229], v[228:229], 0, 64
	v_mfma_f32_16x16x32_bf16 v[12:15], v[212:215], v[154:157], v[12:15]
	v_mfma_f32_16x16x32_bf16 v[8:11], v[212:215], v[158:161], v[8:11]
	v_mfma_f32_16x16x32_bf16 v[4:7], v[212:215], v[162:165], v[4:7]
	s_setprio 0
	s_add_i32 s10, s10, 0x6000
	s_cmp_lg_u32 s10, 0x12000
	s_cselect_b32 s10, s10, 0
	s_sub_i32 s11, s11, 0x6000
	s_cmp_lt_i32 s11, 0
	s_cselect_b32 s11, 0xc000, s11
	s_add_i32 s3, s3, 1
	s_cmp_lt_i32 s3, 15
	s_waitcnt vmcnt(1)
	s_barrier
	s_cbranch_scc1 .Lg3_loop_184
	v_add_u32_e32 v216, s10, v146
	v_add_u32_e32 v217, s10, v2
	ds_read_b128 v[148:151], v217 offset:16384
	ds_read_b128 v[166:169], v216
	ds_read_b128 v[154:157], v217 offset:17408
	ds_read_b128 v[158:161], v217 offset:18432
	ds_read_b128 v[162:165], v217 offset:19456
	ds_read_b128 v[170:173], v216 offset:1024
	ds_read_b128 v[174:177], v216 offset:2048
	ds_read_b128 v[192:195], v216 offset:3072
	ds_read_b128 v[196:199], v216 offset:4096
	ds_read_b128 v[204:207], v216 offset:5120
	ds_read_b128 v[208:211], v216 offset:6144
	ds_read_b128 v[212:215], v216 offset:7168
	s_setprio 1
	s_waitcnt lgkmcnt(10)
	v_mfma_f32_16x16x32_bf16 v[128:131], v[166:169], v[148:151], v[128:131]
	s_waitcnt lgkmcnt(9)
	v_mfma_f32_16x16x32_bf16 v[124:127], v[166:169], v[154:157], v[124:127]
	s_waitcnt lgkmcnt(8)
	v_mfma_f32_16x16x32_bf16 v[120:123], v[166:169], v[158:161], v[120:123]
	s_waitcnt lgkmcnt(7)
	v_mfma_f32_16x16x32_bf16 v[116:119], v[166:169], v[162:165], v[116:119]
	s_waitcnt lgkmcnt(6)
	v_mfma_f32_16x16x32_bf16 v[112:115], v[170:173], v[148:151], v[112:115]
	v_mfma_f32_16x16x32_bf16 v[108:111], v[170:173], v[154:157], v[108:111]
	v_mfma_f32_16x16x32_bf16 v[104:107], v[170:173], v[158:161], v[104:107]
	v_mfma_f32_16x16x32_bf16 v[100:103], v[170:173], v[162:165], v[100:103]
	s_waitcnt lgkmcnt(5)
	v_mfma_f32_16x16x32_bf16 v[96:99], v[174:177], v[148:151], v[96:99]
	v_mfma_f32_16x16x32_bf16 v[92:95], v[174:177], v[154:157], v[92:95]
	v_mfma_f32_16x16x32_bf16 v[88:91], v[174:177], v[158:161], v[88:91]
	v_mfma_f32_16x16x32_bf16 v[84:87], v[174:177], v[162:165], v[84:87]
	s_waitcnt lgkmcnt(4)
	v_mfma_f32_16x16x32_bf16 v[80:83], v[192:195], v[148:151], v[80:83]
	v_mfma_f32_16x16x32_bf16 v[76:79], v[192:195], v[154:157], v[76:79]
	v_mfma_f32_16x16x32_bf16 v[72:75], v[192:195], v[158:161], v[72:75]
	v_mfma_f32_16x16x32_bf16 v[68:71], v[192:195], v[162:165], v[68:71]
	s_waitcnt lgkmcnt(3)
	v_mfma_f32_16x16x32_bf16 v[64:67], v[196:199], v[148:151], v[64:67]
	v_mfma_f32_16x16x32_bf16 v[60:63], v[196:199], v[154:157], v[60:63]
	v_mfma_f32_16x16x32_bf16 v[56:59], v[196:199], v[158:161], v[56:59]
	v_mfma_f32_16x16x32_bf16 v[52:55], v[196:199], v[162:165], v[52:55]
	s_waitcnt lgkmcnt(2)
	v_mfma_f32_16x16x32_bf16 v[48:51], v[204:207], v[148:151], v[48:51]
	v_mfma_f32_16x16x32_bf16 v[44:47], v[204:207], v[154:157], v[44:47]
	v_mfma_f32_16x16x32_bf16 v[40:43], v[204:207], v[158:161], v[40:43]
	v_mfma_f32_16x16x32_bf16 v[36:39], v[204:207], v[162:165], v[36:39]
	s_waitcnt lgkmcnt(1)
	v_mfma_f32_16x16x32_bf16 v[32:35], v[208:211], v[148:151], v[32:35]
	v_mfma_f32_16x16x32_bf16 v[28:31], v[208:211], v[154:157], v[28:31]
	v_mfma_f32_16x16x32_bf16 v[24:27], v[208:211], v[158:161], v[24:27]
	v_mfma_f32_16x16x32_bf16 v[20:23], v[208:211], v[162:165], v[20:23]
	s_waitcnt lgkmcnt(0)
	v_mfma_f32_16x16x32_bf16 v[16:19], v[212:215], v[148:151], v[16:19]
	v_mfma_f32_16x16x32_bf16 v[12:15], v[212:215], v[154:157], v[12:15]
	v_mfma_f32_16x16x32_bf16 v[8:11], v[212:215], v[158:161], v[8:11]
	v_mfma_f32_16x16x32_bf16 v[4:7], v[212:215], v[162:165], v[4:7]
	s_setprio 0
	s_add_i32 s10, s10, 0x6000
	s_cmp_lg_u32 s10, 0x12000
	s_cselect_b32 s10, s10, 0
	s_waitcnt vmcnt(0)
	s_barrier
; DEVI float silu_(float x) { return x / (1.f + __expf(-x)); }
; DEVI f32x4 mfma16(bf16x8 a, bf16x8 b, f32x4 c) { return __builtin_amdgcn_mfma_f32_16x16x32_bf16(a, b, c, 0, 0, 0); }
; DEVI void gemm_core3(f32x4 (&acc)[8][4], const bf* __restrict__ A, int lda, const bf* __restrict__ Bt, int ldb, int K, char* smem) {
;     ...
; #pragma unroll
;     for (int n = 0; n < 4; ++n) bfr[n] = *reinterpret_cast<const bf16x8*>(bbase + so + n * 16 * 64);
; #pragma unroll
;     for (int m = 0; m < 8; ++m) af[m] = *reinterpret_cast<const bf16x8*>(abase + so + m * 16 * 64);
; #pragma unroll
;     for (int i = 0; i < 4; ++i) glds16(Ap + i * sa + k1, dbase + sn + i * 4096);
; #pragma unroll
;     for (int i = 0; i < 2; ++i) glds16(Bp + i * sb + k1, dbase + sn + ASZ + i * 4096);
;     __builtin_amdgcn_s_setprio(1);
; #pragma unroll
;     for (int m = 0; m < 8; ++m)
; #pragma unroll
;       for (int n = 0; n < 4; ++n) acc[m][n] = mfma16(af[m], bfr[n], acc[m][n]);
;     __builtin_amdgcn_s_setprio(0);
; DEVI void ffn1_tile256(const P& p, const bf* W, long row0, int n0  , char* smem) {
;     ...
; #pragma unroll
;   for (int m = 0; m < 8; ++m)
; #pragma unroll
;     for (int pr = 0; pr < 2; ++pr) {
;       const int cl = (wc * 2 + pr) * 16 + l15;
; #pragma unroll
;       for (int j = 0; j < 4; ++j) {
;         const int rl = wr * 128 + m * 16 + quad * 4 + j;
;         float a = acc[m][2 * pr][j], b = acc[m][2 * pr + 1][j];
;         tl[rl * 72 + cl] = f2bf(silu_(a) * b);
;       }
	v_add_u32_e32 v216, s10, v146
	v_add_u32_e32 v217, s10, v2
	ds_read_b128 v[148:151], v217 offset:16384
	ds_read_b128 v[166:169], v216
	ds_read_b128 v[154:157], v217 offset:17408
	ds_read_b128 v[158:161], v217 offset:18432
	ds_read_b128 v[162:165], v217 offset:19456
	ds_read_b128 v[170:173], v216 offset:1024
	ds_read_b128 v[174:177], v216 offset:2048
	ds_read_b128 v[192:195], v216 offset:3072
	ds_read_b128 v[196:199], v216 offset:4096
	ds_read_b128 v[204:207], v216 offset:5120
	ds_read_b128 v[208:211], v216 offset:6144
	ds_read_b128 v[212:215], v216 offset:7168
	s_setprio 1
	s_waitcnt lgkmcnt(10)
	v_mfma_f32_16x16x32_bf16 v[128:131], v[166:169], v[148:151], v[128:131]
	s_waitcnt lgkmcnt(9)
	v_mfma_f32_16x16x32_bf16 v[124:127], v[166:169], v[154:157], v[124:127]
	s_waitcnt lgkmcnt(8)
	v_mfma_f32_16x16x32_bf16 v[120:123], v[166:169], v[158:161], v[120:123]
	s_waitcnt lgkmcnt(7)
	v_mfma_f32_16x16x32_bf16 v[116:119], v[166:169], v[162:165], v[116:119]
	s_waitcnt lgkmcnt(6)
	v_mfma_f32_16x16x32_bf16 v[112:115], v[170:173], v[148:151], v[112:115]
	v_mfma_f32_16x16x32_bf16 v[108:111], v[170:173], v[154:157], v[108:111]
	v_mfma_f32_16x16x32_bf16 v[104:107], v[170:173], v[158:161], v[104:107]
	v_mfma_f32_16x16x32_bf16 v[100:103], v[170:173], v[162:165], v[100:103]
	s_waitcnt lgkmcnt(5)
	v_mfma_f32_16x16x32_bf16 v[96:99], v[174:177], v[148:151], v[96:99]
	v_mfma_f32_16x16x32_bf16 v[92:95], v[174:177], v[154:157], v[92:95]
	v_mfma_f32_16x16x32_bf16 v[88:91], v[174:177], v[158:161], v[88:91]
	v_mfma_f32_16x16x32_bf16 v[84:87], v[174:177], v[162:165], v[84:87]
	s_waitcnt lgkmcnt(4)
	v_mfma_f32_16x16x32_bf16 v[80:83], v[192:195], v[148:151], v[80:83]
	v_mfma_f32_16x16x32_bf16 v[76:79], v[192:195], v[154:157], v[76:79]
	v_mfma_f32_16x16x32_bf16 v[72:75], v[192:195], v[158:161], v[72:75]
	v_mfma_f32_16x16x32_bf16 v[68:71], v[192:195], v[162:165], v[68:71]
	s_waitcnt lgkmcnt(3)
	v_mfma_f32_16x16x32_bf16 v[64:67], v[196:199], v[148:151], v[64:67]
	v_mfma_f32_16x16x32_bf16 v[60:63], v[196:199], v[154:157], v[60:63]
	v_mfma_f32_16x16x32_bf16 v[56:59], v[196:199], v[158:161], v[56:59]
	v_mfma_f32_16x16x32_bf16 v[52:55], v[196:199], v[162:165], v[52:55]
	s_waitcnt lgkmcnt(2)
	v_mfma_f32_16x16x32_bf16 v[48:51], v[204:207], v[148:151], v[48:51]
	v_mfma_f32_16x16x32_bf16 v[44:47], v[204:207], v[154:157], v[44:47]
	v_mfma_f32_16x16x32_bf16 v[40:43], v[204:207], v[158:161], v[40:43]
	v_mfma_f32_16x16x32_bf16 v[36:39], v[204:207], v[162:165], v[36:39]
	s_waitcnt lgkmcnt(1)
	v_mfma_f32_16x16x32_bf16 v[32:35], v[208:211], v[148:151], v[32:35]
	v_mfma_f32_16x16x32_bf16 v[28:31], v[208:211], v[154:157], v[28:31]
	v_mfma_f32_16x16x32_bf16 v[24:27], v[208:211], v[158:161], v[24:27]
	v_mfma_f32_16x16x32_bf16 v[20:23], v[208:211], v[162:165], v[20:23]
	s_waitcnt lgkmcnt(0)
	v_mfma_f32_16x16x32_bf16 v[16:19], v[212:215], v[148:151], v[16:19]
	v_mfma_f32_16x16x32_bf16 v[12:15], v[212:215], v[154:157], v[12:15]
	v_mfma_f32_16x16x32_bf16 v[8:11], v[212:215], v[158:161], v[8:11]
	v_mfma_f32_16x16x32_bf16 v[4:7], v[212:215], v[162:165], v[4:7]
	s_setprio 0
	s_add_i32 s10, s10, 0x6000
	s_cmp_lg_u32 s10, 0x12000
	s_cselect_b32 s10, s10, 0
	s_waitcnt vmcnt(0)
	s_barrier
	v_mul_f32_e32 v2, 0xbfb8aa3b, v128
	v_exp_f32_e32 v2, v2
	v_and_b32_e32 v132, 15, v1
	v_and_b32_e32 v133, 0xfffff80, v1
	v_lshrrev_b32_e32 v134, 2, v1
	v_add_f32_e32 v135, 1.0, v2
	v_div_scale_f32 v136, s[10:11], v135, v135, v128
	v_rcp_f32_e32 v137, v136
	v_lshlrev_b32_e32 v2, 1, v132
	v_and_or_b32 v2, v1, 64, v2
	v_and_or_b32 v133, v134, 12, v133
	v_fma_f32 v1, -v136, v137, 1.0
	v_fmac_f32_e32 v137, v1, v137
	v_div_scale_f32 v1, vcc, v128, v135, v128
	v_mul_f32_e32 v132, v1, v137
	v_fma_f32 v134, -v136, v132, v1
	v_fmac_f32_e32 v132, v134, v137
	v_fma_f32 v1, -v136, v132, v1
	v_div_fmas_f32 v1, v1, v137, v132
	v_mul_f32_e32 v132, 0xbfb8aa3b, v129
	v_exp_f32_e32 v132, v132
	v_div_fixup_f32 v1, v1, v135, v128
	v_mul_f32_e32 v1, v124, v1
	s_movk_i32 s3, 0x90
	v_add_f32_e32 v124, 1.0, v132
	v_div_scale_f32 v128, s[10:11], v124, v124, v129
	v_rcp_f32_e32 v134, v128
	v_cvt_pk_bf16_f32 v1, v1, s0
	v_mad_u64_u32 v[132:133], s[10:11], v133, s3, v[2:3]
	ds_write_b16 v132, v1
	v_fma_f32 v1, -v128, v134, 1.0
	v_fmac_f32_e32 v134, v1, v134
	v_div_scale_f32 v1, vcc, v129, v124, v129
	v_mul_f32_e32 v2, v1, v134
	v_fma_f32 v133, -v128, v2, v1
	v_fmac_f32_e32 v2, v133, v134
	v_fma_f32 v1, -v128, v2, v1
	v_mul_f32_e32 v128, 0xbfb8aa3b, v130
	v_exp_f32_e32 v128, v128
	v_div_fmas_f32 v1, v1, v134, v2
	v_div_fixup_f32 v1, v1, v124, v129
	v_mul_f32_e32 v1, v125, v1
	v_add_f32_e32 v2, 1.0, v128
	v_div_scale_f32 v124, s[10:11], v2, v2, v130
	v_rcp_f32_e32 v128, v124
	v_cvt_pk_bf16_f32 v1, v1, s0
	ds_write_b16 v132, v1 offset:144
	v_readlane_b32 s56, v251, 58
	v_fma_f32 v1, -v124, v128, 1.0
	v_fmac_f32_e32 v128, v1, v128
	v_div_scale_f32 v1, vcc, v130, v2, v130
	v_mul_f32_e32 v125, v1, v128
	v_fma_f32 v129, -v124, v125, v1
	v_fmac_f32_e32 v125, v129, v128
	v_fma_f32 v1, -v124, v125, v1
	v_mul_f32_e32 v124, 0xbfb8aa3b, v131
	v_exp_f32_e32 v124, v124
	v_div_fmas_f32 v1, v1, v128, v125
	v_div_fixup_f32 v1, v1, v2, v130
	v_mul_f32_e32 v1, v126, v1
	v_add_f32_e32 v2, 1.0, v124
	v_div_scale_f32 v124, s[10:11], v2, v2, v131
	v_rcp_f32_e32 v125, v124
	v_cvt_pk_bf16_f32 v1, v1, s0
	ds_write_b16 v132, v1 offset:288
	v_readlane_b32 s58, v251, 60
	v_fma_f32 v1, -v124, v125, 1.0
	v_fmac_f32_e32 v125, v1, v125
	v_div_scale_f32 v1, vcc, v131, v2, v131
	v_mul_f32_e32 v126, v1, v125
	v_fma_f32 v128, -v124, v126, v1
	v_fmac_f32_e32 v126, v128, v125
	v_fma_f32 v1, -v124, v126, v1
	v_mul_f32_e32 v124, 0xbfb8aa3b, v120
	v_exp_f32_e32 v124, v124
; DEVI float silu_(float x) { return x / (1.f + __expf(-x)); }
; DEVI void ffn1_tile256(const P& p, const bf* W, long row0, int n0  , char* smem) {
;     ...
; #pragma unroll
;   for (int m = 0; m < 8; ++m)
; #pragma unroll
;     for (int pr = 0; pr < 2; ++pr) {
;       const int cl = (wc * 2 + pr) * 16 + l15;
; #pragma unroll
;       for (int j = 0; j < 4; ++j) {
;         const int rl = wr * 128 + m * 16 + quad * 4 + j;
;         float a = acc[m][2 * pr][j], b = acc[m][2 * pr + 1][j];
;         tl[rl * 72 + cl] = f2bf(silu_(a) * b);
;       }
	v_div_fmas_f32 v1, v1, v125, v126
	v_div_fixup_f32 v1, v1, v2, v131
	v_mul_f32_e32 v1, v127, v1
	v_add_f32_e32 v2, 1.0, v124
	v_div_scale_f32 v124, s[10:11], v2, v2, v120
	v_rcp_f32_e32 v125, v124
	v_cvt_pk_bf16_f32 v1, v1, s0
	ds_write_b16 v132, v1 offset:432
	v_readlane_b32 s59, v251, 61
	v_fma_f32 v1, -v124, v125, 1.0
	v_fmac_f32_e32 v125, v1, v125
	v_div_scale_f32 v1, vcc, v120, v2, v120
	v_mul_f32_e32 v126, v1, v125
	v_fma_f32 v127, -v124, v126, v1
	v_fmac_f32_e32 v126, v127, v125
	v_fma_f32 v1, -v124, v126, v1
	v_mul_f32_e32 v124, 0xbfb8aa3b, v121
	v_exp_f32_e32 v124, v124
	v_div_fmas_f32 v1, v1, v125, v126
	v_div_fixup_f32 v1, v1, v2, v120
	v_mul_f32_e32 v1, v116, v1
	v_add_f32_e32 v2, 1.0, v124
	v_div_scale_f32 v120, s[10:11], v2, v2, v121
	v_rcp_f32_e32 v124, v120
	v_cvt_pk_bf16_f32 v1, v1, s0
	ds_write_b16 v132, v1 offset:32
	v_readlane_b32 s57, v251, 59
	v_fma_f32 v1, -v120, v124, 1.0
	v_fmac_f32_e32 v124, v1, v124
	v_div_scale_f32 v1, vcc, v121, v2, v121
	v_mul_f32_e32 v116, v1, v124
	v_fma_f32 v125, -v120, v116, v1
	v_fmac_f32_e32 v116, v125, v124
	v_fma_f32 v1, -v120, v116, v1
	v_mul_f32_e32 v120, 0xbfb8aa3b, v122
	v_exp_f32_e32 v120, v120
	v_div_fmas_f32 v1, v1, v124, v116
	v_div_fixup_f32 v1, v1, v2, v121
	v_mul_f32_e32 v1, v117, v1
	v_add_f32_e32 v2, 1.0, v120
	v_div_scale_f32 v116, s[10:11], v2, v2, v122
	v_rcp_f32_e32 v120, v116
	v_cvt_pk_bf16_f32 v1, v1, s0
	ds_write_b16 v132, v1 offset:176
	v_readlane_b32 s60, v251, 62
	v_fma_f32 v1, -v116, v120, 1.0
	v_fmac_f32_e32 v120, v1, v120
	v_div_scale_f32 v1, vcc, v122, v2, v122
	v_mul_f32_e32 v117, v1, v120
	v_fma_f32 v121, -v116, v117, v1
	v_fmac_f32_e32 v117, v121, v120
	v_fma_f32 v1, -v116, v117, v1
	v_mul_f32_e32 v116, 0xbfb8aa3b, v123
	v_exp_f32_e32 v116, v116
	v_div_fmas_f32 v1, v1, v120, v117
	v_div_fixup_f32 v1, v1, v2, v122
	v_mul_f32_e32 v1, v118, v1
	v_add_f32_e32 v2, 1.0, v116
	v_div_scale_f32 v116, s[10:11], v2, v2, v123
	v_rcp_f32_e32 v117, v116
	v_cvt_pk_bf16_f32 v1, v1, s0
	ds_write_b16 v132, v1 offset:320
	v_readlane_b32 s61, v251, 63
	v_fma_f32 v1, -v116, v117, 1.0
	v_fmac_f32_e32 v117, v1, v117
	v_div_scale_f32 v1, vcc, v123, v2, v123
	v_mul_f32_e32 v118, v1, v117
	v_fma_f32 v120, -v116, v118, v1
	v_fmac_f32_e32 v118, v120, v117
	v_fma_f32 v1, -v116, v118, v1
	v_mul_f32_e32 v116, 0xbfb8aa3b, v112
	v_exp_f32_e32 v116, v116
	v_div_fmas_f32 v1, v1, v117, v118
	v_div_fixup_f32 v1, v1, v2, v123
	v_mul_f32_e32 v1, v119, v1
	v_add_f32_e32 v2, 1.0, v116
	v_div_scale_f32 v116, s[10:11], v2, v2, v112
	v_rcp_f32_e32 v117, v116
	v_cvt_pk_bf16_f32 v1, v1, s0
	ds_write_b16 v132, v1 offset:464
	v_readlane_b32 s62, v252, 0
	v_fma_f32 v1, -v116, v117, 1.0
	v_fmac_f32_e32 v117, v1, v117
	v_div_scale_f32 v1, vcc, v112, v2, v112
	v_mul_f32_e32 v118, v1, v117
	v_fma_f32 v119, -v116, v118, v1
	v_fmac_f32_e32 v118, v119, v117
	v_fma_f32 v1, -v116, v118, v1
	v_mul_f32_e32 v116, 0xbfb8aa3b, v113
	v_exp_f32_e32 v116, v116
	v_div_fmas_f32 v1, v1, v117, v118
	v_div_fixup_f32 v1, v1, v2, v112
	v_mul_f32_e32 v1, v108, v1
	v_add_f32_e32 v2, 1.0, v116
	v_div_scale_f32 v112, s[10:11], v2, v2, v113
	v_rcp_f32_e32 v116, v112
	v_cvt_pk_bf16_f32 v1, v1, s0
	ds_write_b16 v132, v1 offset:2304
	v_readlane_b32 s63, v252, 1
	v_fma_f32 v1, -v112, v116, 1.0
	v_fmac_f32_e32 v116, v1, v116
	v_div_scale_f32 v1, vcc, v113, v2, v113
	v_mul_f32_e32 v108, v1, v116
	v_fma_f32 v117, -v112, v108, v1
	v_fmac_f32_e32 v108, v117, v116
	v_fma_f32 v1, -v112, v108, v1
	v_mul_f32_e32 v112, 0xbfb8aa3b, v114
	v_exp_f32_e32 v112, v112
	v_div_fmas_f32 v1, v1, v116, v108
	v_div_fixup_f32 v1, v1, v2, v113
	v_mul_f32_e32 v1, v109, v1
	v_add_f32_e32 v2, 1.0, v112
	v_div_scale_f32 v108, s[10:11], v2, v2, v114
	v_rcp_f32_e32 v112, v108
	v_cvt_pk_bf16_f32 v1, v1, s0
	ds_write_b16 v132, v1 offset:2448
	v_readlane_b32 s64, v252, 2
	v_fma_f32 v1, -v108, v112, 1.0
	v_fmac_f32_e32 v112, v1, v112
	v_div_scale_f32 v1, vcc, v114, v2, v114
	v_mul_f32_e32 v109, v1, v112
	v_fma_f32 v113, -v108, v109, v1
	v_fmac_f32_e32 v109, v113, v112
	v_fma_f32 v1, -v108, v109, v1
	v_mul_f32_e32 v108, 0xbfb8aa3b, v115
	v_exp_f32_e32 v108, v108
	v_div_fmas_f32 v1, v1, v112, v109
	v_div_fixup_f32 v1, v1, v2, v114
	v_mul_f32_e32 v1, v110, v1
	v_add_f32_e32 v2, 1.0, v108
	v_div_scale_f32 v108, s[10:11], v2, v2, v115
	v_rcp_f32_e32 v109, v108
	v_cvt_pk_bf16_f32 v1, v1, s0
	ds_write_b16 v132, v1 offset:2592
	v_readlane_b32 s65, v252, 3
	v_fma_f32 v1, -v108, v109, 1.0
	v_fmac_f32_e32 v109, v1, v109
	v_div_scale_f32 v1, vcc, v115, v2, v115
	v_mul_f32_e32 v110, v1, v109
	v_fma_f32 v112, -v108, v110, v1
	v_fmac_f32_e32 v110, v112, v109
	v_fma_f32 v1, -v108, v110, v1
	v_mul_f32_e32 v108, 0xbfb8aa3b, v104
	v_exp_f32_e32 v108, v108
	v_div_fmas_f32 v1, v1, v109, v110
	v_div_fixup_f32 v1, v1, v2, v115
	v_mul_f32_e32 v1, v111, v1
	v_add_f32_e32 v2, 1.0, v108
	v_div_scale_f32 v108, s[10:11], v2, v2, v104
	v_rcp_f32_e32 v109, v108
	v_cvt_pk_bf16_f32 v1, v1, s0
	ds_write_b16 v132, v1 offset:2736
	v_readlane_b32 s66, v252, 4
	v_fma_f32 v1, -v108, v109, 1.0
	v_fmac_f32_e32 v109, v1, v109
	v_div_scale_f32 v1, vcc, v104, v2, v104
	v_mul_f32_e32 v110, v1, v109
	v_fma_f32 v111, -v108, v110, v1
	v_fmac_f32_e32 v110, v111, v109
	v_fma_f32 v1, -v108, v110, v1
	v_mul_f32_e32 v108, 0xbfb8aa3b, v105
	v_exp_f32_e32 v108, v108
	v_div_fmas_f32 v1, v1, v109, v110
	v_div_fixup_f32 v1, v1, v2, v104
	v_mul_f32_e32 v1, v100, v1
	v_add_f32_e32 v2, 1.0, v108
	v_div_scale_f32 v104, s[10:11], v2, v2, v105
	v_rcp_f32_e32 v108, v104
	v_cvt_pk_bf16_f32 v1, v1, s0
	ds_write_b16 v132, v1 offset:2336
	v_readlane_b32 s67, v252, 5
	v_fma_f32 v1, -v104, v108, 1.0
	v_fmac_f32_e32 v108, v1, v108
; DEVI float silu_(float x) { return x / (1.f + __expf(-x)); }
; DEVI void ffn1_tile256(const P& p, const bf* W, long row0, int n0  , char* smem) {
;     ...
; #pragma unroll
;   for (int m = 0; m < 8; ++m)
; #pragma unroll
;     for (int pr = 0; pr < 2; ++pr) {
;       const int cl = (wc * 2 + pr) * 16 + l15;
; #pragma unroll
;       for (int j = 0; j < 4; ++j) {
;         const int rl = wr * 128 + m * 16 + quad * 4 + j;
;         float a = acc[m][2 * pr][j], b = acc[m][2 * pr + 1][j];
;         tl[rl * 72 + cl] = f2bf(silu_(a) * b);
;       }
	v_div_scale_f32 v1, vcc, v105, v2, v105
	v_mul_f32_e32 v100, v1, v108
	v_fma_f32 v109, -v104, v100, v1
	v_fmac_f32_e32 v100, v109, v108
	v_fma_f32 v1, -v104, v100, v1
	v_mul_f32_e32 v104, 0xbfb8aa3b, v106
	v_exp_f32_e32 v104, v104
	v_div_fmas_f32 v1, v1, v108, v100
	v_div_fixup_f32 v1, v1, v2, v105
	v_mul_f32_e32 v1, v101, v1
	v_add_f32_e32 v2, 1.0, v104
	v_div_scale_f32 v100, s[10:11], v2, v2, v106
	v_rcp_f32_e32 v104, v100
	v_cvt_pk_bf16_f32 v1, v1, s0
	ds_write_b16 v132, v1 offset:2480
	v_readlane_b32 s68, v252, 6
	v_fma_f32 v1, -v100, v104, 1.0
	v_fmac_f32_e32 v104, v1, v104
	v_div_scale_f32 v1, vcc, v106, v2, v106
	v_mul_f32_e32 v101, v1, v104
	v_fma_f32 v105, -v100, v101, v1
	v_fmac_f32_e32 v101, v105, v104
	v_fma_f32 v1, -v100, v101, v1
	v_mul_f32_e32 v100, 0xbfb8aa3b, v107
	v_exp_f32_e32 v100, v100
	v_div_fmas_f32 v1, v1, v104, v101
	v_div_fixup_f32 v1, v1, v2, v106
	v_mul_f32_e32 v1, v102, v1
	v_add_f32_e32 v2, 1.0, v100
	v_div_scale_f32 v100, s[10:11], v2, v2, v107
	v_rcp_f32_e32 v101, v100
	v_cvt_pk_bf16_f32 v1, v1, s0
	ds_write_b16 v132, v1 offset:2624
	v_readlane_b32 s69, v252, 7
	v_fma_f32 v1, -v100, v101, 1.0
	v_fmac_f32_e32 v101, v1, v101
	v_div_scale_f32 v1, vcc, v107, v2, v107
	v_mul_f32_e32 v102, v1, v101
	v_fma_f32 v104, -v100, v102, v1
	v_fmac_f32_e32 v102, v104, v101
	v_fma_f32 v1, -v100, v102, v1
	v_mul_f32_e32 v100, 0xbfb8aa3b, v96
	v_exp_f32_e32 v100, v100
	v_div_fmas_f32 v1, v1, v101, v102
	v_div_fixup_f32 v1, v1, v2, v107
	v_mul_f32_e32 v1, v103, v1
	v_add_f32_e32 v2, 1.0, v100
	v_div_scale_f32 v100, s[10:11], v2, v2, v96
	v_rcp_f32_e32 v101, v100
	v_cvt_pk_bf16_f32 v1, v1, s0
	ds_write_b16 v132, v1 offset:2768
	v_readlane_b32 s70, v252, 8
	v_fma_f32 v1, -v100, v101, 1.0
	v_fmac_f32_e32 v101, v1, v101
	v_div_scale_f32 v1, vcc, v96, v2, v96
	v_mul_f32_e32 v102, v1, v101
	v_fma_f32 v103, -v100, v102, v1
	v_fmac_f32_e32 v102, v103, v101
	v_fma_f32 v1, -v100, v102, v1
	v_mul_f32_e32 v100, 0xbfb8aa3b, v97
	v_exp_f32_e32 v100, v100
	v_div_fmas_f32 v1, v1, v101, v102
	v_div_fixup_f32 v1, v1, v2, v96
	v_mul_f32_e32 v1, v92, v1
	v_add_f32_e32 v2, 1.0, v100
	v_div_scale_f32 v96, s[10:11], v2, v2, v97
	v_rcp_f32_e32 v100, v96
	v_cvt_pk_bf16_f32 v1, v1, s0
	ds_write_b16 v132, v1 offset:4608
	v_readlane_b32 s71, v252, 9
	v_fma_f32 v1, -v96, v100, 1.0
	v_fmac_f32_e32 v100, v1, v100
	v_div_scale_f32 v1, vcc, v97, v2, v97
	v_mul_f32_e32 v92, v1, v100
	v_fma_f32 v101, -v96, v92, v1
	v_fmac_f32_e32 v92, v101, v100
	v_fma_f32 v1, -v96, v92, v1
	v_mul_f32_e32 v96, 0xbfb8aa3b, v98
	v_exp_f32_e32 v96, v96
	v_div_fmas_f32 v1, v1, v100, v92
	v_div_fixup_f32 v1, v1, v2, v97
	v_mul_f32_e32 v1, v93, v1
	v_add_f32_e32 v2, 1.0, v96
	v_div_scale_f32 v92, s[10:11], v2, v2, v98
	v_rcp_f32_e32 v96, v92
	v_cvt_pk_bf16_f32 v1, v1, s0
	ds_write_b16 v132, v1 offset:4752
	v_fma_f32 v1, -v92, v96, 1.0
	v_fmac_f32_e32 v96, v1, v96
	v_div_scale_f32 v1, vcc, v98, v2, v98
	v_mul_f32_e32 v93, v1, v96
	v_fma_f32 v97, -v92, v93, v1
	v_fmac_f32_e32 v93, v97, v96
	v_fma_f32 v1, -v92, v93, v1
	v_mul_f32_e32 v92, 0xbfb8aa3b, v99
	v_exp_f32_e32 v92, v92
	v_div_fmas_f32 v1, v1, v96, v93
	v_div_fixup_f32 v1, v1, v2, v98
	v_mul_f32_e32 v1, v94, v1
	v_add_f32_e32 v2, 1.0, v92
	v_div_scale_f32 v92, s[10:11], v2, v2, v99
	v_rcp_f32_e32 v93, v92
	v_cvt_pk_bf16_f32 v1, v1, s0
	ds_write_b16 v132, v1 offset:4896
	v_fma_f32 v1, -v92, v93, 1.0
	v_fmac_f32_e32 v93, v1, v93
	v_div_scale_f32 v1, vcc, v99, v2, v99
	v_mul_f32_e32 v94, v1, v93
	v_fma_f32 v96, -v92, v94, v1
	v_fmac_f32_e32 v94, v96, v93
	v_fma_f32 v1, -v92, v94, v1
	v_mul_f32_e32 v92, 0xbfb8aa3b, v88
	v_exp_f32_e32 v92, v92
	v_div_fmas_f32 v1, v1, v93, v94
	v_div_fixup_f32 v1, v1, v2, v99
	v_mul_f32_e32 v1, v95, v1
	v_add_f32_e32 v2, 1.0, v92
	v_div_scale_f32 v92, s[10:11], v2, v2, v88
	v_rcp_f32_e32 v93, v92
	v_cvt_pk_bf16_f32 v1, v1, s0
	ds_write_b16 v132, v1 offset:5040
	v_fma_f32 v1, -v92, v93, 1.0
	v_fmac_f32_e32 v93, v1, v93
	v_div_scale_f32 v1, vcc, v88, v2, v88
	v_mul_f32_e32 v94, v1, v93
	v_fma_f32 v95, -v92, v94, v1
	v_fmac_f32_e32 v94, v95, v93
	v_fma_f32 v1, -v92, v94, v1
	v_mul_f32_e32 v92, 0xbfb8aa3b, v89
	v_exp_f32_e32 v92, v92
	v_div_fmas_f32 v1, v1, v93, v94
	v_div_fixup_f32 v1, v1, v2, v88
	v_mul_f32_e32 v1, v84, v1
	v_add_f32_e32 v2, 1.0, v92
	v_div_scale_f32 v88, s[10:11], v2, v2, v89
	v_rcp_f32_e32 v92, v88
	v_cvt_pk_bf16_f32 v1, v1, s0
	ds_write_b16 v132, v1 offset:4640
	v_fma_f32 v1, -v88, v92, 1.0
	v_fmac_f32_e32 v92, v1, v92
	v_div_scale_f32 v1, vcc, v89, v2, v89
	v_mul_f32_e32 v84, v1, v92
	v_fma_f32 v93, -v88, v84, v1
	v_fmac_f32_e32 v84, v93, v92
	v_fma_f32 v1, -v88, v84, v1
	v_mul_f32_e32 v88, 0xbfb8aa3b, v90
	v_exp_f32_e32 v88, v88
	v_div_fmas_f32 v1, v1, v92, v84
	v_div_fixup_f32 v1, v1, v2, v89
	v_mul_f32_e32 v1, v85, v1
	v_add_f32_e32 v2, 1.0, v88
	v_div_scale_f32 v84, s[10:11], v2, v2, v90
	v_rcp_f32_e32 v88, v84
	v_cvt_pk_bf16_f32 v1, v1, s0
	ds_write_b16 v132, v1 offset:4784
	v_fma_f32 v1, -v84, v88, 1.0
	v_fmac_f32_e32 v88, v1, v88
	v_div_scale_f32 v1, vcc, v90, v2, v90
	v_mul_f32_e32 v85, v1, v88
	v_fma_f32 v89, -v84, v85, v1
	v_fmac_f32_e32 v85, v89, v88
	v_fma_f32 v1, -v84, v85, v1
	v_mul_f32_e32 v84, 0xbfb8aa3b, v91
	v_exp_f32_e32 v84, v84
	v_div_fmas_f32 v1, v1, v88, v85
	v_div_fixup_f32 v1, v1, v2, v90
	v_mul_f32_e32 v1, v86, v1
	v_add_f32_e32 v2, 1.0, v84
	v_div_scale_f32 v84, s[10:11], v2, v2, v91
	v_rcp_f32_e32 v85, v84
	v_cvt_pk_bf16_f32 v1, v1, s0
	ds_write_b16 v132, v1 offset:4928
	v_fma_f32 v1, -v84, v85, 1.0
	v_fmac_f32_e32 v85, v1, v85
	v_div_scale_f32 v1, vcc, v91, v2, v91
	v_mul_f32_e32 v86, v1, v85
	v_fma_f32 v88, -v84, v86, v1
	v_fmac_f32_e32 v86, v88, v85
; DEVI float silu_(float x) { return x / (1.f + __expf(-x)); }
; DEVI void ffn1_tile256(const P& p, const bf* W, long row0, int n0  , char* smem) {
;     ...
; #pragma unroll
;   for (int m = 0; m < 8; ++m)
; #pragma unroll
;     for (int pr = 0; pr < 2; ++pr) {
;       const int cl = (wc * 2 + pr) * 16 + l15;
; #pragma unroll
;       for (int j = 0; j < 4; ++j) {
;         const int rl = wr * 128 + m * 16 + quad * 4 + j;
;         float a = acc[m][2 * pr][j], b = acc[m][2 * pr + 1][j];
;         tl[rl * 72 + cl] = f2bf(silu_(a) * b);
;       }
	v_fma_f32 v1, -v84, v86, v1
	v_mul_f32_e32 v84, 0xbfb8aa3b, v80
	v_exp_f32_e32 v84, v84
	v_div_fmas_f32 v1, v1, v85, v86
	v_div_fixup_f32 v1, v1, v2, v91
	v_mul_f32_e32 v1, v87, v1
	v_add_f32_e32 v2, 1.0, v84
	v_div_scale_f32 v84, s[10:11], v2, v2, v80
	v_rcp_f32_e32 v85, v84
	v_cvt_pk_bf16_f32 v1, v1, s0
	ds_write_b16 v132, v1 offset:5072
	v_fma_f32 v1, -v84, v85, 1.0
	v_fmac_f32_e32 v85, v1, v85
	v_div_scale_f32 v1, vcc, v80, v2, v80
	v_mul_f32_e32 v86, v1, v85
	v_fma_f32 v87, -v84, v86, v1
	v_fmac_f32_e32 v86, v87, v85
	v_fma_f32 v1, -v84, v86, v1
	v_mul_f32_e32 v84, 0xbfb8aa3b, v81
	v_exp_f32_e32 v84, v84
	v_div_fmas_f32 v1, v1, v85, v86
	v_div_fixup_f32 v1, v1, v2, v80
	v_mul_f32_e32 v1, v76, v1
	v_add_f32_e32 v2, 1.0, v84
	v_div_scale_f32 v80, s[10:11], v2, v2, v81
	v_rcp_f32_e32 v84, v80
	v_cvt_pk_bf16_f32 v1, v1, s0
	ds_write_b16 v132, v1 offset:6912
	v_fma_f32 v1, -v80, v84, 1.0
	v_fmac_f32_e32 v84, v1, v84
	v_div_scale_f32 v1, vcc, v81, v2, v81
	v_mul_f32_e32 v76, v1, v84
	v_fma_f32 v85, -v80, v76, v1
	v_fmac_f32_e32 v76, v85, v84
	v_fma_f32 v1, -v80, v76, v1
	v_mul_f32_e32 v80, 0xbfb8aa3b, v82
	v_exp_f32_e32 v80, v80
	v_div_fmas_f32 v1, v1, v84, v76
	v_div_fixup_f32 v1, v1, v2, v81
	v_mul_f32_e32 v1, v77, v1
	v_add_f32_e32 v2, 1.0, v80
	v_div_scale_f32 v76, s[10:11], v2, v2, v82
	v_rcp_f32_e32 v80, v76
	v_cvt_pk_bf16_f32 v1, v1, s0
	ds_write_b16 v132, v1 offset:7056
	v_fma_f32 v1, -v76, v80, 1.0
	v_fmac_f32_e32 v80, v1, v80
	v_div_scale_f32 v1, vcc, v82, v2, v82
	v_mul_f32_e32 v77, v1, v80
	v_fma_f32 v81, -v76, v77, v1
	v_fmac_f32_e32 v77, v81, v80
	v_fma_f32 v1, -v76, v77, v1
	v_mul_f32_e32 v76, 0xbfb8aa3b, v83
	v_exp_f32_e32 v76, v76
	v_div_fmas_f32 v1, v1, v80, v77
	v_div_fixup_f32 v1, v1, v2, v82
	v_mul_f32_e32 v1, v78, v1
	v_add_f32_e32 v2, 1.0, v76
	v_div_scale_f32 v76, s[10:11], v2, v2, v83
	v_rcp_f32_e32 v77, v76
	v_cvt_pk_bf16_f32 v1, v1, s0
	ds_write_b16 v132, v1 offset:7200
	v_fma_f32 v1, -v76, v77, 1.0
	v_fmac_f32_e32 v77, v1, v77
	v_div_scale_f32 v1, vcc, v83, v2, v83
	v_mul_f32_e32 v78, v1, v77
	v_fma_f32 v80, -v76, v78, v1
	v_fmac_f32_e32 v78, v80, v77
	v_fma_f32 v1, -v76, v78, v1
	v_mul_f32_e32 v76, 0xbfb8aa3b, v72
	v_exp_f32_e32 v76, v76
	v_div_fmas_f32 v1, v1, v77, v78
	v_div_fixup_f32 v1, v1, v2, v83
	v_mul_f32_e32 v1, v79, v1
	v_add_f32_e32 v2, 1.0, v76
	v_div_scale_f32 v76, s[10:11], v2, v2, v72
	v_rcp_f32_e32 v77, v76
	v_cvt_pk_bf16_f32 v1, v1, s0
	ds_write_b16 v132, v1 offset:7344
	v_fma_f32 v1, -v76, v77, 1.0
	v_fmac_f32_e32 v77, v1, v77
	v_div_scale_f32 v1, vcc, v72, v2, v72
	v_mul_f32_e32 v78, v1, v77
	v_fma_f32 v79, -v76, v78, v1
	v_fmac_f32_e32 v78, v79, v77
	v_fma_f32 v1, -v76, v78, v1
	v_mul_f32_e32 v76, 0xbfb8aa3b, v73
	v_exp_f32_e32 v76, v76
	v_div_fmas_f32 v1, v1, v77, v78
	v_div_fixup_f32 v1, v1, v2, v72
	v_mul_f32_e32 v1, v68, v1
	v_add_f32_e32 v2, 1.0, v76
	v_div_scale_f32 v72, s[10:11], v2, v2, v73
	v_rcp_f32_e32 v76, v72
	v_cvt_pk_bf16_f32 v1, v1, s0
	ds_write_b16 v132, v1 offset:6944
	v_fma_f32 v1, -v72, v76, 1.0
	v_fmac_f32_e32 v76, v1, v76
	v_div_scale_f32 v1, vcc, v73, v2, v73
	v_mul_f32_e32 v68, v1, v76
	v_fma_f32 v77, -v72, v68, v1
	v_fmac_f32_e32 v68, v77, v76
	v_fma_f32 v1, -v72, v68, v1
	v_mul_f32_e32 v72, 0xbfb8aa3b, v74
	v_exp_f32_e32 v72, v72
	v_div_fmas_f32 v1, v1, v76, v68
	v_div_fixup_f32 v1, v1, v2, v73
	v_mul_f32_e32 v1, v69, v1
	v_add_f32_e32 v2, 1.0, v72
	v_div_scale_f32 v68, s[10:11], v2, v2, v74
	v_rcp_f32_e32 v72, v68
	v_cvt_pk_bf16_f32 v1, v1, s0
	ds_write_b16 v132, v1 offset:7088
	v_fma_f32 v1, -v68, v72, 1.0
	v_fmac_f32_e32 v72, v1, v72
	v_div_scale_f32 v1, vcc, v74, v2, v74
	v_mul_f32_e32 v69, v1, v72
	v_fma_f32 v73, -v68, v69, v1
	v_fmac_f32_e32 v69, v73, v72
	v_fma_f32 v1, -v68, v69, v1
	v_mul_f32_e32 v68, 0xbfb8aa3b, v75
	v_exp_f32_e32 v68, v68
	v_div_fmas_f32 v1, v1, v72, v69
	v_div_fixup_f32 v1, v1, v2, v74
	v_mul_f32_e32 v1, v70, v1
	v_add_f32_e32 v2, 1.0, v68
	v_div_scale_f32 v68, s[10:11], v2, v2, v75
	v_rcp_f32_e32 v69, v68
	v_cvt_pk_bf16_f32 v1, v1, s0
	ds_write_b16 v132, v1 offset:7232
	v_fma_f32 v1, -v68, v69, 1.0
	v_fmac_f32_e32 v69, v1, v69
	v_div_scale_f32 v1, vcc, v75, v2, v75
	v_mul_f32_e32 v70, v1, v69
	v_fma_f32 v72, -v68, v70, v1
	v_fmac_f32_e32 v70, v72, v69
	v_fma_f32 v1, -v68, v70, v1
	v_mul_f32_e32 v68, 0xbfb8aa3b, v64
	v_exp_f32_e32 v68, v68
	v_div_fmas_f32 v1, v1, v69, v70
	v_div_fixup_f32 v1, v1, v2, v75
	v_mul_f32_e32 v1, v71, v1
	v_add_f32_e32 v2, 1.0, v68
	v_div_scale_f32 v68, s[10:11], v2, v2, v64
	v_rcp_f32_e32 v69, v68
	v_cvt_pk_bf16_f32 v1, v1, s0
	ds_write_b16 v132, v1 offset:7376
	v_fma_f32 v1, -v68, v69, 1.0
	v_fmac_f32_e32 v69, v1, v69
	v_div_scale_f32 v1, vcc, v64, v2, v64
	v_mul_f32_e32 v70, v1, v69
	v_fma_f32 v71, -v68, v70, v1
	v_fmac_f32_e32 v70, v71, v69
	v_fma_f32 v1, -v68, v70, v1
	v_mul_f32_e32 v68, 0xbfb8aa3b, v65
	v_exp_f32_e32 v68, v68
	v_div_fmas_f32 v1, v1, v69, v70
	v_div_fixup_f32 v1, v1, v2, v64
	v_mul_f32_e32 v1, v60, v1
	v_add_f32_e32 v2, 1.0, v68
	v_div_scale_f32 v64, s[10:11], v2, v2, v65
	v_rcp_f32_e32 v68, v64
	v_cvt_pk_bf16_f32 v1, v1, s0
	ds_write_b16 v132, v1 offset:9216
	v_fma_f32 v1, -v64, v68, 1.0
	v_fmac_f32_e32 v68, v1, v68
	v_div_scale_f32 v1, vcc, v65, v2, v65
	v_mul_f32_e32 v60, v1, v68
	v_fma_f32 v69, -v64, v60, v1
	v_fmac_f32_e32 v60, v69, v68
	v_fma_f32 v1, -v64, v60, v1
	v_mul_f32_e32 v64, 0xbfb8aa3b, v66
	v_exp_f32_e32 v64, v64
	v_div_fmas_f32 v1, v1, v68, v60
	v_div_fixup_f32 v1, v1, v2, v65
	v_mul_f32_e32 v1, v61, v1
	v_add_f32_e32 v2, 1.0, v64
	v_div_scale_f32 v60, s[10:11], v2, v2, v66
	v_rcp_f32_e32 v64, v60
	v_cvt_pk_bf16_f32 v1, v1, s0
	ds_write_b16 v132, v1 offset:9360
; DEVI float silu_(float x) { return x / (1.f + __expf(-x)); }
; DEVI void ffn1_tile256(const P& p, const bf* W, long row0, int n0  , char* smem) {
;     ...
; #pragma unroll
;   for (int m = 0; m < 8; ++m)
; #pragma unroll
;     for (int pr = 0; pr < 2; ++pr) {
;       const int cl = (wc * 2 + pr) * 16 + l15;
; #pragma unroll
;       for (int j = 0; j < 4; ++j) {
;         const int rl = wr * 128 + m * 16 + quad * 4 + j;
;         float a = acc[m][2 * pr][j], b = acc[m][2 * pr + 1][j];
;         tl[rl * 72 + cl] = f2bf(silu_(a) * b);
;       }
;     }
	v_fma_f32 v1, -v60, v64, 1.0
	v_fmac_f32_e32 v64, v1, v64
	v_div_scale_f32 v1, vcc, v66, v2, v66
	v_mul_f32_e32 v61, v1, v64
	v_fma_f32 v65, -v60, v61, v1
	v_fmac_f32_e32 v61, v65, v64
	v_fma_f32 v1, -v60, v61, v1
	v_mul_f32_e32 v60, 0xbfb8aa3b, v67
	v_exp_f32_e32 v60, v60
	v_div_fmas_f32 v1, v1, v64, v61
	v_div_fixup_f32 v1, v1, v2, v66
	v_mul_f32_e32 v1, v62, v1
	v_add_f32_e32 v2, 1.0, v60
	v_div_scale_f32 v60, s[10:11], v2, v2, v67
	v_rcp_f32_e32 v61, v60
	v_cvt_pk_bf16_f32 v1, v1, s0
	ds_write_b16 v132, v1 offset:9504
	v_fma_f32 v1, -v60, v61, 1.0
	v_fmac_f32_e32 v61, v1, v61
	v_div_scale_f32 v1, vcc, v67, v2, v67
	v_mul_f32_e32 v62, v1, v61
	v_fma_f32 v64, -v60, v62, v1
	v_fmac_f32_e32 v62, v64, v61
	v_fma_f32 v1, -v60, v62, v1
	v_mul_f32_e32 v60, 0xbfb8aa3b, v56
	v_exp_f32_e32 v60, v60
	v_div_fmas_f32 v1, v1, v61, v62
	v_div_fixup_f32 v1, v1, v2, v67
	v_mul_f32_e32 v1, v63, v1
	v_add_f32_e32 v2, 1.0, v60
	v_div_scale_f32 v60, s[10:11], v2, v2, v56
	v_rcp_f32_e32 v61, v60
	v_cvt_pk_bf16_f32 v1, v1, s0
	ds_write_b16 v132, v1 offset:9648
	v_fma_f32 v1, -v60, v61, 1.0
	v_fmac_f32_e32 v61, v1, v61
	v_div_scale_f32 v1, vcc, v56, v2, v56
	v_mul_f32_e32 v62, v1, v61
	v_fma_f32 v63, -v60, v62, v1
	v_fmac_f32_e32 v62, v63, v61
	v_fma_f32 v1, -v60, v62, v1
	v_mul_f32_e32 v60, 0xbfb8aa3b, v57
	v_exp_f32_e32 v60, v60
	v_div_fmas_f32 v1, v1, v61, v62
	v_div_fixup_f32 v1, v1, v2, v56
	v_mul_f32_e32 v1, v52, v1
	v_add_f32_e32 v2, 1.0, v60
	v_div_scale_f32 v56, s[10:11], v2, v2, v57
	v_rcp_f32_e32 v60, v56
	v_cvt_pk_bf16_f32 v1, v1, s0
	ds_write_b16 v132, v1 offset:9248
	v_fma_f32 v1, -v56, v60, 1.0
	v_fmac_f32_e32 v60, v1, v60
	v_div_scale_f32 v1, vcc, v57, v2, v57
	v_mul_f32_e32 v52, v1, v60
	v_fma_f32 v61, -v56, v52, v1
	v_fmac_f32_e32 v52, v61, v60
	v_fma_f32 v1, -v56, v52, v1
	v_mul_f32_e32 v56, 0xbfb8aa3b, v58
	v_exp_f32_e32 v56, v56
	v_div_fmas_f32 v1, v1, v60, v52
	v_div_fixup_f32 v1, v1, v2, v57
	v_mul_f32_e32 v1, v53, v1
	v_add_f32_e32 v2, 1.0, v56
	v_div_scale_f32 v52, s[10:11], v2, v2, v58
	v_rcp_f32_e32 v56, v52
	v_cvt_pk_bf16_f32 v1, v1, s0
	ds_write_b16 v132, v1 offset:9392
	v_fma_f32 v1, -v52, v56, 1.0
	v_fmac_f32_e32 v56, v1, v56
	v_div_scale_f32 v1, vcc, v58, v2, v58
	v_mul_f32_e32 v53, v1, v56
	v_fma_f32 v57, -v52, v53, v1
	v_fmac_f32_e32 v53, v57, v56
	v_fma_f32 v1, -v52, v53, v1
	v_mul_f32_e32 v52, 0xbfb8aa3b, v59
	v_exp_f32_e32 v52, v52
	v_div_fmas_f32 v1, v1, v56, v53
	v_div_fixup_f32 v1, v1, v2, v58
	v_mul_f32_e32 v1, v54, v1
	v_add_f32_e32 v2, 1.0, v52
	v_div_scale_f32 v52, s[10:11], v2, v2, v59
	v_rcp_f32_e32 v53, v52
	v_cvt_pk_bf16_f32 v1, v1, s0
	ds_write_b16 v132, v1 offset:9536
	v_fma_f32 v1, -v52, v53, 1.0
	v_fmac_f32_e32 v53, v1, v53
	v_div_scale_f32 v1, vcc, v59, v2, v59
	v_mul_f32_e32 v54, v1, v53
	v_fma_f32 v56, -v52, v54, v1
	v_fmac_f32_e32 v54, v56, v53
	v_fma_f32 v1, -v52, v54, v1
	v_mul_f32_e32 v52, 0xbfb8aa3b, v48
	v_exp_f32_e32 v52, v52
	v_div_fmas_f32 v1, v1, v53, v54
	v_div_fixup_f32 v1, v1, v2, v59
	v_mul_f32_e32 v1, v55, v1
	v_add_f32_e32 v2, 1.0, v52
	v_div_scale_f32 v52, s[10:11], v2, v2, v48
	v_rcp_f32_e32 v53, v52
	v_cvt_pk_bf16_f32 v1, v1, s0
	ds_write_b16 v132, v1 offset:9680
	v_fma_f32 v1, -v52, v53, 1.0
	v_fmac_f32_e32 v53, v1, v53
	v_div_scale_f32 v1, vcc, v48, v2, v48
	v_mul_f32_e32 v54, v1, v53
	v_fma_f32 v55, -v52, v54, v1
	v_fmac_f32_e32 v54, v55, v53
	v_fma_f32 v1, -v52, v54, v1
	v_mul_f32_e32 v52, 0xbfb8aa3b, v49
	v_exp_f32_e32 v52, v52
	v_div_fmas_f32 v1, v1, v53, v54
	v_div_fixup_f32 v1, v1, v2, v48
	v_mul_f32_e32 v1, v44, v1
	v_add_f32_e32 v2, 1.0, v52
	v_div_scale_f32 v48, s[10:11], v2, v2, v49
	v_rcp_f32_e32 v52, v48
	v_cvt_pk_bf16_f32 v1, v1, s0
	ds_write_b16 v132, v1 offset:11520
	v_fma_f32 v1, -v48, v52, 1.0
	v_fmac_f32_e32 v52, v1, v52
	v_div_scale_f32 v1, vcc, v49, v2, v49
	v_mul_f32_e32 v44, v1, v52
	v_fma_f32 v53, -v48, v44, v1
	v_fmac_f32_e32 v44, v53, v52
	v_fma_f32 v1, -v48, v44, v1
	v_mul_f32_e32 v48, 0xbfb8aa3b, v50
	v_exp_f32_e32 v48, v48
	v_div_fmas_f32 v1, v1, v52, v44
	v_div_fixup_f32 v1, v1, v2, v49
	v_mul_f32_e32 v1, v45, v1
	v_add_f32_e32 v2, 1.0, v48
	v_div_scale_f32 v44, s[10:11], v2, v2, v50
	v_rcp_f32_e32 v48, v44
	v_cvt_pk_bf16_f32 v1, v1, s0
	ds_write_b16 v132, v1 offset:11664
	v_fma_f32 v1, -v44, v48, 1.0
	v_fmac_f32_e32 v48, v1, v48
	v_div_scale_f32 v1, vcc, v50, v2, v50
	v_mul_f32_e32 v45, v1, v48
	v_fma_f32 v49, -v44, v45, v1
	v_fmac_f32_e32 v45, v49, v48
	v_fma_f32 v1, -v44, v45, v1
	v_mul_f32_e32 v44, 0xbfb8aa3b, v51
	v_exp_f32_e32 v44, v44
	v_div_fmas_f32 v1, v1, v48, v45
	v_div_fixup_f32 v1, v1, v2, v50
	v_mul_f32_e32 v1, v46, v1
	v_add_f32_e32 v2, 1.0, v44
	v_div_scale_f32 v44, s[10:11], v2, v2, v51
	v_rcp_f32_e32 v45, v44
	v_cvt_pk_bf16_f32 v1, v1, s0
	ds_write_b16 v132, v1 offset:11808
	v_fma_f32 v1, -v44, v45, 1.0
	v_fmac_f32_e32 v45, v1, v45
	v_div_scale_f32 v1, vcc, v51, v2, v51
	v_mul_f32_e32 v46, v1, v45
	v_fma_f32 v48, -v44, v46, v1
	v_fmac_f32_e32 v46, v48, v45
	v_fma_f32 v1, -v44, v46, v1
	v_mul_f32_e32 v44, 0xbfb8aa3b, v40
	v_exp_f32_e32 v44, v44
	v_div_fmas_f32 v1, v1, v45, v46
	v_div_fixup_f32 v1, v1, v2, v51
	v_mul_f32_e32 v1, v47, v1
	v_add_f32_e32 v2, 1.0, v44
	v_div_scale_f32 v44, s[10:11], v2, v2, v40
	v_rcp_f32_e32 v45, v44
	v_cvt_pk_bf16_f32 v1, v1, s0
	ds_write_b16 v132, v1 offset:11952
	v_fma_f32 v1, -v44, v45, 1.0
	v_fmac_f32_e32 v45, v1, v45
	v_div_scale_f32 v1, vcc, v40, v2, v40
	v_mul_f32_e32 v46, v1, v45
	v_fma_f32 v47, -v44, v46, v1
	v_fmac_f32_e32 v46, v47, v45
	v_fma_f32 v1, -v44, v46, v1
	v_mul_f32_e32 v44, 0xbfb8aa3b, v41
	v_exp_f32_e32 v44, v44
	v_div_fmas_f32 v1, v1, v45, v46
	v_div_fixup_f32 v1, v1, v2, v40
; DEVI float silu_(float x) { return x / (1.f + __expf(-x)); }
; DEVI void ffn1_tile256(const P& p, const bf* W, long row0, int n0  , char* smem) {
;     ...
; #pragma unroll
;   for (int m = 0; m < 8; ++m)
; #pragma unroll
;     for (int pr = 0; pr < 2; ++pr) {
;       const int cl = (wc * 2 + pr) * 16 + l15;
; #pragma unroll
;       for (int j = 0; j < 4; ++j) {
;         const int rl = wr * 128 + m * 16 + quad * 4 + j;
;         float a = acc[m][2 * pr][j], b = acc[m][2 * pr + 1][j];
;         tl[rl * 72 + cl] = f2bf(silu_(a) * b);
;       }
;     }
	v_mul_f32_e32 v1, v36, v1
	v_add_f32_e32 v2, 1.0, v44
	v_div_scale_f32 v40, s[10:11], v2, v2, v41
	v_rcp_f32_e32 v44, v40
	v_cvt_pk_bf16_f32 v1, v1, s0
	ds_write_b16 v132, v1 offset:11552
	v_fma_f32 v1, -v40, v44, 1.0
	v_fmac_f32_e32 v44, v1, v44
	v_div_scale_f32 v1, vcc, v41, v2, v41
	v_mul_f32_e32 v36, v1, v44
	v_fma_f32 v45, -v40, v36, v1
	v_fmac_f32_e32 v36, v45, v44
	v_fma_f32 v1, -v40, v36, v1
	v_mul_f32_e32 v40, 0xbfb8aa3b, v42
	v_exp_f32_e32 v40, v40
	v_div_fmas_f32 v1, v1, v44, v36
	v_div_fixup_f32 v1, v1, v2, v41
	v_mul_f32_e32 v1, v37, v1
	v_add_f32_e32 v2, 1.0, v40
	v_div_scale_f32 v36, s[10:11], v2, v2, v42
	v_rcp_f32_e32 v40, v36
	v_cvt_pk_bf16_f32 v1, v1, s0
	ds_write_b16 v132, v1 offset:11696
	v_fma_f32 v1, -v36, v40, 1.0
	v_fmac_f32_e32 v40, v1, v40
	v_div_scale_f32 v1, vcc, v42, v2, v42
	v_mul_f32_e32 v37, v1, v40
	v_fma_f32 v41, -v36, v37, v1
	v_fmac_f32_e32 v37, v41, v40
	v_fma_f32 v1, -v36, v37, v1
	v_mul_f32_e32 v36, 0xbfb8aa3b, v43
	v_exp_f32_e32 v36, v36
	v_div_fmas_f32 v1, v1, v40, v37
	v_div_fixup_f32 v1, v1, v2, v42
	v_mul_f32_e32 v1, v38, v1
	v_add_f32_e32 v2, 1.0, v36
	v_div_scale_f32 v36, s[10:11], v2, v2, v43
	v_rcp_f32_e32 v37, v36
	v_cvt_pk_bf16_f32 v1, v1, s0
	ds_write_b16 v132, v1 offset:11840
	v_fma_f32 v1, -v36, v37, 1.0
	v_fmac_f32_e32 v37, v1, v37
	v_div_scale_f32 v1, vcc, v43, v2, v43
	v_mul_f32_e32 v38, v1, v37
	v_fma_f32 v40, -v36, v38, v1
	v_fmac_f32_e32 v38, v40, v37
	v_fma_f32 v1, -v36, v38, v1
	v_mul_f32_e32 v36, 0xbfb8aa3b, v32
	v_exp_f32_e32 v36, v36
	v_div_fmas_f32 v1, v1, v37, v38
	v_div_fixup_f32 v1, v1, v2, v43
	v_mul_f32_e32 v1, v39, v1
	v_add_f32_e32 v2, 1.0, v36
	v_div_scale_f32 v36, s[10:11], v2, v2, v32
	v_rcp_f32_e32 v37, v36
	v_cvt_pk_bf16_f32 v1, v1, s0
	ds_write_b16 v132, v1 offset:11984
	v_fma_f32 v1, -v36, v37, 1.0
	v_fmac_f32_e32 v37, v1, v37
	v_div_scale_f32 v1, vcc, v32, v2, v32
	v_mul_f32_e32 v38, v1, v37
	v_fma_f32 v39, -v36, v38, v1
	v_fmac_f32_e32 v38, v39, v37
	v_fma_f32 v1, -v36, v38, v1
	v_mul_f32_e32 v36, 0xbfb8aa3b, v33
	v_exp_f32_e32 v36, v36
	v_div_fmas_f32 v1, v1, v37, v38
	v_div_fixup_f32 v1, v1, v2, v32
	v_mul_f32_e32 v1, v28, v1
	v_add_f32_e32 v2, 1.0, v36
	v_div_scale_f32 v32, s[10:11], v2, v2, v33
	v_rcp_f32_e32 v36, v32
	v_cvt_pk_bf16_f32 v1, v1, s0
	ds_write_b16 v132, v1 offset:13824
	v_fma_f32 v1, -v32, v36, 1.0
	v_fmac_f32_e32 v36, v1, v36
	v_div_scale_f32 v1, vcc, v33, v2, v33
	v_mul_f32_e32 v28, v1, v36
	v_fma_f32 v37, -v32, v28, v1
	v_fmac_f32_e32 v28, v37, v36
	v_fma_f32 v1, -v32, v28, v1
	v_mul_f32_e32 v32, 0xbfb8aa3b, v34
	v_exp_f32_e32 v32, v32
	v_div_fmas_f32 v1, v1, v36, v28
	v_div_fixup_f32 v1, v1, v2, v33
	v_mul_f32_e32 v1, v29, v1
	v_add_f32_e32 v2, 1.0, v32
	v_div_scale_f32 v28, s[10:11], v2, v2, v34
	v_rcp_f32_e32 v32, v28
	v_cvt_pk_bf16_f32 v1, v1, s0
	ds_write_b16 v132, v1 offset:13968
	v_fma_f32 v1, -v28, v32, 1.0
	v_fmac_f32_e32 v32, v1, v32
	v_div_scale_f32 v1, vcc, v34, v2, v34
	v_mul_f32_e32 v29, v1, v32
	v_fma_f32 v33, -v28, v29, v1
	v_fmac_f32_e32 v29, v33, v32
	v_fma_f32 v1, -v28, v29, v1
	v_mul_f32_e32 v28, 0xbfb8aa3b, v35
	v_exp_f32_e32 v28, v28
	v_div_fmas_f32 v1, v1, v32, v29
	v_div_fixup_f32 v1, v1, v2, v34
	v_mul_f32_e32 v1, v30, v1
	v_add_f32_e32 v2, 1.0, v28
	v_div_scale_f32 v28, s[10:11], v2, v2, v35
	v_rcp_f32_e32 v29, v28
	v_cvt_pk_bf16_f32 v1, v1, s0
	ds_write_b16 v132, v1 offset:14112
	v_fma_f32 v1, -v28, v29, 1.0
	v_fmac_f32_e32 v29, v1, v29
	v_div_scale_f32 v1, vcc, v35, v2, v35
	v_mul_f32_e32 v30, v1, v29
	v_fma_f32 v32, -v28, v30, v1
	v_fmac_f32_e32 v30, v32, v29
	v_fma_f32 v1, -v28, v30, v1
	v_mul_f32_e32 v28, 0xbfb8aa3b, v24
	v_exp_f32_e32 v28, v28
	v_div_fmas_f32 v1, v1, v29, v30
	v_div_fixup_f32 v1, v1, v2, v35
	v_mul_f32_e32 v1, v31, v1
	v_add_f32_e32 v2, 1.0, v28
	v_div_scale_f32 v28, s[10:11], v2, v2, v24
	v_rcp_f32_e32 v29, v28
	v_cvt_pk_bf16_f32 v1, v1, s0
	ds_write_b16 v132, v1 offset:14256
	v_fma_f32 v1, -v28, v29, 1.0
	v_fmac_f32_e32 v29, v1, v29
	v_div_scale_f32 v1, vcc, v24, v2, v24
	v_mul_f32_e32 v30, v1, v29
	v_fma_f32 v31, -v28, v30, v1
	v_fmac_f32_e32 v30, v31, v29
	v_fma_f32 v1, -v28, v30, v1
	v_mul_f32_e32 v28, 0xbfb8aa3b, v25
	v_exp_f32_e32 v28, v28
	v_div_fmas_f32 v1, v1, v29, v30
	v_div_fixup_f32 v1, v1, v2, v24
	v_mul_f32_e32 v1, v20, v1
	v_add_f32_e32 v2, 1.0, v28
	v_div_scale_f32 v24, s[10:11], v2, v2, v25
	v_rcp_f32_e32 v28, v24
	v_cvt_pk_bf16_f32 v1, v1, s0
	ds_write_b16 v132, v1 offset:13856
	v_fma_f32 v1, -v24, v28, 1.0
	v_fmac_f32_e32 v28, v1, v28
	v_div_scale_f32 v1, vcc, v25, v2, v25
	v_mul_f32_e32 v20, v1, v28
	v_fma_f32 v29, -v24, v20, v1
	v_fmac_f32_e32 v20, v29, v28
	v_fma_f32 v1, -v24, v20, v1
	v_mul_f32_e32 v24, 0xbfb8aa3b, v26
	v_exp_f32_e32 v24, v24
	v_div_fmas_f32 v1, v1, v28, v20
	v_div_fixup_f32 v1, v1, v2, v25
	v_mul_f32_e32 v1, v21, v1
	v_add_f32_e32 v2, 1.0, v24
	v_div_scale_f32 v20, s[10:11], v2, v2, v26
	v_rcp_f32_e32 v24, v20
	v_cvt_pk_bf16_f32 v1, v1, s0
	ds_write_b16 v132, v1 offset:14000
	v_fma_f32 v1, -v20, v24, 1.0
	v_fmac_f32_e32 v24, v1, v24
	v_div_scale_f32 v1, vcc, v26, v2, v26
	v_mul_f32_e32 v21, v1, v24
	v_fma_f32 v25, -v20, v21, v1
	v_fmac_f32_e32 v21, v25, v24
	v_fma_f32 v1, -v20, v21, v1
	v_mul_f32_e32 v20, 0xbfb8aa3b, v27
	v_exp_f32_e32 v20, v20
	v_div_fmas_f32 v1, v1, v24, v21
	v_div_fixup_f32 v1, v1, v2, v26
	v_mul_f32_e32 v1, v22, v1
	v_add_f32_e32 v2, 1.0, v20
	v_div_scale_f32 v20, s[10:11], v2, v2, v27
	v_rcp_f32_e32 v21, v20
	v_cvt_pk_bf16_f32 v1, v1, s0
	ds_write_b16 v132, v1 offset:14144
	v_fma_f32 v1, -v20, v21, 1.0
	v_fmac_f32_e32 v21, v1, v21
	v_div_scale_f32 v1, vcc, v27, v2, v27
	v_mul_f32_e32 v22, v1, v21
	v_fma_f32 v24, -v20, v22, v1
; DEVI float silu_(float x) { return x / (1.f + __expf(-x)); }
; DEVI void ffn1_tile256(const P& p, const bf* W, long row0, int n0  , char* smem) {
;     ...
; #pragma unroll
;   for (int m = 0; m < 8; ++m)
; #pragma unroll
;     for (int pr = 0; pr < 2; ++pr) {
;       const int cl = (wc * 2 + pr) * 16 + l15;
; #pragma unroll
;       for (int j = 0; j < 4; ++j) {
;         const int rl = wr * 128 + m * 16 + quad * 4 + j;
;         float a = acc[m][2 * pr][j], b = acc[m][2 * pr + 1][j];
;         tl[rl * 72 + cl] = f2bf(silu_(a) * b);
;       }
;     }
;   __syncthreads();
	v_fmac_f32_e32 v22, v24, v21
	v_fma_f32 v1, -v20, v22, v1
	v_mul_f32_e32 v20, 0xbfb8aa3b, v16
	v_exp_f32_e32 v20, v20
	v_div_fmas_f32 v1, v1, v21, v22
	v_div_fixup_f32 v1, v1, v2, v27
	v_mul_f32_e32 v1, v23, v1
	v_add_f32_e32 v2, 1.0, v20
	v_div_scale_f32 v20, s[10:11], v2, v2, v16
	v_rcp_f32_e32 v21, v20
	v_cvt_pk_bf16_f32 v1, v1, s0
	ds_write_b16 v132, v1 offset:14288
	v_fma_f32 v1, -v20, v21, 1.0
	v_fmac_f32_e32 v21, v1, v21
	v_div_scale_f32 v1, vcc, v16, v2, v16
	v_mul_f32_e32 v22, v1, v21
	v_fma_f32 v23, -v20, v22, v1
	v_fmac_f32_e32 v22, v23, v21
	v_fma_f32 v1, -v20, v22, v1
	v_mul_f32_e32 v20, 0xbfb8aa3b, v17
	v_exp_f32_e32 v20, v20
	v_div_fmas_f32 v1, v1, v21, v22
	v_div_fixup_f32 v1, v1, v2, v16
	v_mul_f32_e32 v1, v12, v1
	v_add_f32_e32 v2, 1.0, v20
	v_div_scale_f32 v16, s[10:11], v2, v2, v17
	v_rcp_f32_e32 v20, v16
	v_cvt_pk_bf16_f32 v1, v1, s0
	ds_write_b16 v132, v1 offset:16128
	v_fma_f32 v1, -v16, v20, 1.0
	v_fmac_f32_e32 v20, v1, v20
	v_div_scale_f32 v1, vcc, v17, v2, v17
	v_mul_f32_e32 v12, v1, v20
	v_fma_f32 v21, -v16, v12, v1
	v_fmac_f32_e32 v12, v21, v20
	v_fma_f32 v1, -v16, v12, v1
	v_mul_f32_e32 v16, 0xbfb8aa3b, v18
	v_exp_f32_e32 v16, v16
	v_div_fmas_f32 v1, v1, v20, v12
	v_div_fixup_f32 v1, v1, v2, v17
	v_mul_f32_e32 v1, v13, v1
	v_add_f32_e32 v2, 1.0, v16
	v_div_scale_f32 v12, s[10:11], v2, v2, v18
	v_rcp_f32_e32 v16, v12
	v_cvt_pk_bf16_f32 v1, v1, s0
	ds_write_b16 v132, v1 offset:16272
	v_fma_f32 v1, -v12, v16, 1.0
	v_fmac_f32_e32 v16, v1, v16
	v_div_scale_f32 v1, vcc, v18, v2, v18
	v_mul_f32_e32 v13, v1, v16
	v_fma_f32 v17, -v12, v13, v1
	v_fmac_f32_e32 v13, v17, v16
	v_fma_f32 v1, -v12, v13, v1
	v_mul_f32_e32 v12, 0xbfb8aa3b, v19
	v_exp_f32_e32 v12, v12
	v_div_fmas_f32 v1, v1, v16, v13
	v_div_fixup_f32 v1, v1, v2, v18
	v_mul_f32_e32 v1, v14, v1
	v_add_f32_e32 v2, 1.0, v12
	v_div_scale_f32 v12, s[10:11], v2, v2, v19
	v_rcp_f32_e32 v13, v12
	v_cvt_pk_bf16_f32 v1, v1, s0
	ds_write_b16 v132, v1 offset:16416
	v_fma_f32 v1, -v12, v13, 1.0
	v_fmac_f32_e32 v13, v1, v13
	v_div_scale_f32 v1, vcc, v19, v2, v19
	v_mul_f32_e32 v14, v1, v13
	v_fma_f32 v16, -v12, v14, v1
	v_fmac_f32_e32 v14, v16, v13
	v_fma_f32 v1, -v12, v14, v1
	v_mul_f32_e32 v12, 0xbfb8aa3b, v8
	v_exp_f32_e32 v12, v12
	v_div_fmas_f32 v1, v1, v13, v14
	v_div_fixup_f32 v1, v1, v2, v19
	v_mul_f32_e32 v1, v15, v1
	v_add_f32_e32 v2, 1.0, v12
	v_div_scale_f32 v12, s[10:11], v2, v2, v8
	v_rcp_f32_e32 v13, v12
	v_cvt_pk_bf16_f32 v1, v1, s0
	ds_write_b16 v132, v1 offset:16560
	v_fma_f32 v1, -v12, v13, 1.0
	v_fmac_f32_e32 v13, v1, v13
	v_div_scale_f32 v1, vcc, v8, v2, v8
	v_mul_f32_e32 v14, v1, v13
	v_fma_f32 v15, -v12, v14, v1
	v_fmac_f32_e32 v14, v15, v13
	v_fma_f32 v1, -v12, v14, v1
	v_mul_f32_e32 v12, 0xbfb8aa3b, v9
	v_exp_f32_e32 v12, v12
	v_div_fmas_f32 v1, v1, v13, v14
	v_div_fixup_f32 v1, v1, v2, v8
	v_mul_f32_e32 v1, v4, v1
	v_add_f32_e32 v2, 1.0, v12
	v_div_scale_f32 v8, s[10:11], v2, v2, v9
	v_rcp_f32_e32 v12, v8
	v_cvt_pk_bf16_f32 v1, v1, s0
	ds_write_b16 v132, v1 offset:16160
	v_fma_f32 v1, -v8, v12, 1.0
	v_fmac_f32_e32 v12, v1, v12
	v_div_scale_f32 v1, vcc, v9, v2, v9
	v_mul_f32_e32 v4, v1, v12
	v_fma_f32 v13, -v8, v4, v1
	v_fmac_f32_e32 v4, v13, v12
	v_fma_f32 v1, -v8, v4, v1
	v_mul_f32_e32 v8, 0xbfb8aa3b, v10
	v_exp_f32_e32 v8, v8
	v_div_fmas_f32 v1, v1, v12, v4
	v_div_fixup_f32 v1, v1, v2, v9
	v_mul_f32_e32 v1, v5, v1
	v_add_f32_e32 v2, 1.0, v8
	v_div_scale_f32 v4, s[10:11], v2, v2, v10
	v_rcp_f32_e32 v8, v4
	v_cvt_pk_bf16_f32 v1, v1, s0
	ds_write_b16 v132, v1 offset:16304
	v_fma_f32 v1, -v4, v8, 1.0
	v_fmac_f32_e32 v8, v1, v8
	v_div_scale_f32 v1, vcc, v10, v2, v10
	v_mul_f32_e32 v5, v1, v8
	v_fma_f32 v9, -v4, v5, v1
	v_fmac_f32_e32 v5, v9, v8
	v_fma_f32 v1, -v4, v5, v1
	v_mul_f32_e32 v4, 0xbfb8aa3b, v11
	v_exp_f32_e32 v4, v4
	v_div_fmas_f32 v1, v1, v8, v5
	v_div_fixup_f32 v1, v1, v2, v10
	v_mul_f32_e32 v1, v6, v1
	v_add_f32_e32 v2, 1.0, v4
	v_div_scale_f32 v4, s[10:11], v2, v2, v11
	v_rcp_f32_e32 v5, v4
	v_cvt_pk_bf16_f32 v1, v1, s0
	ds_write_b16 v132, v1 offset:16448
	s_ashr_i32 s10, s38, 1
	v_fma_f32 v1, -v4, v5, 1.0
	v_fmac_f32_e32 v5, v1, v5
	v_div_scale_f32 v1, vcc, v11, v2, v11
	v_mul_f32_e32 v6, v1, v5
	v_fma_f32 v8, -v4, v6, v1
	v_fmac_f32_e32 v6, v8, v5
	v_fma_f32 v1, -v4, v6, v1
	v_div_fmas_f32 v1, v1, v5, v6
	v_div_fixup_f32 v1, v1, v2, v11
	v_mul_f32_e32 v1, v7, v1
	v_cvt_pk_bf16_f32 v1, v1, s0
	ds_write_b16 v132, v1 offset:16592
	v_mov_b32_e32 v1, v178
	s_waitcnt lgkmcnt(0)
	s_barrier
; DEVI int get_tid() { int t = threadIdx.x; asm volatile("" : "+v"(t)); return t; }
; template <int BN>
; DEVI void tile_store256(const char* smem, bf* __restrict__ C, long ldc, long row0, int col0) {
;   constexpr int LDT = BN + 8;
;   constexpr int CPR = BN / 8;
;   const int tid = get_tid();
; #pragma unroll
;   for (int i = 0; i < CPR; ++i) {
;     const int q = tid + 256 * i;
;     const int r = q / CPR, c = q - r * CPR;
;     u32x4 v = *reinterpret_cast<const u32x4*>(smem + (r * LDT + c * 8) * 2);
;     *reinterpret_cast<u32x4*>(C + (row0 + r) * ldc + col0 + c * 8) = v;
;   }
; }
; DEVI void phase_ffn1(const P& p, int f, char* smem) {
;     ...
;   for (int v = blockIdx.x; v < 128 * 44; v += gridDim.x) {
;     int m2, nt;
;     lat_tile_map256(v, 44, m2, nt);
;     ffn1_tile256(p, W, lat_row0_256(m2), nt * 128, smem);
;   }
	s_ashr_i32 s11, s10, 31
	v_ashrrev_i32_e32 v2, 31, v1
	v_lshrrev_b32_e32 v2, 29, v2
	s_lshl_b64 s[10:11], s[10:11], 1
	v_add_u32_e32 v2, v1, v2
	s_add_u32 s10, s58, s10
	v_ashrrev_i32_e32 v8, 3, v2
	s_addc_u32 s11, s59, s11
	v_lshlrev_b32_e32 v4, 6, v8
	v_lshlrev_b32_e32 v5, 3, v1
	v_ashrrev_i32_e32 v9, 31, v8
	v_mul_lo_u32 v2, v8, s25
	v_sub_u32_e32 v10, v5, v4
	v_lshl_add_u64 v[8:9], s[34:35], 0, v[8:9]
	v_mov_b64_e32 v[12:13], s[10:11]
	v_add_lshl_u32 v2, v10, v2, 1
	v_mad_u64_u32 v[14:15], s[10:11], v8, s73, v[12:13]
	ds_read_b128 v[4:7], v2
	v_mov_b32_e32 v2, v15
	v_mad_u64_u32 v[8:9], s[10:11], v9, s73, v[2:3]
	v_add_u32_e32 v2, 0x100, v1
	v_mov_b32_e32 v15, v8
	v_ashrrev_i32_e32 v8, 31, v2
	v_lshrrev_b32_e32 v8, 29, v8
	v_add_u32_e32 v8, v2, v8
	v_ashrrev_i32_e32 v16, 3, v8
	v_ashrrev_i32_e32 v11, 31, v10
	v_lshlrev_b32_e32 v9, 6, v16
	v_lshlrev_b32_e32 v2, 3, v2
	v_lshl_add_u64 v[14:15], v[10:11], 1, v[14:15]
	v_mul_lo_u32 v8, v16, s25
	v_sub_u32_e32 v18, v2, v9
	v_ashrrev_i32_e32 v17, 31, v16
	v_add_lshl_u32 v2, v18, v8, 1
	s_waitcnt lgkmcnt(0)
	global_store_dwordx4 v[14:15], v[4:7], off
	ds_read_b128 v[8:11], v2
	v_ashrrev_i32_e32 v19, 31, v18
	v_lshl_add_u64 v[4:5], s[34:35], 0, v[16:17]
	v_mad_u64_u32 v[6:7], s[10:11], v4, s73, v[12:13]
	v_mov_b32_e32 v2, v7
	v_mad_u64_u32 v[4:5], s[10:11], v5, s73, v[2:3]
	v_mov_b32_e32 v7, v4
	v_lshl_add_u64 v[4:5], v[18:19], 1, v[6:7]
	v_add_u32_e32 v2, 0x200, v1
	s_waitcnt lgkmcnt(0)
	global_store_dwordx4 v[4:5], v[8:11], off
	v_ashrrev_i32_e32 v4, 31, v2
	v_lshrrev_b32_e32 v4, 29, v4
	v_add_u32_e32 v4, v2, v4
	v_ashrrev_i32_e32 v8, 3, v4
	v_lshlrev_b32_e32 v5, 6, v8
	v_lshlrev_b32_e32 v2, 3, v2
	v_ashrrev_i32_e32 v9, 31, v8
	v_mul_lo_u32 v4, v8, s25
	v_sub_u32_e32 v10, v2, v5
	v_lshl_add_u64 v[8:9], s[34:35], 0, v[8:9]
	v_add_lshl_u32 v2, v10, v4, 1
	v_mad_u64_u32 v[14:15], s[10:11], v8, s73, v[12:13]
	ds_read_b128 v[4:7], v2
	v_mov_b32_e32 v2, v15
	v_mad_u64_u32 v[8:9], s[10:11], v9, s73, v[2:3]
	v_add_u32_e32 v2, 0x300, v1
	v_mov_b32_e32 v15, v8
	v_ashrrev_i32_e32 v8, 31, v2
	v_lshrrev_b32_e32 v8, 29, v8
	v_add_u32_e32 v8, v2, v8
	v_ashrrev_i32_e32 v16, 3, v8
	v_ashrrev_i32_e32 v11, 31, v10
	v_lshlrev_b32_e32 v9, 6, v16
	v_lshlrev_b32_e32 v2, 3, v2
	v_lshl_add_u64 v[14:15], v[10:11], 1, v[14:15]
	v_mul_lo_u32 v8, v16, s25
	v_sub_u32_e32 v18, v2, v9
	v_ashrrev_i32_e32 v17, 31, v16
	v_add_lshl_u32 v2, v18, v8, 1
	s_waitcnt lgkmcnt(0)
	global_store_dwordx4 v[14:15], v[4:7], off
	ds_read_b128 v[8:11], v2
	v_ashrrev_i32_e32 v19, 31, v18
	v_lshl_add_u64 v[4:5], s[34:35], 0, v[16:17]
	v_mad_u64_u32 v[6:7], s[10:11], v4, s73, v[12:13]
	v_mov_b32_e32 v2, v7
	v_mad_u64_u32 v[4:5], s[10:11], v5, s73, v[2:3]
	v_mov_b32_e32 v7, v4
	v_lshl_add_u64 v[4:5], v[18:19], 1, v[6:7]
	v_add_u32_e32 v2, 0x400, v1
	s_waitcnt lgkmcnt(0)
	global_store_dwordx4 v[4:5], v[8:11], off
	v_ashrrev_i32_e32 v4, 31, v2
	v_lshrrev_b32_e32 v4, 29, v4
	v_add_u32_e32 v4, v2, v4
	v_ashrrev_i32_e32 v8, 3, v4
	v_lshlrev_b32_e32 v5, 6, v8
	v_lshlrev_b32_e32 v2, 3, v2
	v_ashrrev_i32_e32 v9, 31, v8
	v_mul_lo_u32 v4, v8, s25
	v_sub_u32_e32 v10, v2, v5
	v_lshl_add_u64 v[8:9], s[34:35], 0, v[8:9]
	v_add_lshl_u32 v2, v10, v4, 1
	v_mad_u64_u32 v[14:15], s[10:11], v8, s73, v[12:13]
	ds_read_b128 v[4:7], v2
	v_mov_b32_e32 v2, v15
	v_mad_u64_u32 v[8:9], s[10:11], v9, s73, v[2:3]
	v_add_u32_e32 v2, 0x500, v1
	v_mov_b32_e32 v15, v8
	v_ashrrev_i32_e32 v8, 31, v2
	v_lshrrev_b32_e32 v8, 29, v8
	v_add_u32_e32 v8, v2, v8
	v_ashrrev_i32_e32 v16, 3, v8
	v_ashrrev_i32_e32 v11, 31, v10
	v_lshlrev_b32_e32 v9, 6, v16
	v_lshlrev_b32_e32 v2, 3, v2
	v_lshl_add_u64 v[14:15], v[10:11], 1, v[14:15]
	v_mul_lo_u32 v8, v16, s25
	v_sub_u32_e32 v18, v2, v9
	v_ashrrev_i32_e32 v17, 31, v16
	v_add_lshl_u32 v2, v18, v8, 1
	s_waitcnt lgkmcnt(0)
	global_store_dwordx4 v[14:15], v[4:7], off
	ds_read_b128 v[8:11], v2
	v_ashrrev_i32_e32 v19, 31, v18
	v_lshl_add_u64 v[4:5], s[34:35], 0, v[16:17]
	v_mad_u64_u32 v[6:7], s[10:11], v4, s73, v[12:13]
	v_mov_b32_e32 v2, v7
	v_mad_u64_u32 v[4:5], s[10:11], v5, s73, v[2:3]
	v_mov_b32_e32 v7, v4
	v_lshl_add_u64 v[4:5], v[18:19], 1, v[6:7]
	v_add_u32_e32 v2, 0x600, v1
	s_waitcnt lgkmcnt(0)
	global_store_dwordx4 v[4:5], v[8:11], off
	v_ashrrev_i32_e32 v4, 31, v2
	v_lshrrev_b32_e32 v4, 29, v4
	v_add_u32_e32 v4, v2, v4
	v_ashrrev_i32_e32 v8, 3, v4
	v_lshlrev_b32_e32 v5, 6, v8
	v_lshlrev_b32_e32 v2, 3, v2
	v_ashrrev_i32_e32 v9, 31, v8
	v_mul_lo_u32 v4, v8, s25
	v_sub_u32_e32 v10, v2, v5
	v_lshl_add_u64 v[8:9], s[34:35], 0, v[8:9]
	v_add_lshl_u32 v2, v10, v4, 1
	v_mad_u64_u32 v[14:15], s[10:11], v8, s73, v[12:13]
	ds_read_b128 v[4:7], v2
	v_mov_b32_e32 v2, v15
	v_add_u32_e32 v1, 0x700, v1
	v_mad_u64_u32 v[8:9], s[10:11], v9, s73, v[2:3]
	v_ashrrev_i32_e32 v2, 31, v1
	v_lshrrev_b32_e32 v2, 29, v2
	v_add_u32_e32 v2, v1, v2
	v_mov_b32_e32 v15, v8
	v_ashrrev_i32_e32 v11, 31, v10
	v_ashrrev_i32_e32 v16, 3, v2
	v_lshl_add_u64 v[14:15], v[10:11], 1, v[14:15]
	v_lshlrev_b32_e32 v8, 6, v16
	v_lshlrev_b32_e32 v1, 3, v1
	v_ashrrev_i32_e32 v17, 31, v16
	v_mul_lo_u32 v2, v16, s25
	v_sub_u32_e32 v18, v1, v8
	s_waitcnt lgkmcnt(0)
	global_store_dwordx4 v[14:15], v[4:7], off
	v_add_lshl_u32 v1, v18, v2, 1
	ds_read_b128 v[8:11], v1
	v_lshl_add_u64 v[4:5], s[34:35], 0, v[16:17]
	v_mad_u64_u32 v[6:7], s[10:11], v4, s73, v[12:13]
	v_mov_b32_e32 v2, v7
	v_mad_u64_u32 v[4:5], s[10:11], v5, s73, v[2:3]
	v_readlane_b32 s10, v252, 59
	v_mov_b32_e32 v7, v4
	v_ashrrev_i32_e32 v19, 31, v18
	s_add_i32 s2, s2, s10
	v_lshl_add_u64 v[4:5], v[18:19], 1, v[6:7]
	s_cmpk_gt_i32 s2, 0x15ff
	s_waitcnt lgkmcnt(0)
	global_store_dwordx4 v[4:5], v[8:11], off
	s_barrier
	v_readlane_b32 s11, v252, 60
	s_cbranch_scc0 .LBB0_183

; DEVI f32x4 mfma16(bf16x8 a, bf16x8 b, f32x4 c) { return __builtin_amdgcn_mfma_f32_16x16x32_bf16(a, b, c, 0, 0, 0); }
; DEVI void gemm_core3(f32x4 (&acc)[8][4], const bf* __restrict__ A, int lda, const bf* __restrict__ Bt, int ldb, int K, char* smem) {
;     ...
;   for (int kt = 0; kt < nk; ++kt) {
;     const int k1 = min((kt + 1) * 32, klast);
;     const int sn = ((kt + 1) & 1) * STG;
;     const int so = (kt & 1) * STG;
;     bf16x8 bfr[4], af[8];
; #pragma unroll
;     for (int n = 0; n < 4; ++n) bfr[n] = *reinterpret_cast<const bf16x8*>(bbase + so + n * 16 * 64);
; #pragma unroll
;     for (int m = 0; m < 8; ++m) af[m] = *reinterpret_cast<const bf16x8*>(abase + so + m * 16 * 64);
; #pragma unroll
;     for (int i = 0; i < 4; ++i) glds16(Ap + i * sa + k1, dbase + sn + i * 4096);
; #pragma unroll
;     for (int i = 0; i < 2; ++i) glds16(Bp + i * sb + k1, dbase + sn + ASZ + i * 4096);
;     __builtin_amdgcn_s_setprio(1);
; #pragma unroll
;     for (int m = 0; m < 8; ++m)
; #pragma unroll
;       for (int n = 0; n < 4; ++n) acc[m][n] = mfma16(af[m], bfr[n], acc[m][n]);
;     __builtin_amdgcn_s_setprio(0);
;     __syncthreads();
;   }
.Lg3_loop_206:
	v_add_u32_e32 v216, s10, v146
	v_add_u32_e32 v217, s10, v2
	ds_read_b128 v[148:151], v217 offset:16384
	ds_read_b128 v[166:169], v216
	ds_read_b128 v[154:157], v217 offset:17408
	ds_read_b128 v[158:161], v217 offset:18432
	ds_read_b128 v[162:165], v217 offset:19456
	ds_read_b128 v[170:173], v216 offset:1024
	ds_read_b128 v[174:177], v216 offset:2048
	ds_read_b128 v[192:195], v216 offset:3072
	ds_read_b128 v[196:199], v216 offset:4096
	ds_read_b128 v[204:207], v216 offset:5120
	ds_read_b128 v[208:211], v216 offset:6144
	ds_read_b128 v[212:215], v216 offset:7168
	s_setprio 1
	s_waitcnt lgkmcnt(10)
	v_mfma_f32_16x16x32_bf16 v[128:131], v[166:169], v[148:151], v[128:131]
	s_waitcnt lgkmcnt(9)
	v_mfma_f32_16x16x32_bf16 v[124:127], v[166:169], v[154:157], v[124:127]
	s_waitcnt lgkmcnt(8)
	v_mfma_f32_16x16x32_bf16 v[120:123], v[166:169], v[158:161], v[120:123]
	s_waitcnt lgkmcnt(7)
	v_mfma_f32_16x16x32_bf16 v[116:119], v[166:169], v[162:165], v[116:119]
	s_waitcnt lgkmcnt(6)
	v_mfma_f32_16x16x32_bf16 v[112:115], v[170:173], v[148:151], v[112:115]
	v_mfma_f32_16x16x32_bf16 v[108:111], v[170:173], v[154:157], v[108:111]
	v_mfma_f32_16x16x32_bf16 v[104:107], v[170:173], v[158:161], v[104:107]
	v_mfma_f32_16x16x32_bf16 v[100:103], v[170:173], v[162:165], v[100:103]
	s_waitcnt lgkmcnt(5)
	v_mfma_f32_16x16x32_bf16 v[96:99], v[174:177], v[148:151], v[96:99]
	v_mfma_f32_16x16x32_bf16 v[92:95], v[174:177], v[154:157], v[92:95]
	v_mfma_f32_16x16x32_bf16 v[88:91], v[174:177], v[158:161], v[88:91]
	v_mfma_f32_16x16x32_bf16 v[84:87], v[174:177], v[162:165], v[84:87]
	s_waitcnt lgkmcnt(4)
	v_mfma_f32_16x16x32_bf16 v[80:83], v[192:195], v[148:151], v[80:83]
	v_mfma_f32_16x16x32_bf16 v[76:79], v[192:195], v[154:157], v[76:79]
	v_mfma_f32_16x16x32_bf16 v[72:75], v[192:195], v[158:161], v[72:75]
	v_mfma_f32_16x16x32_bf16 v[68:71], v[192:195], v[162:165], v[68:71]
	s_waitcnt lgkmcnt(3)
	v_mfma_f32_16x16x32_bf16 v[64:67], v[196:199], v[148:151], v[64:67]
	v_mfma_f32_16x16x32_bf16 v[60:63], v[196:199], v[154:157], v[60:63]
	v_mfma_f32_16x16x32_bf16 v[56:59], v[196:199], v[158:161], v[56:59]
	v_mfma_f32_16x16x32_bf16 v[52:55], v[196:199], v[162:165], v[52:55]
	s_waitcnt lgkmcnt(2)
	v_mfma_f32_16x16x32_bf16 v[48:51], v[204:207], v[148:151], v[48:51]
	v_mfma_f32_16x16x32_bf16 v[44:47], v[204:207], v[154:157], v[44:47]
	v_mfma_f32_16x16x32_bf16 v[40:43], v[204:207], v[158:161], v[40:43]
	v_mfma_f32_16x16x32_bf16 v[36:39], v[204:207], v[162:165], v[36:39]
	s_waitcnt lgkmcnt(1)
	v_mfma_f32_16x16x32_bf16 v[32:35], v[208:211], v[148:151], v[32:35]
	v_mfma_f32_16x16x32_bf16 v[28:31], v[208:211], v[154:157], v[28:31]
	v_mfma_f32_16x16x32_bf16 v[24:27], v[208:211], v[158:161], v[24:27]
	v_mfma_f32_16x16x32_bf16 v[20:23], v[208:211], v[162:165], v[20:23]
	s_waitcnt lgkmcnt(0)
	v_mfma_f32_16x16x32_bf16 v[16:19], v[212:215], v[148:151], v[16:19]
	v_mfma_f32_16x16x32_bf16 v[12:15], v[212:215], v[154:157], v[12:15]
	v_mfma_f32_16x16x32_bf16 v[8:11], v[212:215], v[158:161], v[8:11]
	v_mfma_f32_16x16x32_bf16 v[4:7], v[212:215], v[162:165], v[4:7]
	s_setprio 0
	s_add_i32 s10, s10, 0x6000
	s_cmp_lg_u32 s10, 0x12000
	s_cselect_b32 s10, s10, 0
	s_waitcnt vmcnt(0)
	s_barrier
	s_setprio 2
	v_add_u32_e32 v216, s10, v146
	v_add_u32_e32 v217, s10, v2
	ds_read_b128 v[148:151], v217 offset:16384
	ds_read_b128 v[166:169], v216
	ds_read_b128 v[154:157], v217 offset:17408
	ds_read_b128 v[158:161], v217 offset:18432
	ds_read_b128 v[162:165], v217 offset:19456
	ds_read_b128 v[170:173], v216 offset:1024
	ds_read_b128 v[174:177], v216 offset:2048
	ds_read_b128 v[192:195], v216 offset:3072
	ds_read_b128 v[196:199], v216 offset:4096
	ds_read_b128 v[204:207], v216 offset:5120
	ds_read_b128 v[208:211], v216 offset:6144
	ds_read_b128 v[212:215], v216 offset:7168
	v_readfirstlane_b32 s17, v140
	s_add_i32 s96, s11, 0x6000
	s_cmp_lg_u32 s96, 0x12000
	s_cselect_b32 s96, s96, 0
	s_add_i32 s96, s96, s17
	s_add_i32 s17, s17, s11
	s_waitcnt lgkmcnt(10)
	s_mov_b32 m0, s17
	s_add_i32 s17, s17, 0x1000
	v_mfma_f32_16x16x32_bf16 v[128:131], v[166:169], v[148:151], v[128:131]
	s_waitcnt lgkmcnt(9)
	v_mfma_f32_16x16x32_bf16 v[124:127], v[166:169], v[154:157], v[124:127]
	global_load_lds_dwordx4 v[218:219], off
	v_lshl_add_u64 v[218:219], v[218:219], 0, 64
	s_waitcnt lgkmcnt(8)
	s_mov_b32 m0, s96
	s_add_i32 s96, s96, 0x1000
	v_mfma_f32_16x16x32_bf16 v[120:123], v[166:169], v[158:161], v[120:123]
	s_waitcnt lgkmcnt(7)
	v_mfma_f32_16x16x32_bf16 v[116:119], v[166:169], v[162:165], v[116:119]
	global_load_lds_dwordx4 v[218:219], off
	v_lshl_add_u64 v[218:219], v[218:219], 0, 64
	s_waitcnt lgkmcnt(6)
	v_mfma_f32_16x16x32_bf16 v[112:115], v[170:173], v[148:151], v[112:115]
	s_mov_b32 m0, s17
	s_add_i32 s17, s17, 0x1000
	v_mfma_f32_16x16x32_bf16 v[108:111], v[170:173], v[154:157], v[108:111]
	v_mfma_f32_16x16x32_bf16 v[104:107], v[170:173], v[158:161], v[104:107]
	global_load_lds_dwordx4 v[220:221], off
	v_lshl_add_u64 v[220:221], v[220:221], 0, 64
	s_mov_b32 m0, s96
	s_add_i32 s96, s96, 0x1000
	v_mfma_f32_16x16x32_bf16 v[100:103], v[170:173], v[162:165], v[100:103]
	s_waitcnt lgkmcnt(5)
	v_mfma_f32_16x16x32_bf16 v[96:99], v[174:177], v[148:151], v[96:99]
	global_load_lds_dwordx4 v[220:221], off
	v_lshl_add_u64 v[220:221], v[220:221], 0, 64
	v_mfma_f32_16x16x32_bf16 v[92:95], v[174:177], v[154:157], v[92:95]
	s_mov_b32 m0, s17
	s_add_i32 s17, s17, 0x1000
	v_mfma_f32_16x16x32_bf16 v[88:91], v[174:177], v[158:161], v[88:91]
	v_mfma_f32_16x16x32_bf16 v[84:87], v[174:177], v[162:165], v[84:87]
	global_load_lds_dwordx4 v[222:223], off
	v_lshl_add_u64 v[222:223], v[222:223], 0, 64
	s_waitcnt lgkmcnt(4)
; DEVI f32x4 mfma16(bf16x8 a, bf16x8 b, f32x4 c) { return __builtin_amdgcn_mfma_f32_16x16x32_bf16(a, b, c, 0, 0, 0); }
; DEVI void gemm_core3(f32x4 (&acc)[8][4], const bf* __restrict__ A, int lda, const bf* __restrict__ Bt, int ldb, int K, char* smem) {
;     ...
;   for (int kt = 0; kt < nk; ++kt) {
;     const int k1 = min((kt + 1) * 32, klast);
;     const int sn = ((kt + 1) & 1) * STG;
;     const int so = (kt & 1) * STG;
;     bf16x8 bfr[4], af[8];
; #pragma unroll
;     for (int n = 0; n < 4; ++n) bfr[n] = *reinterpret_cast<const bf16x8*>(bbase + so + n * 16 * 64);
; #pragma unroll
;     for (int m = 0; m < 8; ++m) af[m] = *reinterpret_cast<const bf16x8*>(abase + so + m * 16 * 64);
; #pragma unroll
;     for (int i = 0; i < 4; ++i) glds16(Ap + i * sa + k1, dbase + sn + i * 4096);
; #pragma unroll
;     for (int i = 0; i < 2; ++i) glds16(Bp + i * sb + k1, dbase + sn + ASZ + i * 4096);
;     __builtin_amdgcn_s_setprio(1);
; #pragma unroll
;     for (int m = 0; m < 8; ++m)
; #pragma unroll
;       for (int n = 0; n < 4; ++n) acc[m][n] = mfma16(af[m], bfr[n], acc[m][n]);
;     __builtin_amdgcn_s_setprio(0);
;     __syncthreads();
;   }
	s_mov_b32 m0, s96
	s_add_i32 s96, s96, 0x1000
	v_mfma_f32_16x16x32_bf16 v[80:83], v[192:195], v[148:151], v[80:83]
	v_mfma_f32_16x16x32_bf16 v[76:79], v[192:195], v[154:157], v[76:79]
	global_load_lds_dwordx4 v[222:223], off
	v_lshl_add_u64 v[222:223], v[222:223], 0, 64
	v_mfma_f32_16x16x32_bf16 v[72:75], v[192:195], v[158:161], v[72:75]
	s_mov_b32 m0, s17
	s_add_i32 s17, s17, 0x1000
	v_mfma_f32_16x16x32_bf16 v[68:71], v[192:195], v[162:165], v[68:71]
	s_waitcnt lgkmcnt(3)
	v_mfma_f32_16x16x32_bf16 v[64:67], v[196:199], v[148:151], v[64:67]
	global_load_lds_dwordx4 v[224:225], off
	v_lshl_add_u64 v[224:225], v[224:225], 0, 64
	s_mov_b32 m0, s96
	s_add_i32 s96, s96, 0x1000
	v_mfma_f32_16x16x32_bf16 v[60:63], v[196:199], v[154:157], v[60:63]
	v_mfma_f32_16x16x32_bf16 v[56:59], v[196:199], v[158:161], v[56:59]
	global_load_lds_dwordx4 v[224:225], off
	v_lshl_add_u64 v[224:225], v[224:225], 0, 64
	v_mfma_f32_16x16x32_bf16 v[52:55], v[196:199], v[162:165], v[52:55]
	s_waitcnt lgkmcnt(2)
	s_mov_b32 m0, s17
	s_add_i32 s17, s17, 0x1000
	v_mfma_f32_16x16x32_bf16 v[48:51], v[204:207], v[148:151], v[48:51]
	v_mfma_f32_16x16x32_bf16 v[44:47], v[204:207], v[154:157], v[44:47]
	global_load_lds_dwordx4 v[226:227], off
	v_lshl_add_u64 v[226:227], v[226:227], 0, 64
	s_mov_b32 m0, s96
	s_add_i32 s96, s96, 0x1000
	v_mfma_f32_16x16x32_bf16 v[40:43], v[204:207], v[158:161], v[40:43]
	v_mfma_f32_16x16x32_bf16 v[36:39], v[204:207], v[162:165], v[36:39]
	global_load_lds_dwordx4 v[226:227], off
	v_lshl_add_u64 v[226:227], v[226:227], 0, 64
	s_waitcnt lgkmcnt(1)
	v_mfma_f32_16x16x32_bf16 v[32:35], v[208:211], v[148:151], v[32:35]
	s_mov_b32 m0, s17
	s_add_i32 s17, s17, 0x1000
	v_mfma_f32_16x16x32_bf16 v[28:31], v[208:211], v[154:157], v[28:31]
	v_mfma_f32_16x16x32_bf16 v[24:27], v[208:211], v[158:161], v[24:27]
	global_load_lds_dwordx4 v[228:229], off
	v_lshl_add_u64 v[228:229], v[228:229], 0, 64
	s_mov_b32 m0, s96
	s_add_i32 s96, s96, 0x1000
	v_mfma_f32_16x16x32_bf16 v[20:23], v[208:211], v[162:165], v[20:23]
	s_waitcnt lgkmcnt(0)
	v_mfma_f32_16x16x32_bf16 v[16:19], v[212:215], v[148:151], v[16:19]
	global_load_lds_dwordx4 v[228:229], off
	v_lshl_add_u64 v[228:229], v[228:229], 0, 64
	v_mfma_f32_16x16x32_bf16 v[12:15], v[212:215], v[154:157], v[12:15]
	v_mfma_f32_16x16x32_bf16 v[8:11], v[212:215], v[158:161], v[8:11]
	v_mfma_f32_16x16x32_bf16 v[4:7], v[212:215], v[162:165], v[4:7]
	s_setprio 0
	s_add_i32 s10, s10, 0x6000
	s_cmp_lg_u32 s10, 0x12000
	s_cselect_b32 s10, s10, 0
	s_sub_i32 s11, s11, 0x6000
	s_cmp_lt_i32 s11, 0
	s_cselect_b32 s11, 0xc000, s11
	s_add_i32 s3, s3, 1
	s_cmp_lt_i32 s3, 15
	s_waitcnt vmcnt(1)
	s_barrier
	s_cbranch_scc1 .Lg3_loop_206
	v_add_u32_e32 v216, s10, v146
	v_add_u32_e32 v217, s10, v2
	ds_read_b128 v[148:151], v217 offset:16384
	ds_read_b128 v[166:169], v216
	ds_read_b128 v[154:157], v217 offset:17408
	ds_read_b128 v[158:161], v217 offset:18432
	ds_read_b128 v[162:165], v217 offset:19456
	ds_read_b128 v[170:173], v216 offset:1024
	ds_read_b128 v[174:177], v216 offset:2048
	ds_read_b128 v[192:195], v216 offset:3072
	ds_read_b128 v[196:199], v216 offset:4096
	ds_read_b128 v[204:207], v216 offset:5120
	ds_read_b128 v[208:211], v216 offset:6144
	ds_read_b128 v[212:215], v216 offset:7168
	s_setprio 1
	s_waitcnt lgkmcnt(10)
	v_mfma_f32_16x16x32_bf16 v[128:131], v[166:169], v[148:151], v[128:131]
	s_waitcnt lgkmcnt(9)
	v_mfma_f32_16x16x32_bf16 v[124:127], v[166:169], v[154:157], v[124:127]
	s_waitcnt lgkmcnt(8)
	v_mfma_f32_16x16x32_bf16 v[120:123], v[166:169], v[158:161], v[120:123]
	s_waitcnt lgkmcnt(7)
	v_mfma_f32_16x16x32_bf16 v[116:119], v[166:169], v[162:165], v[116:119]
	s_waitcnt lgkmcnt(6)
	v_mfma_f32_16x16x32_bf16 v[112:115], v[170:173], v[148:151], v[112:115]
	v_mfma_f32_16x16x32_bf16 v[108:111], v[170:173], v[154:157], v[108:111]
	v_mfma_f32_16x16x32_bf16 v[104:107], v[170:173], v[158:161], v[104:107]
	v_mfma_f32_16x16x32_bf16 v[100:103], v[170:173], v[162:165], v[100:103]
	s_waitcnt lgkmcnt(5)
	v_mfma_f32_16x16x32_bf16 v[96:99], v[174:177], v[148:151], v[96:99]
	v_mfma_f32_16x16x32_bf16 v[92:95], v[174:177], v[154:157], v[92:95]
	v_mfma_f32_16x16x32_bf16 v[88:91], v[174:177], v[158:161], v[88:91]
	v_mfma_f32_16x16x32_bf16 v[84:87], v[174:177], v[162:165], v[84:87]
	s_waitcnt lgkmcnt(4)
	v_mfma_f32_16x16x32_bf16 v[80:83], v[192:195], v[148:151], v[80:83]
	v_mfma_f32_16x16x32_bf16 v[76:79], v[192:195], v[154:157], v[76:79]
	v_mfma_f32_16x16x32_bf16 v[72:75], v[192:195], v[158:161], v[72:75]
	v_mfma_f32_16x16x32_bf16 v[68:71], v[192:195], v[162:165], v[68:71]
	s_waitcnt lgkmcnt(3)
	v_mfma_f32_16x16x32_bf16 v[64:67], v[196:199], v[148:151], v[64:67]
	v_mfma_f32_16x16x32_bf16 v[60:63], v[196:199], v[154:157], v[60:63]
	v_mfma_f32_16x16x32_bf16 v[56:59], v[196:199], v[158:161], v[56:59]
	v_mfma_f32_16x16x32_bf16 v[52:55], v[196:199], v[162:165], v[52:55]
	s_waitcnt lgkmcnt(2)
	v_mfma_f32_16x16x32_bf16 v[48:51], v[204:207], v[148:151], v[48:51]
	v_mfma_f32_16x16x32_bf16 v[44:47], v[204:207], v[154:157], v[44:47]
	v_mfma_f32_16x16x32_bf16 v[40:43], v[204:207], v[158:161], v[40:43]
	v_mfma_f32_16x16x32_bf16 v[36:39], v[204:207], v[162:165], v[36:39]
	s_waitcnt lgkmcnt(1)
	v_mfma_f32_16x16x32_bf16 v[32:35], v[208:211], v[148:151], v[32:35]
	v_mfma_f32_16x16x32_bf16 v[28:31], v[208:211], v[154:157], v[28:31]
	v_mfma_f32_16x16x32_bf16 v[24:27], v[208:211], v[158:161], v[24:27]
	v_mfma_f32_16x16x32_bf16 v[20:23], v[208:211], v[162:165], v[20:23]
	s_waitcnt lgkmcnt(0)
	v_mfma_f32_16x16x32_bf16 v[16:19], v[212:215], v[148:151], v[16:19]
	v_mfma_f32_16x16x32_bf16 v[12:15], v[212:215], v[154:157], v[12:15]
	v_mfma_f32_16x16x32_bf16 v[8:11], v[212:215], v[158:161], v[8:11]
	v_mfma_f32_16x16x32_bf16 v[4:7], v[212:215], v[162:165], v[4:7]
	s_setprio 0
	s_add_i32 s10, s10, 0x6000
	s_cmp_lg_u32 s10, 0x12000
	s_cselect_b32 s10, s10, 0
	s_waitcnt vmcnt(0)
	s_barrier
; DEVI f32x4 mfma16(bf16x8 a, bf16x8 b, f32x4 c) { return __builtin_amdgcn_mfma_f32_16x16x32_bf16(a, b, c, 0, 0, 0); }
; DEVI void gemm_core3(f32x4 (&acc)[8][4], const bf* __restrict__ A, int lda, const bf* __restrict__ Bt, int ldb, int K, char* smem) {
;     ...
;     bf16x8 bfr[4], af[8];
; #pragma unroll
;     for (int n = 0; n < 4; ++n) bfr[n] = *reinterpret_cast<const bf16x8*>(bbase + so + n * 16 * 64);
; #pragma unroll
;     for (int m = 0; m < 8; ++m) af[m] = *reinterpret_cast<const bf16x8*>(abase + so + m * 16 * 64);
; #pragma unroll
;     for (int i = 0; i < 4; ++i) glds16(Ap + i * sa + k1, dbase + sn + i * 4096);
; #pragma unroll
;     for (int i = 0; i < 2; ++i) glds16(Bp + i * sb + k1, dbase + sn + ASZ + i * 4096);
;     __builtin_amdgcn_s_setprio(1);
; #pragma unroll
;     for (int m = 0; m < 8; ++m)
; #pragma unroll
;       for (int n = 0; n < 4; ++n) acc[m][n] = mfma16(af[m], bfr[n], acc[m][n]);
;     __builtin_amdgcn_s_setprio(0);
; DEVI void plain_tile256(const bf* A, int lda, const bf* Wt, int K, bf* C, int ldc, long row0, int n0, char* smem) {
;     ...
;   bf* tl = reinterpret_cast<bf*>(smem);
; #pragma unroll
;   for (int m = 0; m < 8; ++m)
; #pragma unroll
;     for (int n = 0; n < 4; ++n) {
;       const int cl = wc * 64 + n * 16 + l15;
; #pragma unroll
;       for (int j = 0; j < 4; ++j) tl[(wr * 128 + m * 16 + quad * 4 + j) * 136 + cl] = f2bf(acc[m][n][j]);
;     }
	v_add_u32_e32 v216, s10, v146
	v_add_u32_e32 v217, s10, v2
	ds_read_b128 v[148:151], v217 offset:16384
	ds_read_b128 v[166:169], v216
	ds_read_b128 v[154:157], v217 offset:17408
	ds_read_b128 v[158:161], v217 offset:18432
	ds_read_b128 v[162:165], v217 offset:19456
	ds_read_b128 v[170:173], v216 offset:1024
	ds_read_b128 v[174:177], v216 offset:2048
	ds_read_b128 v[192:195], v216 offset:3072
	ds_read_b128 v[196:199], v216 offset:4096
	ds_read_b128 v[204:207], v216 offset:5120
	ds_read_b128 v[208:211], v216 offset:6144
	ds_read_b128 v[212:215], v216 offset:7168
	s_setprio 1
	s_waitcnt lgkmcnt(10)
	v_mfma_f32_16x16x32_bf16 v[128:131], v[166:169], v[148:151], v[128:131]
	s_waitcnt lgkmcnt(9)
	v_mfma_f32_16x16x32_bf16 v[124:127], v[166:169], v[154:157], v[124:127]
	s_waitcnt lgkmcnt(8)
	v_mfma_f32_16x16x32_bf16 v[120:123], v[166:169], v[158:161], v[120:123]
	s_waitcnt lgkmcnt(7)
	v_mfma_f32_16x16x32_bf16 v[116:119], v[166:169], v[162:165], v[116:119]
	s_waitcnt lgkmcnt(6)
	v_mfma_f32_16x16x32_bf16 v[112:115], v[170:173], v[148:151], v[112:115]
	v_mfma_f32_16x16x32_bf16 v[108:111], v[170:173], v[154:157], v[108:111]
	v_mfma_f32_16x16x32_bf16 v[104:107], v[170:173], v[158:161], v[104:107]
	v_mfma_f32_16x16x32_bf16 v[100:103], v[170:173], v[162:165], v[100:103]
	s_waitcnt lgkmcnt(5)
	v_mfma_f32_16x16x32_bf16 v[96:99], v[174:177], v[148:151], v[96:99]
	v_mfma_f32_16x16x32_bf16 v[92:95], v[174:177], v[154:157], v[92:95]
	v_mfma_f32_16x16x32_bf16 v[88:91], v[174:177], v[158:161], v[88:91]
	v_mfma_f32_16x16x32_bf16 v[84:87], v[174:177], v[162:165], v[84:87]
	s_waitcnt lgkmcnt(4)
	v_mfma_f32_16x16x32_bf16 v[80:83], v[192:195], v[148:151], v[80:83]
	v_mfma_f32_16x16x32_bf16 v[76:79], v[192:195], v[154:157], v[76:79]
	v_mfma_f32_16x16x32_bf16 v[72:75], v[192:195], v[158:161], v[72:75]
	v_mfma_f32_16x16x32_bf16 v[68:71], v[192:195], v[162:165], v[68:71]
	s_waitcnt lgkmcnt(3)
	v_mfma_f32_16x16x32_bf16 v[64:67], v[196:199], v[148:151], v[64:67]
	v_mfma_f32_16x16x32_bf16 v[60:63], v[196:199], v[154:157], v[60:63]
	v_mfma_f32_16x16x32_bf16 v[56:59], v[196:199], v[158:161], v[56:59]
	v_mfma_f32_16x16x32_bf16 v[52:55], v[196:199], v[162:165], v[52:55]
	s_waitcnt lgkmcnt(2)
	v_mfma_f32_16x16x32_bf16 v[48:51], v[204:207], v[148:151], v[48:51]
	v_mfma_f32_16x16x32_bf16 v[44:47], v[204:207], v[154:157], v[44:47]
	v_mfma_f32_16x16x32_bf16 v[40:43], v[204:207], v[158:161], v[40:43]
	v_mfma_f32_16x16x32_bf16 v[36:39], v[204:207], v[162:165], v[36:39]
	s_waitcnt lgkmcnt(1)
	v_mfma_f32_16x16x32_bf16 v[32:35], v[208:211], v[148:151], v[32:35]
	v_mfma_f32_16x16x32_bf16 v[28:31], v[208:211], v[154:157], v[28:31]
	v_mfma_f32_16x16x32_bf16 v[24:27], v[208:211], v[158:161], v[24:27]
	v_mfma_f32_16x16x32_bf16 v[20:23], v[208:211], v[162:165], v[20:23]
	s_waitcnt lgkmcnt(0)
	v_mfma_f32_16x16x32_bf16 v[16:19], v[212:215], v[148:151], v[16:19]
	v_mfma_f32_16x16x32_bf16 v[12:15], v[212:215], v[154:157], v[12:15]
	v_mfma_f32_16x16x32_bf16 v[8:11], v[212:215], v[158:161], v[8:11]
	v_mfma_f32_16x16x32_bf16 v[4:7], v[212:215], v[162:165], v[4:7]
	s_setprio 0
	s_add_i32 s10, s10, 0x6000
	s_cmp_lg_u32 s10, 0x12000
	s_cselect_b32 s10, s10, 0
	s_waitcnt vmcnt(0)
	s_barrier
	v_and_b32_e32 v2, 0x4f, v1
	v_and_b32_e32 v132, 0xfffff80, v1
	v_lshrrev_b32_e32 v1, 2, v1
	v_and_or_b32 v1, v1, 12, v132
	v_mul_lo_u32 v1, v1, s16
	v_lshl_add_u32 v1, v2, 1, v1
	v_cvt_pk_bf16_f32 v2, v129, s0
	ds_write_b16 v1, v2 offset:272
	v_cvt_pk_bf16_f32 v2, v130, s0
	ds_write_b16 v1, v2 offset:544
	v_cvt_pk_bf16_f32 v2, v131, s0
	ds_write_b16 v1, v2 offset:816
	v_cvt_pk_bf16_f32 v2, v124, s0
	ds_write_b16 v1, v2 offset:32
	v_cvt_pk_bf16_f32 v2, v125, s0
	ds_write_b16 v1, v2 offset:304
	v_cvt_pk_bf16_f32 v2, v126, s0
	ds_write_b16 v1, v2 offset:576
	v_cvt_pk_bf16_f32 v2, v127, s0
	ds_write_b16 v1, v2 offset:848
	v_cvt_pk_bf16_f32 v2, v120, s0
	ds_write_b16 v1, v2 offset:64
	v_cvt_pk_bf16_f32 v2, v121, s0
	ds_write_b16 v1, v2 offset:336
	v_cvt_pk_bf16_f32 v2, v122, s0
	ds_write_b16 v1, v2 offset:608
	v_cvt_pk_bf16_f32 v2, v123, s0
	ds_write_b16 v1, v2 offset:880
	v_cvt_pk_bf16_f32 v2, v116, s0
	ds_write_b16 v1, v2 offset:96
	v_cvt_pk_bf16_f32 v2, v117, s0
	ds_write_b16 v1, v2 offset:368
	v_cvt_pk_bf16_f32 v2, v118, s0
	ds_write_b16 v1, v2 offset:640
	v_cvt_pk_bf16_f32 v2, v119, s0
	ds_write_b16 v1, v2 offset:912
	v_cvt_pk_bf16_f32 v2, v112, s0
	ds_write_b16 v1, v2 offset:4352
	v_cvt_pk_bf16_f32 v2, v113, s0
	ds_write_b16 v1, v2 offset:4624
	v_cvt_pk_bf16_f32 v2, v114, s0
	ds_write_b16 v1, v2 offset:4896
	v_cvt_pk_bf16_f32 v2, v115, s0
	ds_write_b16 v1, v2 offset:5168
	v_cvt_pk_bf16_f32 v2, v108, s0
	ds_write_b16 v1, v2 offset:4384
	v_cvt_pk_bf16_f32 v2, v109, s0
	ds_write_b16 v1, v2 offset:4656
	v_cvt_pk_bf16_f32 v2, v110, s0
	ds_write_b16 v1, v2 offset:4928
	v_cvt_pk_bf16_f32 v2, v111, s0
	ds_write_b16 v1, v2 offset:5200
	v_cvt_pk_bf16_f32 v2, v104, s0
	ds_write_b16 v1, v2 offset:4416
	v_cvt_pk_bf16_f32 v2, v105, s0
	ds_write_b16 v1, v2 offset:4688
	v_cvt_pk_bf16_f32 v2, v106, s0
	ds_write_b16 v1, v2 offset:4960
	v_cvt_pk_bf16_f32 v2, v107, s0
	ds_write_b16 v1, v2 offset:5232
	v_cvt_pk_bf16_f32 v2, v100, s0
	ds_write_b16 v1, v2 offset:4448
	v_cvt_pk_bf16_f32 v2, v101, s0
	ds_write_b16 v1, v2 offset:4720
	v_cvt_pk_bf16_f32 v2, v102, s0
	ds_write_b16 v1, v2 offset:4992
	v_cvt_pk_bf16_f32 v2, v103, s0
	ds_write_b16 v1, v2 offset:5264
	v_cvt_pk_bf16_f32 v2, v96, s0
	ds_write_b16 v1, v2 offset:8704
	v_cvt_pk_bf16_f32 v2, v97, s0
	ds_write_b16 v1, v2 offset:8976
	v_cvt_pk_bf16_f32 v2, v98, s0
	ds_write_b16 v1, v2 offset:9248
	v_cvt_pk_bf16_f32 v2, v99, s0
	ds_write_b16 v1, v2 offset:9520
	v_cvt_pk_bf16_f32 v2, v92, s0
; DEVI void plain_tile256(const bf* A, int lda, const bf* Wt, int K, bf* C, int ldc, long row0, int n0, char* smem) {
;     ...
; #pragma unroll
;   for (int m = 0; m < 8; ++m)
; #pragma unroll
;     for (int n = 0; n < 4; ++n) {
;       const int cl = wc * 64 + n * 16 + l15;
; #pragma unroll
;       for (int j = 0; j < 4; ++j) tl[(wr * 128 + m * 16 + quad * 4 + j) * 136 + cl] = f2bf(acc[m][n][j]);
;     }
;   __syncthreads();
	ds_write_b16 v1, v2 offset:8736
	v_cvt_pk_bf16_f32 v2, v93, s0
	ds_write_b16 v1, v2 offset:9008
	v_cvt_pk_bf16_f32 v2, v94, s0
	ds_write_b16 v1, v2 offset:9280
	v_cvt_pk_bf16_f32 v2, v95, s0
	ds_write_b16 v1, v2 offset:9552
	v_cvt_pk_bf16_f32 v2, v88, s0
	ds_write_b16 v1, v2 offset:8768
	v_cvt_pk_bf16_f32 v2, v89, s0
	ds_write_b16 v1, v2 offset:9040
	v_cvt_pk_bf16_f32 v2, v90, s0
	ds_write_b16 v1, v2 offset:9312
	v_cvt_pk_bf16_f32 v2, v91, s0
	ds_write_b16 v1, v2 offset:9584
	v_cvt_pk_bf16_f32 v2, v84, s0
	ds_write_b16 v1, v2 offset:8800
	v_cvt_pk_bf16_f32 v2, v85, s0
	ds_write_b16 v1, v2 offset:9072
	v_cvt_pk_bf16_f32 v2, v86, s0
	ds_write_b16 v1, v2 offset:9344
	v_cvt_pk_bf16_f32 v2, v87, s0
	ds_write_b16 v1, v2 offset:9616
	v_cvt_pk_bf16_f32 v2, v80, s0
	ds_write_b16 v1, v2 offset:13056
	v_cvt_pk_bf16_f32 v2, v81, s0
	ds_write_b16 v1, v2 offset:13328
	v_cvt_pk_bf16_f32 v2, v82, s0
	ds_write_b16 v1, v2 offset:13600
	v_cvt_pk_bf16_f32 v2, v83, s0
	ds_write_b16 v1, v2 offset:13872
	v_cvt_pk_bf16_f32 v2, v76, s0
	ds_write_b16 v1, v2 offset:13088
	v_cvt_pk_bf16_f32 v2, v77, s0
	ds_write_b16 v1, v2 offset:13360
	v_cvt_pk_bf16_f32 v2, v78, s0
	ds_write_b16 v1, v2 offset:13632
	v_cvt_pk_bf16_f32 v2, v79, s0
	ds_write_b16 v1, v2 offset:13904
	v_cvt_pk_bf16_f32 v2, v72, s0
	ds_write_b16 v1, v2 offset:13120
	v_cvt_pk_bf16_f32 v2, v73, s0
	ds_write_b16 v1, v2 offset:13392
	v_cvt_pk_bf16_f32 v2, v74, s0
	ds_write_b16 v1, v2 offset:13664
	v_cvt_pk_bf16_f32 v2, v75, s0
	ds_write_b16 v1, v2 offset:13936
	v_cvt_pk_bf16_f32 v2, v68, s0
	ds_write_b16 v1, v2 offset:13152
	v_cvt_pk_bf16_f32 v2, v69, s0
	ds_write_b16 v1, v2 offset:13424
	v_cvt_pk_bf16_f32 v2, v70, s0
	ds_write_b16 v1, v2 offset:13696
	v_cvt_pk_bf16_f32 v2, v71, s0
	ds_write_b16 v1, v2 offset:13968
	v_cvt_pk_bf16_f32 v2, v64, s0
	ds_write_b16 v1, v2 offset:17408
	v_cvt_pk_bf16_f32 v2, v65, s0
	ds_write_b16 v1, v2 offset:17680
	v_cvt_pk_bf16_f32 v2, v66, s0
	ds_write_b16 v1, v2 offset:17952
	v_cvt_pk_bf16_f32 v2, v67, s0
	ds_write_b16 v1, v2 offset:18224
	v_cvt_pk_bf16_f32 v2, v60, s0
	ds_write_b16 v1, v2 offset:17440
	v_cvt_pk_bf16_f32 v2, v61, s0
	ds_write_b16 v1, v2 offset:17712
	v_cvt_pk_bf16_f32 v2, v62, s0
	ds_write_b16 v1, v2 offset:17984
	v_cvt_pk_bf16_f32 v2, v63, s0
	ds_write_b16 v1, v2 offset:18256
	v_cvt_pk_bf16_f32 v2, v56, s0
	ds_write_b16 v1, v2 offset:17472
	v_cvt_pk_bf16_f32 v2, v57, s0
	ds_write_b16 v1, v2 offset:17744
	v_cvt_pk_bf16_f32 v2, v58, s0
	ds_write_b16 v1, v2 offset:18016
	v_cvt_pk_bf16_f32 v2, v59, s0
	ds_write_b16 v1, v2 offset:18288
	v_cvt_pk_bf16_f32 v2, v52, s0
	ds_write_b16 v1, v2 offset:17504
	v_cvt_pk_bf16_f32 v2, v53, s0
	ds_write_b16 v1, v2 offset:17776
	v_cvt_pk_bf16_f32 v2, v54, s0
	ds_write_b16 v1, v2 offset:18048
	v_cvt_pk_bf16_f32 v2, v55, s0
	ds_write_b16 v1, v2 offset:18320
	v_cvt_pk_bf16_f32 v2, v48, s0
	ds_write_b16 v1, v2 offset:21760
	v_cvt_pk_bf16_f32 v2, v49, s0
	ds_write_b16 v1, v2 offset:22032
	v_cvt_pk_bf16_f32 v2, v50, s0
	ds_write_b16 v1, v2 offset:22304
	v_cvt_pk_bf16_f32 v2, v51, s0
	ds_write_b16 v1, v2 offset:22576
	v_cvt_pk_bf16_f32 v2, v44, s0
	ds_write_b16 v1, v2 offset:21792
	v_cvt_pk_bf16_f32 v2, v45, s0
	ds_write_b16 v1, v2 offset:22064
	v_cvt_pk_bf16_f32 v2, v46, s0
	ds_write_b16 v1, v2 offset:22336
	v_cvt_pk_bf16_f32 v2, v47, s0
	ds_write_b16 v1, v2 offset:22608
	v_cvt_pk_bf16_f32 v2, v40, s0
	ds_write_b16 v1, v2 offset:21824
	v_cvt_pk_bf16_f32 v2, v41, s0
	ds_write_b16 v1, v2 offset:22096
	v_cvt_pk_bf16_f32 v2, v42, s0
	ds_write_b16 v1, v2 offset:22368
	v_cvt_pk_bf16_f32 v2, v43, s0
	ds_write_b16 v1, v2 offset:22640
	v_cvt_pk_bf16_f32 v2, v36, s0
	ds_write_b16 v1, v2 offset:21856
	v_cvt_pk_bf16_f32 v2, v37, s0
	ds_write_b16 v1, v2 offset:22128
	v_cvt_pk_bf16_f32 v2, v38, s0
	ds_write_b16 v1, v2 offset:22400
	v_cvt_pk_bf16_f32 v2, v39, s0
	ds_write_b16 v1, v2 offset:22672
	v_cvt_pk_bf16_f32 v2, v32, s0
	ds_write_b16 v1, v2 offset:26112
	v_cvt_pk_bf16_f32 v2, v33, s0
	ds_write_b16 v1, v2 offset:26384
	v_cvt_pk_bf16_f32 v2, v34, s0
	ds_write_b16 v1, v2 offset:26656
	v_cvt_pk_bf16_f32 v2, v35, s0
	ds_write_b16 v1, v2 offset:26928
	v_cvt_pk_bf16_f32 v2, v28, s0
	ds_write_b16 v1, v2 offset:26144
	v_cvt_pk_bf16_f32 v2, v29, s0
	ds_write_b16 v1, v2 offset:26416
	v_cvt_pk_bf16_f32 v2, v30, s0
	ds_write_b16 v1, v2 offset:26688
	v_cvt_pk_bf16_f32 v2, v31, s0
	ds_write_b16 v1, v2 offset:26960
	v_cvt_pk_bf16_f32 v2, v24, s0
	ds_write_b16 v1, v2 offset:26176
	v_cvt_pk_bf16_f32 v2, v25, s0
	ds_write_b16 v1, v2 offset:26448
	v_cvt_pk_bf16_f32 v2, v26, s0
	ds_write_b16 v1, v2 offset:26720
	v_cvt_pk_bf16_f32 v2, v27, s0
	ds_write_b16 v1, v2 offset:26992
	v_cvt_pk_bf16_f32 v2, v20, s0
	ds_write_b16 v1, v2 offset:26208
	v_cvt_pk_bf16_f32 v2, v21, s0
	ds_write_b16 v1, v2 offset:26480
	v_cvt_pk_bf16_f32 v2, v22, s0
	ds_write_b16 v1, v2 offset:26752
	v_cvt_pk_bf16_f32 v2, v23, s0
	ds_write_b16 v1, v2 offset:27024
	v_cvt_pk_bf16_f32 v2, v16, s0
	ds_write_b16 v1, v2 offset:30464
	v_cvt_pk_bf16_f32 v2, v17, s0
	ds_write_b16 v1, v2 offset:30736
	v_cvt_pk_bf16_f32 v2, v18, s0
	ds_write_b16 v1, v2 offset:31008
	v_cvt_pk_bf16_f32 v2, v19, s0
	ds_write_b16 v1, v2 offset:31280
	v_cvt_pk_bf16_f32 v2, v12, s0
	ds_write_b16 v1, v2 offset:30496
	v_cvt_pk_bf16_f32 v2, v13, s0
	ds_write_b16 v1, v2 offset:30768
	v_cvt_pk_bf16_f32 v2, v14, s0
	ds_write_b16 v1, v2 offset:31040
	v_cvt_pk_bf16_f32 v2, v15, s0
	ds_write_b16 v1, v2 offset:31312
	v_cvt_pk_bf16_f32 v2, v8, s0
	ds_write_b16 v1, v2 offset:30528
	v_cvt_pk_bf16_f32 v2, v9, s0
	ds_write_b16 v1, v2 offset:30800
	v_cvt_pk_bf16_f32 v2, v10, s0
	ds_write_b16 v1, v2 offset:31072
	v_cvt_pk_bf16_f32 v2, v11, s0
	ds_write_b16 v1, v2 offset:31344
	v_cvt_pk_bf16_f32 v2, v4, s0
	ds_write_b16 v1, v2 offset:30560
	v_cvt_pk_bf16_f32 v2, v5, s0
	ds_write_b16 v1, v2 offset:30832
	v_cvt_pk_bf16_f32 v2, v6, s0
	v_cvt_pk_bf16_f32 v128, v128, s0
	ds_write_b16 v1, v2 offset:31104
	v_cvt_pk_bf16_f32 v2, v7, s0
	ds_write_b16 v1, v128
	ds_write_b16 v1, v2 offset:31376
	v_mov_b32_e32 v1, v178
	s_waitcnt lgkmcnt(0)
	s_barrier
; DEVI int get_tid() { int t = threadIdx.x; asm volatile("" : "+v"(t)); return t; }
; template <int BN>
; DEVI void tile_store256(const char* smem, bf* __restrict__ C, long ldc, long row0, int col0) {
;   constexpr int LDT = BN + 8;
;   constexpr int CPR = BN / 8;
;   const int tid = get_tid();
; #pragma unroll
;   for (int i = 0; i < CPR; ++i) {
;     const int q = tid + 256 * i;
;     const int r = q / CPR, c = q - r * CPR;
;     u32x4 v = *reinterpret_cast<const u32x4*>(smem + (r * LDT + c * 8) * 2);
;     *reinterpret_cast<u32x4*>(C + (row0 + r) * ldc + col0 + c * 8) = v;
;   }
; }
	v_readlane_b32 s56, v251, 58
	v_ashrrev_i32_e32 v2, 31, v1
	v_lshrrev_b32_e32 v2, 28, v2
	v_add_u32_e32 v2, v1, v2
	v_ashrrev_i32_e32 v8, 4, v2
	s_lshl_b64 s[10:11], s[34:35], 1
	v_readlane_b32 s60, v251, 62
	v_lshlrev_b32_e32 v4, 7, v8
	v_lshlrev_b32_e32 v5, 3, v1
	v_ashrrev_i32_e32 v9, 31, v8
	v_readlane_b32 s61, v251, 63
	s_add_u32 s10, s60, s10
	v_mul_lo_u32 v2, v8, s83
	v_sub_u32_e32 v10, v5, v4
	v_lshl_add_u64 v[8:9], s[12:13], 0, v[8:9]
	s_addc_u32 s11, s61, s11
	v_add_lshl_u32 v2, v10, v2, 1
	v_lshlrev_b64 v[8:9], 11, v[8:9]
	ds_read_b128 v[4:7], v2
	v_lshl_add_u64 v[8:9], s[10:11], 0, v[8:9]
	v_ashrrev_i32_e32 v11, 31, v10
	v_add_u32_e32 v2, 0x100, v1
	v_lshl_add_u64 v[12:13], v[10:11], 1, v[8:9]
	v_ashrrev_i32_e32 v8, 31, v2
	v_lshrrev_b32_e32 v8, 28, v8
	v_add_u32_e32 v8, v2, v8
	v_ashrrev_i32_e32 v14, 4, v8
	v_lshlrev_b32_e32 v9, 7, v14
	v_lshlrev_b32_e32 v2, 3, v2
	v_mul_lo_u32 v8, v14, s83
	v_sub_u32_e32 v16, v2, v9
	v_add_lshl_u32 v2, v16, v8, 1
	ds_read_b128 v[8:11], v2
	v_ashrrev_i32_e32 v15, 31, v14
	s_waitcnt lgkmcnt(1)
	global_store_dwordx4 v[12:13], v[4:7], off
	v_ashrrev_i32_e32 v17, 31, v16
	v_add_u32_e32 v2, 0x200, v1
	v_lshl_add_u64 v[4:5], s[12:13], 0, v[14:15]
	v_lshlrev_b64 v[4:5], 11, v[4:5]
	v_lshl_add_u64 v[4:5], s[10:11], 0, v[4:5]
	v_lshl_add_u64 v[4:5], v[16:17], 1, v[4:5]
	s_waitcnt lgkmcnt(0)
	global_store_dwordx4 v[4:5], v[8:11], off
	v_ashrrev_i32_e32 v4, 31, v2
	v_lshrrev_b32_e32 v4, 28, v4
	v_add_u32_e32 v4, v2, v4
	v_ashrrev_i32_e32 v8, 4, v4
	v_lshlrev_b32_e32 v5, 7, v8
	v_lshlrev_b32_e32 v2, 3, v2
	v_ashrrev_i32_e32 v9, 31, v8
	v_mul_lo_u32 v4, v8, s83
	v_sub_u32_e32 v10, v2, v5
	v_lshl_add_u64 v[8:9], s[12:13], 0, v[8:9]
	v_add_lshl_u32 v2, v10, v4, 1
	v_lshlrev_b64 v[8:9], 11, v[8:9]
	ds_read_b128 v[4:7], v2
	v_lshl_add_u64 v[8:9], s[10:11], 0, v[8:9]
	v_ashrrev_i32_e32 v11, 31, v10
	v_add_u32_e32 v2, 0x300, v1
	v_lshl_add_u64 v[12:13], v[10:11], 1, v[8:9]
	v_ashrrev_i32_e32 v8, 31, v2
	v_lshrrev_b32_e32 v8, 28, v8
	v_add_u32_e32 v8, v2, v8
	v_ashrrev_i32_e32 v14, 4, v8
	v_lshlrev_b32_e32 v9, 7, v14
	v_lshlrev_b32_e32 v2, 3, v2
	v_mul_lo_u32 v8, v14, s83
	v_sub_u32_e32 v16, v2, v9
	v_add_lshl_u32 v2, v16, v8, 1
	ds_read_b128 v[8:11], v2
	v_ashrrev_i32_e32 v15, 31, v14
	s_waitcnt lgkmcnt(1)
	global_store_dwordx4 v[12:13], v[4:7], off
	v_ashrrev_i32_e32 v17, 31, v16
	v_add_u32_e32 v2, 0x400, v1
	v_lshl_add_u64 v[4:5], s[12:13], 0, v[14:15]
	v_lshlrev_b64 v[4:5], 11, v[4:5]
	v_lshl_add_u64 v[4:5], s[10:11], 0, v[4:5]
	v_lshl_add_u64 v[4:5], v[16:17], 1, v[4:5]
	s_waitcnt lgkmcnt(0)
	global_store_dwordx4 v[4:5], v[8:11], off
	v_ashrrev_i32_e32 v4, 31, v2
	v_lshrrev_b32_e32 v4, 28, v4
	v_add_u32_e32 v4, v2, v4
	v_ashrrev_i32_e32 v8, 4, v4
	v_lshlrev_b32_e32 v5, 7, v8
	v_lshlrev_b32_e32 v2, 3, v2
	v_ashrrev_i32_e32 v9, 31, v8
	v_mul_lo_u32 v4, v8, s83
	v_sub_u32_e32 v10, v2, v5
	v_lshl_add_u64 v[8:9], s[12:13], 0, v[8:9]
	v_add_lshl_u32 v2, v10, v4, 1
	v_lshlrev_b64 v[8:9], 11, v[8:9]
	ds_read_b128 v[4:7], v2
	v_lshl_add_u64 v[8:9], s[10:11], 0, v[8:9]
	v_ashrrev_i32_e32 v11, 31, v10
	v_add_u32_e32 v2, 0x500, v1
	v_lshl_add_u64 v[12:13], v[10:11], 1, v[8:9]
	v_ashrrev_i32_e32 v8, 31, v2
	v_lshrrev_b32_e32 v8, 28, v8
	v_add_u32_e32 v8, v2, v8
	v_ashrrev_i32_e32 v14, 4, v8
	v_lshlrev_b32_e32 v9, 7, v14
	v_lshlrev_b32_e32 v2, 3, v2
	v_mul_lo_u32 v8, v14, s83
	v_sub_u32_e32 v16, v2, v9
	v_add_lshl_u32 v2, v16, v8, 1
	ds_read_b128 v[8:11], v2
	v_ashrrev_i32_e32 v15, 31, v14
	s_waitcnt lgkmcnt(1)
	global_store_dwordx4 v[12:13], v[4:7], off
	v_ashrrev_i32_e32 v17, 31, v16
	v_add_u32_e32 v2, 0x600, v1
	v_lshl_add_u64 v[4:5], s[12:13], 0, v[14:15]
	v_lshlrev_b64 v[4:5], 11, v[4:5]
	v_lshl_add_u64 v[4:5], s[10:11], 0, v[4:5]
	v_lshl_add_u64 v[4:5], v[16:17], 1, v[4:5]
	s_waitcnt lgkmcnt(0)
	global_store_dwordx4 v[4:5], v[8:11], off
	v_ashrrev_i32_e32 v4, 31, v2
	v_lshrrev_b32_e32 v4, 28, v4
	v_add_u32_e32 v4, v2, v4
	v_ashrrev_i32_e32 v8, 4, v4
	v_lshlrev_b32_e32 v5, 7, v8
	v_lshlrev_b32_e32 v2, 3, v2
	v_ashrrev_i32_e32 v9, 31, v8
	v_mul_lo_u32 v4, v8, s83
	v_sub_u32_e32 v10, v2, v5
	v_lshl_add_u64 v[8:9], s[12:13], 0, v[8:9]
	v_add_lshl_u32 v2, v10, v4, 1
	v_lshlrev_b64 v[8:9], 11, v[8:9]
	ds_read_b128 v[4:7], v2
	v_lshl_add_u64 v[8:9], s[10:11], 0, v[8:9]
	v_ashrrev_i32_e32 v11, 31, v10
	v_add_u32_e32 v2, 0x700, v1
	v_lshl_add_u64 v[12:13], v[10:11], 1, v[8:9]
	v_ashrrev_i32_e32 v8, 31, v2
	v_lshrrev_b32_e32 v8, 28, v8
	v_add_u32_e32 v8, v2, v8
	v_ashrrev_i32_e32 v14, 4, v8
	v_lshlrev_b32_e32 v9, 7, v14
	v_lshlrev_b32_e32 v2, 3, v2
	v_mul_lo_u32 v8, v14, s83
	v_sub_u32_e32 v16, v2, v9
	v_add_lshl_u32 v2, v16, v8, 1
	ds_read_b128 v[8:11], v2
	v_ashrrev_i32_e32 v15, 31, v14
	s_waitcnt lgkmcnt(1)
	global_store_dwordx4 v[12:13], v[4:7], off
	v_ashrrev_i32_e32 v17, 31, v16
	v_add_u32_e32 v2, 0x800, v1
	v_lshl_add_u64 v[4:5], s[12:13], 0, v[14:15]
	v_lshlrev_b64 v[4:5], 11, v[4:5]
	v_lshl_add_u64 v[4:5], s[10:11], 0, v[4:5]
	v_lshl_add_u64 v[4:5], v[16:17], 1, v[4:5]
	s_waitcnt lgkmcnt(0)
; DEVI int get_tid() { int t = threadIdx.x; asm volatile("" : "+v"(t)); return t; }
; template <int BN>
; DEVI void tile_store256(const char* smem, bf* __restrict__ C, long ldc, long row0, int col0) {
;   constexpr int LDT = BN + 8;
;   constexpr int CPR = BN / 8;
;   const int tid = get_tid();
; #pragma unroll
;   for (int i = 0; i < CPR; ++i) {
;     const int q = tid + 256 * i;
;     const int r = q / CPR, c = q - r * CPR;
;     u32x4 v = *reinterpret_cast<const u32x4*>(smem + (r * LDT + c * 8) * 2);
;     *reinterpret_cast<u32x4*>(C + (row0 + r) * ldc + col0 + c * 8) = v;
;   }
; }
; DEVI void phase_gemm_plain128(const bf* A, int lda, const bf* Wt, int K, int N, bf* C, int ldc, char* smem) {
;     ...
;   for (int v = blockIdx.x; v < 128 * ntn; v += gridDim.x) {
;     int m2, nt;
;     lat_tile_map256(v, ntn, m2, nt);
;     plain_tile256(A, lda, Wt, K, C, ldc, lat_row0_256(m2), nt * 128, smem);
;   }
	global_store_dwordx4 v[4:5], v[8:11], off
	v_ashrrev_i32_e32 v4, 31, v2
	v_lshrrev_b32_e32 v4, 28, v4
	v_add_u32_e32 v4, v2, v4
	v_ashrrev_i32_e32 v8, 4, v4
	v_lshlrev_b32_e32 v5, 7, v8
	v_lshlrev_b32_e32 v2, 3, v2
	v_ashrrev_i32_e32 v9, 31, v8
	v_mul_lo_u32 v4, v8, s83
	v_sub_u32_e32 v10, v2, v5
	v_lshl_add_u64 v[8:9], s[12:13], 0, v[8:9]
	v_add_lshl_u32 v2, v10, v4, 1
	v_lshlrev_b64 v[8:9], 11, v[8:9]
	ds_read_b128 v[4:7], v2
	v_lshl_add_u64 v[8:9], s[10:11], 0, v[8:9]
	v_ashrrev_i32_e32 v11, 31, v10
	v_add_u32_e32 v2, 0x900, v1
	v_lshl_add_u64 v[12:13], v[10:11], 1, v[8:9]
	v_ashrrev_i32_e32 v8, 31, v2
	v_lshrrev_b32_e32 v8, 28, v8
	v_add_u32_e32 v8, v2, v8
	v_ashrrev_i32_e32 v14, 4, v8
	v_lshlrev_b32_e32 v9, 7, v14
	v_lshlrev_b32_e32 v2, 3, v2
	v_mul_lo_u32 v8, v14, s83
	v_sub_u32_e32 v16, v2, v9
	v_add_lshl_u32 v2, v16, v8, 1
	ds_read_b128 v[8:11], v2
	v_ashrrev_i32_e32 v15, 31, v14
	s_waitcnt lgkmcnt(1)
	global_store_dwordx4 v[12:13], v[4:7], off
	v_ashrrev_i32_e32 v17, 31, v16
	v_add_u32_e32 v2, 0xa00, v1
	v_lshl_add_u64 v[4:5], s[12:13], 0, v[14:15]
	v_lshlrev_b64 v[4:5], 11, v[4:5]
	v_lshl_add_u64 v[4:5], s[10:11], 0, v[4:5]
	v_lshl_add_u64 v[4:5], v[16:17], 1, v[4:5]
	s_waitcnt lgkmcnt(0)
	global_store_dwordx4 v[4:5], v[8:11], off
	v_ashrrev_i32_e32 v4, 31, v2
	v_lshrrev_b32_e32 v4, 28, v4
	v_add_u32_e32 v4, v2, v4
	v_ashrrev_i32_e32 v8, 4, v4
	v_lshlrev_b32_e32 v5, 7, v8
	v_lshlrev_b32_e32 v2, 3, v2
	v_ashrrev_i32_e32 v9, 31, v8
	v_mul_lo_u32 v4, v8, s83
	v_sub_u32_e32 v10, v2, v5
	v_lshl_add_u64 v[8:9], s[12:13], 0, v[8:9]
	v_add_lshl_u32 v2, v10, v4, 1
	v_lshlrev_b64 v[8:9], 11, v[8:9]
	ds_read_b128 v[4:7], v2
	v_lshl_add_u64 v[8:9], s[10:11], 0, v[8:9]
	v_ashrrev_i32_e32 v11, 31, v10
	v_add_u32_e32 v2, 0xb00, v1
	v_lshl_add_u64 v[12:13], v[10:11], 1, v[8:9]
	v_ashrrev_i32_e32 v8, 31, v2
	v_lshrrev_b32_e32 v8, 28, v8
	v_add_u32_e32 v8, v2, v8
	v_ashrrev_i32_e32 v14, 4, v8
	v_lshlrev_b32_e32 v9, 7, v14
	v_lshlrev_b32_e32 v2, 3, v2
	v_mul_lo_u32 v8, v14, s83
	v_sub_u32_e32 v16, v2, v9
	v_add_lshl_u32 v2, v16, v8, 1
	ds_read_b128 v[8:11], v2
	v_ashrrev_i32_e32 v15, 31, v14
	s_waitcnt lgkmcnt(1)
	global_store_dwordx4 v[12:13], v[4:7], off
	v_ashrrev_i32_e32 v17, 31, v16
	v_add_u32_e32 v2, 0xc00, v1
	v_lshl_add_u64 v[4:5], s[12:13], 0, v[14:15]
	v_lshlrev_b64 v[4:5], 11, v[4:5]
	v_lshl_add_u64 v[4:5], s[10:11], 0, v[4:5]
	v_lshl_add_u64 v[4:5], v[16:17], 1, v[4:5]
	s_waitcnt lgkmcnt(0)
	global_store_dwordx4 v[4:5], v[8:11], off
	v_ashrrev_i32_e32 v4, 31, v2
	v_lshrrev_b32_e32 v4, 28, v4
	v_add_u32_e32 v4, v2, v4
	v_ashrrev_i32_e32 v8, 4, v4
	v_lshlrev_b32_e32 v5, 7, v8
	v_lshlrev_b32_e32 v2, 3, v2
	v_ashrrev_i32_e32 v9, 31, v8
	v_mul_lo_u32 v4, v8, s83
	v_sub_u32_e32 v10, v2, v5
	v_lshl_add_u64 v[8:9], s[12:13], 0, v[8:9]
	v_add_lshl_u32 v2, v10, v4, 1
	v_lshlrev_b64 v[8:9], 11, v[8:9]
	ds_read_b128 v[4:7], v2
	v_lshl_add_u64 v[8:9], s[10:11], 0, v[8:9]
	v_ashrrev_i32_e32 v11, 31, v10
	v_add_u32_e32 v2, 0xd00, v1
	v_lshl_add_u64 v[12:13], v[10:11], 1, v[8:9]
	v_ashrrev_i32_e32 v8, 31, v2
	v_lshrrev_b32_e32 v8, 28, v8
	v_add_u32_e32 v8, v2, v8
	v_ashrrev_i32_e32 v14, 4, v8
	v_lshlrev_b32_e32 v9, 7, v14
	v_lshlrev_b32_e32 v2, 3, v2
	v_mul_lo_u32 v8, v14, s83
	v_sub_u32_e32 v16, v2, v9
	v_add_lshl_u32 v2, v16, v8, 1
	ds_read_b128 v[8:11], v2
	v_ashrrev_i32_e32 v15, 31, v14
	s_waitcnt lgkmcnt(1)
	global_store_dwordx4 v[12:13], v[4:7], off
	v_ashrrev_i32_e32 v17, 31, v16
	v_add_u32_e32 v2, 0xe00, v1
	v_lshl_add_u64 v[4:5], s[12:13], 0, v[14:15]
	v_lshlrev_b64 v[4:5], 11, v[4:5]
	v_lshl_add_u64 v[4:5], s[10:11], 0, v[4:5]
	v_lshl_add_u64 v[4:5], v[16:17], 1, v[4:5]
	s_waitcnt lgkmcnt(0)
	global_store_dwordx4 v[4:5], v[8:11], off
	v_ashrrev_i32_e32 v4, 31, v2
	v_lshrrev_b32_e32 v4, 28, v4
	v_add_u32_e32 v4, v2, v4
	v_ashrrev_i32_e32 v8, 4, v4
	v_lshlrev_b32_e32 v5, 7, v8
	v_lshlrev_b32_e32 v2, 3, v2
	v_mul_lo_u32 v4, v8, s83
	v_sub_u32_e32 v10, v2, v5
	v_add_lshl_u32 v2, v10, v4, 1
	v_add_u32_e32 v1, 0xf00, v1
	ds_read_b128 v[4:7], v2
	v_ashrrev_i32_e32 v9, 31, v8
	v_ashrrev_i32_e32 v2, 31, v1
	v_lshl_add_u64 v[8:9], s[12:13], 0, v[8:9]
	v_lshrrev_b32_e32 v2, 28, v2
	v_lshlrev_b64 v[8:9], 11, v[8:9]
	v_add_u32_e32 v2, v1, v2
	v_lshl_add_u64 v[8:9], s[10:11], 0, v[8:9]
	v_ashrrev_i32_e32 v11, 31, v10
	v_ashrrev_i32_e32 v14, 4, v2
	v_lshl_add_u64 v[12:13], v[10:11], 1, v[8:9]
	v_lshlrev_b32_e32 v8, 7, v14
	v_lshlrev_b32_e32 v1, 3, v1
	v_mul_lo_u32 v2, v14, s83
	v_sub_u32_e32 v16, v1, v8
	v_add_lshl_u32 v1, v16, v2, 1
	v_ashrrev_i32_e32 v15, 31, v14
	ds_read_b128 v[8:11], v1
	s_waitcnt lgkmcnt(1)
	global_store_dwordx4 v[12:13], v[4:7], off
	v_ashrrev_i32_e32 v17, 31, v16
	v_readlane_b32 s58, v251, 60
	v_lshl_add_u64 v[4:5], s[12:13], 0, v[14:15]
	v_lshlrev_b64 v[4:5], 11, v[4:5]
	v_lshl_add_u64 v[4:5], s[10:11], 0, v[4:5]
	v_readlane_b32 s10, v252, 59
	s_add_i32 s2, s2, s10
	v_readlane_b32 s59, v251, 61
	v_lshl_add_u64 v[4:5], v[16:17], 1, v[4:5]
	s_cmpk_gt_i32 s2, 0x3ff
	s_movk_i32 s27, 0x100
	v_readlane_b32 s57, v251, 59
	v_readlane_b32 s62, v252, 0
	v_readlane_b32 s63, v252, 1
	v_readlane_b32 s64, v252, 2
	v_readlane_b32 s65, v252, 3
	v_readlane_b32 s66, v252, 4
	v_readlane_b32 s67, v252, 5
	v_readlane_b32 s68, v252, 6
	v_readlane_b32 s69, v252, 7
	v_readlane_b32 s70, v252, 8
	v_readlane_b32 s71, v252, 9
	s_waitcnt lgkmcnt(0)
	global_store_dwordx4 v[4:5], v[8:11], off
	s_barrier
	v_readlane_b32 s11, v252, 60
	s_cbranch_scc0 .LBB0_205

; DEVI f32x4 mfma16(bf16x8 a, bf16x8 b, f32x4 c) { return __builtin_amdgcn_mfma_f32_16x16x32_bf16(a, b, c, 0, 0, 0); }
; DEVI void gemm_core3(f32x4 (&acc)[8][4], const bf* __restrict__ A, int lda, const bf* __restrict__ Bt, int ldb, int K, char* smem) {
;     ...
;   for (int kt = 0; kt < nk; ++kt) {
;     const int k1 = min((kt + 1) * 32, klast);
;     const int sn = ((kt + 1) & 1) * STG;
;     const int so = (kt & 1) * STG;
;     bf16x8 bfr[4], af[8];
; #pragma unroll
;     for (int n = 0; n < 4; ++n) bfr[n] = *reinterpret_cast<const bf16x8*>(bbase + so + n * 16 * 64);
; #pragma unroll
;     for (int m = 0; m < 8; ++m) af[m] = *reinterpret_cast<const bf16x8*>(abase + so + m * 16 * 64);
; #pragma unroll
;     for (int i = 0; i < 4; ++i) glds16(Ap + i * sa + k1, dbase + sn + i * 4096);
; #pragma unroll
;     for (int i = 0; i < 2; ++i) glds16(Bp + i * sb + k1, dbase + sn + ASZ + i * 4096);
;     __builtin_amdgcn_s_setprio(1);
; #pragma unroll
;     for (int m = 0; m < 8; ++m)
; #pragma unroll
;       for (int n = 0; n < 4; ++n) acc[m][n] = mfma16(af[m], bfr[n], acc[m][n]);
;     __builtin_amdgcn_s_setprio(0);
;     __syncthreads();
;   }
.Lg3_loop_904:
	v_add_u32_e32 v216, s10, v146
	v_add_u32_e32 v217, s10, v2
	ds_read_b128 v[148:151], v217 offset:16384
	ds_read_b128 v[166:169], v216
	ds_read_b128 v[154:157], v217 offset:17408
	ds_read_b128 v[158:161], v217 offset:18432
	ds_read_b128 v[162:165], v217 offset:19456
	ds_read_b128 v[170:173], v216 offset:1024
	ds_read_b128 v[174:177], v216 offset:2048
	ds_read_b128 v[192:195], v216 offset:3072
	ds_read_b128 v[196:199], v216 offset:4096
	ds_read_b128 v[204:207], v216 offset:5120
	ds_read_b128 v[208:211], v216 offset:6144
	ds_read_b128 v[212:215], v216 offset:7168
	s_setprio 1
	s_waitcnt lgkmcnt(10)
	v_mfma_f32_16x16x32_bf16 v[128:131], v[166:169], v[148:151], v[128:131]
	s_waitcnt lgkmcnt(9)
	v_mfma_f32_16x16x32_bf16 v[124:127], v[166:169], v[154:157], v[124:127]
	s_waitcnt lgkmcnt(8)
	v_mfma_f32_16x16x32_bf16 v[120:123], v[166:169], v[158:161], v[120:123]
	s_waitcnt lgkmcnt(7)
	v_mfma_f32_16x16x32_bf16 v[116:119], v[166:169], v[162:165], v[116:119]
	s_waitcnt lgkmcnt(6)
	v_mfma_f32_16x16x32_bf16 v[112:115], v[170:173], v[148:151], v[112:115]
	v_mfma_f32_16x16x32_bf16 v[108:111], v[170:173], v[154:157], v[108:111]
	v_mfma_f32_16x16x32_bf16 v[104:107], v[170:173], v[158:161], v[104:107]
	v_mfma_f32_16x16x32_bf16 v[100:103], v[170:173], v[162:165], v[100:103]
	s_waitcnt lgkmcnt(5)
	v_mfma_f32_16x16x32_bf16 v[96:99], v[174:177], v[148:151], v[96:99]
	v_mfma_f32_16x16x32_bf16 v[92:95], v[174:177], v[154:157], v[92:95]
	v_mfma_f32_16x16x32_bf16 v[88:91], v[174:177], v[158:161], v[88:91]
	v_mfma_f32_16x16x32_bf16 v[84:87], v[174:177], v[162:165], v[84:87]
	s_waitcnt lgkmcnt(4)
	v_mfma_f32_16x16x32_bf16 v[80:83], v[192:195], v[148:151], v[80:83]
	v_mfma_f32_16x16x32_bf16 v[76:79], v[192:195], v[154:157], v[76:79]
	v_mfma_f32_16x16x32_bf16 v[72:75], v[192:195], v[158:161], v[72:75]
	v_mfma_f32_16x16x32_bf16 v[68:71], v[192:195], v[162:165], v[68:71]
	s_waitcnt lgkmcnt(3)
	v_mfma_f32_16x16x32_bf16 v[64:67], v[196:199], v[148:151], v[64:67]
	v_mfma_f32_16x16x32_bf16 v[60:63], v[196:199], v[154:157], v[60:63]
	v_mfma_f32_16x16x32_bf16 v[56:59], v[196:199], v[158:161], v[56:59]
	v_mfma_f32_16x16x32_bf16 v[52:55], v[196:199], v[162:165], v[52:55]
	s_waitcnt lgkmcnt(2)
	v_mfma_f32_16x16x32_bf16 v[48:51], v[204:207], v[148:151], v[48:51]
	v_mfma_f32_16x16x32_bf16 v[44:47], v[204:207], v[154:157], v[44:47]
	v_mfma_f32_16x16x32_bf16 v[40:43], v[204:207], v[158:161], v[40:43]
	v_mfma_f32_16x16x32_bf16 v[36:39], v[204:207], v[162:165], v[36:39]
	s_waitcnt lgkmcnt(1)
	v_mfma_f32_16x16x32_bf16 v[32:35], v[208:211], v[148:151], v[32:35]
	v_mfma_f32_16x16x32_bf16 v[28:31], v[208:211], v[154:157], v[28:31]
	v_mfma_f32_16x16x32_bf16 v[24:27], v[208:211], v[158:161], v[24:27]
	v_mfma_f32_16x16x32_bf16 v[20:23], v[208:211], v[162:165], v[20:23]
	s_waitcnt lgkmcnt(0)
	v_mfma_f32_16x16x32_bf16 v[16:19], v[212:215], v[148:151], v[16:19]
	v_mfma_f32_16x16x32_bf16 v[12:15], v[212:215], v[154:157], v[12:15]
	v_mfma_f32_16x16x32_bf16 v[8:11], v[212:215], v[158:161], v[8:11]
	v_mfma_f32_16x16x32_bf16 v[4:7], v[212:215], v[162:165], v[4:7]
	s_setprio 0
	s_add_i32 s10, s10, 0x6000
	s_cmp_lg_u32 s10, 0x12000
	s_cselect_b32 s10, s10, 0
	s_waitcnt vmcnt(0)
	s_barrier
	s_setprio 2
	v_add_u32_e32 v216, s10, v146
	v_add_u32_e32 v217, s10, v2
	ds_read_b128 v[148:151], v217 offset:16384
	ds_read_b128 v[166:169], v216
	ds_read_b128 v[154:157], v217 offset:17408
	ds_read_b128 v[158:161], v217 offset:18432
	ds_read_b128 v[162:165], v217 offset:19456
	ds_read_b128 v[170:173], v216 offset:1024
	ds_read_b128 v[174:177], v216 offset:2048
	ds_read_b128 v[192:195], v216 offset:3072
	ds_read_b128 v[196:199], v216 offset:4096
	ds_read_b128 v[204:207], v216 offset:5120
	ds_read_b128 v[208:211], v216 offset:6144
	ds_read_b128 v[212:215], v216 offset:7168
	v_readfirstlane_b32 s17, v140
	s_add_i32 s96, s11, 0x6000
	s_cmp_lg_u32 s96, 0x12000
	s_cselect_b32 s96, s96, 0
	s_add_i32 s96, s96, s17
	s_add_i32 s17, s17, s11
	s_waitcnt lgkmcnt(10)
	s_mov_b32 m0, s17
	s_add_i32 s17, s17, 0x1000
	v_mfma_f32_16x16x32_bf16 v[128:131], v[166:169], v[148:151], v[128:131]
	s_waitcnt lgkmcnt(9)
	v_mfma_f32_16x16x32_bf16 v[124:127], v[166:169], v[154:157], v[124:127]
	global_load_lds_dwordx4 v[218:219], off
	v_lshl_add_u64 v[218:219], v[218:219], 0, 64
	s_waitcnt lgkmcnt(8)
	s_mov_b32 m0, s96
	s_add_i32 s96, s96, 0x1000
	v_mfma_f32_16x16x32_bf16 v[120:123], v[166:169], v[158:161], v[120:123]
	s_waitcnt lgkmcnt(7)
	v_mfma_f32_16x16x32_bf16 v[116:119], v[166:169], v[162:165], v[116:119]
	global_load_lds_dwordx4 v[218:219], off
	v_lshl_add_u64 v[218:219], v[218:219], 0, 64
	s_waitcnt lgkmcnt(6)
	v_mfma_f32_16x16x32_bf16 v[112:115], v[170:173], v[148:151], v[112:115]
	s_mov_b32 m0, s17
	s_add_i32 s17, s17, 0x1000
	v_mfma_f32_16x16x32_bf16 v[108:111], v[170:173], v[154:157], v[108:111]
	v_mfma_f32_16x16x32_bf16 v[104:107], v[170:173], v[158:161], v[104:107]
	global_load_lds_dwordx4 v[220:221], off
	v_lshl_add_u64 v[220:221], v[220:221], 0, 64
	s_mov_b32 m0, s96
	s_add_i32 s96, s96, 0x1000
	v_mfma_f32_16x16x32_bf16 v[100:103], v[170:173], v[162:165], v[100:103]
	s_waitcnt lgkmcnt(5)
	v_mfma_f32_16x16x32_bf16 v[96:99], v[174:177], v[148:151], v[96:99]
	global_load_lds_dwordx4 v[220:221], off
	v_lshl_add_u64 v[220:221], v[220:221], 0, 64
	v_mfma_f32_16x16x32_bf16 v[92:95], v[174:177], v[154:157], v[92:95]
	s_mov_b32 m0, s17
	s_add_i32 s17, s17, 0x1000
	v_mfma_f32_16x16x32_bf16 v[88:91], v[174:177], v[158:161], v[88:91]
	v_mfma_f32_16x16x32_bf16 v[84:87], v[174:177], v[162:165], v[84:87]
	global_load_lds_dwordx4 v[222:223], off
	v_lshl_add_u64 v[222:223], v[222:223], 0, 64
	s_waitcnt lgkmcnt(4)
; DEVI f32x4 mfma16(bf16x8 a, bf16x8 b, f32x4 c) { return __builtin_amdgcn_mfma_f32_16x16x32_bf16(a, b, c, 0, 0, 0); }
; DEVI void gemm_core3(f32x4 (&acc)[8][4], const bf* __restrict__ A, int lda, const bf* __restrict__ Bt, int ldb, int K, char* smem) {
;     ...
;   for (int kt = 0; kt < nk; ++kt) {
;     const int k1 = min((kt + 1) * 32, klast);
;     const int sn = ((kt + 1) & 1) * STG;
;     const int so = (kt & 1) * STG;
;     bf16x8 bfr[4], af[8];
; #pragma unroll
;     for (int n = 0; n < 4; ++n) bfr[n] = *reinterpret_cast<const bf16x8*>(bbase + so + n * 16 * 64);
; #pragma unroll
;     for (int m = 0; m < 8; ++m) af[m] = *reinterpret_cast<const bf16x8*>(abase + so + m * 16 * 64);
; #pragma unroll
;     for (int i = 0; i < 4; ++i) glds16(Ap + i * sa + k1, dbase + sn + i * 4096);
; #pragma unroll
;     for (int i = 0; i < 2; ++i) glds16(Bp + i * sb + k1, dbase + sn + ASZ + i * 4096);
;     __builtin_amdgcn_s_setprio(1);
; #pragma unroll
;     for (int m = 0; m < 8; ++m)
; #pragma unroll
;       for (int n = 0; n < 4; ++n) acc[m][n] = mfma16(af[m], bfr[n], acc[m][n]);
;     __builtin_amdgcn_s_setprio(0);
;     __syncthreads();
;   }
	s_mov_b32 m0, s96
	s_add_i32 s96, s96, 0x1000
	v_mfma_f32_16x16x32_bf16 v[80:83], v[192:195], v[148:151], v[80:83]
	v_mfma_f32_16x16x32_bf16 v[76:79], v[192:195], v[154:157], v[76:79]
	global_load_lds_dwordx4 v[222:223], off
	v_lshl_add_u64 v[222:223], v[222:223], 0, 64
	v_mfma_f32_16x16x32_bf16 v[72:75], v[192:195], v[158:161], v[72:75]
	s_mov_b32 m0, s17
	s_add_i32 s17, s17, 0x1000
	v_mfma_f32_16x16x32_bf16 v[68:71], v[192:195], v[162:165], v[68:71]
	s_waitcnt lgkmcnt(3)
	v_mfma_f32_16x16x32_bf16 v[64:67], v[196:199], v[148:151], v[64:67]
	global_load_lds_dwordx4 v[224:225], off
	v_lshl_add_u64 v[224:225], v[224:225], 0, 64
	s_mov_b32 m0, s96
	s_add_i32 s96, s96, 0x1000
	v_mfma_f32_16x16x32_bf16 v[60:63], v[196:199], v[154:157], v[60:63]
	v_mfma_f32_16x16x32_bf16 v[56:59], v[196:199], v[158:161], v[56:59]
	global_load_lds_dwordx4 v[224:225], off
	v_lshl_add_u64 v[224:225], v[224:225], 0, 64
	v_mfma_f32_16x16x32_bf16 v[52:55], v[196:199], v[162:165], v[52:55]
	s_waitcnt lgkmcnt(2)
	s_mov_b32 m0, s17
	s_add_i32 s17, s17, 0x1000
	v_mfma_f32_16x16x32_bf16 v[48:51], v[204:207], v[148:151], v[48:51]
	v_mfma_f32_16x16x32_bf16 v[44:47], v[204:207], v[154:157], v[44:47]
	global_load_lds_dwordx4 v[226:227], off
	v_lshl_add_u64 v[226:227], v[226:227], 0, 64
	s_mov_b32 m0, s96
	s_add_i32 s96, s96, 0x1000
	v_mfma_f32_16x16x32_bf16 v[40:43], v[204:207], v[158:161], v[40:43]
	v_mfma_f32_16x16x32_bf16 v[36:39], v[204:207], v[162:165], v[36:39]
	global_load_lds_dwordx4 v[226:227], off
	v_lshl_add_u64 v[226:227], v[226:227], 0, 64
	s_waitcnt lgkmcnt(1)
	v_mfma_f32_16x16x32_bf16 v[32:35], v[208:211], v[148:151], v[32:35]
	s_mov_b32 m0, s17
	s_add_i32 s17, s17, 0x1000
	v_mfma_f32_16x16x32_bf16 v[28:31], v[208:211], v[154:157], v[28:31]
	v_mfma_f32_16x16x32_bf16 v[24:27], v[208:211], v[158:161], v[24:27]
	global_load_lds_dwordx4 v[228:229], off
	v_lshl_add_u64 v[228:229], v[228:229], 0, 64
	s_mov_b32 m0, s96
	s_add_i32 s96, s96, 0x1000
	v_mfma_f32_16x16x32_bf16 v[20:23], v[208:211], v[162:165], v[20:23]
	s_waitcnt lgkmcnt(0)
	v_mfma_f32_16x16x32_bf16 v[16:19], v[212:215], v[148:151], v[16:19]
	global_load_lds_dwordx4 v[228:229], off
	v_lshl_add_u64 v[228:229], v[228:229], 0, 64
	v_mfma_f32_16x16x32_bf16 v[12:15], v[212:215], v[154:157], v[12:15]
	v_mfma_f32_16x16x32_bf16 v[8:11], v[212:215], v[158:161], v[8:11]
	v_mfma_f32_16x16x32_bf16 v[4:7], v[212:215], v[162:165], v[4:7]
	s_setprio 0
	s_add_i32 s10, s10, 0x6000
	s_cmp_lg_u32 s10, 0x12000
	s_cselect_b32 s10, s10, 0
	s_sub_i32 s11, s11, 0x6000
	s_cmp_lt_i32 s11, 0
	s_cselect_b32 s11, 0xc000, s11
	s_add_i32 s3, s3, 1
	s_cmp_lt_i32 s3, 15
	s_waitcnt vmcnt(1)
	s_barrier
	s_cbranch_scc1 .Lg3_loop_904
	v_add_u32_e32 v216, s10, v146
	v_add_u32_e32 v217, s10, v2
	ds_read_b128 v[148:151], v217 offset:16384
	ds_read_b128 v[166:169], v216
	ds_read_b128 v[154:157], v217 offset:17408
	ds_read_b128 v[158:161], v217 offset:18432
	ds_read_b128 v[162:165], v217 offset:19456
	ds_read_b128 v[170:173], v216 offset:1024
	ds_read_b128 v[174:177], v216 offset:2048
	ds_read_b128 v[192:195], v216 offset:3072
	ds_read_b128 v[196:199], v216 offset:4096
	ds_read_b128 v[204:207], v216 offset:5120
	ds_read_b128 v[208:211], v216 offset:6144
	ds_read_b128 v[212:215], v216 offset:7168
	s_setprio 1
	s_waitcnt lgkmcnt(10)
	v_mfma_f32_16x16x32_bf16 v[128:131], v[166:169], v[148:151], v[128:131]
	s_waitcnt lgkmcnt(9)
	v_mfma_f32_16x16x32_bf16 v[124:127], v[166:169], v[154:157], v[124:127]
	s_waitcnt lgkmcnt(8)
	v_mfma_f32_16x16x32_bf16 v[120:123], v[166:169], v[158:161], v[120:123]
	s_waitcnt lgkmcnt(7)
	v_mfma_f32_16x16x32_bf16 v[116:119], v[166:169], v[162:165], v[116:119]
	s_waitcnt lgkmcnt(6)
	v_mfma_f32_16x16x32_bf16 v[112:115], v[170:173], v[148:151], v[112:115]
	v_mfma_f32_16x16x32_bf16 v[108:111], v[170:173], v[154:157], v[108:111]
	v_mfma_f32_16x16x32_bf16 v[104:107], v[170:173], v[158:161], v[104:107]
	v_mfma_f32_16x16x32_bf16 v[100:103], v[170:173], v[162:165], v[100:103]
	s_waitcnt lgkmcnt(5)
	v_mfma_f32_16x16x32_bf16 v[96:99], v[174:177], v[148:151], v[96:99]
	v_mfma_f32_16x16x32_bf16 v[92:95], v[174:177], v[154:157], v[92:95]
	v_mfma_f32_16x16x32_bf16 v[88:91], v[174:177], v[158:161], v[88:91]
	v_mfma_f32_16x16x32_bf16 v[84:87], v[174:177], v[162:165], v[84:87]
	s_waitcnt lgkmcnt(4)
	v_mfma_f32_16x16x32_bf16 v[80:83], v[192:195], v[148:151], v[80:83]
	v_mfma_f32_16x16x32_bf16 v[76:79], v[192:195], v[154:157], v[76:79]
	v_mfma_f32_16x16x32_bf16 v[72:75], v[192:195], v[158:161], v[72:75]
	v_mfma_f32_16x16x32_bf16 v[68:71], v[192:195], v[162:165], v[68:71]
	s_waitcnt lgkmcnt(3)
	v_mfma_f32_16x16x32_bf16 v[64:67], v[196:199], v[148:151], v[64:67]
	v_mfma_f32_16x16x32_bf16 v[60:63], v[196:199], v[154:157], v[60:63]
	v_mfma_f32_16x16x32_bf16 v[56:59], v[196:199], v[158:161], v[56:59]
	v_mfma_f32_16x16x32_bf16 v[52:55], v[196:199], v[162:165], v[52:55]
	s_waitcnt lgkmcnt(2)
	v_mfma_f32_16x16x32_bf16 v[48:51], v[204:207], v[148:151], v[48:51]
	v_mfma_f32_16x16x32_bf16 v[44:47], v[204:207], v[154:157], v[44:47]
	v_mfma_f32_16x16x32_bf16 v[40:43], v[204:207], v[158:161], v[40:43]
	v_mfma_f32_16x16x32_bf16 v[36:39], v[204:207], v[162:165], v[36:39]
	s_waitcnt lgkmcnt(1)
	v_mfma_f32_16x16x32_bf16 v[32:35], v[208:211], v[148:151], v[32:35]
	v_mfma_f32_16x16x32_bf16 v[28:31], v[208:211], v[154:157], v[28:31]
	v_mfma_f32_16x16x32_bf16 v[24:27], v[208:211], v[158:161], v[24:27]
	v_mfma_f32_16x16x32_bf16 v[20:23], v[208:211], v[162:165], v[20:23]
	s_waitcnt lgkmcnt(0)
	v_mfma_f32_16x16x32_bf16 v[16:19], v[212:215], v[148:151], v[16:19]
	v_mfma_f32_16x16x32_bf16 v[12:15], v[212:215], v[154:157], v[12:15]
	v_mfma_f32_16x16x32_bf16 v[8:11], v[212:215], v[158:161], v[8:11]
	v_mfma_f32_16x16x32_bf16 v[4:7], v[212:215], v[162:165], v[4:7]
	s_setprio 0
	s_add_i32 s10, s10, 0x6000
	s_cmp_lg_u32 s10, 0x12000
	s_cselect_b32 s10, s10, 0
	s_waitcnt vmcnt(0)
	s_barrier
; DEVI f32x4 mfma16(bf16x8 a, bf16x8 b, f32x4 c) { return __builtin_amdgcn_mfma_f32_16x16x32_bf16(a, b, c, 0, 0, 0); }
; DEVI void gemm_core3(f32x4 (&acc)[8][4], const bf* __restrict__ A, int lda, const bf* __restrict__ Bt, int ldb, int K, char* smem) {
;     ...
;     bf16x8 bfr[4], af[8];
; #pragma unroll
;     for (int n = 0; n < 4; ++n) bfr[n] = *reinterpret_cast<const bf16x8*>(bbase + so + n * 16 * 64);
; #pragma unroll
;     for (int m = 0; m < 8; ++m) af[m] = *reinterpret_cast<const bf16x8*>(abase + so + m * 16 * 64);
; #pragma unroll
;     for (int i = 0; i < 4; ++i) glds16(Ap + i * sa + k1, dbase + sn + i * 4096);
; #pragma unroll
;     for (int i = 0; i < 2; ++i) glds16(Bp + i * sb + k1, dbase + sn + ASZ + i * 4096);
;     __builtin_amdgcn_s_setprio(1);
; #pragma unroll
;     for (int m = 0; m < 8; ++m)
; #pragma unroll
;       for (int n = 0; n < 4; ++n) acc[m][n] = mfma16(af[m], bfr[n], acc[m][n]);
;     __builtin_amdgcn_s_setprio(0);
; DEVI void plain_tile256(const bf* A, int lda, const bf* Wt, int K, bf* C, int ldc, long row0, int n0, char* smem) {
;     ...
;   bf* tl = reinterpret_cast<bf*>(smem);
; #pragma unroll
;   for (int m = 0; m < 8; ++m)
; #pragma unroll
;     for (int n = 0; n < 4; ++n) {
;       const int cl = wc * 64 + n * 16 + l15;
; #pragma unroll
;       for (int j = 0; j < 4; ++j) tl[(wr * 128 + m * 16 + quad * 4 + j) * 136 + cl] = f2bf(acc[m][n][j]);
;     }
	v_add_u32_e32 v216, s10, v146
	v_add_u32_e32 v217, s10, v2
	ds_read_b128 v[148:151], v217 offset:16384
	ds_read_b128 v[166:169], v216
	ds_read_b128 v[154:157], v217 offset:17408
	ds_read_b128 v[158:161], v217 offset:18432
	ds_read_b128 v[162:165], v217 offset:19456
	ds_read_b128 v[170:173], v216 offset:1024
	ds_read_b128 v[174:177], v216 offset:2048
	ds_read_b128 v[192:195], v216 offset:3072
	ds_read_b128 v[196:199], v216 offset:4096
	ds_read_b128 v[204:207], v216 offset:5120
	ds_read_b128 v[208:211], v216 offset:6144
	ds_read_b128 v[212:215], v216 offset:7168
	s_setprio 1
	s_waitcnt lgkmcnt(10)
	v_mfma_f32_16x16x32_bf16 v[128:131], v[166:169], v[148:151], v[128:131]
	s_waitcnt lgkmcnt(9)
	v_mfma_f32_16x16x32_bf16 v[124:127], v[166:169], v[154:157], v[124:127]
	s_waitcnt lgkmcnt(8)
	v_mfma_f32_16x16x32_bf16 v[120:123], v[166:169], v[158:161], v[120:123]
	s_waitcnt lgkmcnt(7)
	v_mfma_f32_16x16x32_bf16 v[116:119], v[166:169], v[162:165], v[116:119]
	s_waitcnt lgkmcnt(6)
	v_mfma_f32_16x16x32_bf16 v[112:115], v[170:173], v[148:151], v[112:115]
	v_mfma_f32_16x16x32_bf16 v[108:111], v[170:173], v[154:157], v[108:111]
	v_mfma_f32_16x16x32_bf16 v[104:107], v[170:173], v[158:161], v[104:107]
	v_mfma_f32_16x16x32_bf16 v[100:103], v[170:173], v[162:165], v[100:103]
	s_waitcnt lgkmcnt(5)
	v_mfma_f32_16x16x32_bf16 v[96:99], v[174:177], v[148:151], v[96:99]
	v_mfma_f32_16x16x32_bf16 v[92:95], v[174:177], v[154:157], v[92:95]
	v_mfma_f32_16x16x32_bf16 v[88:91], v[174:177], v[158:161], v[88:91]
	v_mfma_f32_16x16x32_bf16 v[84:87], v[174:177], v[162:165], v[84:87]
	s_waitcnt lgkmcnt(4)
	v_mfma_f32_16x16x32_bf16 v[80:83], v[192:195], v[148:151], v[80:83]
	v_mfma_f32_16x16x32_bf16 v[76:79], v[192:195], v[154:157], v[76:79]
	v_mfma_f32_16x16x32_bf16 v[72:75], v[192:195], v[158:161], v[72:75]
	v_mfma_f32_16x16x32_bf16 v[68:71], v[192:195], v[162:165], v[68:71]
	s_waitcnt lgkmcnt(3)
	v_mfma_f32_16x16x32_bf16 v[64:67], v[196:199], v[148:151], v[64:67]
	v_mfma_f32_16x16x32_bf16 v[60:63], v[196:199], v[154:157], v[60:63]
	v_mfma_f32_16x16x32_bf16 v[56:59], v[196:199], v[158:161], v[56:59]
	v_mfma_f32_16x16x32_bf16 v[52:55], v[196:199], v[162:165], v[52:55]
	s_waitcnt lgkmcnt(2)
	v_mfma_f32_16x16x32_bf16 v[48:51], v[204:207], v[148:151], v[48:51]
	v_mfma_f32_16x16x32_bf16 v[44:47], v[204:207], v[154:157], v[44:47]
	v_mfma_f32_16x16x32_bf16 v[40:43], v[204:207], v[158:161], v[40:43]
	v_mfma_f32_16x16x32_bf16 v[36:39], v[204:207], v[162:165], v[36:39]
	s_waitcnt lgkmcnt(1)
	v_mfma_f32_16x16x32_bf16 v[32:35], v[208:211], v[148:151], v[32:35]
	v_mfma_f32_16x16x32_bf16 v[28:31], v[208:211], v[154:157], v[28:31]
	v_mfma_f32_16x16x32_bf16 v[24:27], v[208:211], v[158:161], v[24:27]
	v_mfma_f32_16x16x32_bf16 v[20:23], v[208:211], v[162:165], v[20:23]
	s_waitcnt lgkmcnt(0)
	v_mfma_f32_16x16x32_bf16 v[16:19], v[212:215], v[148:151], v[16:19]
	v_mfma_f32_16x16x32_bf16 v[12:15], v[212:215], v[154:157], v[12:15]
	v_mfma_f32_16x16x32_bf16 v[8:11], v[212:215], v[158:161], v[8:11]
	v_mfma_f32_16x16x32_bf16 v[4:7], v[212:215], v[162:165], v[4:7]
	s_setprio 0
	s_add_i32 s10, s10, 0x6000
	s_cmp_lg_u32 s10, 0x12000
	s_cselect_b32 s10, s10, 0
	s_waitcnt vmcnt(0)
	s_barrier
	v_and_b32_e32 v2, 0x4f, v1
	v_and_b32_e32 v132, 0xfffff80, v1
	v_lshrrev_b32_e32 v1, 2, v1
	v_and_or_b32 v1, v1, 12, v132
	v_mul_lo_u32 v1, v1, s16
	v_lshl_add_u32 v1, v2, 1, v1
	v_cvt_pk_bf16_f32 v2, v129, s0
	ds_write_b16 v1, v2 offset:272
	v_cvt_pk_bf16_f32 v2, v130, s0
	ds_write_b16 v1, v2 offset:544
	v_cvt_pk_bf16_f32 v2, v131, s0
	ds_write_b16 v1, v2 offset:816
	v_cvt_pk_bf16_f32 v2, v124, s0
	ds_write_b16 v1, v2 offset:32
	v_cvt_pk_bf16_f32 v2, v125, s0
	ds_write_b16 v1, v2 offset:304
	v_cvt_pk_bf16_f32 v2, v126, s0
	ds_write_b16 v1, v2 offset:576
	v_cvt_pk_bf16_f32 v2, v127, s0
	ds_write_b16 v1, v2 offset:848
	v_cvt_pk_bf16_f32 v2, v120, s0
	ds_write_b16 v1, v2 offset:64
	v_cvt_pk_bf16_f32 v2, v121, s0
	ds_write_b16 v1, v2 offset:336
	v_cvt_pk_bf16_f32 v2, v122, s0
	ds_write_b16 v1, v2 offset:608
	v_cvt_pk_bf16_f32 v2, v123, s0
	ds_write_b16 v1, v2 offset:880
	v_cvt_pk_bf16_f32 v2, v116, s0
	ds_write_b16 v1, v2 offset:96
	v_cvt_pk_bf16_f32 v2, v117, s0
	ds_write_b16 v1, v2 offset:368
	v_cvt_pk_bf16_f32 v2, v118, s0
	ds_write_b16 v1, v2 offset:640
	v_cvt_pk_bf16_f32 v2, v119, s0
	ds_write_b16 v1, v2 offset:912
	v_cvt_pk_bf16_f32 v2, v112, s0
	ds_write_b16 v1, v2 offset:4352
	v_cvt_pk_bf16_f32 v2, v113, s0
	ds_write_b16 v1, v2 offset:4624
	v_cvt_pk_bf16_f32 v2, v114, s0
	ds_write_b16 v1, v2 offset:4896
	v_cvt_pk_bf16_f32 v2, v115, s0
	ds_write_b16 v1, v2 offset:5168
	v_cvt_pk_bf16_f32 v2, v108, s0
	ds_write_b16 v1, v2 offset:4384
	v_cvt_pk_bf16_f32 v2, v109, s0
	ds_write_b16 v1, v2 offset:4656
	v_cvt_pk_bf16_f32 v2, v110, s0
	ds_write_b16 v1, v2 offset:4928
	v_cvt_pk_bf16_f32 v2, v111, s0
	ds_write_b16 v1, v2 offset:5200
	v_cvt_pk_bf16_f32 v2, v104, s0
	ds_write_b16 v1, v2 offset:4416
	v_cvt_pk_bf16_f32 v2, v105, s0
	ds_write_b16 v1, v2 offset:4688
	v_cvt_pk_bf16_f32 v2, v106, s0
	ds_write_b16 v1, v2 offset:4960
	v_cvt_pk_bf16_f32 v2, v107, s0
	ds_write_b16 v1, v2 offset:5232
	v_cvt_pk_bf16_f32 v2, v100, s0
	ds_write_b16 v1, v2 offset:4448
	v_cvt_pk_bf16_f32 v2, v101, s0
	ds_write_b16 v1, v2 offset:4720
	v_cvt_pk_bf16_f32 v2, v102, s0
	ds_write_b16 v1, v2 offset:4992
	v_cvt_pk_bf16_f32 v2, v103, s0
	ds_write_b16 v1, v2 offset:5264
	v_cvt_pk_bf16_f32 v2, v96, s0
	ds_write_b16 v1, v2 offset:8704
	v_cvt_pk_bf16_f32 v2, v97, s0
	ds_write_b16 v1, v2 offset:8976
	v_cvt_pk_bf16_f32 v2, v98, s0
	ds_write_b16 v1, v2 offset:9248
	v_cvt_pk_bf16_f32 v2, v99, s0
	ds_write_b16 v1, v2 offset:9520
	v_cvt_pk_bf16_f32 v2, v92, s0
; DEVI void plain_tile256(const bf* A, int lda, const bf* Wt, int K, bf* C, int ldc, long row0, int n0, char* smem) {
;     ...
; #pragma unroll
;   for (int m = 0; m < 8; ++m)
; #pragma unroll
;     for (int n = 0; n < 4; ++n) {
;       const int cl = wc * 64 + n * 16 + l15;
; #pragma unroll
;       for (int j = 0; j < 4; ++j) tl[(wr * 128 + m * 16 + quad * 4 + j) * 136 + cl] = f2bf(acc[m][n][j]);
;     }
;   __syncthreads();
	ds_write_b16 v1, v2 offset:8736
	v_cvt_pk_bf16_f32 v2, v93, s0
	ds_write_b16 v1, v2 offset:9008
	v_cvt_pk_bf16_f32 v2, v94, s0
	ds_write_b16 v1, v2 offset:9280
	v_cvt_pk_bf16_f32 v2, v95, s0
	ds_write_b16 v1, v2 offset:9552
	v_cvt_pk_bf16_f32 v2, v88, s0
	ds_write_b16 v1, v2 offset:8768
	v_cvt_pk_bf16_f32 v2, v89, s0
	ds_write_b16 v1, v2 offset:9040
	v_cvt_pk_bf16_f32 v2, v90, s0
	ds_write_b16 v1, v2 offset:9312
	v_cvt_pk_bf16_f32 v2, v91, s0
	ds_write_b16 v1, v2 offset:9584
	v_cvt_pk_bf16_f32 v2, v84, s0
	ds_write_b16 v1, v2 offset:8800
	v_cvt_pk_bf16_f32 v2, v85, s0
	ds_write_b16 v1, v2 offset:9072
	v_cvt_pk_bf16_f32 v2, v86, s0
	ds_write_b16 v1, v2 offset:9344
	v_cvt_pk_bf16_f32 v2, v87, s0
	ds_write_b16 v1, v2 offset:9616
	v_cvt_pk_bf16_f32 v2, v80, s0
	ds_write_b16 v1, v2 offset:13056
	v_cvt_pk_bf16_f32 v2, v81, s0
	ds_write_b16 v1, v2 offset:13328
	v_cvt_pk_bf16_f32 v2, v82, s0
	ds_write_b16 v1, v2 offset:13600
	v_cvt_pk_bf16_f32 v2, v83, s0
	ds_write_b16 v1, v2 offset:13872
	v_cvt_pk_bf16_f32 v2, v76, s0
	ds_write_b16 v1, v2 offset:13088
	v_cvt_pk_bf16_f32 v2, v77, s0
	ds_write_b16 v1, v2 offset:13360
	v_cvt_pk_bf16_f32 v2, v78, s0
	ds_write_b16 v1, v2 offset:13632
	v_cvt_pk_bf16_f32 v2, v79, s0
	ds_write_b16 v1, v2 offset:13904
	v_cvt_pk_bf16_f32 v2, v72, s0
	ds_write_b16 v1, v2 offset:13120
	v_cvt_pk_bf16_f32 v2, v73, s0
	ds_write_b16 v1, v2 offset:13392
	v_cvt_pk_bf16_f32 v2, v74, s0
	ds_write_b16 v1, v2 offset:13664
	v_cvt_pk_bf16_f32 v2, v75, s0
	ds_write_b16 v1, v2 offset:13936
	v_cvt_pk_bf16_f32 v2, v68, s0
	ds_write_b16 v1, v2 offset:13152
	v_cvt_pk_bf16_f32 v2, v69, s0
	ds_write_b16 v1, v2 offset:13424
	v_cvt_pk_bf16_f32 v2, v70, s0
	ds_write_b16 v1, v2 offset:13696
	v_cvt_pk_bf16_f32 v2, v71, s0
	ds_write_b16 v1, v2 offset:13968
	v_cvt_pk_bf16_f32 v2, v64, s0
	ds_write_b16 v1, v2 offset:17408
	v_cvt_pk_bf16_f32 v2, v65, s0
	ds_write_b16 v1, v2 offset:17680
	v_cvt_pk_bf16_f32 v2, v66, s0
	ds_write_b16 v1, v2 offset:17952
	v_cvt_pk_bf16_f32 v2, v67, s0
	ds_write_b16 v1, v2 offset:18224
	v_cvt_pk_bf16_f32 v2, v60, s0
	ds_write_b16 v1, v2 offset:17440
	v_cvt_pk_bf16_f32 v2, v61, s0
	ds_write_b16 v1, v2 offset:17712
	v_cvt_pk_bf16_f32 v2, v62, s0
	ds_write_b16 v1, v2 offset:17984
	v_cvt_pk_bf16_f32 v2, v63, s0
	ds_write_b16 v1, v2 offset:18256
	v_cvt_pk_bf16_f32 v2, v56, s0
	ds_write_b16 v1, v2 offset:17472
	v_cvt_pk_bf16_f32 v2, v57, s0
	ds_write_b16 v1, v2 offset:17744
	v_cvt_pk_bf16_f32 v2, v58, s0
	ds_write_b16 v1, v2 offset:18016
	v_cvt_pk_bf16_f32 v2, v59, s0
	ds_write_b16 v1, v2 offset:18288
	v_cvt_pk_bf16_f32 v2, v52, s0
	ds_write_b16 v1, v2 offset:17504
	v_cvt_pk_bf16_f32 v2, v53, s0
	ds_write_b16 v1, v2 offset:17776
	v_cvt_pk_bf16_f32 v2, v54, s0
	ds_write_b16 v1, v2 offset:18048
	v_cvt_pk_bf16_f32 v2, v55, s0
	ds_write_b16 v1, v2 offset:18320
	v_cvt_pk_bf16_f32 v2, v48, s0
	ds_write_b16 v1, v2 offset:21760
	v_cvt_pk_bf16_f32 v2, v49, s0
	ds_write_b16 v1, v2 offset:22032
	v_cvt_pk_bf16_f32 v2, v50, s0
	ds_write_b16 v1, v2 offset:22304
	v_cvt_pk_bf16_f32 v2, v51, s0
	ds_write_b16 v1, v2 offset:22576
	v_cvt_pk_bf16_f32 v2, v44, s0
	ds_write_b16 v1, v2 offset:21792
	v_cvt_pk_bf16_f32 v2, v45, s0
	ds_write_b16 v1, v2 offset:22064
	v_cvt_pk_bf16_f32 v2, v46, s0
	ds_write_b16 v1, v2 offset:22336
	v_cvt_pk_bf16_f32 v2, v47, s0
	ds_write_b16 v1, v2 offset:22608
	v_cvt_pk_bf16_f32 v2, v40, s0
	ds_write_b16 v1, v2 offset:21824
	v_cvt_pk_bf16_f32 v2, v41, s0
	ds_write_b16 v1, v2 offset:22096
	v_cvt_pk_bf16_f32 v2, v42, s0
	ds_write_b16 v1, v2 offset:22368
	v_cvt_pk_bf16_f32 v2, v43, s0
	ds_write_b16 v1, v2 offset:22640
	v_cvt_pk_bf16_f32 v2, v36, s0
	ds_write_b16 v1, v2 offset:21856
	v_cvt_pk_bf16_f32 v2, v37, s0
	ds_write_b16 v1, v2 offset:22128
	v_cvt_pk_bf16_f32 v2, v38, s0
	ds_write_b16 v1, v2 offset:22400
	v_cvt_pk_bf16_f32 v2, v39, s0
	ds_write_b16 v1, v2 offset:22672
	v_cvt_pk_bf16_f32 v2, v32, s0
	ds_write_b16 v1, v2 offset:26112
	v_cvt_pk_bf16_f32 v2, v33, s0
	ds_write_b16 v1, v2 offset:26384
	v_cvt_pk_bf16_f32 v2, v34, s0
	ds_write_b16 v1, v2 offset:26656
	v_cvt_pk_bf16_f32 v2, v35, s0
	ds_write_b16 v1, v2 offset:26928
	v_cvt_pk_bf16_f32 v2, v28, s0
	ds_write_b16 v1, v2 offset:26144
	v_cvt_pk_bf16_f32 v2, v29, s0
	ds_write_b16 v1, v2 offset:26416
	v_cvt_pk_bf16_f32 v2, v30, s0
	ds_write_b16 v1, v2 offset:26688
	v_cvt_pk_bf16_f32 v2, v31, s0
	ds_write_b16 v1, v2 offset:26960
	v_cvt_pk_bf16_f32 v2, v24, s0
	ds_write_b16 v1, v2 offset:26176
	v_cvt_pk_bf16_f32 v2, v25, s0
	ds_write_b16 v1, v2 offset:26448
	v_cvt_pk_bf16_f32 v2, v26, s0
	ds_write_b16 v1, v2 offset:26720
	v_cvt_pk_bf16_f32 v2, v27, s0
	ds_write_b16 v1, v2 offset:26992
	v_cvt_pk_bf16_f32 v2, v20, s0
	ds_write_b16 v1, v2 offset:26208
	v_cvt_pk_bf16_f32 v2, v21, s0
	ds_write_b16 v1, v2 offset:26480
	v_cvt_pk_bf16_f32 v2, v22, s0
	ds_write_b16 v1, v2 offset:26752
	v_cvt_pk_bf16_f32 v2, v23, s0
	ds_write_b16 v1, v2 offset:27024
	v_cvt_pk_bf16_f32 v2, v16, s0
	ds_write_b16 v1, v2 offset:30464
	v_cvt_pk_bf16_f32 v2, v17, s0
	ds_write_b16 v1, v2 offset:30736
	v_cvt_pk_bf16_f32 v2, v18, s0
	ds_write_b16 v1, v2 offset:31008
	v_cvt_pk_bf16_f32 v2, v19, s0
	ds_write_b16 v1, v2 offset:31280
	v_cvt_pk_bf16_f32 v2, v12, s0
	ds_write_b16 v1, v2 offset:30496
	v_cvt_pk_bf16_f32 v2, v13, s0
	ds_write_b16 v1, v2 offset:30768
	v_cvt_pk_bf16_f32 v2, v14, s0
	ds_write_b16 v1, v2 offset:31040
	v_cvt_pk_bf16_f32 v2, v15, s0
	ds_write_b16 v1, v2 offset:31312
	v_cvt_pk_bf16_f32 v2, v8, s0
	ds_write_b16 v1, v2 offset:30528
	v_cvt_pk_bf16_f32 v2, v9, s0
	ds_write_b16 v1, v2 offset:30800
	v_cvt_pk_bf16_f32 v2, v10, s0
	ds_write_b16 v1, v2 offset:31072
	v_cvt_pk_bf16_f32 v2, v11, s0
	ds_write_b16 v1, v2 offset:31344
	v_cvt_pk_bf16_f32 v2, v4, s0
	ds_write_b16 v1, v2 offset:30560
	v_cvt_pk_bf16_f32 v2, v5, s0
	ds_write_b16 v1, v2 offset:30832
	v_cvt_pk_bf16_f32 v2, v6, s0
	v_cvt_pk_bf16_f32 v128, v128, s0
	ds_write_b16 v1, v2 offset:31104
	v_cvt_pk_bf16_f32 v2, v7, s0
	ds_write_b16 v1, v128
	ds_write_b16 v1, v2 offset:31376
	v_mov_b32_e32 v1, v178
	s_waitcnt lgkmcnt(0)
	s_barrier
; DEVI int get_tid() { int t = threadIdx.x; asm volatile("" : "+v"(t)); return t; }
; template <int BN>
; DEVI void tile_store256(const char* smem, bf* __restrict__ C, long ldc, long row0, int col0) {
;   constexpr int LDT = BN + 8;
;   constexpr int CPR = BN / 8;
;   const int tid = get_tid();
; #pragma unroll
;   for (int i = 0; i < CPR; ++i) {
;     const int q = tid + 256 * i;
;     const int r = q / CPR, c = q - r * CPR;
;     u32x4 v = *reinterpret_cast<const u32x4*>(smem + (r * LDT + c * 8) * 2);
;     *reinterpret_cast<u32x4*>(C + (row0 + r) * ldc + col0 + c * 8) = v;
;   }
; }
	v_readlane_b32 s56, v251, 58
	v_ashrrev_i32_e32 v2, 31, v1
	v_lshrrev_b32_e32 v2, 28, v2
	v_add_u32_e32 v2, v1, v2
	s_lshl_b64 s[10:11], s[34:35], 1
	v_readlane_b32 s58, v251, 60
	v_ashrrev_i32_e32 v4, 4, v2
	v_readlane_b32 s59, v251, 61
	s_add_u32 s10, s58, s10
	v_lshlrev_b32_e32 v5, 7, v4
	v_lshlrev_b32_e32 v6, 3, v1
	s_addc_u32 s11, s59, s11
	v_sub_u32_e32 v10, v6, v5
	v_ashrrev_i32_e32 v5, 31, v4
	v_mul_lo_u32 v2, v4, s29
	v_lshl_add_u64 v[12:13], s[12:13], 0, v[4:5]
	v_mov_b64_e32 v[4:5], s[10:11]
	v_add_lshl_u32 v2, v10, v2, 1
	v_mad_u64_u32 v[14:15], s[10:11], v12, s39, v[4:5]
	ds_read_b128 v[6:9], v2
	v_mov_b32_e32 v2, v15
	v_mad_u64_u32 v[12:13], s[10:11], v13, s39, v[2:3]
	v_mov_b32_e32 v15, v12
	v_ashrrev_i32_e32 v11, 31, v10
	v_add_u32_e32 v2, 0x100, v1
	v_lshl_add_u64 v[14:15], v[10:11], 1, v[14:15]
	v_ashrrev_i32_e32 v10, 31, v2
	v_lshrrev_b32_e32 v10, 28, v10
	v_add_u32_e32 v10, v2, v10
	v_ashrrev_i32_e32 v16, 4, v10
	v_lshlrev_b32_e32 v11, 7, v16
	v_lshlrev_b32_e32 v2, 3, v2
	v_mul_lo_u32 v10, v16, s29
	v_sub_u32_e32 v18, v2, v11
	v_ashrrev_i32_e32 v17, 31, v16
	v_add_lshl_u32 v2, v18, v10, 1
	s_waitcnt lgkmcnt(0)
	global_store_dwordx4 v[14:15], v[6:9], off
	ds_read_b128 v[10:13], v2
	v_ashrrev_i32_e32 v19, 31, v18
	v_lshl_add_u64 v[6:7], s[12:13], 0, v[16:17]
	v_mad_u64_u32 v[8:9], s[10:11], v6, s39, v[4:5]
	v_mov_b32_e32 v2, v9
	v_mad_u64_u32 v[6:7], s[10:11], v7, s39, v[2:3]
	v_mov_b32_e32 v9, v6
	v_lshl_add_u64 v[6:7], v[18:19], 1, v[8:9]
	v_add_u32_e32 v2, 0x200, v1
	s_waitcnt lgkmcnt(0)
	global_store_dwordx4 v[6:7], v[10:13], off
	v_ashrrev_i32_e32 v6, 31, v2
	v_lshrrev_b32_e32 v6, 28, v6
	v_add_u32_e32 v6, v2, v6
	v_ashrrev_i32_e32 v10, 4, v6
	v_lshlrev_b32_e32 v7, 7, v10
	v_lshlrev_b32_e32 v2, 3, v2
	v_ashrrev_i32_e32 v11, 31, v10
	v_mul_lo_u32 v6, v10, s29
	v_sub_u32_e32 v12, v2, v7
	v_lshl_add_u64 v[10:11], s[12:13], 0, v[10:11]
	v_add_lshl_u32 v2, v12, v6, 1
	v_mad_u64_u32 v[14:15], s[10:11], v10, s39, v[4:5]
	ds_read_b128 v[6:9], v2
	v_mov_b32_e32 v2, v15
	v_mad_u64_u32 v[10:11], s[10:11], v11, s39, v[2:3]
	v_add_u32_e32 v2, 0x300, v1
	v_mov_b32_e32 v15, v10
	v_ashrrev_i32_e32 v10, 31, v2
	v_lshrrev_b32_e32 v10, 28, v10
	v_add_u32_e32 v10, v2, v10
	v_ashrrev_i32_e32 v16, 4, v10
	v_ashrrev_i32_e32 v13, 31, v12
	v_lshlrev_b32_e32 v11, 7, v16
	v_lshlrev_b32_e32 v2, 3, v2
	v_lshl_add_u64 v[14:15], v[12:13], 1, v[14:15]
	v_mul_lo_u32 v10, v16, s29
	v_sub_u32_e32 v18, v2, v11
	v_ashrrev_i32_e32 v17, 31, v16
	v_add_lshl_u32 v2, v18, v10, 1
	s_waitcnt lgkmcnt(0)
	global_store_dwordx4 v[14:15], v[6:9], off
	ds_read_b128 v[10:13], v2
	v_ashrrev_i32_e32 v19, 31, v18
	v_lshl_add_u64 v[6:7], s[12:13], 0, v[16:17]
	v_mad_u64_u32 v[8:9], s[10:11], v6, s39, v[4:5]
	v_mov_b32_e32 v2, v9
	v_mad_u64_u32 v[6:7], s[10:11], v7, s39, v[2:3]
	v_mov_b32_e32 v9, v6
	v_lshl_add_u64 v[6:7], v[18:19], 1, v[8:9]
	v_add_u32_e32 v2, 0x400, v1
	s_waitcnt lgkmcnt(0)
	global_store_dwordx4 v[6:7], v[10:13], off
	v_ashrrev_i32_e32 v6, 31, v2
	v_lshrrev_b32_e32 v6, 28, v6
	v_add_u32_e32 v6, v2, v6
	v_ashrrev_i32_e32 v10, 4, v6
	v_lshlrev_b32_e32 v7, 7, v10
	v_lshlrev_b32_e32 v2, 3, v2
	v_ashrrev_i32_e32 v11, 31, v10
	v_mul_lo_u32 v6, v10, s29
	v_sub_u32_e32 v12, v2, v7
	v_lshl_add_u64 v[10:11], s[12:13], 0, v[10:11]
	v_add_lshl_u32 v2, v12, v6, 1
	v_mad_u64_u32 v[14:15], s[10:11], v10, s39, v[4:5]
	ds_read_b128 v[6:9], v2
	v_mov_b32_e32 v2, v15
	v_mad_u64_u32 v[10:11], s[10:11], v11, s39, v[2:3]
	v_add_u32_e32 v2, 0x500, v1
	v_mov_b32_e32 v15, v10
	v_ashrrev_i32_e32 v10, 31, v2
	v_lshrrev_b32_e32 v10, 28, v10
	v_add_u32_e32 v10, v2, v10
	v_ashrrev_i32_e32 v16, 4, v10
	v_ashrrev_i32_e32 v13, 31, v12
	v_lshlrev_b32_e32 v11, 7, v16
	v_lshlrev_b32_e32 v2, 3, v2
	v_lshl_add_u64 v[14:15], v[12:13], 1, v[14:15]
	v_mul_lo_u32 v10, v16, s29
	v_sub_u32_e32 v18, v2, v11
	v_ashrrev_i32_e32 v17, 31, v16
	v_add_lshl_u32 v2, v18, v10, 1
	s_waitcnt lgkmcnt(0)
	global_store_dwordx4 v[14:15], v[6:9], off
	ds_read_b128 v[10:13], v2
	v_ashrrev_i32_e32 v19, 31, v18
	v_lshl_add_u64 v[6:7], s[12:13], 0, v[16:17]
	v_mad_u64_u32 v[8:9], s[10:11], v6, s39, v[4:5]
	v_mov_b32_e32 v2, v9
	v_mad_u64_u32 v[6:7], s[10:11], v7, s39, v[2:3]
	v_mov_b32_e32 v9, v6
	v_lshl_add_u64 v[6:7], v[18:19], 1, v[8:9]
	v_add_u32_e32 v2, 0x600, v1
	s_waitcnt lgkmcnt(0)
	global_store_dwordx4 v[6:7], v[10:13], off
	v_ashrrev_i32_e32 v6, 31, v2
	v_lshrrev_b32_e32 v6, 28, v6
	v_add_u32_e32 v6, v2, v6
	v_ashrrev_i32_e32 v10, 4, v6
	v_lshlrev_b32_e32 v7, 7, v10
	v_lshlrev_b32_e32 v2, 3, v2
	v_ashrrev_i32_e32 v11, 31, v10
	v_mul_lo_u32 v6, v10, s29
	v_sub_u32_e32 v12, v2, v7
	v_lshl_add_u64 v[10:11], s[12:13], 0, v[10:11]
	v_add_lshl_u32 v2, v12, v6, 1
	v_mad_u64_u32 v[14:15], s[10:11], v10, s39, v[4:5]
	ds_read_b128 v[6:9], v2
	v_mov_b32_e32 v2, v15
	v_mad_u64_u32 v[10:11], s[10:11], v11, s39, v[2:3]
	v_add_u32_e32 v2, 0x700, v1
	v_mov_b32_e32 v15, v10
	v_ashrrev_i32_e32 v10, 31, v2
	v_lshrrev_b32_e32 v10, 28, v10
	v_add_u32_e32 v10, v2, v10
	v_ashrrev_i32_e32 v16, 4, v10
	v_ashrrev_i32_e32 v13, 31, v12
	v_lshlrev_b32_e32 v11, 7, v16
	v_lshlrev_b32_e32 v2, 3, v2
	v_lshl_add_u64 v[14:15], v[12:13], 1, v[14:15]
	v_mul_lo_u32 v10, v16, s29
	v_sub_u32_e32 v18, v2, v11
	v_ashrrev_i32_e32 v17, 31, v16
	v_add_lshl_u32 v2, v18, v10, 1
	s_waitcnt lgkmcnt(0)
	global_store_dwordx4 v[14:15], v[6:9], off
	ds_read_b128 v[10:13], v2
	v_ashrrev_i32_e32 v19, 31, v18
	v_lshl_add_u64 v[6:7], s[12:13], 0, v[16:17]
	v_mad_u64_u32 v[8:9], s[10:11], v6, s39, v[4:5]
	v_mov_b32_e32 v2, v9
	v_mad_u64_u32 v[6:7], s[10:11], v7, s39, v[2:3]
	v_mov_b32_e32 v9, v6
	v_lshl_add_u64 v[6:7], v[18:19], 1, v[8:9]
	v_add_u32_e32 v2, 0x800, v1
	s_waitcnt lgkmcnt(0)
; DEVI int get_tid() { int t = threadIdx.x; asm volatile("" : "+v"(t)); return t; }
; template <int BN>
; DEVI void tile_store256(const char* smem, bf* __restrict__ C, long ldc, long row0, int col0) {
;   constexpr int LDT = BN + 8;
;   constexpr int CPR = BN / 8;
;   const int tid = get_tid();
; #pragma unroll
;   for (int i = 0; i < CPR; ++i) {
;     const int q = tid + 256 * i;
;     const int r = q / CPR, c = q - r * CPR;
;     u32x4 v = *reinterpret_cast<const u32x4*>(smem + (r * LDT + c * 8) * 2);
;     *reinterpret_cast<u32x4*>(C + (row0 + r) * ldc + col0 + c * 8) = v;
;   }
; }
; DEVI void phase_gemm_plain128(const bf* A, int lda, const bf* Wt, int K, int N, bf* C, int ldc, char* smem) {
;     ...
;   for (int v = blockIdx.x; v < 128 * ntn; v += gridDim.x) {
;     int m2, nt;
;     lat_tile_map256(v, ntn, m2, nt);
;     plain_tile256(A, lda, Wt, K, C, ldc, lat_row0_256(m2), nt * 128, smem);
;   }
	global_store_dwordx4 v[6:7], v[10:13], off
	v_ashrrev_i32_e32 v6, 31, v2
	v_lshrrev_b32_e32 v6, 28, v6
	v_add_u32_e32 v6, v2, v6
	v_ashrrev_i32_e32 v10, 4, v6
	v_lshlrev_b32_e32 v7, 7, v10
	v_lshlrev_b32_e32 v2, 3, v2
	v_ashrrev_i32_e32 v11, 31, v10
	v_mul_lo_u32 v6, v10, s29
	v_sub_u32_e32 v12, v2, v7
	v_lshl_add_u64 v[10:11], s[12:13], 0, v[10:11]
	v_add_lshl_u32 v2, v12, v6, 1
	v_mad_u64_u32 v[14:15], s[10:11], v10, s39, v[4:5]
	ds_read_b128 v[6:9], v2
	v_mov_b32_e32 v2, v15
	v_mad_u64_u32 v[10:11], s[10:11], v11, s39, v[2:3]
	v_add_u32_e32 v2, 0x900, v1
	v_mov_b32_e32 v15, v10
	v_ashrrev_i32_e32 v10, 31, v2
	v_lshrrev_b32_e32 v10, 28, v10
	v_add_u32_e32 v10, v2, v10
	v_ashrrev_i32_e32 v16, 4, v10
	v_ashrrev_i32_e32 v13, 31, v12
	v_lshlrev_b32_e32 v11, 7, v16
	v_lshlrev_b32_e32 v2, 3, v2
	v_lshl_add_u64 v[14:15], v[12:13], 1, v[14:15]
	v_mul_lo_u32 v10, v16, s29
	v_sub_u32_e32 v18, v2, v11
	v_ashrrev_i32_e32 v17, 31, v16
	v_add_lshl_u32 v2, v18, v10, 1
	s_waitcnt lgkmcnt(0)
	global_store_dwordx4 v[14:15], v[6:9], off
	ds_read_b128 v[10:13], v2
	v_ashrrev_i32_e32 v19, 31, v18
	v_lshl_add_u64 v[6:7], s[12:13], 0, v[16:17]
	v_mad_u64_u32 v[8:9], s[10:11], v6, s39, v[4:5]
	v_mov_b32_e32 v2, v9
	v_mad_u64_u32 v[6:7], s[10:11], v7, s39, v[2:3]
	v_mov_b32_e32 v9, v6
	v_lshl_add_u64 v[6:7], v[18:19], 1, v[8:9]
	v_add_u32_e32 v2, 0xa00, v1
	s_waitcnt lgkmcnt(0)
	global_store_dwordx4 v[6:7], v[10:13], off
	v_ashrrev_i32_e32 v6, 31, v2
	v_lshrrev_b32_e32 v6, 28, v6
	v_add_u32_e32 v6, v2, v6
	v_ashrrev_i32_e32 v10, 4, v6
	v_lshlrev_b32_e32 v7, 7, v10
	v_lshlrev_b32_e32 v2, 3, v2
	v_ashrrev_i32_e32 v11, 31, v10
	v_mul_lo_u32 v6, v10, s29
	v_sub_u32_e32 v12, v2, v7
	v_lshl_add_u64 v[10:11], s[12:13], 0, v[10:11]
	v_add_lshl_u32 v2, v12, v6, 1
	v_mad_u64_u32 v[14:15], s[10:11], v10, s39, v[4:5]
	ds_read_b128 v[6:9], v2
	v_mov_b32_e32 v2, v15
	v_mad_u64_u32 v[10:11], s[10:11], v11, s39, v[2:3]
	v_add_u32_e32 v2, 0xb00, v1
	v_mov_b32_e32 v15, v10
	v_ashrrev_i32_e32 v10, 31, v2
	v_lshrrev_b32_e32 v10, 28, v10
	v_add_u32_e32 v10, v2, v10
	v_ashrrev_i32_e32 v16, 4, v10
	v_ashrrev_i32_e32 v13, 31, v12
	v_lshlrev_b32_e32 v11, 7, v16
	v_lshlrev_b32_e32 v2, 3, v2
	v_lshl_add_u64 v[14:15], v[12:13], 1, v[14:15]
	v_mul_lo_u32 v10, v16, s29
	v_sub_u32_e32 v18, v2, v11
	v_ashrrev_i32_e32 v17, 31, v16
	v_add_lshl_u32 v2, v18, v10, 1
	s_waitcnt lgkmcnt(0)
	global_store_dwordx4 v[14:15], v[6:9], off
	ds_read_b128 v[10:13], v2
	v_ashrrev_i32_e32 v19, 31, v18
	v_lshl_add_u64 v[6:7], s[12:13], 0, v[16:17]
	v_mad_u64_u32 v[8:9], s[10:11], v6, s39, v[4:5]
	v_mov_b32_e32 v2, v9
	v_mad_u64_u32 v[6:7], s[10:11], v7, s39, v[2:3]
	v_mov_b32_e32 v9, v6
	v_lshl_add_u64 v[6:7], v[18:19], 1, v[8:9]
	v_add_u32_e32 v2, 0xc00, v1
	s_waitcnt lgkmcnt(0)
	global_store_dwordx4 v[6:7], v[10:13], off
	v_ashrrev_i32_e32 v6, 31, v2
	v_lshrrev_b32_e32 v6, 28, v6
	v_add_u32_e32 v6, v2, v6
	v_ashrrev_i32_e32 v10, 4, v6
	v_lshlrev_b32_e32 v7, 7, v10
	v_lshlrev_b32_e32 v2, 3, v2
	v_ashrrev_i32_e32 v11, 31, v10
	v_mul_lo_u32 v6, v10, s29
	v_sub_u32_e32 v12, v2, v7
	v_lshl_add_u64 v[10:11], s[12:13], 0, v[10:11]
	v_add_lshl_u32 v2, v12, v6, 1
	v_mad_u64_u32 v[14:15], s[10:11], v10, s39, v[4:5]
	ds_read_b128 v[6:9], v2
	v_mov_b32_e32 v2, v15
	v_mad_u64_u32 v[10:11], s[10:11], v11, s39, v[2:3]
	v_add_u32_e32 v2, 0xd00, v1
	v_mov_b32_e32 v15, v10
	v_ashrrev_i32_e32 v10, 31, v2
	v_lshrrev_b32_e32 v10, 28, v10
	v_add_u32_e32 v10, v2, v10
	v_ashrrev_i32_e32 v16, 4, v10
	v_ashrrev_i32_e32 v13, 31, v12
	v_lshlrev_b32_e32 v11, 7, v16
	v_lshlrev_b32_e32 v2, 3, v2
	v_lshl_add_u64 v[14:15], v[12:13], 1, v[14:15]
	v_mul_lo_u32 v10, v16, s29
	v_sub_u32_e32 v18, v2, v11
	v_ashrrev_i32_e32 v17, 31, v16
	v_add_lshl_u32 v2, v18, v10, 1
	s_waitcnt lgkmcnt(0)
	global_store_dwordx4 v[14:15], v[6:9], off
	ds_read_b128 v[10:13], v2
	v_ashrrev_i32_e32 v19, 31, v18
	v_lshl_add_u64 v[6:7], s[12:13], 0, v[16:17]
	v_mad_u64_u32 v[8:9], s[10:11], v6, s39, v[4:5]
	v_mov_b32_e32 v2, v9
	v_mad_u64_u32 v[6:7], s[10:11], v7, s39, v[2:3]
	v_mov_b32_e32 v9, v6
	v_lshl_add_u64 v[6:7], v[18:19], 1, v[8:9]
	v_add_u32_e32 v2, 0xe00, v1
	s_waitcnt lgkmcnt(0)
	global_store_dwordx4 v[6:7], v[10:13], off
	v_ashrrev_i32_e32 v6, 31, v2
	v_lshrrev_b32_e32 v6, 28, v6
	v_add_u32_e32 v6, v2, v6
	v_ashrrev_i32_e32 v10, 4, v6
	v_lshlrev_b32_e32 v7, 7, v10
	v_lshlrev_b32_e32 v2, 3, v2
	v_ashrrev_i32_e32 v11, 31, v10
	v_mul_lo_u32 v6, v10, s29
	v_sub_u32_e32 v12, v2, v7
	v_lshl_add_u64 v[10:11], s[12:13], 0, v[10:11]
	v_add_lshl_u32 v2, v12, v6, 1
	v_mad_u64_u32 v[14:15], s[10:11], v10, s39, v[4:5]
	ds_read_b128 v[6:9], v2
	v_mov_b32_e32 v2, v15
	v_add_u32_e32 v1, 0xf00, v1
	v_mad_u64_u32 v[10:11], s[10:11], v11, s39, v[2:3]
	v_ashrrev_i32_e32 v2, 31, v1
	v_lshrrev_b32_e32 v2, 28, v2
	v_add_u32_e32 v2, v1, v2
	v_mov_b32_e32 v15, v10
	v_ashrrev_i32_e32 v13, 31, v12
	v_ashrrev_i32_e32 v16, 4, v2
	v_lshl_add_u64 v[14:15], v[12:13], 1, v[14:15]
	v_lshlrev_b32_e32 v10, 7, v16
	v_lshlrev_b32_e32 v1, 3, v1
	v_ashrrev_i32_e32 v17, 31, v16
	v_mul_lo_u32 v2, v16, s29
	v_sub_u32_e32 v18, v1, v10
	s_waitcnt lgkmcnt(0)
	global_store_dwordx4 v[14:15], v[6:9], off
	v_add_lshl_u32 v1, v18, v2, 1
	ds_read_b128 v[10:13], v1
	v_lshl_add_u64 v[6:7], s[12:13], 0, v[16:17]
	v_mad_u64_u32 v[4:5], s[10:11], v6, s39, v[4:5]
	v_mov_b32_e32 v2, v5
	v_mad_u64_u32 v[6:7], s[10:11], v7, s39, v[2:3]
	v_readlane_b32 s10, v252, 59
	v_mov_b32_e32 v5, v6
	v_ashrrev_i32_e32 v19, 31, v18
	s_add_i32 s2, s2, s10
	v_readlane_b32 s57, v251, 59
	v_lshl_add_u64 v[4:5], v[18:19], 1, v[4:5]
	s_cmpk_gt_i32 s2, 0x97f
	v_readlane_b32 s60, v251, 62
	v_readlane_b32 s61, v251, 63
	v_readlane_b32 s62, v252, 0
	v_readlane_b32 s63, v252, 1
	v_readlane_b32 s64, v252, 2
	v_readlane_b32 s65, v252, 3
	v_readlane_b32 s66, v252, 4
	v_readlane_b32 s67, v252, 5
	v_readlane_b32 s68, v252, 6
	v_readlane_b32 s69, v252, 7
	v_readlane_b32 s70, v252, 8
	v_readlane_b32 s71, v252, 9
	s_waitcnt lgkmcnt(0)
	global_store_dwordx4 v[4:5], v[10:13], off
	s_barrier
	v_readlane_b32 s11, v252, 60
	s_cbranch_scc0 .LBB0_903

; DEVI f32x4 mfma16(bf16x8 a, bf16x8 b, f32x4 c) { return __builtin_amdgcn_mfma_f32_16x16x32_bf16(a, b, c, 0, 0, 0); }
; DEVI void gemm_core3(f32x4 (&acc)[8][4], const bf* __restrict__ A, int lda, const bf* __restrict__ Bt, int ldb, int K, char* smem) {
;     ...
;   for (int kt = 0; kt < nk; ++kt) {
;     const int k1 = min((kt + 1) * 32, klast);
;     const int sn = ((kt + 1) & 1) * STG;
;     const int so = (kt & 1) * STG;
;     bf16x8 bfr[4], af[8];
; #pragma unroll
;     for (int n = 0; n < 4; ++n) bfr[n] = *reinterpret_cast<const bf16x8*>(bbase + so + n * 16 * 64);
; #pragma unroll
;     for (int m = 0; m < 8; ++m) af[m] = *reinterpret_cast<const bf16x8*>(abase + so + m * 16 * 64);
; #pragma unroll
;     for (int i = 0; i < 4; ++i) glds16(Ap + i * sa + k1, dbase + sn + i * 4096);
; #pragma unroll
;     for (int i = 0; i < 2; ++i) glds16(Bp + i * sb + k1, dbase + sn + ASZ + i * 4096);
;     __builtin_amdgcn_s_setprio(1);
; #pragma unroll
;     for (int m = 0; m < 8; ++m)
; #pragma unroll
;       for (int n = 0; n < 4; ++n) acc[m][n] = mfma16(af[m], bfr[n], acc[m][n]);
;     __builtin_amdgcn_s_setprio(0);
;     __syncthreads();
;   }
.Lg3_loop_926:
	v_add_u32_e32 v216, s10, v146
	v_add_u32_e32 v217, s10, v2
	ds_read_b128 v[148:151], v217 offset:16384
	ds_read_b128 v[166:169], v216
	ds_read_b128 v[154:157], v217 offset:17408
	ds_read_b128 v[158:161], v217 offset:18432
	ds_read_b128 v[162:165], v217 offset:19456
	ds_read_b128 v[170:173], v216 offset:1024
	ds_read_b128 v[174:177], v216 offset:2048
	ds_read_b128 v[192:195], v216 offset:3072
	ds_read_b128 v[196:199], v216 offset:4096
	ds_read_b128 v[204:207], v216 offset:5120
	ds_read_b128 v[208:211], v216 offset:6144
	ds_read_b128 v[212:215], v216 offset:7168
	s_setprio 1
	s_waitcnt lgkmcnt(10)
	v_mfma_f32_16x16x32_bf16 v[128:131], v[166:169], v[148:151], v[128:131]
	s_waitcnt lgkmcnt(9)
	v_mfma_f32_16x16x32_bf16 v[124:127], v[166:169], v[154:157], v[124:127]
	s_waitcnt lgkmcnt(8)
	v_mfma_f32_16x16x32_bf16 v[120:123], v[166:169], v[158:161], v[120:123]
	s_waitcnt lgkmcnt(7)
	v_mfma_f32_16x16x32_bf16 v[116:119], v[166:169], v[162:165], v[116:119]
	s_waitcnt lgkmcnt(6)
	v_mfma_f32_16x16x32_bf16 v[112:115], v[170:173], v[148:151], v[112:115]
	v_mfma_f32_16x16x32_bf16 v[108:111], v[170:173], v[154:157], v[108:111]
	v_mfma_f32_16x16x32_bf16 v[104:107], v[170:173], v[158:161], v[104:107]
	v_mfma_f32_16x16x32_bf16 v[100:103], v[170:173], v[162:165], v[100:103]
	s_waitcnt lgkmcnt(5)
	v_mfma_f32_16x16x32_bf16 v[96:99], v[174:177], v[148:151], v[96:99]
	v_mfma_f32_16x16x32_bf16 v[92:95], v[174:177], v[154:157], v[92:95]
	v_mfma_f32_16x16x32_bf16 v[88:91], v[174:177], v[158:161], v[88:91]
	v_mfma_f32_16x16x32_bf16 v[84:87], v[174:177], v[162:165], v[84:87]
	s_waitcnt lgkmcnt(4)
	v_mfma_f32_16x16x32_bf16 v[80:83], v[192:195], v[148:151], v[80:83]
	v_mfma_f32_16x16x32_bf16 v[76:79], v[192:195], v[154:157], v[76:79]
	v_mfma_f32_16x16x32_bf16 v[72:75], v[192:195], v[158:161], v[72:75]
	v_mfma_f32_16x16x32_bf16 v[68:71], v[192:195], v[162:165], v[68:71]
	s_waitcnt lgkmcnt(3)
	v_mfma_f32_16x16x32_bf16 v[64:67], v[196:199], v[148:151], v[64:67]
	v_mfma_f32_16x16x32_bf16 v[60:63], v[196:199], v[154:157], v[60:63]
	v_mfma_f32_16x16x32_bf16 v[56:59], v[196:199], v[158:161], v[56:59]
	v_mfma_f32_16x16x32_bf16 v[52:55], v[196:199], v[162:165], v[52:55]
	s_waitcnt lgkmcnt(2)
	v_mfma_f32_16x16x32_bf16 v[48:51], v[204:207], v[148:151], v[48:51]
	v_mfma_f32_16x16x32_bf16 v[44:47], v[204:207], v[154:157], v[44:47]
	v_mfma_f32_16x16x32_bf16 v[40:43], v[204:207], v[158:161], v[40:43]
	v_mfma_f32_16x16x32_bf16 v[36:39], v[204:207], v[162:165], v[36:39]
	s_waitcnt lgkmcnt(1)
	v_mfma_f32_16x16x32_bf16 v[32:35], v[208:211], v[148:151], v[32:35]
	v_mfma_f32_16x16x32_bf16 v[28:31], v[208:211], v[154:157], v[28:31]
	v_mfma_f32_16x16x32_bf16 v[24:27], v[208:211], v[158:161], v[24:27]
	v_mfma_f32_16x16x32_bf16 v[20:23], v[208:211], v[162:165], v[20:23]
	s_waitcnt lgkmcnt(0)
	v_mfma_f32_16x16x32_bf16 v[16:19], v[212:215], v[148:151], v[16:19]
	v_mfma_f32_16x16x32_bf16 v[12:15], v[212:215], v[154:157], v[12:15]
	v_mfma_f32_16x16x32_bf16 v[8:11], v[212:215], v[158:161], v[8:11]
	v_mfma_f32_16x16x32_bf16 v[4:7], v[212:215], v[162:165], v[4:7]
	s_setprio 0
	s_add_i32 s10, s10, 0x6000
	s_cmp_lg_u32 s10, 0x12000
	s_cselect_b32 s10, s10, 0
	s_waitcnt vmcnt(0)
	s_barrier
	s_setprio 2
	v_add_u32_e32 v216, s10, v146
	v_add_u32_e32 v217, s10, v2
	ds_read_b128 v[148:151], v217 offset:16384
	ds_read_b128 v[166:169], v216
	ds_read_b128 v[154:157], v217 offset:17408
	ds_read_b128 v[158:161], v217 offset:18432
	ds_read_b128 v[162:165], v217 offset:19456
	ds_read_b128 v[170:173], v216 offset:1024
	ds_read_b128 v[174:177], v216 offset:2048
	ds_read_b128 v[192:195], v216 offset:3072
	ds_read_b128 v[196:199], v216 offset:4096
	ds_read_b128 v[204:207], v216 offset:5120
	ds_read_b128 v[208:211], v216 offset:6144
	ds_read_b128 v[212:215], v216 offset:7168
	v_readfirstlane_b32 s17, v140
	s_add_i32 s96, s11, 0x6000
	s_cmp_lg_u32 s96, 0x12000
	s_cselect_b32 s96, s96, 0
	s_add_i32 s96, s96, s17
	s_add_i32 s17, s17, s11
	s_waitcnt lgkmcnt(10)
	s_mov_b32 m0, s17
	s_add_i32 s17, s17, 0x1000
	v_mfma_f32_16x16x32_bf16 v[128:131], v[166:169], v[148:151], v[128:131]
	s_waitcnt lgkmcnt(9)
	v_mfma_f32_16x16x32_bf16 v[124:127], v[166:169], v[154:157], v[124:127]
	global_load_lds_dwordx4 v[218:219], off
	v_lshl_add_u64 v[218:219], v[218:219], 0, 64
	s_waitcnt lgkmcnt(8)
	s_mov_b32 m0, s96
	s_add_i32 s96, s96, 0x1000
	v_mfma_f32_16x16x32_bf16 v[120:123], v[166:169], v[158:161], v[120:123]
	s_waitcnt lgkmcnt(7)
	v_mfma_f32_16x16x32_bf16 v[116:119], v[166:169], v[162:165], v[116:119]
	global_load_lds_dwordx4 v[218:219], off
	v_lshl_add_u64 v[218:219], v[218:219], 0, 64
	s_waitcnt lgkmcnt(6)
	v_mfma_f32_16x16x32_bf16 v[112:115], v[170:173], v[148:151], v[112:115]
	s_mov_b32 m0, s17
	s_add_i32 s17, s17, 0x1000
	v_mfma_f32_16x16x32_bf16 v[108:111], v[170:173], v[154:157], v[108:111]
	v_mfma_f32_16x16x32_bf16 v[104:107], v[170:173], v[158:161], v[104:107]
	global_load_lds_dwordx4 v[220:221], off
	v_lshl_add_u64 v[220:221], v[220:221], 0, 64
	s_mov_b32 m0, s96
	s_add_i32 s96, s96, 0x1000
	v_mfma_f32_16x16x32_bf16 v[100:103], v[170:173], v[162:165], v[100:103]
	s_waitcnt lgkmcnt(5)
	v_mfma_f32_16x16x32_bf16 v[96:99], v[174:177], v[148:151], v[96:99]
	global_load_lds_dwordx4 v[220:221], off
	v_lshl_add_u64 v[220:221], v[220:221], 0, 64
	v_mfma_f32_16x16x32_bf16 v[92:95], v[174:177], v[154:157], v[92:95]
	s_mov_b32 m0, s17
	s_add_i32 s17, s17, 0x1000
	v_mfma_f32_16x16x32_bf16 v[88:91], v[174:177], v[158:161], v[88:91]
	v_mfma_f32_16x16x32_bf16 v[84:87], v[174:177], v[162:165], v[84:87]
	global_load_lds_dwordx4 v[222:223], off
	v_lshl_add_u64 v[222:223], v[222:223], 0, 64
	s_waitcnt lgkmcnt(4)
; DEVI f32x4 mfma16(bf16x8 a, bf16x8 b, f32x4 c) { return __builtin_amdgcn_mfma_f32_16x16x32_bf16(a, b, c, 0, 0, 0); }
; DEVI void gemm_core3(f32x4 (&acc)[8][4], const bf* __restrict__ A, int lda, const bf* __restrict__ Bt, int ldb, int K, char* smem) {
;     ...
;   for (int kt = 0; kt < nk; ++kt) {
;     const int k1 = min((kt + 1) * 32, klast);
;     const int sn = ((kt + 1) & 1) * STG;
;     const int so = (kt & 1) * STG;
;     bf16x8 bfr[4], af[8];
; #pragma unroll
;     for (int n = 0; n < 4; ++n) bfr[n] = *reinterpret_cast<const bf16x8*>(bbase + so + n * 16 * 64);
; #pragma unroll
;     for (int m = 0; m < 8; ++m) af[m] = *reinterpret_cast<const bf16x8*>(abase + so + m * 16 * 64);
; #pragma unroll
;     for (int i = 0; i < 4; ++i) glds16(Ap + i * sa + k1, dbase + sn + i * 4096);
; #pragma unroll
;     for (int i = 0; i < 2; ++i) glds16(Bp + i * sb + k1, dbase + sn + ASZ + i * 4096);
;     __builtin_amdgcn_s_setprio(1);
; #pragma unroll
;     for (int m = 0; m < 8; ++m)
; #pragma unroll
;       for (int n = 0; n < 4; ++n) acc[m][n] = mfma16(af[m], bfr[n], acc[m][n]);
;     __builtin_amdgcn_s_setprio(0);
;     __syncthreads();
;   }
	s_mov_b32 m0, s96
	s_add_i32 s96, s96, 0x1000
	v_mfma_f32_16x16x32_bf16 v[80:83], v[192:195], v[148:151], v[80:83]
	v_mfma_f32_16x16x32_bf16 v[76:79], v[192:195], v[154:157], v[76:79]
	global_load_lds_dwordx4 v[222:223], off
	v_lshl_add_u64 v[222:223], v[222:223], 0, 64
	v_mfma_f32_16x16x32_bf16 v[72:75], v[192:195], v[158:161], v[72:75]
	s_mov_b32 m0, s17
	s_add_i32 s17, s17, 0x1000
	v_mfma_f32_16x16x32_bf16 v[68:71], v[192:195], v[162:165], v[68:71]
	s_waitcnt lgkmcnt(3)
	v_mfma_f32_16x16x32_bf16 v[64:67], v[196:199], v[148:151], v[64:67]
	global_load_lds_dwordx4 v[224:225], off
	v_lshl_add_u64 v[224:225], v[224:225], 0, 64
	s_mov_b32 m0, s96
	s_add_i32 s96, s96, 0x1000
	v_mfma_f32_16x16x32_bf16 v[60:63], v[196:199], v[154:157], v[60:63]
	v_mfma_f32_16x16x32_bf16 v[56:59], v[196:199], v[158:161], v[56:59]
	global_load_lds_dwordx4 v[224:225], off
	v_lshl_add_u64 v[224:225], v[224:225], 0, 64
	v_mfma_f32_16x16x32_bf16 v[52:55], v[196:199], v[162:165], v[52:55]
	s_waitcnt lgkmcnt(2)
	s_mov_b32 m0, s17
	s_add_i32 s17, s17, 0x1000
	v_mfma_f32_16x16x32_bf16 v[48:51], v[204:207], v[148:151], v[48:51]
	v_mfma_f32_16x16x32_bf16 v[44:47], v[204:207], v[154:157], v[44:47]
	global_load_lds_dwordx4 v[226:227], off
	v_lshl_add_u64 v[226:227], v[226:227], 0, 64
	s_mov_b32 m0, s96
	s_add_i32 s96, s96, 0x1000
	v_mfma_f32_16x16x32_bf16 v[40:43], v[204:207], v[158:161], v[40:43]
	v_mfma_f32_16x16x32_bf16 v[36:39], v[204:207], v[162:165], v[36:39]
	global_load_lds_dwordx4 v[226:227], off
	v_lshl_add_u64 v[226:227], v[226:227], 0, 64
	s_waitcnt lgkmcnt(1)
	v_mfma_f32_16x16x32_bf16 v[32:35], v[208:211], v[148:151], v[32:35]
	s_mov_b32 m0, s17
	s_add_i32 s17, s17, 0x1000
	v_mfma_f32_16x16x32_bf16 v[28:31], v[208:211], v[154:157], v[28:31]
	v_mfma_f32_16x16x32_bf16 v[24:27], v[208:211], v[158:161], v[24:27]
	global_load_lds_dwordx4 v[228:229], off
	v_lshl_add_u64 v[228:229], v[228:229], 0, 64
	s_mov_b32 m0, s96
	s_add_i32 s96, s96, 0x1000
	v_mfma_f32_16x16x32_bf16 v[20:23], v[208:211], v[162:165], v[20:23]
	s_waitcnt lgkmcnt(0)
	v_mfma_f32_16x16x32_bf16 v[16:19], v[212:215], v[148:151], v[16:19]
	global_load_lds_dwordx4 v[228:229], off
	v_lshl_add_u64 v[228:229], v[228:229], 0, 64
	v_mfma_f32_16x16x32_bf16 v[12:15], v[212:215], v[154:157], v[12:15]
	v_mfma_f32_16x16x32_bf16 v[8:11], v[212:215], v[158:161], v[8:11]
	v_mfma_f32_16x16x32_bf16 v[4:7], v[212:215], v[162:165], v[4:7]
	s_setprio 0
	s_add_i32 s10, s10, 0x6000
	s_cmp_lg_u32 s10, 0x12000
	s_cselect_b32 s10, s10, 0
	s_sub_i32 s11, s11, 0x6000
	s_cmp_lt_i32 s11, 0
	s_cselect_b32 s11, 0xc000, s11
	s_add_i32 s3, s3, 1
	s_cmp_lt_i32 s3, 43
	s_waitcnt vmcnt(1)
	s_barrier
	s_cbranch_scc1 .Lg3_loop_926
	v_add_u32_e32 v216, s10, v146
	v_add_u32_e32 v217, s10, v2
	ds_read_b128 v[148:151], v217 offset:16384
	ds_read_b128 v[166:169], v216
	ds_read_b128 v[154:157], v217 offset:17408
	ds_read_b128 v[158:161], v217 offset:18432
	ds_read_b128 v[162:165], v217 offset:19456
	ds_read_b128 v[170:173], v216 offset:1024
	ds_read_b128 v[174:177], v216 offset:2048
	ds_read_b128 v[192:195], v216 offset:3072
	ds_read_b128 v[196:199], v216 offset:4096
	ds_read_b128 v[204:207], v216 offset:5120
	ds_read_b128 v[208:211], v216 offset:6144
	ds_read_b128 v[212:215], v216 offset:7168
	s_setprio 1
	s_waitcnt lgkmcnt(10)
	v_mfma_f32_16x16x32_bf16 v[128:131], v[166:169], v[148:151], v[128:131]
	s_waitcnt lgkmcnt(9)
	v_mfma_f32_16x16x32_bf16 v[124:127], v[166:169], v[154:157], v[124:127]
	s_waitcnt lgkmcnt(8)
	v_mfma_f32_16x16x32_bf16 v[120:123], v[166:169], v[158:161], v[120:123]
	s_waitcnt lgkmcnt(7)
	v_mfma_f32_16x16x32_bf16 v[116:119], v[166:169], v[162:165], v[116:119]
	s_waitcnt lgkmcnt(6)
	v_mfma_f32_16x16x32_bf16 v[112:115], v[170:173], v[148:151], v[112:115]
	v_mfma_f32_16x16x32_bf16 v[108:111], v[170:173], v[154:157], v[108:111]
	v_mfma_f32_16x16x32_bf16 v[104:107], v[170:173], v[158:161], v[104:107]
	v_mfma_f32_16x16x32_bf16 v[100:103], v[170:173], v[162:165], v[100:103]
	s_waitcnt lgkmcnt(5)
	v_mfma_f32_16x16x32_bf16 v[96:99], v[174:177], v[148:151], v[96:99]
	v_mfma_f32_16x16x32_bf16 v[92:95], v[174:177], v[154:157], v[92:95]
	v_mfma_f32_16x16x32_bf16 v[88:91], v[174:177], v[158:161], v[88:91]
	v_mfma_f32_16x16x32_bf16 v[84:87], v[174:177], v[162:165], v[84:87]
	s_waitcnt lgkmcnt(4)
	v_mfma_f32_16x16x32_bf16 v[80:83], v[192:195], v[148:151], v[80:83]
	v_mfma_f32_16x16x32_bf16 v[76:79], v[192:195], v[154:157], v[76:79]
	v_mfma_f32_16x16x32_bf16 v[72:75], v[192:195], v[158:161], v[72:75]
	v_mfma_f32_16x16x32_bf16 v[68:71], v[192:195], v[162:165], v[68:71]
	s_waitcnt lgkmcnt(3)
	v_mfma_f32_16x16x32_bf16 v[64:67], v[196:199], v[148:151], v[64:67]
	v_mfma_f32_16x16x32_bf16 v[60:63], v[196:199], v[154:157], v[60:63]
	v_mfma_f32_16x16x32_bf16 v[56:59], v[196:199], v[158:161], v[56:59]
	v_mfma_f32_16x16x32_bf16 v[52:55], v[196:199], v[162:165], v[52:55]
	s_waitcnt lgkmcnt(2)
	v_mfma_f32_16x16x32_bf16 v[48:51], v[204:207], v[148:151], v[48:51]
	v_mfma_f32_16x16x32_bf16 v[44:47], v[204:207], v[154:157], v[44:47]
	v_mfma_f32_16x16x32_bf16 v[40:43], v[204:207], v[158:161], v[40:43]
	v_mfma_f32_16x16x32_bf16 v[36:39], v[204:207], v[162:165], v[36:39]
	s_waitcnt lgkmcnt(1)
	v_mfma_f32_16x16x32_bf16 v[32:35], v[208:211], v[148:151], v[32:35]
	v_mfma_f32_16x16x32_bf16 v[28:31], v[208:211], v[154:157], v[28:31]
	v_mfma_f32_16x16x32_bf16 v[24:27], v[208:211], v[158:161], v[24:27]
	v_mfma_f32_16x16x32_bf16 v[20:23], v[208:211], v[162:165], v[20:23]
	s_waitcnt lgkmcnt(0)
	v_mfma_f32_16x16x32_bf16 v[16:19], v[212:215], v[148:151], v[16:19]
	v_mfma_f32_16x16x32_bf16 v[12:15], v[212:215], v[154:157], v[12:15]
	v_mfma_f32_16x16x32_bf16 v[8:11], v[212:215], v[158:161], v[8:11]
	v_mfma_f32_16x16x32_bf16 v[4:7], v[212:215], v[162:165], v[4:7]
	s_setprio 0
	s_add_i32 s10, s10, 0x6000
	s_cmp_lg_u32 s10, 0x12000
	s_cselect_b32 s10, s10, 0
	s_waitcnt vmcnt(0)
	s_barrier
; DEVI f32x4 mfma16(bf16x8 a, bf16x8 b, f32x4 c) { return __builtin_amdgcn_mfma_f32_16x16x32_bf16(a, b, c, 0, 0, 0); }
; DEVI void gemm_core3(f32x4 (&acc)[8][4], const bf* __restrict__ A, int lda, const bf* __restrict__ Bt, int ldb, int K, char* smem) {
;     ...
;     bf16x8 bfr[4], af[8];
; #pragma unroll
;     for (int n = 0; n < 4; ++n) bfr[n] = *reinterpret_cast<const bf16x8*>(bbase + so + n * 16 * 64);
; #pragma unroll
;     for (int m = 0; m < 8; ++m) af[m] = *reinterpret_cast<const bf16x8*>(abase + so + m * 16 * 64);
; #pragma unroll
;     for (int i = 0; i < 4; ++i) glds16(Ap + i * sa + k1, dbase + sn + i * 4096);
; #pragma unroll
;     for (int i = 0; i < 2; ++i) glds16(Bp + i * sb + k1, dbase + sn + ASZ + i * 4096);
;     __builtin_amdgcn_s_setprio(1);
; #pragma unroll
;     for (int m = 0; m < 8; ++m)
; #pragma unroll
;       for (int n = 0; n < 4; ++n) acc[m][n] = mfma16(af[m], bfr[n], acc[m][n]);
;     __builtin_amdgcn_s_setprio(0);
; DEVI void plain_tile256(const bf* A, int lda, const bf* Wt, int K, bf* C, int ldc, long row0, int n0, char* smem) {
;     ...
;   bf* tl = reinterpret_cast<bf*>(smem);
; #pragma unroll
;   for (int m = 0; m < 8; ++m)
; #pragma unroll
;     for (int n = 0; n < 4; ++n) {
;       const int cl = wc * 64 + n * 16 + l15;
; #pragma unroll
;       for (int j = 0; j < 4; ++j) tl[(wr * 128 + m * 16 + quad * 4 + j) * 136 + cl] = f2bf(acc[m][n][j]);
;     }
	v_add_u32_e32 v216, s10, v146
	v_add_u32_e32 v217, s10, v2
	ds_read_b128 v[148:151], v217 offset:16384
	ds_read_b128 v[166:169], v216
	ds_read_b128 v[154:157], v217 offset:17408
	ds_read_b128 v[158:161], v217 offset:18432
	ds_read_b128 v[162:165], v217 offset:19456
	ds_read_b128 v[170:173], v216 offset:1024
	ds_read_b128 v[174:177], v216 offset:2048
	ds_read_b128 v[192:195], v216 offset:3072
	ds_read_b128 v[196:199], v216 offset:4096
	ds_read_b128 v[204:207], v216 offset:5120
	ds_read_b128 v[208:211], v216 offset:6144
	ds_read_b128 v[212:215], v216 offset:7168
	s_setprio 1
	s_waitcnt lgkmcnt(10)
	v_mfma_f32_16x16x32_bf16 v[128:131], v[166:169], v[148:151], v[128:131]
	s_waitcnt lgkmcnt(9)
	v_mfma_f32_16x16x32_bf16 v[124:127], v[166:169], v[154:157], v[124:127]
	s_waitcnt lgkmcnt(8)
	v_mfma_f32_16x16x32_bf16 v[120:123], v[166:169], v[158:161], v[120:123]
	s_waitcnt lgkmcnt(7)
	v_mfma_f32_16x16x32_bf16 v[116:119], v[166:169], v[162:165], v[116:119]
	s_waitcnt lgkmcnt(6)
	v_mfma_f32_16x16x32_bf16 v[112:115], v[170:173], v[148:151], v[112:115]
	v_mfma_f32_16x16x32_bf16 v[108:111], v[170:173], v[154:157], v[108:111]
	v_mfma_f32_16x16x32_bf16 v[104:107], v[170:173], v[158:161], v[104:107]
	v_mfma_f32_16x16x32_bf16 v[100:103], v[170:173], v[162:165], v[100:103]
	s_waitcnt lgkmcnt(5)
	v_mfma_f32_16x16x32_bf16 v[96:99], v[174:177], v[148:151], v[96:99]
	v_mfma_f32_16x16x32_bf16 v[92:95], v[174:177], v[154:157], v[92:95]
	v_mfma_f32_16x16x32_bf16 v[88:91], v[174:177], v[158:161], v[88:91]
	v_mfma_f32_16x16x32_bf16 v[84:87], v[174:177], v[162:165], v[84:87]
	s_waitcnt lgkmcnt(4)
	v_mfma_f32_16x16x32_bf16 v[80:83], v[192:195], v[148:151], v[80:83]
	v_mfma_f32_16x16x32_bf16 v[76:79], v[192:195], v[154:157], v[76:79]
	v_mfma_f32_16x16x32_bf16 v[72:75], v[192:195], v[158:161], v[72:75]
	v_mfma_f32_16x16x32_bf16 v[68:71], v[192:195], v[162:165], v[68:71]
	s_waitcnt lgkmcnt(3)
	v_mfma_f32_16x16x32_bf16 v[64:67], v[196:199], v[148:151], v[64:67]
	v_mfma_f32_16x16x32_bf16 v[60:63], v[196:199], v[154:157], v[60:63]
	v_mfma_f32_16x16x32_bf16 v[56:59], v[196:199], v[158:161], v[56:59]
	v_mfma_f32_16x16x32_bf16 v[52:55], v[196:199], v[162:165], v[52:55]
	s_waitcnt lgkmcnt(2)
	v_mfma_f32_16x16x32_bf16 v[48:51], v[204:207], v[148:151], v[48:51]
	v_mfma_f32_16x16x32_bf16 v[44:47], v[204:207], v[154:157], v[44:47]
	v_mfma_f32_16x16x32_bf16 v[40:43], v[204:207], v[158:161], v[40:43]
	v_mfma_f32_16x16x32_bf16 v[36:39], v[204:207], v[162:165], v[36:39]
	s_waitcnt lgkmcnt(1)
	v_mfma_f32_16x16x32_bf16 v[32:35], v[208:211], v[148:151], v[32:35]
	v_mfma_f32_16x16x32_bf16 v[28:31], v[208:211], v[154:157], v[28:31]
	v_mfma_f32_16x16x32_bf16 v[24:27], v[208:211], v[158:161], v[24:27]
	v_mfma_f32_16x16x32_bf16 v[20:23], v[208:211], v[162:165], v[20:23]
	s_waitcnt lgkmcnt(0)
	v_mfma_f32_16x16x32_bf16 v[16:19], v[212:215], v[148:151], v[16:19]
	v_mfma_f32_16x16x32_bf16 v[12:15], v[212:215], v[154:157], v[12:15]
	v_mfma_f32_16x16x32_bf16 v[8:11], v[212:215], v[158:161], v[8:11]
	v_mfma_f32_16x16x32_bf16 v[4:7], v[212:215], v[162:165], v[4:7]
	s_setprio 0
	s_add_i32 s10, s10, 0x6000
	s_cmp_lg_u32 s10, 0x12000
	s_cselect_b32 s10, s10, 0
	s_waitcnt vmcnt(0)
	s_barrier
	v_and_b32_e32 v2, 0x4f, v1
	v_and_b32_e32 v132, 0xfffff80, v1
	v_lshrrev_b32_e32 v1, 2, v1
	v_and_or_b32 v1, v1, 12, v132
	v_mul_lo_u32 v1, v1, s16
	v_lshl_add_u32 v1, v2, 1, v1
	v_cvt_pk_bf16_f32 v2, v129, s0
	ds_write_b16 v1, v2 offset:272
	v_cvt_pk_bf16_f32 v2, v130, s0
	ds_write_b16 v1, v2 offset:544
	v_cvt_pk_bf16_f32 v2, v131, s0
	ds_write_b16 v1, v2 offset:816
	v_cvt_pk_bf16_f32 v2, v124, s0
	ds_write_b16 v1, v2 offset:32
	v_cvt_pk_bf16_f32 v2, v125, s0
	ds_write_b16 v1, v2 offset:304
	v_cvt_pk_bf16_f32 v2, v126, s0
	ds_write_b16 v1, v2 offset:576
	v_cvt_pk_bf16_f32 v2, v127, s0
	ds_write_b16 v1, v2 offset:848
	v_cvt_pk_bf16_f32 v2, v120, s0
	ds_write_b16 v1, v2 offset:64
	v_cvt_pk_bf16_f32 v2, v121, s0
	ds_write_b16 v1, v2 offset:336
	v_cvt_pk_bf16_f32 v2, v122, s0
	ds_write_b16 v1, v2 offset:608
	v_cvt_pk_bf16_f32 v2, v123, s0
	ds_write_b16 v1, v2 offset:880
	v_cvt_pk_bf16_f32 v2, v116, s0
	ds_write_b16 v1, v2 offset:96
	v_cvt_pk_bf16_f32 v2, v117, s0
	ds_write_b16 v1, v2 offset:368
	v_cvt_pk_bf16_f32 v2, v118, s0
	ds_write_b16 v1, v2 offset:640
	v_cvt_pk_bf16_f32 v2, v119, s0
	ds_write_b16 v1, v2 offset:912
	v_cvt_pk_bf16_f32 v2, v112, s0
	ds_write_b16 v1, v2 offset:4352
	v_cvt_pk_bf16_f32 v2, v113, s0
	ds_write_b16 v1, v2 offset:4624
	v_cvt_pk_bf16_f32 v2, v114, s0
	ds_write_b16 v1, v2 offset:4896
	v_cvt_pk_bf16_f32 v2, v115, s0
	ds_write_b16 v1, v2 offset:5168
	v_cvt_pk_bf16_f32 v2, v108, s0
	ds_write_b16 v1, v2 offset:4384
	v_cvt_pk_bf16_f32 v2, v109, s0
	ds_write_b16 v1, v2 offset:4656
	v_cvt_pk_bf16_f32 v2, v110, s0
	ds_write_b16 v1, v2 offset:4928
	v_cvt_pk_bf16_f32 v2, v111, s0
	ds_write_b16 v1, v2 offset:5200
	v_cvt_pk_bf16_f32 v2, v104, s0
	ds_write_b16 v1, v2 offset:4416
	v_cvt_pk_bf16_f32 v2, v105, s0
	ds_write_b16 v1, v2 offset:4688
	v_cvt_pk_bf16_f32 v2, v106, s0
	ds_write_b16 v1, v2 offset:4960
	v_cvt_pk_bf16_f32 v2, v107, s0
	ds_write_b16 v1, v2 offset:5232
	v_cvt_pk_bf16_f32 v2, v100, s0
	ds_write_b16 v1, v2 offset:4448
	v_cvt_pk_bf16_f32 v2, v101, s0
	ds_write_b16 v1, v2 offset:4720
	v_cvt_pk_bf16_f32 v2, v102, s0
	ds_write_b16 v1, v2 offset:4992
	v_cvt_pk_bf16_f32 v2, v103, s0
	ds_write_b16 v1, v2 offset:5264
	v_cvt_pk_bf16_f32 v2, v96, s0
	ds_write_b16 v1, v2 offset:8704
	v_cvt_pk_bf16_f32 v2, v97, s0
	ds_write_b16 v1, v2 offset:8976
	v_cvt_pk_bf16_f32 v2, v98, s0
	ds_write_b16 v1, v2 offset:9248
	v_cvt_pk_bf16_f32 v2, v99, s0
	ds_write_b16 v1, v2 offset:9520
	v_cvt_pk_bf16_f32 v2, v92, s0
; DEVI void plain_tile256(const bf* A, int lda, const bf* Wt, int K, bf* C, int ldc, long row0, int n0, char* smem) {
;     ...
; #pragma unroll
;   for (int m = 0; m < 8; ++m)
; #pragma unroll
;     for (int n = 0; n < 4; ++n) {
;       const int cl = wc * 64 + n * 16 + l15;
; #pragma unroll
;       for (int j = 0; j < 4; ++j) tl[(wr * 128 + m * 16 + quad * 4 + j) * 136 + cl] = f2bf(acc[m][n][j]);
;     }
;   __syncthreads();
	ds_write_b16 v1, v2 offset:8736
	v_cvt_pk_bf16_f32 v2, v93, s0
	ds_write_b16 v1, v2 offset:9008
	v_cvt_pk_bf16_f32 v2, v94, s0
	ds_write_b16 v1, v2 offset:9280
	v_cvt_pk_bf16_f32 v2, v95, s0
	ds_write_b16 v1, v2 offset:9552
	v_cvt_pk_bf16_f32 v2, v88, s0
	ds_write_b16 v1, v2 offset:8768
	v_cvt_pk_bf16_f32 v2, v89, s0
	ds_write_b16 v1, v2 offset:9040
	v_cvt_pk_bf16_f32 v2, v90, s0
	ds_write_b16 v1, v2 offset:9312
	v_cvt_pk_bf16_f32 v2, v91, s0
	ds_write_b16 v1, v2 offset:9584
	v_cvt_pk_bf16_f32 v2, v84, s0
	ds_write_b16 v1, v2 offset:8800
	v_cvt_pk_bf16_f32 v2, v85, s0
	ds_write_b16 v1, v2 offset:9072
	v_cvt_pk_bf16_f32 v2, v86, s0
	ds_write_b16 v1, v2 offset:9344
	v_cvt_pk_bf16_f32 v2, v87, s0
	ds_write_b16 v1, v2 offset:9616
	v_cvt_pk_bf16_f32 v2, v80, s0
	ds_write_b16 v1, v2 offset:13056
	v_cvt_pk_bf16_f32 v2, v81, s0
	ds_write_b16 v1, v2 offset:13328
	v_cvt_pk_bf16_f32 v2, v82, s0
	ds_write_b16 v1, v2 offset:13600
	v_cvt_pk_bf16_f32 v2, v83, s0
	ds_write_b16 v1, v2 offset:13872
	v_cvt_pk_bf16_f32 v2, v76, s0
	ds_write_b16 v1, v2 offset:13088
	v_cvt_pk_bf16_f32 v2, v77, s0
	ds_write_b16 v1, v2 offset:13360
	v_cvt_pk_bf16_f32 v2, v78, s0
	ds_write_b16 v1, v2 offset:13632
	v_cvt_pk_bf16_f32 v2, v79, s0
	ds_write_b16 v1, v2 offset:13904
	v_cvt_pk_bf16_f32 v2, v72, s0
	ds_write_b16 v1, v2 offset:13120
	v_cvt_pk_bf16_f32 v2, v73, s0
	ds_write_b16 v1, v2 offset:13392
	v_cvt_pk_bf16_f32 v2, v74, s0
	ds_write_b16 v1, v2 offset:13664
	v_cvt_pk_bf16_f32 v2, v75, s0
	ds_write_b16 v1, v2 offset:13936
	v_cvt_pk_bf16_f32 v2, v68, s0
	ds_write_b16 v1, v2 offset:13152
	v_cvt_pk_bf16_f32 v2, v69, s0
	ds_write_b16 v1, v2 offset:13424
	v_cvt_pk_bf16_f32 v2, v70, s0
	ds_write_b16 v1, v2 offset:13696
	v_cvt_pk_bf16_f32 v2, v71, s0
	ds_write_b16 v1, v2 offset:13968
	v_cvt_pk_bf16_f32 v2, v64, s0
	ds_write_b16 v1, v2 offset:17408
	v_cvt_pk_bf16_f32 v2, v65, s0
	ds_write_b16 v1, v2 offset:17680
	v_cvt_pk_bf16_f32 v2, v66, s0
	ds_write_b16 v1, v2 offset:17952
	v_cvt_pk_bf16_f32 v2, v67, s0
	ds_write_b16 v1, v2 offset:18224
	v_cvt_pk_bf16_f32 v2, v60, s0
	ds_write_b16 v1, v2 offset:17440
	v_cvt_pk_bf16_f32 v2, v61, s0
	ds_write_b16 v1, v2 offset:17712
	v_cvt_pk_bf16_f32 v2, v62, s0
	ds_write_b16 v1, v2 offset:17984
	v_cvt_pk_bf16_f32 v2, v63, s0
	ds_write_b16 v1, v2 offset:18256
	v_cvt_pk_bf16_f32 v2, v56, s0
	ds_write_b16 v1, v2 offset:17472
	v_cvt_pk_bf16_f32 v2, v57, s0
	ds_write_b16 v1, v2 offset:17744
	v_cvt_pk_bf16_f32 v2, v58, s0
	ds_write_b16 v1, v2 offset:18016
	v_cvt_pk_bf16_f32 v2, v59, s0
	ds_write_b16 v1, v2 offset:18288
	v_cvt_pk_bf16_f32 v2, v52, s0
	ds_write_b16 v1, v2 offset:17504
	v_cvt_pk_bf16_f32 v2, v53, s0
	ds_write_b16 v1, v2 offset:17776
	v_cvt_pk_bf16_f32 v2, v54, s0
	ds_write_b16 v1, v2 offset:18048
	v_cvt_pk_bf16_f32 v2, v55, s0
	ds_write_b16 v1, v2 offset:18320
	v_cvt_pk_bf16_f32 v2, v48, s0
	ds_write_b16 v1, v2 offset:21760
	v_cvt_pk_bf16_f32 v2, v49, s0
	ds_write_b16 v1, v2 offset:22032
	v_cvt_pk_bf16_f32 v2, v50, s0
	ds_write_b16 v1, v2 offset:22304
	v_cvt_pk_bf16_f32 v2, v51, s0
	ds_write_b16 v1, v2 offset:22576
	v_cvt_pk_bf16_f32 v2, v44, s0
	ds_write_b16 v1, v2 offset:21792
	v_cvt_pk_bf16_f32 v2, v45, s0
	ds_write_b16 v1, v2 offset:22064
	v_cvt_pk_bf16_f32 v2, v46, s0
	ds_write_b16 v1, v2 offset:22336
	v_cvt_pk_bf16_f32 v2, v47, s0
	ds_write_b16 v1, v2 offset:22608
	v_cvt_pk_bf16_f32 v2, v40, s0
	ds_write_b16 v1, v2 offset:21824
	v_cvt_pk_bf16_f32 v2, v41, s0
	ds_write_b16 v1, v2 offset:22096
	v_cvt_pk_bf16_f32 v2, v42, s0
	ds_write_b16 v1, v2 offset:22368
	v_cvt_pk_bf16_f32 v2, v43, s0
	ds_write_b16 v1, v2 offset:22640
	v_cvt_pk_bf16_f32 v2, v36, s0
	ds_write_b16 v1, v2 offset:21856
	v_cvt_pk_bf16_f32 v2, v37, s0
	ds_write_b16 v1, v2 offset:22128
	v_cvt_pk_bf16_f32 v2, v38, s0
	ds_write_b16 v1, v2 offset:22400
	v_cvt_pk_bf16_f32 v2, v39, s0
	ds_write_b16 v1, v2 offset:22672
	v_cvt_pk_bf16_f32 v2, v32, s0
	ds_write_b16 v1, v2 offset:26112
	v_cvt_pk_bf16_f32 v2, v33, s0
	ds_write_b16 v1, v2 offset:26384
	v_cvt_pk_bf16_f32 v2, v34, s0
	ds_write_b16 v1, v2 offset:26656
	v_cvt_pk_bf16_f32 v2, v35, s0
	ds_write_b16 v1, v2 offset:26928
	v_cvt_pk_bf16_f32 v2, v28, s0
	ds_write_b16 v1, v2 offset:26144
	v_cvt_pk_bf16_f32 v2, v29, s0
	ds_write_b16 v1, v2 offset:26416
	v_cvt_pk_bf16_f32 v2, v30, s0
	ds_write_b16 v1, v2 offset:26688
	v_cvt_pk_bf16_f32 v2, v31, s0
	ds_write_b16 v1, v2 offset:26960
	v_cvt_pk_bf16_f32 v2, v24, s0
	ds_write_b16 v1, v2 offset:26176
	v_cvt_pk_bf16_f32 v2, v25, s0
	ds_write_b16 v1, v2 offset:26448
	v_cvt_pk_bf16_f32 v2, v26, s0
	ds_write_b16 v1, v2 offset:26720
	v_cvt_pk_bf16_f32 v2, v27, s0
	ds_write_b16 v1, v2 offset:26992
	v_cvt_pk_bf16_f32 v2, v20, s0
	ds_write_b16 v1, v2 offset:26208
	v_cvt_pk_bf16_f32 v2, v21, s0
	ds_write_b16 v1, v2 offset:26480
	v_cvt_pk_bf16_f32 v2, v22, s0
	ds_write_b16 v1, v2 offset:26752
	v_cvt_pk_bf16_f32 v2, v23, s0
	ds_write_b16 v1, v2 offset:27024
	v_cvt_pk_bf16_f32 v2, v16, s0
	ds_write_b16 v1, v2 offset:30464
	v_cvt_pk_bf16_f32 v2, v17, s0
	ds_write_b16 v1, v2 offset:30736
	v_cvt_pk_bf16_f32 v2, v18, s0
	ds_write_b16 v1, v2 offset:31008
	v_cvt_pk_bf16_f32 v2, v19, s0
	ds_write_b16 v1, v2 offset:31280
	v_cvt_pk_bf16_f32 v2, v12, s0
	ds_write_b16 v1, v2 offset:30496
	v_cvt_pk_bf16_f32 v2, v13, s0
	ds_write_b16 v1, v2 offset:30768
	v_cvt_pk_bf16_f32 v2, v14, s0
	ds_write_b16 v1, v2 offset:31040
	v_cvt_pk_bf16_f32 v2, v15, s0
	ds_write_b16 v1, v2 offset:31312
	v_cvt_pk_bf16_f32 v2, v8, s0
	ds_write_b16 v1, v2 offset:30528
	v_cvt_pk_bf16_f32 v2, v9, s0
	ds_write_b16 v1, v2 offset:30800
	v_cvt_pk_bf16_f32 v2, v10, s0
	ds_write_b16 v1, v2 offset:31072
	v_cvt_pk_bf16_f32 v2, v11, s0
	ds_write_b16 v1, v2 offset:31344
	v_cvt_pk_bf16_f32 v2, v4, s0
	ds_write_b16 v1, v2 offset:30560
	v_cvt_pk_bf16_f32 v2, v5, s0
	ds_write_b16 v1, v2 offset:30832
	v_cvt_pk_bf16_f32 v2, v6, s0
	v_cvt_pk_bf16_f32 v128, v128, s0
	ds_write_b16 v1, v2 offset:31104
	v_cvt_pk_bf16_f32 v2, v7, s0
	ds_write_b16 v1, v128
	ds_write_b16 v1, v2 offset:31376
	v_mov_b32_e32 v1, v178
	s_waitcnt lgkmcnt(0)
	s_barrier
; DEVI int get_tid() { int t = threadIdx.x; asm volatile("" : "+v"(t)); return t; }
; template <int BN>
; DEVI void tile_store256(const char* smem, bf* __restrict__ C, long ldc, long row0, int col0) {
;   constexpr int LDT = BN + 8;
;   constexpr int CPR = BN / 8;
;   const int tid = get_tid();
; #pragma unroll
;   for (int i = 0; i < CPR; ++i) {
;     const int q = tid + 256 * i;
;     const int r = q / CPR, c = q - r * CPR;
;     u32x4 v = *reinterpret_cast<const u32x4*>(smem + (r * LDT + c * 8) * 2);
;     *reinterpret_cast<u32x4*>(C + (row0 + r) * ldc + col0 + c * 8) = v;
;   }
; }
	v_readlane_b32 s56, v251, 58
	v_ashrrev_i32_e32 v2, 31, v1
	v_lshrrev_b32_e32 v2, 28, v2
	v_add_u32_e32 v2, v1, v2
	v_ashrrev_i32_e32 v8, 4, v2
	s_lshl_b64 s[10:11], s[34:35], 1
	v_readlane_b32 s60, v251, 62
	v_lshlrev_b32_e32 v4, 7, v8
	v_lshlrev_b32_e32 v5, 3, v1
	v_ashrrev_i32_e32 v9, 31, v8
	v_readlane_b32 s61, v251, 63
	s_add_u32 s10, s60, s10
	v_mul_lo_u32 v2, v8, s38
	v_sub_u32_e32 v10, v5, v4
	v_lshl_add_u64 v[8:9], s[12:13], 0, v[8:9]
	s_addc_u32 s11, s61, s11
	v_add_lshl_u32 v2, v10, v2, 1
	v_lshlrev_b64 v[8:9], 11, v[8:9]
	ds_read_b128 v[4:7], v2
	v_lshl_add_u64 v[8:9], s[10:11], 0, v[8:9]
	v_ashrrev_i32_e32 v11, 31, v10
	v_add_u32_e32 v2, 0x100, v1
	v_lshl_add_u64 v[12:13], v[10:11], 1, v[8:9]
	v_ashrrev_i32_e32 v8, 31, v2
	v_lshrrev_b32_e32 v8, 28, v8
	v_add_u32_e32 v8, v2, v8
	v_ashrrev_i32_e32 v14, 4, v8
	v_lshlrev_b32_e32 v9, 7, v14
	v_lshlrev_b32_e32 v2, 3, v2
	v_mul_lo_u32 v8, v14, s38
	v_sub_u32_e32 v16, v2, v9
	v_add_lshl_u32 v2, v16, v8, 1
	ds_read_b128 v[8:11], v2
	v_ashrrev_i32_e32 v15, 31, v14
	s_waitcnt lgkmcnt(1)
	global_store_dwordx4 v[12:13], v[4:7], off
	v_ashrrev_i32_e32 v17, 31, v16
	v_add_u32_e32 v2, 0x200, v1
	v_lshl_add_u64 v[4:5], s[12:13], 0, v[14:15]
	v_lshlrev_b64 v[4:5], 11, v[4:5]
	v_lshl_add_u64 v[4:5], s[10:11], 0, v[4:5]
	v_lshl_add_u64 v[4:5], v[16:17], 1, v[4:5]
	s_waitcnt lgkmcnt(0)
	global_store_dwordx4 v[4:5], v[8:11], off
	v_ashrrev_i32_e32 v4, 31, v2
	v_lshrrev_b32_e32 v4, 28, v4
	v_add_u32_e32 v4, v2, v4
	v_ashrrev_i32_e32 v8, 4, v4
	v_lshlrev_b32_e32 v5, 7, v8
	v_lshlrev_b32_e32 v2, 3, v2
	v_ashrrev_i32_e32 v9, 31, v8
	v_mul_lo_u32 v4, v8, s38
	v_sub_u32_e32 v10, v2, v5
	v_lshl_add_u64 v[8:9], s[12:13], 0, v[8:9]
	v_add_lshl_u32 v2, v10, v4, 1
	v_lshlrev_b64 v[8:9], 11, v[8:9]
	ds_read_b128 v[4:7], v2
	v_lshl_add_u64 v[8:9], s[10:11], 0, v[8:9]
	v_ashrrev_i32_e32 v11, 31, v10
	v_add_u32_e32 v2, 0x300, v1
	v_lshl_add_u64 v[12:13], v[10:11], 1, v[8:9]
	v_ashrrev_i32_e32 v8, 31, v2
	v_lshrrev_b32_e32 v8, 28, v8
	v_add_u32_e32 v8, v2, v8
	v_ashrrev_i32_e32 v14, 4, v8
	v_lshlrev_b32_e32 v9, 7, v14
	v_lshlrev_b32_e32 v2, 3, v2
	v_mul_lo_u32 v8, v14, s38
	v_sub_u32_e32 v16, v2, v9
	v_add_lshl_u32 v2, v16, v8, 1
	ds_read_b128 v[8:11], v2
	v_ashrrev_i32_e32 v15, 31, v14
	s_waitcnt lgkmcnt(1)
	global_store_dwordx4 v[12:13], v[4:7], off
	v_ashrrev_i32_e32 v17, 31, v16
	v_add_u32_e32 v2, 0x400, v1
	v_lshl_add_u64 v[4:5], s[12:13], 0, v[14:15]
	v_lshlrev_b64 v[4:5], 11, v[4:5]
	v_lshl_add_u64 v[4:5], s[10:11], 0, v[4:5]
	v_lshl_add_u64 v[4:5], v[16:17], 1, v[4:5]
	s_waitcnt lgkmcnt(0)
	global_store_dwordx4 v[4:5], v[8:11], off
	v_ashrrev_i32_e32 v4, 31, v2
	v_lshrrev_b32_e32 v4, 28, v4
	v_add_u32_e32 v4, v2, v4
	v_ashrrev_i32_e32 v8, 4, v4
	v_lshlrev_b32_e32 v5, 7, v8
	v_lshlrev_b32_e32 v2, 3, v2
	v_ashrrev_i32_e32 v9, 31, v8
	v_mul_lo_u32 v4, v8, s38
	v_sub_u32_e32 v10, v2, v5
	v_lshl_add_u64 v[8:9], s[12:13], 0, v[8:9]
	v_add_lshl_u32 v2, v10, v4, 1
	v_lshlrev_b64 v[8:9], 11, v[8:9]
	ds_read_b128 v[4:7], v2
	v_lshl_add_u64 v[8:9], s[10:11], 0, v[8:9]
	v_ashrrev_i32_e32 v11, 31, v10
	v_add_u32_e32 v2, 0x500, v1
	v_lshl_add_u64 v[12:13], v[10:11], 1, v[8:9]
	v_ashrrev_i32_e32 v8, 31, v2
	v_lshrrev_b32_e32 v8, 28, v8
	v_add_u32_e32 v8, v2, v8
	v_ashrrev_i32_e32 v14, 4, v8
	v_lshlrev_b32_e32 v9, 7, v14
	v_lshlrev_b32_e32 v2, 3, v2
	v_mul_lo_u32 v8, v14, s38
	v_sub_u32_e32 v16, v2, v9
	v_add_lshl_u32 v2, v16, v8, 1
	ds_read_b128 v[8:11], v2
	v_ashrrev_i32_e32 v15, 31, v14
	s_waitcnt lgkmcnt(1)
	global_store_dwordx4 v[12:13], v[4:7], off
	v_ashrrev_i32_e32 v17, 31, v16
	v_add_u32_e32 v2, 0x600, v1
	v_lshl_add_u64 v[4:5], s[12:13], 0, v[14:15]
	v_lshlrev_b64 v[4:5], 11, v[4:5]
	v_lshl_add_u64 v[4:5], s[10:11], 0, v[4:5]
	v_lshl_add_u64 v[4:5], v[16:17], 1, v[4:5]
	s_waitcnt lgkmcnt(0)
	global_store_dwordx4 v[4:5], v[8:11], off
	v_ashrrev_i32_e32 v4, 31, v2
	v_lshrrev_b32_e32 v4, 28, v4
	v_add_u32_e32 v4, v2, v4
	v_ashrrev_i32_e32 v8, 4, v4
	v_lshlrev_b32_e32 v5, 7, v8
	v_lshlrev_b32_e32 v2, 3, v2
	v_ashrrev_i32_e32 v9, 31, v8
	v_mul_lo_u32 v4, v8, s38
	v_sub_u32_e32 v10, v2, v5
	v_lshl_add_u64 v[8:9], s[12:13], 0, v[8:9]
	v_add_lshl_u32 v2, v10, v4, 1
	v_lshlrev_b64 v[8:9], 11, v[8:9]
	ds_read_b128 v[4:7], v2
	v_lshl_add_u64 v[8:9], s[10:11], 0, v[8:9]
	v_ashrrev_i32_e32 v11, 31, v10
	v_add_u32_e32 v2, 0x700, v1
	v_lshl_add_u64 v[12:13], v[10:11], 1, v[8:9]
	v_ashrrev_i32_e32 v8, 31, v2
	v_lshrrev_b32_e32 v8, 28, v8
	v_add_u32_e32 v8, v2, v8
	v_ashrrev_i32_e32 v14, 4, v8
	v_lshlrev_b32_e32 v9, 7, v14
	v_lshlrev_b32_e32 v2, 3, v2
	v_mul_lo_u32 v8, v14, s38
	v_sub_u32_e32 v16, v2, v9
	v_add_lshl_u32 v2, v16, v8, 1
	ds_read_b128 v[8:11], v2
	v_ashrrev_i32_e32 v15, 31, v14
	s_waitcnt lgkmcnt(1)
	global_store_dwordx4 v[12:13], v[4:7], off
	v_ashrrev_i32_e32 v17, 31, v16
	v_add_u32_e32 v2, 0x800, v1
	v_lshl_add_u64 v[4:5], s[12:13], 0, v[14:15]
	v_lshlrev_b64 v[4:5], 11, v[4:5]
	v_lshl_add_u64 v[4:5], s[10:11], 0, v[4:5]
	v_lshl_add_u64 v[4:5], v[16:17], 1, v[4:5]
	s_waitcnt lgkmcnt(0)
; DEVI int get_tid() { int t = threadIdx.x; asm volatile("" : "+v"(t)); return t; }
; template <int BN>
; DEVI void tile_store256(const char* smem, bf* __restrict__ C, long ldc, long row0, int col0) {
;   constexpr int LDT = BN + 8;
;   constexpr int CPR = BN / 8;
;   const int tid = get_tid();
; #pragma unroll
;   for (int i = 0; i < CPR; ++i) {
;     const int q = tid + 256 * i;
;     const int r = q / CPR, c = q - r * CPR;
;     u32x4 v = *reinterpret_cast<const u32x4*>(smem + (r * LDT + c * 8) * 2);
;     *reinterpret_cast<u32x4*>(C + (row0 + r) * ldc + col0 + c * 8) = v;
;   }
; }
; DEVI void phase_gemm_plain128(const bf* A, int lda, const bf* Wt, int K, int N, bf* C, int ldc, char* smem) {
;     ...
;   for (int v = blockIdx.x; v < 128 * ntn; v += gridDim.x) {
;     int m2, nt;
;     lat_tile_map256(v, ntn, m2, nt);
;     plain_tile256(A, lda, Wt, K, C, ldc, lat_row0_256(m2), nt * 128, smem);
	global_store_dwordx4 v[4:5], v[8:11], off
	v_ashrrev_i32_e32 v4, 31, v2
	v_lshrrev_b32_e32 v4, 28, v4
	v_add_u32_e32 v4, v2, v4
	v_ashrrev_i32_e32 v8, 4, v4
	v_lshlrev_b32_e32 v5, 7, v8
	v_lshlrev_b32_e32 v2, 3, v2
	v_ashrrev_i32_e32 v9, 31, v8
	v_mul_lo_u32 v4, v8, s38
	v_sub_u32_e32 v10, v2, v5
	v_lshl_add_u64 v[8:9], s[12:13], 0, v[8:9]
	v_add_lshl_u32 v2, v10, v4, 1
	v_lshlrev_b64 v[8:9], 11, v[8:9]
	ds_read_b128 v[4:7], v2
	v_lshl_add_u64 v[8:9], s[10:11], 0, v[8:9]
	v_ashrrev_i32_e32 v11, 31, v10
	v_add_u32_e32 v2, 0x900, v1
	v_lshl_add_u64 v[12:13], v[10:11], 1, v[8:9]
	v_ashrrev_i32_e32 v8, 31, v2
	v_lshrrev_b32_e32 v8, 28, v8
	v_add_u32_e32 v8, v2, v8
	v_ashrrev_i32_e32 v14, 4, v8
	v_lshlrev_b32_e32 v9, 7, v14
	v_lshlrev_b32_e32 v2, 3, v2
	v_mul_lo_u32 v8, v14, s38
	v_sub_u32_e32 v16, v2, v9
	v_add_lshl_u32 v2, v16, v8, 1
	ds_read_b128 v[8:11], v2
	v_ashrrev_i32_e32 v15, 31, v14
	s_waitcnt lgkmcnt(1)
	global_store_dwordx4 v[12:13], v[4:7], off
	v_ashrrev_i32_e32 v17, 31, v16
	v_add_u32_e32 v2, 0xa00, v1
	v_lshl_add_u64 v[4:5], s[12:13], 0, v[14:15]
	v_lshlrev_b64 v[4:5], 11, v[4:5]
	v_lshl_add_u64 v[4:5], s[10:11], 0, v[4:5]
	v_lshl_add_u64 v[4:5], v[16:17], 1, v[4:5]
	s_waitcnt lgkmcnt(0)
	global_store_dwordx4 v[4:5], v[8:11], off
	v_ashrrev_i32_e32 v4, 31, v2
	v_lshrrev_b32_e32 v4, 28, v4
	v_add_u32_e32 v4, v2, v4
	v_ashrrev_i32_e32 v8, 4, v4
	v_lshlrev_b32_e32 v5, 7, v8
	v_lshlrev_b32_e32 v2, 3, v2
	v_ashrrev_i32_e32 v9, 31, v8
	v_mul_lo_u32 v4, v8, s38
	v_sub_u32_e32 v10, v2, v5
	v_lshl_add_u64 v[8:9], s[12:13], 0, v[8:9]
	v_add_lshl_u32 v2, v10, v4, 1
	v_lshlrev_b64 v[8:9], 11, v[8:9]
	ds_read_b128 v[4:7], v2
	v_lshl_add_u64 v[8:9], s[10:11], 0, v[8:9]
	v_ashrrev_i32_e32 v11, 31, v10
	v_add_u32_e32 v2, 0xb00, v1
	v_lshl_add_u64 v[12:13], v[10:11], 1, v[8:9]
	v_ashrrev_i32_e32 v8, 31, v2
	v_lshrrev_b32_e32 v8, 28, v8
	v_add_u32_e32 v8, v2, v8
	v_ashrrev_i32_e32 v14, 4, v8
	v_lshlrev_b32_e32 v9, 7, v14
	v_lshlrev_b32_e32 v2, 3, v2
	v_mul_lo_u32 v8, v14, s38
	v_sub_u32_e32 v16, v2, v9
	v_add_lshl_u32 v2, v16, v8, 1
	ds_read_b128 v[8:11], v2
	v_ashrrev_i32_e32 v15, 31, v14
	s_waitcnt lgkmcnt(1)
	global_store_dwordx4 v[12:13], v[4:7], off
	v_ashrrev_i32_e32 v17, 31, v16
	v_add_u32_e32 v2, 0xc00, v1
	v_lshl_add_u64 v[4:5], s[12:13], 0, v[14:15]
	v_lshlrev_b64 v[4:5], 11, v[4:5]
	v_lshl_add_u64 v[4:5], s[10:11], 0, v[4:5]
	v_lshl_add_u64 v[4:5], v[16:17], 1, v[4:5]
	s_waitcnt lgkmcnt(0)
	global_store_dwordx4 v[4:5], v[8:11], off
	v_ashrrev_i32_e32 v4, 31, v2
	v_lshrrev_b32_e32 v4, 28, v4
	v_add_u32_e32 v4, v2, v4
	v_ashrrev_i32_e32 v8, 4, v4
	v_lshlrev_b32_e32 v5, 7, v8
	v_lshlrev_b32_e32 v2, 3, v2
	v_ashrrev_i32_e32 v9, 31, v8
	v_mul_lo_u32 v4, v8, s38
	v_sub_u32_e32 v10, v2, v5
	v_lshl_add_u64 v[8:9], s[12:13], 0, v[8:9]
	v_add_lshl_u32 v2, v10, v4, 1
	v_lshlrev_b64 v[8:9], 11, v[8:9]
	ds_read_b128 v[4:7], v2
	v_lshl_add_u64 v[8:9], s[10:11], 0, v[8:9]
	v_ashrrev_i32_e32 v11, 31, v10
	v_add_u32_e32 v2, 0xd00, v1
	v_lshl_add_u64 v[12:13], v[10:11], 1, v[8:9]
	v_ashrrev_i32_e32 v8, 31, v2
	v_lshrrev_b32_e32 v8, 28, v8
	v_add_u32_e32 v8, v2, v8
	v_ashrrev_i32_e32 v14, 4, v8
	v_lshlrev_b32_e32 v9, 7, v14
	v_lshlrev_b32_e32 v2, 3, v2
	v_mul_lo_u32 v8, v14, s38
	v_sub_u32_e32 v16, v2, v9
	v_add_lshl_u32 v2, v16, v8, 1
	ds_read_b128 v[8:11], v2
	v_ashrrev_i32_e32 v15, 31, v14
	s_waitcnt lgkmcnt(1)
	global_store_dwordx4 v[12:13], v[4:7], off
	v_ashrrev_i32_e32 v17, 31, v16
	v_add_u32_e32 v2, 0xe00, v1
	v_lshl_add_u64 v[4:5], s[12:13], 0, v[14:15]
	v_lshlrev_b64 v[4:5], 11, v[4:5]
	v_lshl_add_u64 v[4:5], s[10:11], 0, v[4:5]
	v_lshl_add_u64 v[4:5], v[16:17], 1, v[4:5]
	s_waitcnt lgkmcnt(0)
	global_store_dwordx4 v[4:5], v[8:11], off
	v_ashrrev_i32_e32 v4, 31, v2
	v_lshrrev_b32_e32 v4, 28, v4
	v_add_u32_e32 v4, v2, v4
	v_ashrrev_i32_e32 v8, 4, v4
	v_lshlrev_b32_e32 v5, 7, v8
	v_lshlrev_b32_e32 v2, 3, v2
	v_mul_lo_u32 v4, v8, s38
	v_sub_u32_e32 v10, v2, v5
	v_add_lshl_u32 v2, v10, v4, 1
	v_add_u32_e32 v1, 0xf00, v1
	ds_read_b128 v[4:7], v2
	v_ashrrev_i32_e32 v9, 31, v8
	v_ashrrev_i32_e32 v2, 31, v1
	v_lshl_add_u64 v[8:9], s[12:13], 0, v[8:9]
	v_lshrrev_b32_e32 v2, 28, v2
	v_lshlrev_b64 v[8:9], 11, v[8:9]
	v_add_u32_e32 v2, v1, v2
	v_lshl_add_u64 v[8:9], s[10:11], 0, v[8:9]
	v_ashrrev_i32_e32 v11, 31, v10
	v_ashrrev_i32_e32 v14, 4, v2
	v_lshl_add_u64 v[12:13], v[10:11], 1, v[8:9]
	v_lshlrev_b32_e32 v8, 7, v14
	v_lshlrev_b32_e32 v1, 3, v1
	v_mul_lo_u32 v2, v14, s38
	v_sub_u32_e32 v16, v1, v8
	v_add_lshl_u32 v1, v16, v2, 1
	v_ashrrev_i32_e32 v15, 31, v14
	ds_read_b128 v[8:11], v1
	s_waitcnt lgkmcnt(1)
	global_store_dwordx4 v[12:13], v[4:7], off
	v_ashrrev_i32_e32 v17, 31, v16
	v_readlane_b32 s58, v251, 60
	v_lshl_add_u64 v[4:5], s[12:13], 0, v[14:15]
	v_lshlrev_b64 v[4:5], 11, v[4:5]
	v_lshl_add_u64 v[4:5], s[10:11], 0, v[4:5]
	v_readlane_b32 s10, v252, 59
	s_add_i32 s2, s2, s10
	v_readlane_b32 s59, v251, 61
	v_lshl_add_u64 v[4:5], v[16:17], 1, v[4:5]
	s_cmpk_gt_i32 s2, 0x3ff
	v_readlane_b32 s57, v251, 59
	v_readlane_b32 s62, v252, 0
	v_readlane_b32 s63, v252, 1
	v_readlane_b32 s64, v252, 2
	v_readlane_b32 s65, v252, 3
	v_readlane_b32 s66, v252, 4
	v_readlane_b32 s67, v252, 5
	v_readlane_b32 s68, v252, 6
	v_readlane_b32 s69, v252, 7
	v_readlane_b32 s70, v252, 8
	v_readlane_b32 s71, v252, 9
	s_waitcnt lgkmcnt(0)
	global_store_dwordx4 v[4:5], v[8:11], off
	s_barrier
	v_readlane_b32 s11, v252, 60
	s_cbranch_scc0 .LBB0_925

; DEVI f32x4 mfma16(bf16x8 a, bf16x8 b, f32x4 c) { return __builtin_amdgcn_mfma_f32_16x16x32_bf16(a, b, c, 0, 0, 0); }
; DEVI void gemm_core3(f32x4 (&acc)[8][4], const bf* __restrict__ A, int lda, const bf* __restrict__ Bt, int ldb, int K, char* smem) {
;     ...
;   for (int kt = 0; kt < nk; ++kt) {
;     const int k1 = min((kt + 1) * 32, klast);
;     const int sn = ((kt + 1) & 1) * STG;
;     const int so = (kt & 1) * STG;
;     bf16x8 bfr[4], af[8];
; #pragma unroll
;     for (int n = 0; n < 4; ++n) bfr[n] = *reinterpret_cast<const bf16x8*>(bbase + so + n * 16 * 64);
; #pragma unroll
;     for (int m = 0; m < 8; ++m) af[m] = *reinterpret_cast<const bf16x8*>(abase + so + m * 16 * 64);
; #pragma unroll
;     for (int i = 0; i < 4; ++i) glds16(Ap + i * sa + k1, dbase + sn + i * 4096);
; #pragma unroll
;     for (int i = 0; i < 2; ++i) glds16(Bp + i * sb + k1, dbase + sn + ASZ + i * 4096);
;     __builtin_amdgcn_s_setprio(1);
; #pragma unroll
;     for (int m = 0; m < 8; ++m)
; #pragma unroll
;       for (int n = 0; n < 4; ++n) acc[m][n] = mfma16(af[m], bfr[n], acc[m][n]);
;     __builtin_amdgcn_s_setprio(0);
;     __syncthreads();
;   }
.Lg3_loop_936:
	v_add_u32_e32 v216, s10, v146
	v_add_u32_e32 v217, s10, v2
	ds_read_b128 v[148:151], v217 offset:16384
	ds_read_b128 v[166:169], v216
	ds_read_b128 v[154:157], v217 offset:17408
	ds_read_b128 v[158:161], v217 offset:18432
	ds_read_b128 v[162:165], v217 offset:19456
	ds_read_b128 v[170:173], v216 offset:1024
	ds_read_b128 v[174:177], v216 offset:2048
	ds_read_b128 v[192:195], v216 offset:3072
	ds_read_b128 v[196:199], v216 offset:4096
	ds_read_b128 v[204:207], v216 offset:5120
	ds_read_b128 v[208:211], v216 offset:6144
	ds_read_b128 v[212:215], v216 offset:7168
	s_setprio 1
	s_waitcnt lgkmcnt(10)
	v_mfma_f32_16x16x32_bf16 v[128:131], v[166:169], v[148:151], v[128:131]
	s_waitcnt lgkmcnt(9)
	v_mfma_f32_16x16x32_bf16 v[124:127], v[166:169], v[154:157], v[124:127]
	s_waitcnt lgkmcnt(8)
	v_mfma_f32_16x16x32_bf16 v[120:123], v[166:169], v[158:161], v[120:123]
	s_waitcnt lgkmcnt(7)
	v_mfma_f32_16x16x32_bf16 v[116:119], v[166:169], v[162:165], v[116:119]
	s_waitcnt lgkmcnt(6)
	v_mfma_f32_16x16x32_bf16 v[112:115], v[170:173], v[148:151], v[112:115]
	v_mfma_f32_16x16x32_bf16 v[108:111], v[170:173], v[154:157], v[108:111]
	v_mfma_f32_16x16x32_bf16 v[104:107], v[170:173], v[158:161], v[104:107]
	v_mfma_f32_16x16x32_bf16 v[100:103], v[170:173], v[162:165], v[100:103]
	s_waitcnt lgkmcnt(5)
	v_mfma_f32_16x16x32_bf16 v[96:99], v[174:177], v[148:151], v[96:99]
	v_mfma_f32_16x16x32_bf16 v[92:95], v[174:177], v[154:157], v[92:95]
	v_mfma_f32_16x16x32_bf16 v[88:91], v[174:177], v[158:161], v[88:91]
	v_mfma_f32_16x16x32_bf16 v[84:87], v[174:177], v[162:165], v[84:87]
	s_waitcnt lgkmcnt(4)
	v_mfma_f32_16x16x32_bf16 v[80:83], v[192:195], v[148:151], v[80:83]
	v_mfma_f32_16x16x32_bf16 v[76:79], v[192:195], v[154:157], v[76:79]
	v_mfma_f32_16x16x32_bf16 v[72:75], v[192:195], v[158:161], v[72:75]
	v_mfma_f32_16x16x32_bf16 v[68:71], v[192:195], v[162:165], v[68:71]
	s_waitcnt lgkmcnt(3)
	v_mfma_f32_16x16x32_bf16 v[64:67], v[196:199], v[148:151], v[64:67]
	v_mfma_f32_16x16x32_bf16 v[60:63], v[196:199], v[154:157], v[60:63]
	v_mfma_f32_16x16x32_bf16 v[56:59], v[196:199], v[158:161], v[56:59]
	v_mfma_f32_16x16x32_bf16 v[52:55], v[196:199], v[162:165], v[52:55]
	s_waitcnt lgkmcnt(2)
	v_mfma_f32_16x16x32_bf16 v[48:51], v[204:207], v[148:151], v[48:51]
	v_mfma_f32_16x16x32_bf16 v[44:47], v[204:207], v[154:157], v[44:47]
	v_mfma_f32_16x16x32_bf16 v[40:43], v[204:207], v[158:161], v[40:43]
	v_mfma_f32_16x16x32_bf16 v[36:39], v[204:207], v[162:165], v[36:39]
	s_waitcnt lgkmcnt(1)
	v_mfma_f32_16x16x32_bf16 v[32:35], v[208:211], v[148:151], v[32:35]
	v_mfma_f32_16x16x32_bf16 v[28:31], v[208:211], v[154:157], v[28:31]
	v_mfma_f32_16x16x32_bf16 v[24:27], v[208:211], v[158:161], v[24:27]
	v_mfma_f32_16x16x32_bf16 v[20:23], v[208:211], v[162:165], v[20:23]
	s_waitcnt lgkmcnt(0)
	v_mfma_f32_16x16x32_bf16 v[16:19], v[212:215], v[148:151], v[16:19]
	v_mfma_f32_16x16x32_bf16 v[12:15], v[212:215], v[154:157], v[12:15]
	v_mfma_f32_16x16x32_bf16 v[8:11], v[212:215], v[158:161], v[8:11]
	v_mfma_f32_16x16x32_bf16 v[4:7], v[212:215], v[162:165], v[4:7]
	s_setprio 0
	s_add_i32 s10, s10, 0x6000
	s_cmp_lg_u32 s10, 0x12000
	s_cselect_b32 s10, s10, 0
	s_waitcnt vmcnt(0)
	s_barrier
	s_setprio 2
	v_add_u32_e32 v216, s10, v146
	v_add_u32_e32 v217, s10, v2
	ds_read_b128 v[148:151], v217 offset:16384
	ds_read_b128 v[166:169], v216
	ds_read_b128 v[154:157], v217 offset:17408
	ds_read_b128 v[158:161], v217 offset:18432
	ds_read_b128 v[162:165], v217 offset:19456
	ds_read_b128 v[170:173], v216 offset:1024
	ds_read_b128 v[174:177], v216 offset:2048
	ds_read_b128 v[192:195], v216 offset:3072
	ds_read_b128 v[196:199], v216 offset:4096
	ds_read_b128 v[204:207], v216 offset:5120
	ds_read_b128 v[208:211], v216 offset:6144
	ds_read_b128 v[212:215], v216 offset:7168
	v_readfirstlane_b32 s17, v140
	s_add_i32 s96, s11, 0x6000
	s_cmp_lg_u32 s96, 0x12000
	s_cselect_b32 s96, s96, 0
	s_add_i32 s96, s96, s17
	s_add_i32 s17, s17, s11
	s_waitcnt lgkmcnt(10)
	s_mov_b32 m0, s17
	s_add_i32 s17, s17, 0x1000
	v_mfma_f32_16x16x32_bf16 v[128:131], v[166:169], v[148:151], v[128:131]
	s_waitcnt lgkmcnt(9)
	v_mfma_f32_16x16x32_bf16 v[124:127], v[166:169], v[154:157], v[124:127]
	global_load_lds_dwordx4 v[218:219], off
	v_lshl_add_u64 v[218:219], v[218:219], 0, 64
	s_waitcnt lgkmcnt(8)
	s_mov_b32 m0, s96
	s_add_i32 s96, s96, 0x1000
	v_mfma_f32_16x16x32_bf16 v[120:123], v[166:169], v[158:161], v[120:123]
	s_waitcnt lgkmcnt(7)
	v_mfma_f32_16x16x32_bf16 v[116:119], v[166:169], v[162:165], v[116:119]
	global_load_lds_dwordx4 v[218:219], off
	v_lshl_add_u64 v[218:219], v[218:219], 0, 64
	s_waitcnt lgkmcnt(6)
	v_mfma_f32_16x16x32_bf16 v[112:115], v[170:173], v[148:151], v[112:115]
	s_mov_b32 m0, s17
	s_add_i32 s17, s17, 0x1000
	v_mfma_f32_16x16x32_bf16 v[108:111], v[170:173], v[154:157], v[108:111]
	v_mfma_f32_16x16x32_bf16 v[104:107], v[170:173], v[158:161], v[104:107]
	global_load_lds_dwordx4 v[220:221], off
	v_lshl_add_u64 v[220:221], v[220:221], 0, 64
	s_mov_b32 m0, s96
	s_add_i32 s96, s96, 0x1000
	v_mfma_f32_16x16x32_bf16 v[100:103], v[170:173], v[162:165], v[100:103]
	s_waitcnt lgkmcnt(5)
	v_mfma_f32_16x16x32_bf16 v[96:99], v[174:177], v[148:151], v[96:99]
	global_load_lds_dwordx4 v[220:221], off
	v_lshl_add_u64 v[220:221], v[220:221], 0, 64
	v_mfma_f32_16x16x32_bf16 v[92:95], v[174:177], v[154:157], v[92:95]
	s_mov_b32 m0, s17
	s_add_i32 s17, s17, 0x1000
	v_mfma_f32_16x16x32_bf16 v[88:91], v[174:177], v[158:161], v[88:91]
	v_mfma_f32_16x16x32_bf16 v[84:87], v[174:177], v[162:165], v[84:87]
	global_load_lds_dwordx4 v[222:223], off
	v_lshl_add_u64 v[222:223], v[222:223], 0, 64
	s_waitcnt lgkmcnt(4)
; DEVI f32x4 mfma16(bf16x8 a, bf16x8 b, f32x4 c) { return __builtin_amdgcn_mfma_f32_16x16x32_bf16(a, b, c, 0, 0, 0); }
; DEVI void gemm_core3(f32x4 (&acc)[8][4], const bf* __restrict__ A, int lda, const bf* __restrict__ Bt, int ldb, int K, char* smem) {
;     ...
;     bf16x8 bfr[4], af[8];
; #pragma unroll
;     for (int n = 0; n < 4; ++n) bfr[n] = *reinterpret_cast<const bf16x8*>(bbase + so + n * 16 * 64);
; #pragma unroll
;     for (int m = 0; m < 8; ++m) af[m] = *reinterpret_cast<const bf16x8*>(abase + so + m * 16 * 64);
; #pragma unroll
;     for (int i = 0; i < 4; ++i) glds16(Ap + i * sa + k1, dbase + sn + i * 4096);
; #pragma unroll
;     for (int i = 0; i < 2; ++i) glds16(Bp + i * sb + k1, dbase + sn + ASZ + i * 4096);
;     __builtin_amdgcn_s_setprio(1);
; #pragma unroll
;     for (int m = 0; m < 8; ++m)
; #pragma unroll
;       for (int n = 0; n < 4; ++n) acc[m][n] = mfma16(af[m], bfr[n], acc[m][n]);
;     __builtin_amdgcn_s_setprio(0);
;     __syncthreads();
	s_mov_b32 m0, s96
	s_add_i32 s96, s96, 0x1000
	v_mfma_f32_16x16x32_bf16 v[80:83], v[192:195], v[148:151], v[80:83]
	v_mfma_f32_16x16x32_bf16 v[76:79], v[192:195], v[154:157], v[76:79]
	global_load_lds_dwordx4 v[222:223], off
	v_lshl_add_u64 v[222:223], v[222:223], 0, 64
	v_mfma_f32_16x16x32_bf16 v[72:75], v[192:195], v[158:161], v[72:75]
	s_mov_b32 m0, s17
	s_add_i32 s17, s17, 0x1000
	v_mfma_f32_16x16x32_bf16 v[68:71], v[192:195], v[162:165], v[68:71]
	s_waitcnt lgkmcnt(3)
	v_mfma_f32_16x16x32_bf16 v[64:67], v[196:199], v[148:151], v[64:67]
	global_load_lds_dwordx4 v[224:225], off
	v_lshl_add_u64 v[224:225], v[224:225], 0, 64
	s_mov_b32 m0, s96
	s_add_i32 s96, s96, 0x1000
	v_mfma_f32_16x16x32_bf16 v[60:63], v[196:199], v[154:157], v[60:63]
	v_mfma_f32_16x16x32_bf16 v[56:59], v[196:199], v[158:161], v[56:59]
	global_load_lds_dwordx4 v[224:225], off
	v_lshl_add_u64 v[224:225], v[224:225], 0, 64
	v_mfma_f32_16x16x32_bf16 v[52:55], v[196:199], v[162:165], v[52:55]
	s_waitcnt lgkmcnt(2)
	s_mov_b32 m0, s17
	s_add_i32 s17, s17, 0x1000
	v_mfma_f32_16x16x32_bf16 v[48:51], v[204:207], v[148:151], v[48:51]
	v_mfma_f32_16x16x32_bf16 v[44:47], v[204:207], v[154:157], v[44:47]
	global_load_lds_dwordx4 v[226:227], off
	v_lshl_add_u64 v[226:227], v[226:227], 0, 64
	s_mov_b32 m0, s96
	s_add_i32 s96, s96, 0x1000
	v_mfma_f32_16x16x32_bf16 v[40:43], v[204:207], v[158:161], v[40:43]
	v_mfma_f32_16x16x32_bf16 v[36:39], v[204:207], v[162:165], v[36:39]
	global_load_lds_dwordx4 v[226:227], off
	v_lshl_add_u64 v[226:227], v[226:227], 0, 64
	s_waitcnt lgkmcnt(1)
	v_mfma_f32_16x16x32_bf16 v[32:35], v[208:211], v[148:151], v[32:35]
	s_mov_b32 m0, s17
	s_add_i32 s17, s17, 0x1000
	v_mfma_f32_16x16x32_bf16 v[28:31], v[208:211], v[154:157], v[28:31]
	v_mfma_f32_16x16x32_bf16 v[24:27], v[208:211], v[158:161], v[24:27]
	global_load_lds_dwordx4 v[228:229], off
	v_lshl_add_u64 v[228:229], v[228:229], 0, 64
	s_mov_b32 m0, s96
	s_add_i32 s96, s96, 0x1000
	v_mfma_f32_16x16x32_bf16 v[20:23], v[208:211], v[162:165], v[20:23]
	s_waitcnt lgkmcnt(0)
	v_mfma_f32_16x16x32_bf16 v[16:19], v[212:215], v[148:151], v[16:19]
	global_load_lds_dwordx4 v[228:229], off
	v_lshl_add_u64 v[228:229], v[228:229], 0, 64
	v_mfma_f32_16x16x32_bf16 v[12:15], v[212:215], v[154:157], v[12:15]
	v_mfma_f32_16x16x32_bf16 v[8:11], v[212:215], v[158:161], v[8:11]
	v_mfma_f32_16x16x32_bf16 v[4:7], v[212:215], v[162:165], v[4:7]
	s_setprio 0
	s_add_i32 s10, s10, 0x6000
	s_cmp_lg_u32 s10, 0x12000
	s_cselect_b32 s10, s10, 0
	s_sub_i32 s11, s11, 0x6000
	s_cmp_lt_i32 s11, 0
	s_cselect_b32 s11, 0xc000, s11
	s_add_i32 s3, s3, 1
	s_cmp_lt_i32 s3, 15
	s_waitcnt vmcnt(1)
	s_barrier
	s_cbranch_scc1 .Lg3_loop_936
	v_add_u32_e32 v216, s10, v146
	v_add_u32_e32 v217, s10, v2
	ds_read_b128 v[148:151], v217 offset:16384
	ds_read_b128 v[166:169], v216
	ds_read_b128 v[154:157], v217 offset:17408
	ds_read_b128 v[158:161], v217 offset:18432
	ds_read_b128 v[162:165], v217 offset:19456
	ds_read_b128 v[170:173], v216 offset:1024
	ds_read_b128 v[174:177], v216 offset:2048
	ds_read_b128 v[192:195], v216 offset:3072
	ds_read_b128 v[196:199], v216 offset:4096
	ds_read_b128 v[204:207], v216 offset:5120
	ds_read_b128 v[208:211], v216 offset:6144
	ds_read_b128 v[212:215], v216 offset:7168
	s_setprio 1
	s_waitcnt lgkmcnt(10)
	v_mfma_f32_16x16x32_bf16 v[128:131], v[166:169], v[148:151], v[128:131]
	s_waitcnt lgkmcnt(9)
	v_mfma_f32_16x16x32_bf16 v[124:127], v[166:169], v[154:157], v[124:127]
	s_waitcnt lgkmcnt(8)
	v_mfma_f32_16x16x32_bf16 v[120:123], v[166:169], v[158:161], v[120:123]
	s_waitcnt lgkmcnt(7)
	v_mfma_f32_16x16x32_bf16 v[116:119], v[166:169], v[162:165], v[116:119]
	s_waitcnt lgkmcnt(6)
	v_mfma_f32_16x16x32_bf16 v[112:115], v[170:173], v[148:151], v[112:115]
	v_mfma_f32_16x16x32_bf16 v[108:111], v[170:173], v[154:157], v[108:111]
	v_mfma_f32_16x16x32_bf16 v[104:107], v[170:173], v[158:161], v[104:107]
	v_mfma_f32_16x16x32_bf16 v[100:103], v[170:173], v[162:165], v[100:103]
	s_waitcnt lgkmcnt(5)
	v_mfma_f32_16x16x32_bf16 v[96:99], v[174:177], v[148:151], v[96:99]
	v_mfma_f32_16x16x32_bf16 v[92:95], v[174:177], v[154:157], v[92:95]
	v_mfma_f32_16x16x32_bf16 v[88:91], v[174:177], v[158:161], v[88:91]
	v_mfma_f32_16x16x32_bf16 v[84:87], v[174:177], v[162:165], v[84:87]
	s_waitcnt lgkmcnt(4)
	v_mfma_f32_16x16x32_bf16 v[80:83], v[192:195], v[148:151], v[80:83]
	v_mfma_f32_16x16x32_bf16 v[76:79], v[192:195], v[154:157], v[76:79]
	v_mfma_f32_16x16x32_bf16 v[72:75], v[192:195], v[158:161], v[72:75]
	v_mfma_f32_16x16x32_bf16 v[68:71], v[192:195], v[162:165], v[68:71]
	s_waitcnt lgkmcnt(3)
	v_mfma_f32_16x16x32_bf16 v[64:67], v[196:199], v[148:151], v[64:67]
	v_mfma_f32_16x16x32_bf16 v[60:63], v[196:199], v[154:157], v[60:63]
	v_mfma_f32_16x16x32_bf16 v[56:59], v[196:199], v[158:161], v[56:59]
	v_mfma_f32_16x16x32_bf16 v[52:55], v[196:199], v[162:165], v[52:55]
	s_waitcnt lgkmcnt(2)
	v_mfma_f32_16x16x32_bf16 v[48:51], v[204:207], v[148:151], v[48:51]
	v_mfma_f32_16x16x32_bf16 v[44:47], v[204:207], v[154:157], v[44:47]
	v_mfma_f32_16x16x32_bf16 v[40:43], v[204:207], v[158:161], v[40:43]
	v_mfma_f32_16x16x32_bf16 v[36:39], v[204:207], v[162:165], v[36:39]
	s_waitcnt lgkmcnt(1)
	v_mfma_f32_16x16x32_bf16 v[32:35], v[208:211], v[148:151], v[32:35]
	v_mfma_f32_16x16x32_bf16 v[28:31], v[208:211], v[154:157], v[28:31]
	v_mfma_f32_16x16x32_bf16 v[24:27], v[208:211], v[158:161], v[24:27]
	v_mfma_f32_16x16x32_bf16 v[20:23], v[208:211], v[162:165], v[20:23]
	s_waitcnt lgkmcnt(0)
	v_mfma_f32_16x16x32_bf16 v[16:19], v[212:215], v[148:151], v[16:19]
	v_mfma_f32_16x16x32_bf16 v[12:15], v[212:215], v[154:157], v[12:15]
	v_mfma_f32_16x16x32_bf16 v[8:11], v[212:215], v[158:161], v[8:11]
	v_mfma_f32_16x16x32_bf16 v[4:7], v[212:215], v[162:165], v[4:7]
	s_setprio 0
	s_add_i32 s10, s10, 0x6000
	s_cmp_lg_u32 s10, 0x12000
	s_cselect_b32 s10, s10, 0
	s_waitcnt vmcnt(0)
	s_barrier
; DEVI float silu_(float x) { return x / (1.f + __expf(-x)); }
; DEVI f32x4 mfma16(bf16x8 a, bf16x8 b, f32x4 c) { return __builtin_amdgcn_mfma_f32_16x16x32_bf16(a, b, c, 0, 0, 0); }
; DEVI void gemm_core3(f32x4 (&acc)[8][4], const bf* __restrict__ A, int lda, const bf* __restrict__ Bt, int ldb, int K, char* smem) {
;     ...
;   for (int kt = 0; kt < nk; ++kt) {
;     const int k1 = min((kt + 1) * 32, klast);
;     const int sn = ((kt + 1) & 1) * STG;
;     const int so = (kt & 1) * STG;
;     bf16x8 bfr[4], af[8];
; #pragma unroll
;     for (int n = 0; n < 4; ++n) bfr[n] = *reinterpret_cast<const bf16x8*>(bbase + so + n * 16 * 64);
; #pragma unroll
;     for (int m = 0; m < 8; ++m) af[m] = *reinterpret_cast<const bf16x8*>(abase + so + m * 16 * 64);
; #pragma unroll
;     for (int i = 0; i < 4; ++i) glds16(Ap + i * sa + k1, dbase + sn + i * 4096);
; #pragma unroll
;     for (int i = 0; i < 2; ++i) glds16(Bp + i * sb + k1, dbase + sn + ASZ + i * 4096);
;     __builtin_amdgcn_s_setprio(1);
; #pragma unroll
;     for (int m = 0; m < 8; ++m)
; #pragma unroll
;       for (int n = 0; n < 4; ++n) acc[m][n] = mfma16(af[m], bfr[n], acc[m][n]);
;     __builtin_amdgcn_s_setprio(0);
;     __syncthreads();
;   }
; DEVI void ffn1_tile256(const P& p, const bf* W, long row0, int n0  , char* smem) {
;     ...
; #pragma unroll
;   for (int m = 0; m < 8; ++m)
; #pragma unroll
;     for (int pr = 0; pr < 2; ++pr) {
;       const int cl = (wc * 2 + pr) * 16 + l15;
; #pragma unroll
;       for (int j = 0; j < 4; ++j) {
;         const int rl = wr * 128 + m * 16 + quad * 4 + j;
;         float a = acc[m][2 * pr][j], b = acc[m][2 * pr + 1][j];
;         tl[rl * 72 + cl] = f2bf(silu_(a) * b);
;       }
;     }
;   __syncthreads();
	v_add_u32_e32 v216, s10, v146
	v_add_u32_e32 v217, s10, v2
	ds_read_b128 v[148:151], v217 offset:16384
	ds_read_b128 v[166:169], v216
	ds_read_b128 v[154:157], v217 offset:17408
	ds_read_b128 v[158:161], v217 offset:18432
	ds_read_b128 v[162:165], v217 offset:19456
	ds_read_b128 v[170:173], v216 offset:1024
	ds_read_b128 v[174:177], v216 offset:2048
	ds_read_b128 v[192:195], v216 offset:3072
	ds_read_b128 v[196:199], v216 offset:4096
	ds_read_b128 v[204:207], v216 offset:5120
	ds_read_b128 v[208:211], v216 offset:6144
	ds_read_b128 v[212:215], v216 offset:7168
	s_setprio 1
	s_waitcnt lgkmcnt(10)
	v_mfma_f32_16x16x32_bf16 v[128:131], v[166:169], v[148:151], v[128:131]
	s_waitcnt lgkmcnt(9)
	v_mfma_f32_16x16x32_bf16 v[124:127], v[166:169], v[154:157], v[124:127]
	s_waitcnt lgkmcnt(8)
	v_mfma_f32_16x16x32_bf16 v[120:123], v[166:169], v[158:161], v[120:123]
	s_waitcnt lgkmcnt(7)
	v_mfma_f32_16x16x32_bf16 v[116:119], v[166:169], v[162:165], v[116:119]
	s_waitcnt lgkmcnt(6)
	v_mfma_f32_16x16x32_bf16 v[112:115], v[170:173], v[148:151], v[112:115]
	v_mfma_f32_16x16x32_bf16 v[108:111], v[170:173], v[154:157], v[108:111]
	v_mfma_f32_16x16x32_bf16 v[104:107], v[170:173], v[158:161], v[104:107]
	v_mfma_f32_16x16x32_bf16 v[100:103], v[170:173], v[162:165], v[100:103]
	s_waitcnt lgkmcnt(5)
	v_mfma_f32_16x16x32_bf16 v[96:99], v[174:177], v[148:151], v[96:99]
	v_mfma_f32_16x16x32_bf16 v[92:95], v[174:177], v[154:157], v[92:95]
	v_mfma_f32_16x16x32_bf16 v[88:91], v[174:177], v[158:161], v[88:91]
	v_mfma_f32_16x16x32_bf16 v[84:87], v[174:177], v[162:165], v[84:87]
	s_waitcnt lgkmcnt(4)
	v_mfma_f32_16x16x32_bf16 v[80:83], v[192:195], v[148:151], v[80:83]
	v_mfma_f32_16x16x32_bf16 v[76:79], v[192:195], v[154:157], v[76:79]
	v_mfma_f32_16x16x32_bf16 v[72:75], v[192:195], v[158:161], v[72:75]
	v_mfma_f32_16x16x32_bf16 v[68:71], v[192:195], v[162:165], v[68:71]
	s_waitcnt lgkmcnt(3)
	v_mfma_f32_16x16x32_bf16 v[64:67], v[196:199], v[148:151], v[64:67]
	v_mfma_f32_16x16x32_bf16 v[60:63], v[196:199], v[154:157], v[60:63]
	v_mfma_f32_16x16x32_bf16 v[56:59], v[196:199], v[158:161], v[56:59]
	v_mfma_f32_16x16x32_bf16 v[52:55], v[196:199], v[162:165], v[52:55]
	s_waitcnt lgkmcnt(2)
	v_mfma_f32_16x16x32_bf16 v[48:51], v[204:207], v[148:151], v[48:51]
	v_mfma_f32_16x16x32_bf16 v[44:47], v[204:207], v[154:157], v[44:47]
	v_mfma_f32_16x16x32_bf16 v[40:43], v[204:207], v[158:161], v[40:43]
	v_mfma_f32_16x16x32_bf16 v[36:39], v[204:207], v[162:165], v[36:39]
	s_waitcnt lgkmcnt(1)
	v_mfma_f32_16x16x32_bf16 v[32:35], v[208:211], v[148:151], v[32:35]
	v_mfma_f32_16x16x32_bf16 v[28:31], v[208:211], v[154:157], v[28:31]
	v_mfma_f32_16x16x32_bf16 v[24:27], v[208:211], v[158:161], v[24:27]
	v_mfma_f32_16x16x32_bf16 v[20:23], v[208:211], v[162:165], v[20:23]
	s_waitcnt lgkmcnt(0)
	v_mfma_f32_16x16x32_bf16 v[16:19], v[212:215], v[148:151], v[16:19]
	v_mfma_f32_16x16x32_bf16 v[12:15], v[212:215], v[154:157], v[12:15]
	v_mfma_f32_16x16x32_bf16 v[8:11], v[212:215], v[158:161], v[8:11]
	v_mfma_f32_16x16x32_bf16 v[4:7], v[212:215], v[162:165], v[4:7]
	s_setprio 0
	s_add_i32 s10, s10, 0x6000
	s_cmp_lg_u32 s10, 0x12000
	s_cselect_b32 s10, s10, 0
	s_waitcnt vmcnt(0)
	s_barrier
	v_mul_f32_e32 v2, 0xbfb8aa3b, v128
	v_exp_f32_e32 v2, v2
	v_and_b32_e32 v132, 15, v1
	v_and_b32_e32 v133, 0xfffff80, v1
	v_lshrrev_b32_e32 v134, 2, v1
	v_add_f32_e32 v135, 1.0, v2
	v_div_scale_f32 v136, s[10:11], v135, v135, v128
	v_rcp_f32_e32 v137, v136
	v_lshlrev_b32_e32 v2, 1, v132
	v_and_or_b32 v2, v1, 64, v2
	v_and_or_b32 v133, v134, 12, v133
	v_fma_f32 v1, -v136, v137, 1.0
	v_fmac_f32_e32 v137, v1, v137
	v_div_scale_f32 v1, vcc, v128, v135, v128
	v_mul_f32_e32 v132, v1, v137
	v_fma_f32 v134, -v136, v132, v1
	v_fmac_f32_e32 v132, v134, v137
	v_fma_f32 v1, -v136, v132, v1
	v_div_fmas_f32 v1, v1, v137, v132
	v_mul_f32_e32 v132, 0xbfb8aa3b, v129
	v_exp_f32_e32 v132, v132
	v_div_fixup_f32 v1, v1, v135, v128
	v_mul_f32_e32 v1, v124, v1
	s_movk_i32 s3, 0x90
	v_add_f32_e32 v124, 1.0, v132
	v_div_scale_f32 v128, s[10:11], v124, v124, v129
	v_rcp_f32_e32 v134, v128
	v_cvt_pk_bf16_f32 v1, v1, s0
	v_mad_u64_u32 v[132:133], s[10:11], v133, s3, v[2:3]
	ds_write_b16 v132, v1
	v_fma_f32 v1, -v128, v134, 1.0
	v_fmac_f32_e32 v134, v1, v134
	v_div_scale_f32 v1, vcc, v129, v124, v129
	v_mul_f32_e32 v2, v1, v134
	v_fma_f32 v133, -v128, v2, v1
	v_fmac_f32_e32 v2, v133, v134
	v_fma_f32 v1, -v128, v2, v1
	v_mul_f32_e32 v128, 0xbfb8aa3b, v130
	v_exp_f32_e32 v128, v128
	v_div_fmas_f32 v1, v1, v134, v2
	v_div_fixup_f32 v1, v1, v124, v129
	v_mul_f32_e32 v1, v125, v1
	v_add_f32_e32 v2, 1.0, v128
	v_div_scale_f32 v124, s[10:11], v2, v2, v130
	v_rcp_f32_e32 v128, v124
	v_cvt_pk_bf16_f32 v1, v1, s0
	ds_write_b16 v132, v1 offset:144
	v_readlane_b32 s56, v251, 58
	v_fma_f32 v1, -v124, v128, 1.0
	v_fmac_f32_e32 v128, v1, v128
	v_div_scale_f32 v1, vcc, v130, v2, v130
	v_mul_f32_e32 v125, v1, v128
	v_fma_f32 v129, -v124, v125, v1
	v_fmac_f32_e32 v125, v129, v128
	v_fma_f32 v1, -v124, v125, v1
	v_mul_f32_e32 v124, 0xbfb8aa3b, v131
	v_exp_f32_e32 v124, v124
	v_div_fmas_f32 v1, v1, v128, v125
	v_div_fixup_f32 v1, v1, v2, v130
	v_mul_f32_e32 v1, v126, v1
	v_add_f32_e32 v2, 1.0, v124
	v_div_scale_f32 v124, s[10:11], v2, v2, v131
	v_rcp_f32_e32 v125, v124
	v_cvt_pk_bf16_f32 v1, v1, s0
	ds_write_b16 v132, v1 offset:288
	v_readlane_b32 s58, v251, 60
	v_fma_f32 v1, -v124, v125, 1.0
	v_fmac_f32_e32 v125, v1, v125
	v_div_scale_f32 v1, vcc, v131, v2, v131
	v_mul_f32_e32 v126, v1, v125
	v_fma_f32 v128, -v124, v126, v1
	v_fmac_f32_e32 v126, v128, v125
	v_fma_f32 v1, -v124, v126, v1
	v_mul_f32_e32 v124, 0xbfb8aa3b, v120
	v_exp_f32_e32 v124, v124
; DEVI float silu_(float x) { return x / (1.f + __expf(-x)); }
; DEVI void ffn1_tile256(const P& p, const bf* W, long row0, int n0  , char* smem) {
;     ...
; #pragma unroll
;   for (int m = 0; m < 8; ++m)
; #pragma unroll
;     for (int pr = 0; pr < 2; ++pr) {
;       const int cl = (wc * 2 + pr) * 16 + l15;
; #pragma unroll
;       for (int j = 0; j < 4; ++j) {
;         const int rl = wr * 128 + m * 16 + quad * 4 + j;
;         float a = acc[m][2 * pr][j], b = acc[m][2 * pr + 1][j];
;         tl[rl * 72 + cl] = f2bf(silu_(a) * b);
;       }
;     }
;   __syncthreads();
	v_div_fmas_f32 v1, v1, v125, v126
	v_div_fixup_f32 v1, v1, v2, v131
	v_mul_f32_e32 v1, v127, v1
	v_add_f32_e32 v2, 1.0, v124
	v_div_scale_f32 v124, s[10:11], v2, v2, v120
	v_rcp_f32_e32 v125, v124
	v_cvt_pk_bf16_f32 v1, v1, s0
	ds_write_b16 v132, v1 offset:432
	v_readlane_b32 s59, v251, 61
	v_fma_f32 v1, -v124, v125, 1.0
	v_fmac_f32_e32 v125, v1, v125
	v_div_scale_f32 v1, vcc, v120, v2, v120
	v_mul_f32_e32 v126, v1, v125
	v_fma_f32 v127, -v124, v126, v1
	v_fmac_f32_e32 v126, v127, v125
	v_fma_f32 v1, -v124, v126, v1
	v_mul_f32_e32 v124, 0xbfb8aa3b, v121
	v_exp_f32_e32 v124, v124
	v_div_fmas_f32 v1, v1, v125, v126
	v_div_fixup_f32 v1, v1, v2, v120
	v_mul_f32_e32 v1, v116, v1
	v_add_f32_e32 v2, 1.0, v124
	v_div_scale_f32 v120, s[10:11], v2, v2, v121
	v_rcp_f32_e32 v124, v120
	v_cvt_pk_bf16_f32 v1, v1, s0
	ds_write_b16 v132, v1 offset:32
	v_readlane_b32 s57, v251, 59
	v_fma_f32 v1, -v120, v124, 1.0
	v_fmac_f32_e32 v124, v1, v124
	v_div_scale_f32 v1, vcc, v121, v2, v121
	v_mul_f32_e32 v116, v1, v124
	v_fma_f32 v125, -v120, v116, v1
	v_fmac_f32_e32 v116, v125, v124
	v_fma_f32 v1, -v120, v116, v1
	v_mul_f32_e32 v120, 0xbfb8aa3b, v122
	v_exp_f32_e32 v120, v120
	v_div_fmas_f32 v1, v1, v124, v116
	v_div_fixup_f32 v1, v1, v2, v121
	v_mul_f32_e32 v1, v117, v1
	v_add_f32_e32 v2, 1.0, v120
	v_div_scale_f32 v116, s[10:11], v2, v2, v122
	v_rcp_f32_e32 v120, v116
	v_cvt_pk_bf16_f32 v1, v1, s0
	ds_write_b16 v132, v1 offset:176
	v_readlane_b32 s60, v251, 62
	v_fma_f32 v1, -v116, v120, 1.0
	v_fmac_f32_e32 v120, v1, v120
	v_div_scale_f32 v1, vcc, v122, v2, v122
	v_mul_f32_e32 v117, v1, v120
	v_fma_f32 v121, -v116, v117, v1
	v_fmac_f32_e32 v117, v121, v120
	v_fma_f32 v1, -v116, v117, v1
	v_mul_f32_e32 v116, 0xbfb8aa3b, v123
	v_exp_f32_e32 v116, v116
	v_div_fmas_f32 v1, v1, v120, v117
	v_div_fixup_f32 v1, v1, v2, v122
	v_mul_f32_e32 v1, v118, v1
	v_add_f32_e32 v2, 1.0, v116
	v_div_scale_f32 v116, s[10:11], v2, v2, v123
	v_rcp_f32_e32 v117, v116
	v_cvt_pk_bf16_f32 v1, v1, s0
	ds_write_b16 v132, v1 offset:320
	v_readlane_b32 s61, v251, 63
	v_fma_f32 v1, -v116, v117, 1.0
	v_fmac_f32_e32 v117, v1, v117
	v_div_scale_f32 v1, vcc, v123, v2, v123
	v_mul_f32_e32 v118, v1, v117
	v_fma_f32 v120, -v116, v118, v1
	v_fmac_f32_e32 v118, v120, v117
	v_fma_f32 v1, -v116, v118, v1
	v_mul_f32_e32 v116, 0xbfb8aa3b, v112
	v_exp_f32_e32 v116, v116
	v_div_fmas_f32 v1, v1, v117, v118
	v_div_fixup_f32 v1, v1, v2, v123
	v_mul_f32_e32 v1, v119, v1
	v_add_f32_e32 v2, 1.0, v116
	v_div_scale_f32 v116, s[10:11], v2, v2, v112
	v_rcp_f32_e32 v117, v116
	v_cvt_pk_bf16_f32 v1, v1, s0
	ds_write_b16 v132, v1 offset:464
	v_readlane_b32 s62, v252, 0
	v_fma_f32 v1, -v116, v117, 1.0
	v_fmac_f32_e32 v117, v1, v117
	v_div_scale_f32 v1, vcc, v112, v2, v112
	v_mul_f32_e32 v118, v1, v117
	v_fma_f32 v119, -v116, v118, v1
	v_fmac_f32_e32 v118, v119, v117
	v_fma_f32 v1, -v116, v118, v1
	v_mul_f32_e32 v116, 0xbfb8aa3b, v113
	v_exp_f32_e32 v116, v116
	v_div_fmas_f32 v1, v1, v117, v118
	v_div_fixup_f32 v1, v1, v2, v112
	v_mul_f32_e32 v1, v108, v1
	v_add_f32_e32 v2, 1.0, v116
	v_div_scale_f32 v112, s[10:11], v2, v2, v113
	v_rcp_f32_e32 v116, v112
	v_cvt_pk_bf16_f32 v1, v1, s0
	ds_write_b16 v132, v1 offset:2304
	v_readlane_b32 s63, v252, 1
	v_fma_f32 v1, -v112, v116, 1.0
	v_fmac_f32_e32 v116, v1, v116
	v_div_scale_f32 v1, vcc, v113, v2, v113
	v_mul_f32_e32 v108, v1, v116
	v_fma_f32 v117, -v112, v108, v1
	v_fmac_f32_e32 v108, v117, v116
	v_fma_f32 v1, -v112, v108, v1
	v_mul_f32_e32 v112, 0xbfb8aa3b, v114
	v_exp_f32_e32 v112, v112
	v_div_fmas_f32 v1, v1, v116, v108
	v_div_fixup_f32 v1, v1, v2, v113
	v_mul_f32_e32 v1, v109, v1
	v_add_f32_e32 v2, 1.0, v112
	v_div_scale_f32 v108, s[10:11], v2, v2, v114
	v_rcp_f32_e32 v112, v108
	v_cvt_pk_bf16_f32 v1, v1, s0
	ds_write_b16 v132, v1 offset:2448
	v_readlane_b32 s64, v252, 2
	v_fma_f32 v1, -v108, v112, 1.0
	v_fmac_f32_e32 v112, v1, v112
	v_div_scale_f32 v1, vcc, v114, v2, v114
	v_mul_f32_e32 v109, v1, v112
	v_fma_f32 v113, -v108, v109, v1
	v_fmac_f32_e32 v109, v113, v112
	v_fma_f32 v1, -v108, v109, v1
	v_mul_f32_e32 v108, 0xbfb8aa3b, v115
	v_exp_f32_e32 v108, v108
	v_div_fmas_f32 v1, v1, v112, v109
	v_div_fixup_f32 v1, v1, v2, v114
	v_mul_f32_e32 v1, v110, v1
	v_add_f32_e32 v2, 1.0, v108
	v_div_scale_f32 v108, s[10:11], v2, v2, v115
	v_rcp_f32_e32 v109, v108
	v_cvt_pk_bf16_f32 v1, v1, s0
	ds_write_b16 v132, v1 offset:2592
	v_readlane_b32 s65, v252, 3
	v_fma_f32 v1, -v108, v109, 1.0
	v_fmac_f32_e32 v109, v1, v109
	v_div_scale_f32 v1, vcc, v115, v2, v115
	v_mul_f32_e32 v110, v1, v109
	v_fma_f32 v112, -v108, v110, v1
	v_fmac_f32_e32 v110, v112, v109
	v_fma_f32 v1, -v108, v110, v1
	v_mul_f32_e32 v108, 0xbfb8aa3b, v104
	v_exp_f32_e32 v108, v108
	v_div_fmas_f32 v1, v1, v109, v110
	v_div_fixup_f32 v1, v1, v2, v115
	v_mul_f32_e32 v1, v111, v1
	v_add_f32_e32 v2, 1.0, v108
	v_div_scale_f32 v108, s[10:11], v2, v2, v104
	v_rcp_f32_e32 v109, v108
	v_cvt_pk_bf16_f32 v1, v1, s0
	ds_write_b16 v132, v1 offset:2736
	v_readlane_b32 s66, v252, 4
	v_fma_f32 v1, -v108, v109, 1.0
	v_fmac_f32_e32 v109, v1, v109
	v_div_scale_f32 v1, vcc, v104, v2, v104
	v_mul_f32_e32 v110, v1, v109
	v_fma_f32 v111, -v108, v110, v1
	v_fmac_f32_e32 v110, v111, v109
	v_fma_f32 v1, -v108, v110, v1
	v_mul_f32_e32 v108, 0xbfb8aa3b, v105
	v_exp_f32_e32 v108, v108
	v_div_fmas_f32 v1, v1, v109, v110
	v_div_fixup_f32 v1, v1, v2, v104
	v_mul_f32_e32 v1, v100, v1
	v_add_f32_e32 v2, 1.0, v108
	v_div_scale_f32 v104, s[10:11], v2, v2, v105
	v_rcp_f32_e32 v108, v104
	v_cvt_pk_bf16_f32 v1, v1, s0
	ds_write_b16 v132, v1 offset:2336
	v_readlane_b32 s67, v252, 5
	v_fma_f32 v1, -v104, v108, 1.0
	v_fmac_f32_e32 v108, v1, v108
; DEVI float silu_(float x) { return x / (1.f + __expf(-x)); }
; DEVI void ffn1_tile256(const P& p, const bf* W, long row0, int n0  , char* smem) {
;     ...
; #pragma unroll
;   for (int m = 0; m < 8; ++m)
; #pragma unroll
;     for (int pr = 0; pr < 2; ++pr) {
;       const int cl = (wc * 2 + pr) * 16 + l15;
; #pragma unroll
;       for (int j = 0; j < 4; ++j) {
;         const int rl = wr * 128 + m * 16 + quad * 4 + j;
;         float a = acc[m][2 * pr][j], b = acc[m][2 * pr + 1][j];
;         tl[rl * 72 + cl] = f2bf(silu_(a) * b);
;       }
;     }
;   __syncthreads();
	v_div_scale_f32 v1, vcc, v105, v2, v105
	v_mul_f32_e32 v100, v1, v108
	v_fma_f32 v109, -v104, v100, v1
	v_fmac_f32_e32 v100, v109, v108
	v_fma_f32 v1, -v104, v100, v1
	v_mul_f32_e32 v104, 0xbfb8aa3b, v106
	v_exp_f32_e32 v104, v104
	v_div_fmas_f32 v1, v1, v108, v100
	v_div_fixup_f32 v1, v1, v2, v105
	v_mul_f32_e32 v1, v101, v1
	v_add_f32_e32 v2, 1.0, v104
	v_div_scale_f32 v100, s[10:11], v2, v2, v106
	v_rcp_f32_e32 v104, v100
	v_cvt_pk_bf16_f32 v1, v1, s0
	ds_write_b16 v132, v1 offset:2480
	v_readlane_b32 s68, v252, 6
	v_fma_f32 v1, -v100, v104, 1.0
	v_fmac_f32_e32 v104, v1, v104
	v_div_scale_f32 v1, vcc, v106, v2, v106
	v_mul_f32_e32 v101, v1, v104
	v_fma_f32 v105, -v100, v101, v1
	v_fmac_f32_e32 v101, v105, v104
	v_fma_f32 v1, -v100, v101, v1
	v_mul_f32_e32 v100, 0xbfb8aa3b, v107
	v_exp_f32_e32 v100, v100
	v_div_fmas_f32 v1, v1, v104, v101
	v_div_fixup_f32 v1, v1, v2, v106
	v_mul_f32_e32 v1, v102, v1
	v_add_f32_e32 v2, 1.0, v100
	v_div_scale_f32 v100, s[10:11], v2, v2, v107
	v_rcp_f32_e32 v101, v100
	v_cvt_pk_bf16_f32 v1, v1, s0
	ds_write_b16 v132, v1 offset:2624
	v_readlane_b32 s69, v252, 7
	v_fma_f32 v1, -v100, v101, 1.0
	v_fmac_f32_e32 v101, v1, v101
	v_div_scale_f32 v1, vcc, v107, v2, v107
	v_mul_f32_e32 v102, v1, v101
	v_fma_f32 v104, -v100, v102, v1
	v_fmac_f32_e32 v102, v104, v101
	v_fma_f32 v1, -v100, v102, v1
	v_mul_f32_e32 v100, 0xbfb8aa3b, v96
	v_exp_f32_e32 v100, v100
	v_div_fmas_f32 v1, v1, v101, v102
	v_div_fixup_f32 v1, v1, v2, v107
	v_mul_f32_e32 v1, v103, v1
	v_add_f32_e32 v2, 1.0, v100
	v_div_scale_f32 v100, s[10:11], v2, v2, v96
	v_rcp_f32_e32 v101, v100
	v_cvt_pk_bf16_f32 v1, v1, s0
	ds_write_b16 v132, v1 offset:2768
	v_readlane_b32 s70, v252, 8
	v_fma_f32 v1, -v100, v101, 1.0
	v_fmac_f32_e32 v101, v1, v101
	v_div_scale_f32 v1, vcc, v96, v2, v96
	v_mul_f32_e32 v102, v1, v101
	v_fma_f32 v103, -v100, v102, v1
	v_fmac_f32_e32 v102, v103, v101
	v_fma_f32 v1, -v100, v102, v1
	v_mul_f32_e32 v100, 0xbfb8aa3b, v97
	v_exp_f32_e32 v100, v100
	v_div_fmas_f32 v1, v1, v101, v102
	v_div_fixup_f32 v1, v1, v2, v96
	v_mul_f32_e32 v1, v92, v1
	v_add_f32_e32 v2, 1.0, v100
	v_div_scale_f32 v96, s[10:11], v2, v2, v97
	v_rcp_f32_e32 v100, v96
	v_cvt_pk_bf16_f32 v1, v1, s0
	ds_write_b16 v132, v1 offset:4608
	v_readlane_b32 s71, v252, 9
	v_fma_f32 v1, -v96, v100, 1.0
	v_fmac_f32_e32 v100, v1, v100
	v_div_scale_f32 v1, vcc, v97, v2, v97
	v_mul_f32_e32 v92, v1, v100
	v_fma_f32 v101, -v96, v92, v1
	v_fmac_f32_e32 v92, v101, v100
	v_fma_f32 v1, -v96, v92, v1
	v_mul_f32_e32 v96, 0xbfb8aa3b, v98
	v_exp_f32_e32 v96, v96
	v_div_fmas_f32 v1, v1, v100, v92
	v_div_fixup_f32 v1, v1, v2, v97
	v_mul_f32_e32 v1, v93, v1
	v_add_f32_e32 v2, 1.0, v96
	v_div_scale_f32 v92, s[10:11], v2, v2, v98
	v_rcp_f32_e32 v96, v92
	v_cvt_pk_bf16_f32 v1, v1, s0
	ds_write_b16 v132, v1 offset:4752
	v_fma_f32 v1, -v92, v96, 1.0
	v_fmac_f32_e32 v96, v1, v96
	v_div_scale_f32 v1, vcc, v98, v2, v98
	v_mul_f32_e32 v93, v1, v96
	v_fma_f32 v97, -v92, v93, v1
	v_fmac_f32_e32 v93, v97, v96
	v_fma_f32 v1, -v92, v93, v1
	v_mul_f32_e32 v92, 0xbfb8aa3b, v99
	v_exp_f32_e32 v92, v92
	v_div_fmas_f32 v1, v1, v96, v93
	v_div_fixup_f32 v1, v1, v2, v98
	v_mul_f32_e32 v1, v94, v1
	v_add_f32_e32 v2, 1.0, v92
	v_div_scale_f32 v92, s[10:11], v2, v2, v99
	v_rcp_f32_e32 v93, v92
	v_cvt_pk_bf16_f32 v1, v1, s0
	ds_write_b16 v132, v1 offset:4896
	v_fma_f32 v1, -v92, v93, 1.0
	v_fmac_f32_e32 v93, v1, v93
	v_div_scale_f32 v1, vcc, v99, v2, v99
	v_mul_f32_e32 v94, v1, v93
	v_fma_f32 v96, -v92, v94, v1
	v_fmac_f32_e32 v94, v96, v93
	v_fma_f32 v1, -v92, v94, v1
	v_mul_f32_e32 v92, 0xbfb8aa3b, v88
	v_exp_f32_e32 v92, v92
	v_div_fmas_f32 v1, v1, v93, v94
	v_div_fixup_f32 v1, v1, v2, v99
	v_mul_f32_e32 v1, v95, v1
	v_add_f32_e32 v2, 1.0, v92
	v_div_scale_f32 v92, s[10:11], v2, v2, v88
	v_rcp_f32_e32 v93, v92
	v_cvt_pk_bf16_f32 v1, v1, s0
	ds_write_b16 v132, v1 offset:5040
	v_fma_f32 v1, -v92, v93, 1.0
	v_fmac_f32_e32 v93, v1, v93
	v_div_scale_f32 v1, vcc, v88, v2, v88
	v_mul_f32_e32 v94, v1, v93
	v_fma_f32 v95, -v92, v94, v1
	v_fmac_f32_e32 v94, v95, v93
	v_fma_f32 v1, -v92, v94, v1
	v_mul_f32_e32 v92, 0xbfb8aa3b, v89
	v_exp_f32_e32 v92, v92
	v_div_fmas_f32 v1, v1, v93, v94
	v_div_fixup_f32 v1, v1, v2, v88
	v_mul_f32_e32 v1, v84, v1
	v_add_f32_e32 v2, 1.0, v92
	v_div_scale_f32 v88, s[10:11], v2, v2, v89
	v_rcp_f32_e32 v92, v88
	v_cvt_pk_bf16_f32 v1, v1, s0
	ds_write_b16 v132, v1 offset:4640
	v_fma_f32 v1, -v88, v92, 1.0
	v_fmac_f32_e32 v92, v1, v92
	v_div_scale_f32 v1, vcc, v89, v2, v89
	v_mul_f32_e32 v84, v1, v92
	v_fma_f32 v93, -v88, v84, v1
	v_fmac_f32_e32 v84, v93, v92
	v_fma_f32 v1, -v88, v84, v1
	v_mul_f32_e32 v88, 0xbfb8aa3b, v90
	v_exp_f32_e32 v88, v88
	v_div_fmas_f32 v1, v1, v92, v84
	v_div_fixup_f32 v1, v1, v2, v89
	v_mul_f32_e32 v1, v85, v1
	v_add_f32_e32 v2, 1.0, v88
	v_div_scale_f32 v84, s[10:11], v2, v2, v90
	v_rcp_f32_e32 v88, v84
	v_cvt_pk_bf16_f32 v1, v1, s0
	ds_write_b16 v132, v1 offset:4784
	v_fma_f32 v1, -v84, v88, 1.0
	v_fmac_f32_e32 v88, v1, v88
	v_div_scale_f32 v1, vcc, v90, v2, v90
	v_mul_f32_e32 v85, v1, v88
	v_fma_f32 v89, -v84, v85, v1
	v_fmac_f32_e32 v85, v89, v88
	v_fma_f32 v1, -v84, v85, v1
	v_mul_f32_e32 v84, 0xbfb8aa3b, v91
	v_exp_f32_e32 v84, v84
	v_div_fmas_f32 v1, v1, v88, v85
	v_div_fixup_f32 v1, v1, v2, v90
	v_mul_f32_e32 v1, v86, v1
	v_add_f32_e32 v2, 1.0, v84
	v_div_scale_f32 v84, s[10:11], v2, v2, v91
	v_rcp_f32_e32 v85, v84
	v_cvt_pk_bf16_f32 v1, v1, s0
	ds_write_b16 v132, v1 offset:4928
	v_fma_f32 v1, -v84, v85, 1.0
	v_fmac_f32_e32 v85, v1, v85
	v_div_scale_f32 v1, vcc, v91, v2, v91
	v_mul_f32_e32 v86, v1, v85
	v_fma_f32 v88, -v84, v86, v1
	v_fmac_f32_e32 v86, v88, v85
; DEVI float silu_(float x) { return x / (1.f + __expf(-x)); }
; DEVI void ffn1_tile256(const P& p, const bf* W, long row0, int n0  , char* smem) {
;     ...
; #pragma unroll
;   for (int m = 0; m < 8; ++m)
; #pragma unroll
;     for (int pr = 0; pr < 2; ++pr) {
;       const int cl = (wc * 2 + pr) * 16 + l15;
; #pragma unroll
;       for (int j = 0; j < 4; ++j) {
;         const int rl = wr * 128 + m * 16 + quad * 4 + j;
;         float a = acc[m][2 * pr][j], b = acc[m][2 * pr + 1][j];
;         tl[rl * 72 + cl] = f2bf(silu_(a) * b);
;       }
;     }
;   __syncthreads();
	v_fma_f32 v1, -v84, v86, v1
	v_mul_f32_e32 v84, 0xbfb8aa3b, v80
	v_exp_f32_e32 v84, v84
	v_div_fmas_f32 v1, v1, v85, v86
	v_div_fixup_f32 v1, v1, v2, v91
	v_mul_f32_e32 v1, v87, v1
	v_add_f32_e32 v2, 1.0, v84
	v_div_scale_f32 v84, s[10:11], v2, v2, v80
	v_rcp_f32_e32 v85, v84
	v_cvt_pk_bf16_f32 v1, v1, s0
	ds_write_b16 v132, v1 offset:5072
	v_fma_f32 v1, -v84, v85, 1.0
	v_fmac_f32_e32 v85, v1, v85
	v_div_scale_f32 v1, vcc, v80, v2, v80
	v_mul_f32_e32 v86, v1, v85
	v_fma_f32 v87, -v84, v86, v1
	v_fmac_f32_e32 v86, v87, v85
	v_fma_f32 v1, -v84, v86, v1
	v_mul_f32_e32 v84, 0xbfb8aa3b, v81
	v_exp_f32_e32 v84, v84
	v_div_fmas_f32 v1, v1, v85, v86
	v_div_fixup_f32 v1, v1, v2, v80
	v_mul_f32_e32 v1, v76, v1
	v_add_f32_e32 v2, 1.0, v84
	v_div_scale_f32 v80, s[10:11], v2, v2, v81
	v_rcp_f32_e32 v84, v80
	v_cvt_pk_bf16_f32 v1, v1, s0
	ds_write_b16 v132, v1 offset:6912
	v_fma_f32 v1, -v80, v84, 1.0
	v_fmac_f32_e32 v84, v1, v84
	v_div_scale_f32 v1, vcc, v81, v2, v81
	v_mul_f32_e32 v76, v1, v84
	v_fma_f32 v85, -v80, v76, v1
	v_fmac_f32_e32 v76, v85, v84
	v_fma_f32 v1, -v80, v76, v1
	v_mul_f32_e32 v80, 0xbfb8aa3b, v82
	v_exp_f32_e32 v80, v80
	v_div_fmas_f32 v1, v1, v84, v76
	v_div_fixup_f32 v1, v1, v2, v81
	v_mul_f32_e32 v1, v77, v1
	v_add_f32_e32 v2, 1.0, v80
	v_div_scale_f32 v76, s[10:11], v2, v2, v82
	v_rcp_f32_e32 v80, v76
	v_cvt_pk_bf16_f32 v1, v1, s0
	ds_write_b16 v132, v1 offset:7056
	v_fma_f32 v1, -v76, v80, 1.0
	v_fmac_f32_e32 v80, v1, v80
	v_div_scale_f32 v1, vcc, v82, v2, v82
	v_mul_f32_e32 v77, v1, v80
	v_fma_f32 v81, -v76, v77, v1
	v_fmac_f32_e32 v77, v81, v80
	v_fma_f32 v1, -v76, v77, v1
	v_mul_f32_e32 v76, 0xbfb8aa3b, v83
	v_exp_f32_e32 v76, v76
	v_div_fmas_f32 v1, v1, v80, v77
	v_div_fixup_f32 v1, v1, v2, v82
	v_mul_f32_e32 v1, v78, v1
	v_add_f32_e32 v2, 1.0, v76
	v_div_scale_f32 v76, s[10:11], v2, v2, v83
	v_rcp_f32_e32 v77, v76
	v_cvt_pk_bf16_f32 v1, v1, s0
	ds_write_b16 v132, v1 offset:7200
	v_fma_f32 v1, -v76, v77, 1.0
	v_fmac_f32_e32 v77, v1, v77
	v_div_scale_f32 v1, vcc, v83, v2, v83
	v_mul_f32_e32 v78, v1, v77
	v_fma_f32 v80, -v76, v78, v1
	v_fmac_f32_e32 v78, v80, v77
	v_fma_f32 v1, -v76, v78, v1
	v_mul_f32_e32 v76, 0xbfb8aa3b, v72
	v_exp_f32_e32 v76, v76
	v_div_fmas_f32 v1, v1, v77, v78
	v_div_fixup_f32 v1, v1, v2, v83
	v_mul_f32_e32 v1, v79, v1
	v_add_f32_e32 v2, 1.0, v76
	v_div_scale_f32 v76, s[10:11], v2, v2, v72
	v_rcp_f32_e32 v77, v76
	v_cvt_pk_bf16_f32 v1, v1, s0
	ds_write_b16 v132, v1 offset:7344
	v_fma_f32 v1, -v76, v77, 1.0
	v_fmac_f32_e32 v77, v1, v77
	v_div_scale_f32 v1, vcc, v72, v2, v72
	v_mul_f32_e32 v78, v1, v77
	v_fma_f32 v79, -v76, v78, v1
	v_fmac_f32_e32 v78, v79, v77
	v_fma_f32 v1, -v76, v78, v1
	v_mul_f32_e32 v76, 0xbfb8aa3b, v73
	v_exp_f32_e32 v76, v76
	v_div_fmas_f32 v1, v1, v77, v78
	v_div_fixup_f32 v1, v1, v2, v72
	v_mul_f32_e32 v1, v68, v1
	v_add_f32_e32 v2, 1.0, v76
	v_div_scale_f32 v72, s[10:11], v2, v2, v73
	v_rcp_f32_e32 v76, v72
	v_cvt_pk_bf16_f32 v1, v1, s0
	ds_write_b16 v132, v1 offset:6944
	v_fma_f32 v1, -v72, v76, 1.0
	v_fmac_f32_e32 v76, v1, v76
	v_div_scale_f32 v1, vcc, v73, v2, v73
	v_mul_f32_e32 v68, v1, v76
	v_fma_f32 v77, -v72, v68, v1
	v_fmac_f32_e32 v68, v77, v76
	v_fma_f32 v1, -v72, v68, v1
	v_mul_f32_e32 v72, 0xbfb8aa3b, v74
	v_exp_f32_e32 v72, v72
	v_div_fmas_f32 v1, v1, v76, v68
	v_div_fixup_f32 v1, v1, v2, v73
	v_mul_f32_e32 v1, v69, v1
	v_add_f32_e32 v2, 1.0, v72
	v_div_scale_f32 v68, s[10:11], v2, v2, v74
	v_rcp_f32_e32 v72, v68
	v_cvt_pk_bf16_f32 v1, v1, s0
	ds_write_b16 v132, v1 offset:7088
	v_fma_f32 v1, -v68, v72, 1.0
	v_fmac_f32_e32 v72, v1, v72
	v_div_scale_f32 v1, vcc, v74, v2, v74
	v_mul_f32_e32 v69, v1, v72
	v_fma_f32 v73, -v68, v69, v1
	v_fmac_f32_e32 v69, v73, v72
	v_fma_f32 v1, -v68, v69, v1
	v_mul_f32_e32 v68, 0xbfb8aa3b, v75
	v_exp_f32_e32 v68, v68
	v_div_fmas_f32 v1, v1, v72, v69
	v_div_fixup_f32 v1, v1, v2, v74
	v_mul_f32_e32 v1, v70, v1
	v_add_f32_e32 v2, 1.0, v68
	v_div_scale_f32 v68, s[10:11], v2, v2, v75
	v_rcp_f32_e32 v69, v68
	v_cvt_pk_bf16_f32 v1, v1, s0
	ds_write_b16 v132, v1 offset:7232
	v_fma_f32 v1, -v68, v69, 1.0
	v_fmac_f32_e32 v69, v1, v69
	v_div_scale_f32 v1, vcc, v75, v2, v75
	v_mul_f32_e32 v70, v1, v69
	v_fma_f32 v72, -v68, v70, v1
	v_fmac_f32_e32 v70, v72, v69
	v_fma_f32 v1, -v68, v70, v1
	v_mul_f32_e32 v68, 0xbfb8aa3b, v64
	v_exp_f32_e32 v68, v68
	v_div_fmas_f32 v1, v1, v69, v70
	v_div_fixup_f32 v1, v1, v2, v75
	v_mul_f32_e32 v1, v71, v1
	v_add_f32_e32 v2, 1.0, v68
	v_div_scale_f32 v68, s[10:11], v2, v2, v64
	v_rcp_f32_e32 v69, v68
	v_cvt_pk_bf16_f32 v1, v1, s0
	ds_write_b16 v132, v1 offset:7376
	v_fma_f32 v1, -v68, v69, 1.0
	v_fmac_f32_e32 v69, v1, v69
	v_div_scale_f32 v1, vcc, v64, v2, v64
	v_mul_f32_e32 v70, v1, v69
	v_fma_f32 v71, -v68, v70, v1
	v_fmac_f32_e32 v70, v71, v69
	v_fma_f32 v1, -v68, v70, v1
	v_mul_f32_e32 v68, 0xbfb8aa3b, v65
	v_exp_f32_e32 v68, v68
	v_div_fmas_f32 v1, v1, v69, v70
	v_div_fixup_f32 v1, v1, v2, v64
	v_mul_f32_e32 v1, v60, v1
	v_add_f32_e32 v2, 1.0, v68
	v_div_scale_f32 v64, s[10:11], v2, v2, v65
	v_rcp_f32_e32 v68, v64
	v_cvt_pk_bf16_f32 v1, v1, s0
	ds_write_b16 v132, v1 offset:9216
	v_fma_f32 v1, -v64, v68, 1.0
	v_fmac_f32_e32 v68, v1, v68
	v_div_scale_f32 v1, vcc, v65, v2, v65
	v_mul_f32_e32 v60, v1, v68
	v_fma_f32 v69, -v64, v60, v1
	v_fmac_f32_e32 v60, v69, v68
	v_fma_f32 v1, -v64, v60, v1
	v_mul_f32_e32 v64, 0xbfb8aa3b, v66
	v_exp_f32_e32 v64, v64
	v_div_fmas_f32 v1, v1, v68, v60
	v_div_fixup_f32 v1, v1, v2, v65
	v_mul_f32_e32 v1, v61, v1
	v_add_f32_e32 v2, 1.0, v64
	v_div_scale_f32 v60, s[10:11], v2, v2, v66
	v_rcp_f32_e32 v64, v60
	v_cvt_pk_bf16_f32 v1, v1, s0
	ds_write_b16 v132, v1 offset:9360
; DEVI float silu_(float x) { return x / (1.f + __expf(-x)); }
; DEVI void ffn1_tile256(const P& p, const bf* W, long row0, int n0  , char* smem) {
;     ...
; #pragma unroll
;   for (int m = 0; m < 8; ++m)
; #pragma unroll
;     for (int pr = 0; pr < 2; ++pr) {
;       const int cl = (wc * 2 + pr) * 16 + l15;
; #pragma unroll
;       for (int j = 0; j < 4; ++j) {
;         const int rl = wr * 128 + m * 16 + quad * 4 + j;
;         float a = acc[m][2 * pr][j], b = acc[m][2 * pr + 1][j];
;         tl[rl * 72 + cl] = f2bf(silu_(a) * b);
;       }
;     }
;   __syncthreads();
	v_fma_f32 v1, -v60, v64, 1.0
	v_fmac_f32_e32 v64, v1, v64
	v_div_scale_f32 v1, vcc, v66, v2, v66
	v_mul_f32_e32 v61, v1, v64
	v_fma_f32 v65, -v60, v61, v1
	v_fmac_f32_e32 v61, v65, v64
	v_fma_f32 v1, -v60, v61, v1
	v_mul_f32_e32 v60, 0xbfb8aa3b, v67
	v_exp_f32_e32 v60, v60
	v_div_fmas_f32 v1, v1, v64, v61
	v_div_fixup_f32 v1, v1, v2, v66
	v_mul_f32_e32 v1, v62, v1
	v_add_f32_e32 v2, 1.0, v60
	v_div_scale_f32 v60, s[10:11], v2, v2, v67
	v_rcp_f32_e32 v61, v60
	v_cvt_pk_bf16_f32 v1, v1, s0
	ds_write_b16 v132, v1 offset:9504
	v_fma_f32 v1, -v60, v61, 1.0
	v_fmac_f32_e32 v61, v1, v61
	v_div_scale_f32 v1, vcc, v67, v2, v67
	v_mul_f32_e32 v62, v1, v61
	v_fma_f32 v64, -v60, v62, v1
	v_fmac_f32_e32 v62, v64, v61
	v_fma_f32 v1, -v60, v62, v1
	v_mul_f32_e32 v60, 0xbfb8aa3b, v56
	v_exp_f32_e32 v60, v60
	v_div_fmas_f32 v1, v1, v61, v62
	v_div_fixup_f32 v1, v1, v2, v67
	v_mul_f32_e32 v1, v63, v1
	v_add_f32_e32 v2, 1.0, v60
	v_div_scale_f32 v60, s[10:11], v2, v2, v56
	v_rcp_f32_e32 v61, v60
	v_cvt_pk_bf16_f32 v1, v1, s0
	ds_write_b16 v132, v1 offset:9648
	v_fma_f32 v1, -v60, v61, 1.0
	v_fmac_f32_e32 v61, v1, v61
	v_div_scale_f32 v1, vcc, v56, v2, v56
	v_mul_f32_e32 v62, v1, v61
	v_fma_f32 v63, -v60, v62, v1
	v_fmac_f32_e32 v62, v63, v61
	v_fma_f32 v1, -v60, v62, v1
	v_mul_f32_e32 v60, 0xbfb8aa3b, v57
	v_exp_f32_e32 v60, v60
	v_div_fmas_f32 v1, v1, v61, v62
	v_div_fixup_f32 v1, v1, v2, v56
	v_mul_f32_e32 v1, v52, v1
	v_add_f32_e32 v2, 1.0, v60
	v_div_scale_f32 v56, s[10:11], v2, v2, v57
	v_rcp_f32_e32 v60, v56
	v_cvt_pk_bf16_f32 v1, v1, s0
	ds_write_b16 v132, v1 offset:9248
	v_fma_f32 v1, -v56, v60, 1.0
	v_fmac_f32_e32 v60, v1, v60
	v_div_scale_f32 v1, vcc, v57, v2, v57
	v_mul_f32_e32 v52, v1, v60
	v_fma_f32 v61, -v56, v52, v1
	v_fmac_f32_e32 v52, v61, v60
	v_fma_f32 v1, -v56, v52, v1
	v_mul_f32_e32 v56, 0xbfb8aa3b, v58
	v_exp_f32_e32 v56, v56
	v_div_fmas_f32 v1, v1, v60, v52
	v_div_fixup_f32 v1, v1, v2, v57
	v_mul_f32_e32 v1, v53, v1
	v_add_f32_e32 v2, 1.0, v56
	v_div_scale_f32 v52, s[10:11], v2, v2, v58
	v_rcp_f32_e32 v56, v52
	v_cvt_pk_bf16_f32 v1, v1, s0
	ds_write_b16 v132, v1 offset:9392
	v_fma_f32 v1, -v52, v56, 1.0
	v_fmac_f32_e32 v56, v1, v56
	v_div_scale_f32 v1, vcc, v58, v2, v58
	v_mul_f32_e32 v53, v1, v56
	v_fma_f32 v57, -v52, v53, v1
	v_fmac_f32_e32 v53, v57, v56
	v_fma_f32 v1, -v52, v53, v1
	v_mul_f32_e32 v52, 0xbfb8aa3b, v59
	v_exp_f32_e32 v52, v52
	v_div_fmas_f32 v1, v1, v56, v53
	v_div_fixup_f32 v1, v1, v2, v58
	v_mul_f32_e32 v1, v54, v1
	v_add_f32_e32 v2, 1.0, v52
	v_div_scale_f32 v52, s[10:11], v2, v2, v59
	v_rcp_f32_e32 v53, v52
	v_cvt_pk_bf16_f32 v1, v1, s0
	ds_write_b16 v132, v1 offset:9536
	v_fma_f32 v1, -v52, v53, 1.0
	v_fmac_f32_e32 v53, v1, v53
	v_div_scale_f32 v1, vcc, v59, v2, v59
	v_mul_f32_e32 v54, v1, v53
	v_fma_f32 v56, -v52, v54, v1
	v_fmac_f32_e32 v54, v56, v53
	v_fma_f32 v1, -v52, v54, v1
	v_mul_f32_e32 v52, 0xbfb8aa3b, v48
	v_exp_f32_e32 v52, v52
	v_div_fmas_f32 v1, v1, v53, v54
	v_div_fixup_f32 v1, v1, v2, v59
	v_mul_f32_e32 v1, v55, v1
	v_add_f32_e32 v2, 1.0, v52
	v_div_scale_f32 v52, s[10:11], v2, v2, v48
	v_rcp_f32_e32 v53, v52
	v_cvt_pk_bf16_f32 v1, v1, s0
	ds_write_b16 v132, v1 offset:9680
	v_fma_f32 v1, -v52, v53, 1.0
	v_fmac_f32_e32 v53, v1, v53
	v_div_scale_f32 v1, vcc, v48, v2, v48
	v_mul_f32_e32 v54, v1, v53
	v_fma_f32 v55, -v52, v54, v1
	v_fmac_f32_e32 v54, v55, v53
	v_fma_f32 v1, -v52, v54, v1
	v_mul_f32_e32 v52, 0xbfb8aa3b, v49
	v_exp_f32_e32 v52, v52
	v_div_fmas_f32 v1, v1, v53, v54
	v_div_fixup_f32 v1, v1, v2, v48
	v_mul_f32_e32 v1, v44, v1
	v_add_f32_e32 v2, 1.0, v52
	v_div_scale_f32 v48, s[10:11], v2, v2, v49
	v_rcp_f32_e32 v52, v48
	v_cvt_pk_bf16_f32 v1, v1, s0
	ds_write_b16 v132, v1 offset:11520
	v_fma_f32 v1, -v48, v52, 1.0
	v_fmac_f32_e32 v52, v1, v52
	v_div_scale_f32 v1, vcc, v49, v2, v49
	v_mul_f32_e32 v44, v1, v52
	v_fma_f32 v53, -v48, v44, v1
	v_fmac_f32_e32 v44, v53, v52
	v_fma_f32 v1, -v48, v44, v1
	v_mul_f32_e32 v48, 0xbfb8aa3b, v50
	v_exp_f32_e32 v48, v48
	v_div_fmas_f32 v1, v1, v52, v44
	v_div_fixup_f32 v1, v1, v2, v49
	v_mul_f32_e32 v1, v45, v1
	v_add_f32_e32 v2, 1.0, v48
	v_div_scale_f32 v44, s[10:11], v2, v2, v50
	v_rcp_f32_e32 v48, v44
	v_cvt_pk_bf16_f32 v1, v1, s0
	ds_write_b16 v132, v1 offset:11664
	v_fma_f32 v1, -v44, v48, 1.0
	v_fmac_f32_e32 v48, v1, v48
	v_div_scale_f32 v1, vcc, v50, v2, v50
	v_mul_f32_e32 v45, v1, v48
	v_fma_f32 v49, -v44, v45, v1
	v_fmac_f32_e32 v45, v49, v48
	v_fma_f32 v1, -v44, v45, v1
	v_mul_f32_e32 v44, 0xbfb8aa3b, v51
	v_exp_f32_e32 v44, v44
	v_div_fmas_f32 v1, v1, v48, v45
	v_div_fixup_f32 v1, v1, v2, v50
	v_mul_f32_e32 v1, v46, v1
	v_add_f32_e32 v2, 1.0, v44
	v_div_scale_f32 v44, s[10:11], v2, v2, v51
	v_rcp_f32_e32 v45, v44
	v_cvt_pk_bf16_f32 v1, v1, s0
	ds_write_b16 v132, v1 offset:11808
	v_fma_f32 v1, -v44, v45, 1.0
	v_fmac_f32_e32 v45, v1, v45
	v_div_scale_f32 v1, vcc, v51, v2, v51
	v_mul_f32_e32 v46, v1, v45
	v_fma_f32 v48, -v44, v46, v1
	v_fmac_f32_e32 v46, v48, v45
	v_fma_f32 v1, -v44, v46, v1
	v_mul_f32_e32 v44, 0xbfb8aa3b, v40
	v_exp_f32_e32 v44, v44
	v_div_fmas_f32 v1, v1, v45, v46
	v_div_fixup_f32 v1, v1, v2, v51
	v_mul_f32_e32 v1, v47, v1
	v_add_f32_e32 v2, 1.0, v44
	v_div_scale_f32 v44, s[10:11], v2, v2, v40
	v_rcp_f32_e32 v45, v44
	v_cvt_pk_bf16_f32 v1, v1, s0
	ds_write_b16 v132, v1 offset:11952
	v_fma_f32 v1, -v44, v45, 1.0
	v_fmac_f32_e32 v45, v1, v45
	v_div_scale_f32 v1, vcc, v40, v2, v40
	v_mul_f32_e32 v46, v1, v45
	v_fma_f32 v47, -v44, v46, v1
	v_fmac_f32_e32 v46, v47, v45
	v_fma_f32 v1, -v44, v46, v1
	v_mul_f32_e32 v44, 0xbfb8aa3b, v41
	v_exp_f32_e32 v44, v44
	v_div_fmas_f32 v1, v1, v45, v46
	v_div_fixup_f32 v1, v1, v2, v40
; DEVI float silu_(float x) { return x / (1.f + __expf(-x)); }
; DEVI void ffn1_tile256(const P& p, const bf* W, long row0, int n0  , char* smem) {
;     ...
; #pragma unroll
;   for (int m = 0; m < 8; ++m)
; #pragma unroll
;     for (int pr = 0; pr < 2; ++pr) {
;       const int cl = (wc * 2 + pr) * 16 + l15;
; #pragma unroll
;       for (int j = 0; j < 4; ++j) {
;         const int rl = wr * 128 + m * 16 + quad * 4 + j;
;         float a = acc[m][2 * pr][j], b = acc[m][2 * pr + 1][j];
;         tl[rl * 72 + cl] = f2bf(silu_(a) * b);
;       }
;     }
;   __syncthreads();
	v_mul_f32_e32 v1, v36, v1
	v_add_f32_e32 v2, 1.0, v44
	v_div_scale_f32 v40, s[10:11], v2, v2, v41
	v_rcp_f32_e32 v44, v40
	v_cvt_pk_bf16_f32 v1, v1, s0
	ds_write_b16 v132, v1 offset:11552
	v_fma_f32 v1, -v40, v44, 1.0
	v_fmac_f32_e32 v44, v1, v44
	v_div_scale_f32 v1, vcc, v41, v2, v41
	v_mul_f32_e32 v36, v1, v44
	v_fma_f32 v45, -v40, v36, v1
	v_fmac_f32_e32 v36, v45, v44
	v_fma_f32 v1, -v40, v36, v1
	v_mul_f32_e32 v40, 0xbfb8aa3b, v42
	v_exp_f32_e32 v40, v40
	v_div_fmas_f32 v1, v1, v44, v36
	v_div_fixup_f32 v1, v1, v2, v41
	v_mul_f32_e32 v1, v37, v1
	v_add_f32_e32 v2, 1.0, v40
	v_div_scale_f32 v36, s[10:11], v2, v2, v42
	v_rcp_f32_e32 v40, v36
	v_cvt_pk_bf16_f32 v1, v1, s0
	ds_write_b16 v132, v1 offset:11696
	v_fma_f32 v1, -v36, v40, 1.0
	v_fmac_f32_e32 v40, v1, v40
	v_div_scale_f32 v1, vcc, v42, v2, v42
	v_mul_f32_e32 v37, v1, v40
	v_fma_f32 v41, -v36, v37, v1
	v_fmac_f32_e32 v37, v41, v40
	v_fma_f32 v1, -v36, v37, v1
	v_mul_f32_e32 v36, 0xbfb8aa3b, v43
	v_exp_f32_e32 v36, v36
	v_div_fmas_f32 v1, v1, v40, v37
	v_div_fixup_f32 v1, v1, v2, v42
	v_mul_f32_e32 v1, v38, v1
	v_add_f32_e32 v2, 1.0, v36
	v_div_scale_f32 v36, s[10:11], v2, v2, v43
	v_rcp_f32_e32 v37, v36
	v_cvt_pk_bf16_f32 v1, v1, s0
	ds_write_b16 v132, v1 offset:11840
	v_fma_f32 v1, -v36, v37, 1.0
	v_fmac_f32_e32 v37, v1, v37
	v_div_scale_f32 v1, vcc, v43, v2, v43
	v_mul_f32_e32 v38, v1, v37
	v_fma_f32 v40, -v36, v38, v1
	v_fmac_f32_e32 v38, v40, v37
	v_fma_f32 v1, -v36, v38, v1
	v_mul_f32_e32 v36, 0xbfb8aa3b, v32
	v_exp_f32_e32 v36, v36
	v_div_fmas_f32 v1, v1, v37, v38
	v_div_fixup_f32 v1, v1, v2, v43
	v_mul_f32_e32 v1, v39, v1
	v_add_f32_e32 v2, 1.0, v36
	v_div_scale_f32 v36, s[10:11], v2, v2, v32
	v_rcp_f32_e32 v37, v36
	v_cvt_pk_bf16_f32 v1, v1, s0
	ds_write_b16 v132, v1 offset:11984
	v_fma_f32 v1, -v36, v37, 1.0
	v_fmac_f32_e32 v37, v1, v37
	v_div_scale_f32 v1, vcc, v32, v2, v32
	v_mul_f32_e32 v38, v1, v37
	v_fma_f32 v39, -v36, v38, v1
	v_fmac_f32_e32 v38, v39, v37
	v_fma_f32 v1, -v36, v38, v1
	v_mul_f32_e32 v36, 0xbfb8aa3b, v33
	v_exp_f32_e32 v36, v36
	v_div_fmas_f32 v1, v1, v37, v38
	v_div_fixup_f32 v1, v1, v2, v32
	v_mul_f32_e32 v1, v28, v1
	v_add_f32_e32 v2, 1.0, v36
	v_div_scale_f32 v32, s[10:11], v2, v2, v33
	v_rcp_f32_e32 v36, v32
	v_cvt_pk_bf16_f32 v1, v1, s0
	ds_write_b16 v132, v1 offset:13824
	v_fma_f32 v1, -v32, v36, 1.0
	v_fmac_f32_e32 v36, v1, v36
	v_div_scale_f32 v1, vcc, v33, v2, v33
	v_mul_f32_e32 v28, v1, v36
	v_fma_f32 v37, -v32, v28, v1
	v_fmac_f32_e32 v28, v37, v36
	v_fma_f32 v1, -v32, v28, v1
	v_mul_f32_e32 v32, 0xbfb8aa3b, v34
	v_exp_f32_e32 v32, v32
	v_div_fmas_f32 v1, v1, v36, v28
	v_div_fixup_f32 v1, v1, v2, v33
	v_mul_f32_e32 v1, v29, v1
	v_add_f32_e32 v2, 1.0, v32
	v_div_scale_f32 v28, s[10:11], v2, v2, v34
	v_rcp_f32_e32 v32, v28
	v_cvt_pk_bf16_f32 v1, v1, s0
	ds_write_b16 v132, v1 offset:13968
	v_fma_f32 v1, -v28, v32, 1.0
	v_fmac_f32_e32 v32, v1, v32
	v_div_scale_f32 v1, vcc, v34, v2, v34
	v_mul_f32_e32 v29, v1, v32
	v_fma_f32 v33, -v28, v29, v1
	v_fmac_f32_e32 v29, v33, v32
	v_fma_f32 v1, -v28, v29, v1
	v_mul_f32_e32 v28, 0xbfb8aa3b, v35
	v_exp_f32_e32 v28, v28
	v_div_fmas_f32 v1, v1, v32, v29
	v_div_fixup_f32 v1, v1, v2, v34
	v_mul_f32_e32 v1, v30, v1
	v_add_f32_e32 v2, 1.0, v28
	v_div_scale_f32 v28, s[10:11], v2, v2, v35
	v_rcp_f32_e32 v29, v28
	v_cvt_pk_bf16_f32 v1, v1, s0
	ds_write_b16 v132, v1 offset:14112
	v_fma_f32 v1, -v28, v29, 1.0
	v_fmac_f32_e32 v29, v1, v29
	v_div_scale_f32 v1, vcc, v35, v2, v35
	v_mul_f32_e32 v30, v1, v29
	v_fma_f32 v32, -v28, v30, v1
	v_fmac_f32_e32 v30, v32, v29
	v_fma_f32 v1, -v28, v30, v1
	v_mul_f32_e32 v28, 0xbfb8aa3b, v24
	v_exp_f32_e32 v28, v28
	v_div_fmas_f32 v1, v1, v29, v30
	v_div_fixup_f32 v1, v1, v2, v35
	v_mul_f32_e32 v1, v31, v1
	v_add_f32_e32 v2, 1.0, v28
	v_div_scale_f32 v28, s[10:11], v2, v2, v24
	v_rcp_f32_e32 v29, v28
	v_cvt_pk_bf16_f32 v1, v1, s0
	ds_write_b16 v132, v1 offset:14256
	v_fma_f32 v1, -v28, v29, 1.0
	v_fmac_f32_e32 v29, v1, v29
	v_div_scale_f32 v1, vcc, v24, v2, v24
	v_mul_f32_e32 v30, v1, v29
	v_fma_f32 v31, -v28, v30, v1
	v_fmac_f32_e32 v30, v31, v29
	v_fma_f32 v1, -v28, v30, v1
	v_mul_f32_e32 v28, 0xbfb8aa3b, v25
	v_exp_f32_e32 v28, v28
	v_div_fmas_f32 v1, v1, v29, v30
	v_div_fixup_f32 v1, v1, v2, v24
	v_mul_f32_e32 v1, v20, v1
	v_add_f32_e32 v2, 1.0, v28
	v_div_scale_f32 v24, s[10:11], v2, v2, v25
	v_rcp_f32_e32 v28, v24
	v_cvt_pk_bf16_f32 v1, v1, s0
	ds_write_b16 v132, v1 offset:13856
	v_fma_f32 v1, -v24, v28, 1.0
	v_fmac_f32_e32 v28, v1, v28
	v_div_scale_f32 v1, vcc, v25, v2, v25
	v_mul_f32_e32 v20, v1, v28
	v_fma_f32 v29, -v24, v20, v1
	v_fmac_f32_e32 v20, v29, v28
	v_fma_f32 v1, -v24, v20, v1
	v_mul_f32_e32 v24, 0xbfb8aa3b, v26
	v_exp_f32_e32 v24, v24
	v_div_fmas_f32 v1, v1, v28, v20
	v_div_fixup_f32 v1, v1, v2, v25
	v_mul_f32_e32 v1, v21, v1
	v_add_f32_e32 v2, 1.0, v24
	v_div_scale_f32 v20, s[10:11], v2, v2, v26
	v_rcp_f32_e32 v24, v20
	v_cvt_pk_bf16_f32 v1, v1, s0
	ds_write_b16 v132, v1 offset:14000
	v_fma_f32 v1, -v20, v24, 1.0
	v_fmac_f32_e32 v24, v1, v24
	v_div_scale_f32 v1, vcc, v26, v2, v26
	v_mul_f32_e32 v21, v1, v24
	v_fma_f32 v25, -v20, v21, v1
	v_fmac_f32_e32 v21, v25, v24
	v_fma_f32 v1, -v20, v21, v1
	v_mul_f32_e32 v20, 0xbfb8aa3b, v27
	v_exp_f32_e32 v20, v20
	v_div_fmas_f32 v1, v1, v24, v21
	v_div_fixup_f32 v1, v1, v2, v26
	v_mul_f32_e32 v1, v22, v1
	v_add_f32_e32 v2, 1.0, v20
	v_div_scale_f32 v20, s[10:11], v2, v2, v27
	v_rcp_f32_e32 v21, v20
	v_cvt_pk_bf16_f32 v1, v1, s0
	ds_write_b16 v132, v1 offset:14144
	v_fma_f32 v1, -v20, v21, 1.0
	v_fmac_f32_e32 v21, v1, v21
	v_div_scale_f32 v1, vcc, v27, v2, v27
	v_mul_f32_e32 v22, v1, v21
	v_fma_f32 v24, -v20, v22, v1
; DEVI float silu_(float x) { return x / (1.f + __expf(-x)); }
; DEVI void ffn1_tile256(const P& p, const bf* W, long row0, int n0  , char* smem) {
;     ...
; #pragma unroll
;   for (int m = 0; m < 8; ++m)
; #pragma unroll
;     for (int pr = 0; pr < 2; ++pr) {
;       const int cl = (wc * 2 + pr) * 16 + l15;
; #pragma unroll
;       for (int j = 0; j < 4; ++j) {
;         const int rl = wr * 128 + m * 16 + quad * 4 + j;
;         float a = acc[m][2 * pr][j], b = acc[m][2 * pr + 1][j];
;         tl[rl * 72 + cl] = f2bf(silu_(a) * b);
;       }
;     }
;   __syncthreads();
	v_fmac_f32_e32 v22, v24, v21
	v_fma_f32 v1, -v20, v22, v1
	v_mul_f32_e32 v20, 0xbfb8aa3b, v16
	v_exp_f32_e32 v20, v20
	v_div_fmas_f32 v1, v1, v21, v22
	v_div_fixup_f32 v1, v1, v2, v27
	v_mul_f32_e32 v1, v23, v1
	v_add_f32_e32 v2, 1.0, v20
	v_div_scale_f32 v20, s[10:11], v2, v2, v16
	v_rcp_f32_e32 v21, v20
	v_cvt_pk_bf16_f32 v1, v1, s0
	ds_write_b16 v132, v1 offset:14288
	v_fma_f32 v1, -v20, v21, 1.0
	v_fmac_f32_e32 v21, v1, v21
	v_div_scale_f32 v1, vcc, v16, v2, v16
	v_mul_f32_e32 v22, v1, v21
	v_fma_f32 v23, -v20, v22, v1
	v_fmac_f32_e32 v22, v23, v21
	v_fma_f32 v1, -v20, v22, v1
	v_mul_f32_e32 v20, 0xbfb8aa3b, v17
	v_exp_f32_e32 v20, v20
	v_div_fmas_f32 v1, v1, v21, v22
	v_div_fixup_f32 v1, v1, v2, v16
	v_mul_f32_e32 v1, v12, v1
	v_add_f32_e32 v2, 1.0, v20
	v_div_scale_f32 v16, s[10:11], v2, v2, v17
	v_rcp_f32_e32 v20, v16
	v_cvt_pk_bf16_f32 v1, v1, s0
	ds_write_b16 v132, v1 offset:16128
	v_fma_f32 v1, -v16, v20, 1.0
	v_fmac_f32_e32 v20, v1, v20
	v_div_scale_f32 v1, vcc, v17, v2, v17
	v_mul_f32_e32 v12, v1, v20
	v_fma_f32 v21, -v16, v12, v1
	v_fmac_f32_e32 v12, v21, v20
	v_fma_f32 v1, -v16, v12, v1
	v_mul_f32_e32 v16, 0xbfb8aa3b, v18
	v_exp_f32_e32 v16, v16
	v_div_fmas_f32 v1, v1, v20, v12
	v_div_fixup_f32 v1, v1, v2, v17
	v_mul_f32_e32 v1, v13, v1
	v_add_f32_e32 v2, 1.0, v16
	v_div_scale_f32 v12, s[10:11], v2, v2, v18
	v_rcp_f32_e32 v16, v12
	v_cvt_pk_bf16_f32 v1, v1, s0
	ds_write_b16 v132, v1 offset:16272
	v_fma_f32 v1, -v12, v16, 1.0
	v_fmac_f32_e32 v16, v1, v16
	v_div_scale_f32 v1, vcc, v18, v2, v18
	v_mul_f32_e32 v13, v1, v16
	v_fma_f32 v17, -v12, v13, v1
	v_fmac_f32_e32 v13, v17, v16
	v_fma_f32 v1, -v12, v13, v1
	v_mul_f32_e32 v12, 0xbfb8aa3b, v19
	v_exp_f32_e32 v12, v12
	v_div_fmas_f32 v1, v1, v16, v13
	v_div_fixup_f32 v1, v1, v2, v18
	v_mul_f32_e32 v1, v14, v1
	v_add_f32_e32 v2, 1.0, v12
	v_div_scale_f32 v12, s[10:11], v2, v2, v19
	v_rcp_f32_e32 v13, v12
	v_cvt_pk_bf16_f32 v1, v1, s0
	ds_write_b16 v132, v1 offset:16416
	v_fma_f32 v1, -v12, v13, 1.0
	v_fmac_f32_e32 v13, v1, v13
	v_div_scale_f32 v1, vcc, v19, v2, v19
	v_mul_f32_e32 v14, v1, v13
	v_fma_f32 v16, -v12, v14, v1
	v_fmac_f32_e32 v14, v16, v13
	v_fma_f32 v1, -v12, v14, v1
	v_mul_f32_e32 v12, 0xbfb8aa3b, v8
	v_exp_f32_e32 v12, v12
	v_div_fmas_f32 v1, v1, v13, v14
	v_div_fixup_f32 v1, v1, v2, v19
	v_mul_f32_e32 v1, v15, v1
	v_add_f32_e32 v2, 1.0, v12
	v_div_scale_f32 v12, s[10:11], v2, v2, v8
	v_rcp_f32_e32 v13, v12
	v_cvt_pk_bf16_f32 v1, v1, s0
	ds_write_b16 v132, v1 offset:16560
	v_fma_f32 v1, -v12, v13, 1.0
	v_fmac_f32_e32 v13, v1, v13
	v_div_scale_f32 v1, vcc, v8, v2, v8
	v_mul_f32_e32 v14, v1, v13
	v_fma_f32 v15, -v12, v14, v1
	v_fmac_f32_e32 v14, v15, v13
	v_fma_f32 v1, -v12, v14, v1
	v_mul_f32_e32 v12, 0xbfb8aa3b, v9
	v_exp_f32_e32 v12, v12
	v_div_fmas_f32 v1, v1, v13, v14
	v_div_fixup_f32 v1, v1, v2, v8
	v_mul_f32_e32 v1, v4, v1
	v_add_f32_e32 v2, 1.0, v12
	v_div_scale_f32 v8, s[10:11], v2, v2, v9
	v_rcp_f32_e32 v12, v8
	v_cvt_pk_bf16_f32 v1, v1, s0
	ds_write_b16 v132, v1 offset:16160
	v_fma_f32 v1, -v8, v12, 1.0
	v_fmac_f32_e32 v12, v1, v12
	v_div_scale_f32 v1, vcc, v9, v2, v9
	v_mul_f32_e32 v4, v1, v12
	v_fma_f32 v13, -v8, v4, v1
	v_fmac_f32_e32 v4, v13, v12
	v_fma_f32 v1, -v8, v4, v1
	v_mul_f32_e32 v8, 0xbfb8aa3b, v10
	v_exp_f32_e32 v8, v8
	v_div_fmas_f32 v1, v1, v12, v4
	v_div_fixup_f32 v1, v1, v2, v9
	v_mul_f32_e32 v1, v5, v1
	v_add_f32_e32 v2, 1.0, v8
	v_div_scale_f32 v4, s[10:11], v2, v2, v10
	v_rcp_f32_e32 v8, v4
	v_cvt_pk_bf16_f32 v1, v1, s0
	ds_write_b16 v132, v1 offset:16304
	v_fma_f32 v1, -v4, v8, 1.0
	v_fmac_f32_e32 v8, v1, v8
	v_div_scale_f32 v1, vcc, v10, v2, v10
	v_mul_f32_e32 v5, v1, v8
	v_fma_f32 v9, -v4, v5, v1
	v_fmac_f32_e32 v5, v9, v8
	v_fma_f32 v1, -v4, v5, v1
	v_mul_f32_e32 v4, 0xbfb8aa3b, v11
	v_exp_f32_e32 v4, v4
	v_div_fmas_f32 v1, v1, v8, v5
	v_div_fixup_f32 v1, v1, v2, v10
	v_mul_f32_e32 v1, v6, v1
	v_add_f32_e32 v2, 1.0, v4
	v_div_scale_f32 v4, s[10:11], v2, v2, v11
	v_rcp_f32_e32 v5, v4
	v_cvt_pk_bf16_f32 v1, v1, s0
	ds_write_b16 v132, v1 offset:16448
	s_ashr_i32 s10, s38, 1
	v_fma_f32 v1, -v4, v5, 1.0
	v_fmac_f32_e32 v5, v1, v5
	v_div_scale_f32 v1, vcc, v11, v2, v11
	v_mul_f32_e32 v6, v1, v5
	v_fma_f32 v8, -v4, v6, v1
	v_fmac_f32_e32 v6, v8, v5
	v_fma_f32 v1, -v4, v6, v1
	v_div_fmas_f32 v1, v1, v5, v6
	v_div_fixup_f32 v1, v1, v2, v11
	v_mul_f32_e32 v1, v7, v1
	v_cvt_pk_bf16_f32 v1, v1, s0
	ds_write_b16 v132, v1 offset:16592
	v_mov_b32_e32 v1, v178
	s_waitcnt lgkmcnt(0)
	s_barrier
; DEVI int get_tid() { int t = threadIdx.x; asm volatile("" : "+v"(t)); return t; }
; template <int BN>
; DEVI void tile_store256(const char* smem, bf* __restrict__ C, long ldc, long row0, int col0) {
;   constexpr int LDT = BN + 8;
;   constexpr int CPR = BN / 8;
;   const int tid = get_tid();
; #pragma unroll
;   for (int i = 0; i < CPR; ++i) {
;     const int q = tid + 256 * i;
;     const int r = q / CPR, c = q - r * CPR;
;     u32x4 v = *reinterpret_cast<const u32x4*>(smem + (r * LDT + c * 8) * 2);
;     *reinterpret_cast<u32x4*>(C + (row0 + r) * ldc + col0 + c * 8) = v;
;   }
; }
; DEVI void ffn1_tile256(const P& p, const bf* W, long row0, int n0  , char* smem) {
;     ...
;   tile_store256<64>(smem, p.UZ, DFF, row0, n0 / 2);
;   __syncthreads();
; DEVI void phase_ffn1(const P& p, int f, char* smem) {
;     ...
;   for (int v = blockIdx.x; v < 128 * 44; v += gridDim.x) {
;     int m2, nt;
;     lat_tile_map256(v, 44, m2, nt);
;     ffn1_tile256(p, W, lat_row0_256(m2), nt * 128, smem);
	s_ashr_i32 s11, s10, 31
	v_ashrrev_i32_e32 v2, 31, v1
	v_lshrrev_b32_e32 v2, 29, v2
	s_lshl_b64 s[10:11], s[10:11], 1
	v_add_u32_e32 v2, v1, v2
	s_add_u32 s10, s58, s10
	v_ashrrev_i32_e32 v8, 3, v2
	s_addc_u32 s11, s59, s11
	v_lshlrev_b32_e32 v4, 6, v8
	v_lshlrev_b32_e32 v5, 3, v1
	v_ashrrev_i32_e32 v9, 31, v8
	v_mul_lo_u32 v2, v8, s80
	v_sub_u32_e32 v10, v5, v4
	v_lshl_add_u64 v[8:9], s[34:35], 0, v[8:9]
	v_mov_b64_e32 v[12:13], s[10:11]
	v_add_lshl_u32 v2, v10, v2, 1
	v_mad_u64_u32 v[14:15], s[10:11], v8, s31, v[12:13]
	ds_read_b128 v[4:7], v2
	v_mov_b32_e32 v2, v15
	v_mad_u64_u32 v[8:9], s[10:11], v9, s31, v[2:3]
	v_add_u32_e32 v2, 0x100, v1
	v_mov_b32_e32 v15, v8
	v_ashrrev_i32_e32 v8, 31, v2
	v_lshrrev_b32_e32 v8, 29, v8
	v_add_u32_e32 v8, v2, v8
	v_ashrrev_i32_e32 v16, 3, v8
	v_ashrrev_i32_e32 v11, 31, v10
	v_lshlrev_b32_e32 v9, 6, v16
	v_lshlrev_b32_e32 v2, 3, v2
	v_lshl_add_u64 v[14:15], v[10:11], 1, v[14:15]
	v_mul_lo_u32 v8, v16, s80
	v_sub_u32_e32 v18, v2, v9
	v_ashrrev_i32_e32 v17, 31, v16
	v_add_lshl_u32 v2, v18, v8, 1
	s_waitcnt lgkmcnt(0)
	global_store_dwordx4 v[14:15], v[4:7], off
	ds_read_b128 v[8:11], v2
	v_ashrrev_i32_e32 v19, 31, v18
	v_lshl_add_u64 v[4:5], s[34:35], 0, v[16:17]
	v_mad_u64_u32 v[6:7], s[10:11], v4, s31, v[12:13]
	v_mov_b32_e32 v2, v7
	v_mad_u64_u32 v[4:5], s[10:11], v5, s31, v[2:3]
	v_mov_b32_e32 v7, v4
	v_lshl_add_u64 v[4:5], v[18:19], 1, v[6:7]
	v_add_u32_e32 v2, 0x200, v1
	s_waitcnt lgkmcnt(0)
	global_store_dwordx4 v[4:5], v[8:11], off
	v_ashrrev_i32_e32 v4, 31, v2
	v_lshrrev_b32_e32 v4, 29, v4
	v_add_u32_e32 v4, v2, v4
	v_ashrrev_i32_e32 v8, 3, v4
	v_lshlrev_b32_e32 v5, 6, v8
	v_lshlrev_b32_e32 v2, 3, v2
	v_ashrrev_i32_e32 v9, 31, v8
	v_mul_lo_u32 v4, v8, s80
	v_sub_u32_e32 v10, v2, v5
	v_lshl_add_u64 v[8:9], s[34:35], 0, v[8:9]
	v_add_lshl_u32 v2, v10, v4, 1
	v_mad_u64_u32 v[14:15], s[10:11], v8, s31, v[12:13]
	ds_read_b128 v[4:7], v2
	v_mov_b32_e32 v2, v15
	v_mad_u64_u32 v[8:9], s[10:11], v9, s31, v[2:3]
	v_add_u32_e32 v2, 0x300, v1
	v_mov_b32_e32 v15, v8
	v_ashrrev_i32_e32 v8, 31, v2
	v_lshrrev_b32_e32 v8, 29, v8
	v_add_u32_e32 v8, v2, v8
	v_ashrrev_i32_e32 v16, 3, v8
	v_ashrrev_i32_e32 v11, 31, v10
	v_lshlrev_b32_e32 v9, 6, v16
	v_lshlrev_b32_e32 v2, 3, v2
	v_lshl_add_u64 v[14:15], v[10:11], 1, v[14:15]
	v_mul_lo_u32 v8, v16, s80
	v_sub_u32_e32 v18, v2, v9
	v_ashrrev_i32_e32 v17, 31, v16
	v_add_lshl_u32 v2, v18, v8, 1
	s_waitcnt lgkmcnt(0)
	global_store_dwordx4 v[14:15], v[4:7], off
	ds_read_b128 v[8:11], v2
	v_ashrrev_i32_e32 v19, 31, v18
	v_lshl_add_u64 v[4:5], s[34:35], 0, v[16:17]
	v_mad_u64_u32 v[6:7], s[10:11], v4, s31, v[12:13]
	v_mov_b32_e32 v2, v7
	v_mad_u64_u32 v[4:5], s[10:11], v5, s31, v[2:3]
	v_mov_b32_e32 v7, v4
	v_lshl_add_u64 v[4:5], v[18:19], 1, v[6:7]
	v_add_u32_e32 v2, 0x400, v1
	s_waitcnt lgkmcnt(0)
	global_store_dwordx4 v[4:5], v[8:11], off
	v_ashrrev_i32_e32 v4, 31, v2
	v_lshrrev_b32_e32 v4, 29, v4
	v_add_u32_e32 v4, v2, v4
	v_ashrrev_i32_e32 v8, 3, v4
	v_lshlrev_b32_e32 v5, 6, v8
	v_lshlrev_b32_e32 v2, 3, v2
	v_ashrrev_i32_e32 v9, 31, v8
	v_mul_lo_u32 v4, v8, s80
	v_sub_u32_e32 v10, v2, v5
	v_lshl_add_u64 v[8:9], s[34:35], 0, v[8:9]
	v_add_lshl_u32 v2, v10, v4, 1
	v_mad_u64_u32 v[14:15], s[10:11], v8, s31, v[12:13]
	ds_read_b128 v[4:7], v2
	v_mov_b32_e32 v2, v15
	v_mad_u64_u32 v[8:9], s[10:11], v9, s31, v[2:3]
	v_add_u32_e32 v2, 0x500, v1
	v_mov_b32_e32 v15, v8
	v_ashrrev_i32_e32 v8, 31, v2
	v_lshrrev_b32_e32 v8, 29, v8
	v_add_u32_e32 v8, v2, v8
	v_ashrrev_i32_e32 v16, 3, v8
	v_ashrrev_i32_e32 v11, 31, v10
	v_lshlrev_b32_e32 v9, 6, v16
	v_lshlrev_b32_e32 v2, 3, v2
	v_lshl_add_u64 v[14:15], v[10:11], 1, v[14:15]
	v_mul_lo_u32 v8, v16, s80
	v_sub_u32_e32 v18, v2, v9
	v_ashrrev_i32_e32 v17, 31, v16
	v_add_lshl_u32 v2, v18, v8, 1
	s_waitcnt lgkmcnt(0)
	global_store_dwordx4 v[14:15], v[4:7], off
	ds_read_b128 v[8:11], v2
	v_ashrrev_i32_e32 v19, 31, v18
	v_lshl_add_u64 v[4:5], s[34:35], 0, v[16:17]
	v_mad_u64_u32 v[6:7], s[10:11], v4, s31, v[12:13]
	v_mov_b32_e32 v2, v7
	v_mad_u64_u32 v[4:5], s[10:11], v5, s31, v[2:3]
	v_mov_b32_e32 v7, v4
	v_lshl_add_u64 v[4:5], v[18:19], 1, v[6:7]
	v_add_u32_e32 v2, 0x600, v1
	s_waitcnt lgkmcnt(0)
	global_store_dwordx4 v[4:5], v[8:11], off
	v_ashrrev_i32_e32 v4, 31, v2
	v_lshrrev_b32_e32 v4, 29, v4
	v_add_u32_e32 v4, v2, v4
	v_ashrrev_i32_e32 v8, 3, v4
	v_lshlrev_b32_e32 v5, 6, v8
	v_lshlrev_b32_e32 v2, 3, v2
	v_ashrrev_i32_e32 v9, 31, v8
	v_mul_lo_u32 v4, v8, s80
	v_sub_u32_e32 v10, v2, v5
	v_lshl_add_u64 v[8:9], s[34:35], 0, v[8:9]
	v_add_lshl_u32 v2, v10, v4, 1
	v_mad_u64_u32 v[14:15], s[10:11], v8, s31, v[12:13]
	ds_read_b128 v[4:7], v2
	v_mov_b32_e32 v2, v15
	v_add_u32_e32 v1, 0x700, v1
	v_mad_u64_u32 v[8:9], s[10:11], v9, s31, v[2:3]
	v_ashrrev_i32_e32 v2, 31, v1
	v_lshrrev_b32_e32 v2, 29, v2
	v_add_u32_e32 v2, v1, v2
	v_mov_b32_e32 v15, v8
	v_ashrrev_i32_e32 v11, 31, v10
	v_ashrrev_i32_e32 v16, 3, v2
	v_lshl_add_u64 v[14:15], v[10:11], 1, v[14:15]
	v_lshlrev_b32_e32 v8, 6, v16
	v_lshlrev_b32_e32 v1, 3, v1
	v_ashrrev_i32_e32 v17, 31, v16
	v_mul_lo_u32 v2, v16, s80
	v_sub_u32_e32 v18, v1, v8
	s_waitcnt lgkmcnt(0)
	global_store_dwordx4 v[14:15], v[4:7], off
	v_add_lshl_u32 v1, v18, v2, 1
	ds_read_b128 v[8:11], v1
	v_lshl_add_u64 v[4:5], s[34:35], 0, v[16:17]
	v_mad_u64_u32 v[6:7], s[10:11], v4, s31, v[12:13]
	v_mov_b32_e32 v2, v7
	v_mad_u64_u32 v[4:5], s[10:11], v5, s31, v[2:3]
	v_readlane_b32 s10, v252, 59
	v_mov_b32_e32 v7, v4
	v_ashrrev_i32_e32 v19, 31, v18
	s_add_i32 s2, s2, s10
	v_lshl_add_u64 v[4:5], v[18:19], 1, v[6:7]
	s_cmpk_gt_i32 s2, 0x15ff
	s_waitcnt lgkmcnt(0)
	global_store_dwordx4 v[4:5], v[8:11], off
	s_barrier
	v_readlane_b32 s11, v252, 60
	s_cbranch_scc0 .LBB0_935
